# hyena FFT passes: each ds_read2_b64 split into two ds_read_b64 (LDS table: 256 vs 128 B/clk), lgkmcnt waits recounted
# baseline (speedup 1.0000x reference)
; __device__ __forceinline__ float2 cmul(float2 a, float2 b) { return make_float2(a.x * b.x - a.y * b.y, a.x * b.y + a.y * b.x); }
; template <int R, bool INV>
; __device__ __forceinline__ void butterflies(c32 (&v)[1 << R], float turns0) {
;     ...
;   for (int kk = 0; kk < R; ++kk) {
;     const int k = INV ? (R - 1 - kk) : kk;
;     const int hd = RAD >> (k + 1);
; #pragma unroll
;     for (int j = 0; j < RAD; ++j) {
;       if ((j & hd) == 0) {
;         const int m = (j & (hd - 1)) * (16 / hd);
;         const float2 c = make_float2(TC[m], INV ? TS[m] : -TS[m]);
;         const float2 twf = cmul(tbs[k], c);
;         const c32 tw = {twf.x, twf.y};
;         const c32 a = v[j], b = v[j + hd];
;         if (!INV) { v[j] = a + b; v[j + hd] = cmul_pk(a - b, tw); }
;         else { const c32 bt = cmul_pk(b, tw); v[j] = a + bt; v[j + hd] = a - bt; }
; template <int LOGN, int R, int DLOG, bool INV, int MODE, class F>
; __device__ __forceinline__ void fft_pass(float2* X, const F& f) {
;     ...
;   for (int g = tid0; g < NGR; g += 512) {
;     const int lo = g & (dmin - 1), base = gbase(g), pb = phys(base);
;     c32 v[RAD];
;     if constexpr (MODE == 1) {
; #pragma unroll
;       for (int j = 0; j < RAD; ++j) v[j] = nxt[j];
;       if (g + 512 < NGR) fetch(g + 512, nxt);
;     } else {
; #pragma unroll
;       for (int j = 0; j < RAD; ++j) v[j] = Xc[(DLOG >= 5) ? pb + j * PSTEP : phys(base + (j << DLOG))];
.LBB0_658:
	v_and_b32_e32 v66, 0xfffffc00, v65
	v_ashrrev_i32_e32 v67, 2, v66
	v_add_u32_e32 v67, 0, v67
	v_lshlrev_b32_e32 v66, 3, v66
	v_lshlrev_b32_e32 v68, 3, v32
	v_add3_u32 v132, v67, v66, v68
	v_add_u32_e32 v133, 0x800, v132
	v_add_u32_e32 v134, 0x1000, v132
	ds_read_b64 v[66:67], v132
	ds_read_b64 v[68:69], v132 offset:264
	ds_read_b64 v[70:71], v132 offset:528
	ds_read_b64 v[72:73], v132 offset:792
	ds_read_b64 v[74:75], v132 offset:1056
	ds_read_b64 v[76:77], v132 offset:1320
	ds_read_b64 v[78:79], v132 offset:1584
	ds_read_b64 v[80:81], v132 offset:1848
	ds_read_b64 v[82:83], v133 offset:64
	ds_read_b64 v[84:85], v133 offset:328
	ds_read_b64 v[86:87], v133 offset:592
	ds_read_b64 v[88:89], v133 offset:856
	ds_read_b64 v[90:91], v133 offset:1120
	ds_read_b64 v[92:93], v133 offset:1384
	ds_read_b64 v[94:95], v133 offset:1648
	ds_read_b64 v[96:97], v133 offset:1912
	ds_read_b64 v[98:99], v134 offset:128
	ds_read_b64 v[100:101], v134 offset:392
	ds_read_b64 v[102:103], v134 offset:656
	ds_read_b64 v[104:105], v134 offset:920
	ds_read_b64 v[106:107], v134 offset:1184
	ds_read_b64 v[108:109], v134 offset:1448
	ds_read_b64 v[110:111], v134 offset:1712
	ds_read_b64 v[112:113], v134 offset:1976
	v_add_u32_e32 v135, 0x1800, v132
	s_waitcnt lgkmcnt(6)
	v_pk_add_f32 v[130:131], v[66:67], v[98:99]
	v_pk_add_f32 v[66:67], v[66:67], v[98:99] neg_lo:[0,1] neg_hi:[0,1]
	ds_read_b64 v[114:115], v135 offset:192
	ds_read_b64 v[116:117], v135 offset:456
	ds_read_b64 v[118:119], v135 offset:720
	ds_read_b64 v[120:121], v135 offset:984
	ds_read_b64 v[122:123], v135 offset:1248
	ds_read_b64 v[124:125], v135 offset:1512
	ds_read_b64 v[126:127], v135 offset:1776
	ds_read_b64 v[128:129], v135 offset:2040
	v_pk_mul_f32 v[98:99], v[66:67], v[0:1] op_sel:[0,0] op_sel_hi:[0,1]
	v_add_u32_e32 v64, 0x200, v64
	v_pk_fma_f32 v[66:67], v[66:67], v[0:1], v[98:99] op_sel:[1,1,0] op_sel_hi:[1,0,1] neg_lo:[0,1,0]
	v_pk_add_f32 v[98:99], v[68:69], v[100:101]
	v_pk_add_f32 v[68:69], v[68:69], v[100:101] neg_lo:[0,1] neg_hi:[0,1]
	v_cmp_lt_i32_e32 vcc, -1, v64
	v_pk_mul_f32 v[100:101], v[68:69], v[24:25] op_sel:[0,0] op_sel_hi:[0,1]
	v_add_u32_e32 v65, 0x4000, v65
	v_pk_fma_f32 v[68:69], v[68:69], v[24:25], v[100:101] op_sel:[1,1,0] op_sel_hi:[1,0,1] neg_lo:[0,1,0]
	s_waitcnt lgkmcnt(12)
	v_pk_add_f32 v[100:101], v[70:71], v[102:103]
	v_pk_add_f32 v[70:71], v[70:71], v[102:103] neg_lo:[0,1] neg_hi:[0,1]
	s_or_b64 s[24:25], vcc, s[24:25]
	v_pk_mul_f32 v[102:103], v[70:71], v[16:17] op_sel:[0,0] op_sel_hi:[0,1]
	s_nop 0
	v_pk_fma_f32 v[70:71], v[70:71], v[16:17], v[102:103] op_sel:[1,1,0] op_sel_hi:[1,0,1] neg_lo:[0,1,0]
	v_pk_add_f32 v[102:103], v[72:73], v[104:105]
	v_pk_add_f32 v[72:73], v[72:73], v[104:105] neg_lo:[0,1] neg_hi:[0,1]
	s_nop 0
	v_pk_mul_f32 v[104:105], v[72:73], v[8:9] op_sel:[0,0] op_sel_hi:[0,1]
	s_nop 0
	v_pk_fma_f32 v[72:73], v[72:73], v[8:9], v[104:105] op_sel:[1,1,0] op_sel_hi:[1,0,1] neg_lo:[0,1,0]
	s_waitcnt lgkmcnt(10)
	v_pk_add_f32 v[104:105], v[74:75], v[106:107]
	v_pk_add_f32 v[74:75], v[74:75], v[106:107] neg_lo:[0,1] neg_hi:[0,1]
	s_nop 0
	v_pk_mul_f32 v[106:107], v[74:75], v[4:5] op_sel:[0,0] op_sel_hi:[0,1]
	s_nop 0
	v_pk_fma_f32 v[74:75], v[74:75], v[4:5], v[106:107] op_sel:[1,1,0] op_sel_hi:[1,0,1] neg_lo:[0,1,0]
	v_pk_add_f32 v[106:107], v[76:77], v[108:109]
	v_pk_add_f32 v[76:77], v[76:77], v[108:109] neg_lo:[0,1] neg_hi:[0,1]
	s_nop 0
	v_pk_mul_f32 v[108:109], v[76:77], v[14:15] op_sel:[0,0] op_sel_hi:[0,1]
	s_nop 0
	v_pk_fma_f32 v[76:77], v[76:77], v[14:15], v[108:109] op_sel:[1,1,0] op_sel_hi:[1,0,1] neg_lo:[0,1,0]
	s_waitcnt lgkmcnt(8)
	v_pk_add_f32 v[108:109], v[78:79], v[110:111]
	v_pk_add_f32 v[78:79], v[78:79], v[110:111] neg_lo:[0,1] neg_hi:[0,1]
	s_nop 0
	v_pk_mul_f32 v[110:111], v[78:79], v[22:23] op_sel:[0,0] op_sel_hi:[0,1]
	s_nop 0
	v_pk_fma_f32 v[78:79], v[78:79], v[22:23], v[110:111] op_sel:[1,1,0] op_sel_hi:[1,0,1] neg_lo:[0,1,0]
	v_pk_add_f32 v[110:111], v[80:81], v[112:113]
	v_pk_add_f32 v[80:81], v[80:81], v[112:113] neg_lo:[0,1] neg_hi:[0,1]
	s_nop 0
	v_pk_mul_f32 v[112:113], v[80:81], v[30:31] op_sel:[0,0] op_sel_hi:[0,1]
	s_nop 0
	v_pk_fma_f32 v[80:81], v[80:81], v[30:31], v[112:113] op_sel:[1,1,0] op_sel_hi:[1,0,1] neg_lo:[0,1,0]
	s_waitcnt lgkmcnt(6)
	v_pk_add_f32 v[112:113], v[82:83], v[114:115]
	v_pk_add_f32 v[82:83], v[82:83], v[114:115] neg_lo:[0,1] neg_hi:[0,1]
	s_nop 0
	v_pk_mul_f32 v[114:115], v[82:83], v[2:3] op_sel:[0,0] op_sel_hi:[0,1]
	s_nop 0
	v_pk_fma_f32 v[82:83], v[82:83], v[2:3], v[114:115] op_sel:[1,1,0] op_sel_hi:[1,0,1] neg_lo:[0,1,0]
	v_pk_add_f32 v[114:115], v[84:85], v[116:117]
	v_pk_add_f32 v[84:85], v[84:85], v[116:117] neg_lo:[0,1] neg_hi:[0,1]
	s_nop 0
	v_pk_mul_f32 v[116:117], v[84:85], v[28:29] op_sel:[0,0] op_sel_hi:[0,1]
	s_nop 0
	v_pk_fma_f32 v[84:85], v[84:85], v[28:29], v[116:117] op_sel:[1,1,0] op_sel_hi:[1,0,1] neg_lo:[0,1,0]
	s_waitcnt lgkmcnt(4)
	v_pk_add_f32 v[116:117], v[86:87], v[118:119]
	v_pk_add_f32 v[86:87], v[86:87], v[118:119] neg_lo:[0,1] neg_hi:[0,1]
	s_nop 0
	v_pk_mul_f32 v[118:119], v[86:87], v[20:21] op_sel:[0,0] op_sel_hi:[0,1]
	s_nop 0
	v_pk_fma_f32 v[86:87], v[86:87], v[20:21], v[118:119] op_sel:[1,1,0] op_sel_hi:[1,0,1] neg_lo:[0,1,0]
	v_pk_add_f32 v[118:119], v[88:89], v[120:121]
	v_pk_add_f32 v[88:89], v[88:89], v[120:121] neg_lo:[0,1] neg_hi:[0,1]
	s_nop 0
	v_pk_mul_f32 v[120:121], v[88:89], v[12:13] op_sel:[0,0] op_sel_hi:[0,1]
	s_nop 0
	v_pk_fma_f32 v[88:89], v[88:89], v[12:13], v[120:121] op_sel:[1,1,0] op_sel_hi:[1,0,1] neg_lo:[0,1,0]
	s_waitcnt lgkmcnt(2)
; __device__ __forceinline__ float2 cmul(float2 a, float2 b) { return make_float2(a.x * b.x - a.y * b.y, a.x * b.y + a.y * b.x); }
; template <int R, bool INV>
; __device__ __forceinline__ void butterflies(c32 (&v)[1 << R], float turns0) {
;     ...
;   for (int kk = 0; kk < R; ++kk) {
;     const int k = INV ? (R - 1 - kk) : kk;
;     const int hd = RAD >> (k + 1);
; #pragma unroll
;     for (int j = 0; j < RAD; ++j) {
;       if ((j & hd) == 0) {
;         const int m = (j & (hd - 1)) * (16 / hd);
;         const float2 c = make_float2(TC[m], INV ? TS[m] : -TS[m]);
;         const float2 twf = cmul(tbs[k], c);
;         const c32 tw = {twf.x, twf.y};
;         const c32 a = v[j], b = v[j + hd];
;         if (!INV) { v[j] = a + b; v[j + hd] = cmul_pk(a - b, tw); }
;         else { const c32 bt = cmul_pk(b, tw); v[j] = a + bt; v[j + hd] = a - bt; }
	v_pk_add_f32 v[120:121], v[90:91], v[122:123]
	v_pk_add_f32 v[90:91], v[90:91], v[122:123] neg_lo:[0,1] neg_hi:[0,1]
	s_nop 0
	v_pk_mul_f32 v[122:123], v[90:91], v[6:7] op_sel:[0,0] op_sel_hi:[0,1]
	s_nop 0
	v_pk_fma_f32 v[90:91], v[90:91], v[6:7], v[122:123] op_sel:[1,1,0] op_sel_hi:[1,0,1] neg_lo:[0,1,0]
	v_pk_add_f32 v[122:123], v[92:93], v[124:125]
	v_pk_add_f32 v[92:93], v[92:93], v[124:125] neg_lo:[0,1] neg_hi:[0,1]
	s_nop 0
	v_pk_mul_f32 v[124:125], v[92:93], v[10:11] op_sel:[0,0] op_sel_hi:[0,1]
	s_nop 0
	v_pk_fma_f32 v[92:93], v[92:93], v[10:11], v[124:125] op_sel:[1,1,0] op_sel_hi:[1,0,1] neg_lo:[0,1,0]
	s_waitcnt lgkmcnt(0)
	v_pk_add_f32 v[124:125], v[94:95], v[126:127]
	v_pk_add_f32 v[94:95], v[94:95], v[126:127] neg_lo:[0,1] neg_hi:[0,1]
	s_nop 0
	v_pk_mul_f32 v[126:127], v[94:95], v[18:19] op_sel:[0,0] op_sel_hi:[0,1]
	s_nop 0
	v_pk_fma_f32 v[94:95], v[94:95], v[18:19], v[126:127] op_sel:[1,1,0] op_sel_hi:[1,0,1] neg_lo:[0,1,0]
	v_pk_add_f32 v[126:127], v[96:97], v[128:129]
	v_pk_add_f32 v[96:97], v[96:97], v[128:129] neg_lo:[0,1] neg_hi:[0,1]
	s_nop 0
	v_pk_mul_f32 v[128:129], v[96:97], v[26:27] op_sel:[0,0] op_sel_hi:[0,1]
	s_nop 0
	v_pk_fma_f32 v[96:97], v[96:97], v[26:27], v[128:129] op_sel:[1,1,0] op_sel_hi:[1,0,1] neg_lo:[0,1,0]
	v_pk_add_f32 v[128:129], v[130:131], v[112:113]
	v_pk_add_f32 v[112:113], v[130:131], v[112:113] neg_lo:[0,1] neg_hi:[0,1]
	s_nop 0
	v_pk_mul_f32 v[130:131], v[112:113], v[34:35] op_sel:[0,0] op_sel_hi:[0,1]
	s_nop 0
	v_pk_fma_f32 v[112:113], v[112:113], v[34:35], v[130:131] op_sel:[1,1,0] op_sel_hi:[1,0,1] neg_lo:[0,1,0]
	v_pk_add_f32 v[130:131], v[98:99], v[114:115]
	v_pk_add_f32 v[98:99], v[98:99], v[114:115] neg_lo:[0,1] neg_hi:[0,1]
	s_nop 0
	v_pk_mul_f32 v[114:115], v[98:99], v[42:43] op_sel:[0,0] op_sel_hi:[0,1]
	s_nop 0
	v_pk_fma_f32 v[98:99], v[98:99], v[42:43], v[114:115] op_sel:[1,1,0] op_sel_hi:[1,0,1] neg_lo:[0,1,0]
	v_pk_add_f32 v[114:115], v[100:101], v[116:117]
	v_pk_add_f32 v[100:101], v[100:101], v[116:117] neg_lo:[0,1] neg_hi:[0,1]
	s_nop 0
	v_pk_mul_f32 v[116:117], v[100:101], v[38:39] op_sel:[0,0] op_sel_hi:[0,1]
	s_nop 0
	v_pk_fma_f32 v[100:101], v[100:101], v[38:39], v[116:117] op_sel:[1,1,0] op_sel_hi:[1,0,1] neg_lo:[0,1,0]
	v_pk_add_f32 v[116:117], v[102:103], v[118:119]
	v_pk_add_f32 v[102:103], v[102:103], v[118:119] neg_lo:[0,1] neg_hi:[0,1]
	s_nop 0
	v_pk_mul_f32 v[118:119], v[102:103], v[48:49] op_sel:[0,0] op_sel_hi:[0,1]
	s_nop 0
	v_pk_fma_f32 v[102:103], v[102:103], v[48:49], v[118:119] op_sel:[1,1,0] op_sel_hi:[1,0,1] neg_lo:[0,1,0]
	v_pk_add_f32 v[118:119], v[104:105], v[120:121]
	v_pk_add_f32 v[104:105], v[104:105], v[120:121] neg_lo:[0,1] neg_hi:[0,1]
	s_nop 0
	v_pk_mul_f32 v[120:121], v[104:105], v[36:37] op_sel:[0,0] op_sel_hi:[0,1]
	s_nop 0
	v_pk_fma_f32 v[104:105], v[104:105], v[36:37], v[120:121] op_sel:[1,1,0] op_sel_hi:[1,0,1] neg_lo:[0,1,0]
	v_pk_add_f32 v[120:121], v[106:107], v[122:123]
	v_pk_add_f32 v[106:107], v[106:107], v[122:123] neg_lo:[0,1] neg_hi:[0,1]
	s_nop 0
	v_pk_mul_f32 v[122:123], v[106:107], v[46:47] op_sel:[0,0] op_sel_hi:[0,1]
	s_nop 0
	v_pk_fma_f32 v[106:107], v[106:107], v[46:47], v[122:123] op_sel:[1,1,0] op_sel_hi:[1,0,1] neg_lo:[0,1,0]
	v_pk_add_f32 v[122:123], v[108:109], v[124:125]
	v_pk_add_f32 v[108:109], v[108:109], v[124:125] neg_lo:[0,1] neg_hi:[0,1]
	s_nop 0
	v_pk_mul_f32 v[124:125], v[108:109], v[40:41] op_sel:[0,0] op_sel_hi:[0,1]
	s_nop 0
	v_pk_fma_f32 v[108:109], v[108:109], v[40:41], v[124:125] op_sel:[1,1,0] op_sel_hi:[1,0,1] neg_lo:[0,1,0]
	v_pk_add_f32 v[124:125], v[110:111], v[126:127]
	v_pk_add_f32 v[110:111], v[110:111], v[126:127] neg_lo:[0,1] neg_hi:[0,1]
	s_nop 0
	v_pk_mul_f32 v[126:127], v[110:111], v[44:45] op_sel:[0,0] op_sel_hi:[0,1]
	s_nop 0
	v_pk_fma_f32 v[110:111], v[110:111], v[44:45], v[126:127] op_sel:[1,1,0] op_sel_hi:[1,0,1] neg_lo:[0,1,0]
	v_pk_add_f32 v[126:127], v[66:67], v[82:83]
	v_pk_add_f32 v[66:67], v[66:67], v[82:83] neg_lo:[0,1] neg_hi:[0,1]
	s_nop 0
	v_pk_mul_f32 v[82:83], v[66:67], v[34:35] op_sel:[0,0] op_sel_hi:[0,1]
	s_nop 0
	v_pk_fma_f32 v[66:67], v[66:67], v[34:35], v[82:83] op_sel:[1,1,0] op_sel_hi:[1,0,1] neg_lo:[0,1,0]
	v_pk_add_f32 v[82:83], v[68:69], v[84:85]
	v_pk_add_f32 v[68:69], v[68:69], v[84:85] neg_lo:[0,1] neg_hi:[0,1]
	s_nop 0
	v_pk_mul_f32 v[84:85], v[68:69], v[42:43] op_sel:[0,0] op_sel_hi:[0,1]
	s_nop 0
	v_pk_fma_f32 v[68:69], v[68:69], v[42:43], v[84:85] op_sel:[1,1,0] op_sel_hi:[1,0,1] neg_lo:[0,1,0]
	v_pk_add_f32 v[84:85], v[70:71], v[86:87]
	v_pk_add_f32 v[70:71], v[70:71], v[86:87] neg_lo:[0,1] neg_hi:[0,1]
	s_nop 0
	v_pk_mul_f32 v[86:87], v[70:71], v[38:39] op_sel:[0,0] op_sel_hi:[0,1]
	s_nop 0
	v_pk_fma_f32 v[70:71], v[70:71], v[38:39], v[86:87] op_sel:[1,1,0] op_sel_hi:[1,0,1] neg_lo:[0,1,0]
	v_pk_add_f32 v[86:87], v[72:73], v[88:89]
	v_pk_add_f32 v[72:73], v[72:73], v[88:89] neg_lo:[0,1] neg_hi:[0,1]
	s_nop 0
	v_pk_mul_f32 v[88:89], v[72:73], v[48:49] op_sel:[0,0] op_sel_hi:[0,1]
	s_nop 0
	v_pk_fma_f32 v[72:73], v[72:73], v[48:49], v[88:89] op_sel:[1,1,0] op_sel_hi:[1,0,1] neg_lo:[0,1,0]
	v_pk_add_f32 v[88:89], v[74:75], v[90:91]
	v_pk_add_f32 v[74:75], v[74:75], v[90:91] neg_lo:[0,1] neg_hi:[0,1]
	s_nop 0
	v_pk_mul_f32 v[90:91], v[74:75], v[36:37] op_sel:[0,0] op_sel_hi:[0,1]
	s_nop 0
	v_pk_fma_f32 v[74:75], v[74:75], v[36:37], v[90:91] op_sel:[1,1,0] op_sel_hi:[1,0,1] neg_lo:[0,1,0]
	v_pk_add_f32 v[90:91], v[76:77], v[92:93]
	v_pk_add_f32 v[76:77], v[76:77], v[92:93] neg_lo:[0,1] neg_hi:[0,1]
	s_nop 0
	v_pk_mul_f32 v[92:93], v[76:77], v[46:47] op_sel:[0,0] op_sel_hi:[0,1]
	s_nop 0
	v_pk_fma_f32 v[76:77], v[76:77], v[46:47], v[92:93] op_sel:[1,1,0] op_sel_hi:[1,0,1] neg_lo:[0,1,0]
; __device__ __forceinline__ float2 cmul(float2 a, float2 b) { return make_float2(a.x * b.x - a.y * b.y, a.x * b.y + a.y * b.x); }
; template <int R, bool INV>
; __device__ __forceinline__ void butterflies(c32 (&v)[1 << R], float turns0) {
;     ...
;   for (int kk = 0; kk < R; ++kk) {
;     const int k = INV ? (R - 1 - kk) : kk;
;     const int hd = RAD >> (k + 1);
; #pragma unroll
;     for (int j = 0; j < RAD; ++j) {
;       if ((j & hd) == 0) {
;         const int m = (j & (hd - 1)) * (16 / hd);
;         const float2 c = make_float2(TC[m], INV ? TS[m] : -TS[m]);
;         const float2 twf = cmul(tbs[k], c);
;         const c32 tw = {twf.x, twf.y};
;         const c32 a = v[j], b = v[j + hd];
;         if (!INV) { v[j] = a + b; v[j + hd] = cmul_pk(a - b, tw); }
;         else { const c32 bt = cmul_pk(b, tw); v[j] = a + bt; v[j + hd] = a - bt; }
	v_pk_add_f32 v[92:93], v[78:79], v[94:95]
	v_pk_add_f32 v[78:79], v[78:79], v[94:95] neg_lo:[0,1] neg_hi:[0,1]
	s_nop 0
	v_pk_mul_f32 v[94:95], v[78:79], v[40:41] op_sel:[0,0] op_sel_hi:[0,1]
	s_nop 0
	v_pk_fma_f32 v[78:79], v[78:79], v[40:41], v[94:95] op_sel:[1,1,0] op_sel_hi:[1,0,1] neg_lo:[0,1,0]
	v_pk_add_f32 v[94:95], v[80:81], v[96:97]
	v_pk_add_f32 v[80:81], v[80:81], v[96:97] neg_lo:[0,1] neg_hi:[0,1]
	s_nop 0
	v_pk_mul_f32 v[96:97], v[80:81], v[44:45] op_sel:[0,0] op_sel_hi:[0,1]
	s_nop 0
	v_pk_fma_f32 v[80:81], v[80:81], v[44:45], v[96:97] op_sel:[1,1,0] op_sel_hi:[1,0,1] neg_lo:[0,1,0]
	v_pk_add_f32 v[96:97], v[128:129], v[118:119]
	v_pk_add_f32 v[118:119], v[128:129], v[118:119] neg_lo:[0,1] neg_hi:[0,1]
	s_nop 0
	v_pk_mul_f32 v[128:129], v[118:119], v[50:51] op_sel:[0,0] op_sel_hi:[0,1]
	s_nop 0
	v_pk_fma_f32 v[118:119], v[118:119], v[50:51], v[128:129] op_sel:[1,1,0] op_sel_hi:[1,0,1] neg_lo:[0,1,0]
	v_pk_add_f32 v[128:129], v[130:131], v[120:121]
	v_pk_add_f32 v[120:121], v[130:131], v[120:121] neg_lo:[0,1] neg_hi:[0,1]
	s_nop 0
	v_pk_mul_f32 v[130:131], v[120:121], v[54:55] op_sel:[0,0] op_sel_hi:[0,1]
	s_nop 0
	v_pk_fma_f32 v[120:121], v[120:121], v[54:55], v[130:131] op_sel:[1,1,0] op_sel_hi:[1,0,1] neg_lo:[0,1,0]
	v_pk_add_f32 v[130:131], v[114:115], v[122:123]
	v_pk_add_f32 v[114:115], v[114:115], v[122:123] neg_lo:[0,1] neg_hi:[0,1]
	s_nop 0
	v_pk_mul_f32 v[122:123], v[114:115], v[52:53] op_sel:[0,0] op_sel_hi:[0,1]
	s_nop 0
	v_pk_fma_f32 v[114:115], v[114:115], v[52:53], v[122:123] op_sel:[1,1,0] op_sel_hi:[1,0,1] neg_lo:[0,1,0]
	v_pk_add_f32 v[122:123], v[116:117], v[124:125]
	v_pk_add_f32 v[116:117], v[116:117], v[124:125] neg_lo:[0,1] neg_hi:[0,1]
	s_nop 0
	v_pk_mul_f32 v[124:125], v[116:117], v[56:57] op_sel:[0,0] op_sel_hi:[0,1]
	s_nop 0
	v_pk_fma_f32 v[116:117], v[116:117], v[56:57], v[124:125] op_sel:[1,1,0] op_sel_hi:[1,0,1] neg_lo:[0,1,0]
	v_pk_add_f32 v[124:125], v[112:113], v[104:105]
	v_pk_add_f32 v[104:105], v[112:113], v[104:105] neg_lo:[0,1] neg_hi:[0,1]
	s_nop 0
	v_pk_mul_f32 v[112:113], v[104:105], v[50:51] op_sel:[0,0] op_sel_hi:[0,1]
	s_nop 0
	v_pk_fma_f32 v[104:105], v[104:105], v[50:51], v[112:113] op_sel:[1,1,0] op_sel_hi:[1,0,1] neg_lo:[0,1,0]
	v_pk_add_f32 v[112:113], v[98:99], v[106:107]
	v_pk_add_f32 v[98:99], v[98:99], v[106:107] neg_lo:[0,1] neg_hi:[0,1]
	s_nop 0
	v_pk_mul_f32 v[106:107], v[98:99], v[54:55] op_sel:[0,0] op_sel_hi:[0,1]
	s_nop 0
	v_pk_fma_f32 v[98:99], v[98:99], v[54:55], v[106:107] op_sel:[1,1,0] op_sel_hi:[1,0,1] neg_lo:[0,1,0]
	v_pk_add_f32 v[106:107], v[100:101], v[108:109]
	v_pk_add_f32 v[100:101], v[100:101], v[108:109] neg_lo:[0,1] neg_hi:[0,1]
	s_nop 0
	v_pk_mul_f32 v[108:109], v[100:101], v[52:53] op_sel:[0,0] op_sel_hi:[0,1]
	s_nop 0
	v_pk_fma_f32 v[100:101], v[100:101], v[52:53], v[108:109] op_sel:[1,1,0] op_sel_hi:[1,0,1] neg_lo:[0,1,0]
	v_pk_add_f32 v[108:109], v[102:103], v[110:111]
	v_pk_add_f32 v[102:103], v[102:103], v[110:111] neg_lo:[0,1] neg_hi:[0,1]
	s_nop 0
	v_pk_mul_f32 v[110:111], v[102:103], v[56:57] op_sel:[0,0] op_sel_hi:[0,1]
	s_nop 0
	v_pk_fma_f32 v[102:103], v[102:103], v[56:57], v[110:111] op_sel:[1,1,0] op_sel_hi:[1,0,1] neg_lo:[0,1,0]
	v_pk_add_f32 v[110:111], v[126:127], v[88:89]
	v_pk_add_f32 v[88:89], v[126:127], v[88:89] neg_lo:[0,1] neg_hi:[0,1]
	s_nop 0
	v_pk_mul_f32 v[126:127], v[88:89], v[50:51] op_sel:[0,0] op_sel_hi:[0,1]
	s_nop 0
	v_pk_fma_f32 v[88:89], v[88:89], v[50:51], v[126:127] op_sel:[1,1,0] op_sel_hi:[1,0,1] neg_lo:[0,1,0]
	v_pk_add_f32 v[126:127], v[82:83], v[90:91]
	v_pk_add_f32 v[82:83], v[82:83], v[90:91] neg_lo:[0,1] neg_hi:[0,1]
	s_nop 0
	v_pk_mul_f32 v[90:91], v[82:83], v[54:55] op_sel:[0,0] op_sel_hi:[0,1]
	s_nop 0
	v_pk_fma_f32 v[82:83], v[82:83], v[54:55], v[90:91] op_sel:[1,1,0] op_sel_hi:[1,0,1] neg_lo:[0,1,0]
	v_pk_add_f32 v[90:91], v[84:85], v[92:93]
	v_pk_add_f32 v[84:85], v[84:85], v[92:93] neg_lo:[0,1] neg_hi:[0,1]
	s_nop 0
	v_pk_mul_f32 v[92:93], v[84:85], v[52:53] op_sel:[0,0] op_sel_hi:[0,1]
	s_nop 0
	v_pk_fma_f32 v[84:85], v[84:85], v[52:53], v[92:93] op_sel:[1,1,0] op_sel_hi:[1,0,1] neg_lo:[0,1,0]
	v_pk_add_f32 v[92:93], v[86:87], v[94:95]
	v_pk_add_f32 v[86:87], v[86:87], v[94:95] neg_lo:[0,1] neg_hi:[0,1]
	s_nop 0
	v_pk_mul_f32 v[94:95], v[86:87], v[56:57] op_sel:[0,0] op_sel_hi:[0,1]
	s_nop 0
	v_pk_fma_f32 v[86:87], v[86:87], v[56:57], v[94:95] op_sel:[1,1,0] op_sel_hi:[1,0,1] neg_lo:[0,1,0]
	v_pk_add_f32 v[94:95], v[66:67], v[74:75]
	v_pk_add_f32 v[66:67], v[66:67], v[74:75] neg_lo:[0,1] neg_hi:[0,1]
	s_nop 0
	v_pk_mul_f32 v[74:75], v[66:67], v[50:51] op_sel:[0,0] op_sel_hi:[0,1]
	s_nop 0
	v_pk_fma_f32 v[66:67], v[66:67], v[50:51], v[74:75] op_sel:[1,1,0] op_sel_hi:[1,0,1] neg_lo:[0,1,0]
	v_pk_add_f32 v[74:75], v[68:69], v[76:77]
	v_pk_add_f32 v[68:69], v[68:69], v[76:77] neg_lo:[0,1] neg_hi:[0,1]
	s_nop 0
	v_pk_mul_f32 v[76:77], v[68:69], v[54:55] op_sel:[0,0] op_sel_hi:[0,1]
	s_nop 0
	v_pk_fma_f32 v[68:69], v[68:69], v[54:55], v[76:77] op_sel:[1,1,0] op_sel_hi:[1,0,1] neg_lo:[0,1,0]
	v_pk_add_f32 v[76:77], v[70:71], v[78:79]
	v_pk_add_f32 v[70:71], v[70:71], v[78:79] neg_lo:[0,1] neg_hi:[0,1]
	s_nop 0
	v_pk_mul_f32 v[78:79], v[70:71], v[52:53] op_sel:[0,0] op_sel_hi:[0,1]
	s_nop 0
	v_pk_fma_f32 v[70:71], v[70:71], v[52:53], v[78:79] op_sel:[1,1,0] op_sel_hi:[1,0,1] neg_lo:[0,1,0]
	v_pk_add_f32 v[78:79], v[72:73], v[80:81]
	v_pk_add_f32 v[72:73], v[72:73], v[80:81] neg_lo:[0,1] neg_hi:[0,1]
	s_nop 0
	v_pk_mul_f32 v[80:81], v[72:73], v[56:57] op_sel:[0,0] op_sel_hi:[0,1]
	s_nop 0
	v_pk_fma_f32 v[72:73], v[72:73], v[56:57], v[80:81] op_sel:[1,1,0] op_sel_hi:[1,0,1] neg_lo:[0,1,0]
; __device__ __forceinline__ float2 cmul(float2 a, float2 b) { return make_float2(a.x * b.x - a.y * b.y, a.x * b.y + a.y * b.x); }
; template <int R, bool INV>
; __device__ __forceinline__ void butterflies(c32 (&v)[1 << R], float turns0) {
;     ...
;   for (int kk = 0; kk < R; ++kk) {
;     const int k = INV ? (R - 1 - kk) : kk;
;     const int hd = RAD >> (k + 1);
; #pragma unroll
;     for (int j = 0; j < RAD; ++j) {
;       if ((j & hd) == 0) {
;         const int m = (j & (hd - 1)) * (16 / hd);
;         const float2 c = make_float2(TC[m], INV ? TS[m] : -TS[m]);
;         const float2 twf = cmul(tbs[k], c);
;         const c32 tw = {twf.x, twf.y};
;         const c32 a = v[j], b = v[j + hd];
;         if (!INV) { v[j] = a + b; v[j + hd] = cmul_pk(a - b, tw); }
;         else { const c32 bt = cmul_pk(b, tw); v[j] = a + bt; v[j + hd] = a - bt; }
	v_pk_add_f32 v[80:81], v[96:97], v[130:131]
	v_pk_add_f32 v[96:97], v[96:97], v[130:131] neg_lo:[0,1] neg_hi:[0,1]
	s_nop 0
	v_pk_mul_f32 v[130:131], v[96:97], v[58:59] op_sel:[0,0] op_sel_hi:[0,1]
	s_nop 0
	v_pk_fma_f32 v[96:97], v[96:97], v[58:59], v[130:131] op_sel:[1,1,0] op_sel_hi:[1,0,1] neg_lo:[0,1,0]
	v_pk_add_f32 v[130:131], v[128:129], v[122:123]
	v_pk_add_f32 v[122:123], v[128:129], v[122:123] neg_lo:[0,1] neg_hi:[0,1]
	s_nop 0
	v_pk_mul_f32 v[128:129], v[122:123], v[60:61] op_sel:[0,0] op_sel_hi:[0,1]
	s_nop 0
	v_pk_fma_f32 v[122:123], v[122:123], v[60:61], v[128:129] op_sel:[1,1,0] op_sel_hi:[1,0,1] neg_lo:[0,1,0]
	v_pk_add_f32 v[128:129], v[118:119], v[114:115]
	v_pk_add_f32 v[114:115], v[118:119], v[114:115] neg_lo:[0,1] neg_hi:[0,1]
	s_nop 0
	v_pk_mul_f32 v[118:119], v[114:115], v[58:59] op_sel:[0,0] op_sel_hi:[0,1]
	s_nop 0
	v_pk_fma_f32 v[114:115], v[114:115], v[58:59], v[118:119] op_sel:[1,1,0] op_sel_hi:[1,0,1] neg_lo:[0,1,0]
	v_pk_add_f32 v[118:119], v[120:121], v[116:117]
	v_pk_add_f32 v[116:117], v[120:121], v[116:117] neg_lo:[0,1] neg_hi:[0,1]
	s_nop 0
	v_pk_mul_f32 v[120:121], v[116:117], v[60:61] op_sel:[0,0] op_sel_hi:[0,1]
	s_nop 0
	v_pk_fma_f32 v[116:117], v[116:117], v[60:61], v[120:121] op_sel:[1,1,0] op_sel_hi:[1,0,1] neg_lo:[0,1,0]
	v_pk_add_f32 v[120:121], v[124:125], v[106:107]
	v_pk_add_f32 v[106:107], v[124:125], v[106:107] neg_lo:[0,1] neg_hi:[0,1]
	s_nop 0
	v_pk_mul_f32 v[124:125], v[106:107], v[58:59] op_sel:[0,0] op_sel_hi:[0,1]
	s_nop 0
	v_pk_fma_f32 v[106:107], v[106:107], v[58:59], v[124:125] op_sel:[1,1,0] op_sel_hi:[1,0,1] neg_lo:[0,1,0]
	v_pk_add_f32 v[124:125], v[112:113], v[108:109]
	v_pk_add_f32 v[108:109], v[112:113], v[108:109] neg_lo:[0,1] neg_hi:[0,1]
	s_nop 0
	v_pk_mul_f32 v[112:113], v[108:109], v[60:61] op_sel:[0,0] op_sel_hi:[0,1]
	s_nop 0
	v_pk_fma_f32 v[108:109], v[108:109], v[60:61], v[112:113] op_sel:[1,1,0] op_sel_hi:[1,0,1] neg_lo:[0,1,0]
	v_pk_add_f32 v[112:113], v[104:105], v[100:101]
	v_pk_add_f32 v[100:101], v[104:105], v[100:101] neg_lo:[0,1] neg_hi:[0,1]
	s_nop 0
	v_pk_mul_f32 v[104:105], v[100:101], v[58:59] op_sel:[0,0] op_sel_hi:[0,1]
	s_nop 0
	v_pk_fma_f32 v[100:101], v[100:101], v[58:59], v[104:105] op_sel:[1,1,0] op_sel_hi:[1,0,1] neg_lo:[0,1,0]
	v_pk_add_f32 v[104:105], v[98:99], v[102:103]
	v_pk_add_f32 v[98:99], v[98:99], v[102:103] neg_lo:[0,1] neg_hi:[0,1]
	s_nop 0
	v_pk_mul_f32 v[102:103], v[98:99], v[60:61] op_sel:[0,0] op_sel_hi:[0,1]
	s_nop 0
	v_pk_fma_f32 v[98:99], v[98:99], v[60:61], v[102:103] op_sel:[1,1,0] op_sel_hi:[1,0,1] neg_lo:[0,1,0]
	v_pk_add_f32 v[102:103], v[110:111], v[90:91]
	v_pk_add_f32 v[90:91], v[110:111], v[90:91] neg_lo:[0,1] neg_hi:[0,1]
	s_nop 0
	v_pk_mul_f32 v[110:111], v[90:91], v[58:59] op_sel:[0,0] op_sel_hi:[0,1]
	s_nop 0
	v_pk_fma_f32 v[90:91], v[90:91], v[58:59], v[110:111] op_sel:[1,1,0] op_sel_hi:[1,0,1] neg_lo:[0,1,0]
	v_pk_add_f32 v[110:111], v[126:127], v[92:93]
	v_pk_add_f32 v[92:93], v[126:127], v[92:93] neg_lo:[0,1] neg_hi:[0,1]
	s_nop 0
	v_pk_mul_f32 v[126:127], v[92:93], v[60:61] op_sel:[0,0] op_sel_hi:[0,1]
	s_nop 0
	v_pk_fma_f32 v[92:93], v[92:93], v[60:61], v[126:127] op_sel:[1,1,0] op_sel_hi:[1,0,1] neg_lo:[0,1,0]
	v_pk_add_f32 v[126:127], v[88:89], v[84:85]
	v_pk_add_f32 v[84:85], v[88:89], v[84:85] neg_lo:[0,1] neg_hi:[0,1]
	s_nop 0
	v_pk_mul_f32 v[88:89], v[84:85], v[58:59] op_sel:[0,0] op_sel_hi:[0,1]
	s_nop 0
	v_pk_fma_f32 v[84:85], v[84:85], v[58:59], v[88:89] op_sel:[1,1,0] op_sel_hi:[1,0,1] neg_lo:[0,1,0]
	v_pk_add_f32 v[88:89], v[82:83], v[86:87]
	v_pk_add_f32 v[82:83], v[82:83], v[86:87] neg_lo:[0,1] neg_hi:[0,1]
	s_nop 0
	v_pk_mul_f32 v[86:87], v[82:83], v[60:61] op_sel:[0,0] op_sel_hi:[0,1]
	s_nop 0
	v_pk_fma_f32 v[82:83], v[82:83], v[60:61], v[86:87] op_sel:[1,1,0] op_sel_hi:[1,0,1] neg_lo:[0,1,0]
	v_pk_add_f32 v[86:87], v[94:95], v[76:77]
	v_pk_add_f32 v[76:77], v[94:95], v[76:77] neg_lo:[0,1] neg_hi:[0,1]
	s_nop 0
	v_pk_mul_f32 v[94:95], v[76:77], v[58:59] op_sel:[0,0] op_sel_hi:[0,1]
	s_nop 0
	v_pk_fma_f32 v[76:77], v[76:77], v[58:59], v[94:95] op_sel:[1,1,0] op_sel_hi:[1,0,1] neg_lo:[0,1,0]
	v_pk_add_f32 v[94:95], v[74:75], v[78:79]
	v_pk_add_f32 v[74:75], v[74:75], v[78:79] neg_lo:[0,1] neg_hi:[0,1]
	s_nop 0
	v_pk_mul_f32 v[78:79], v[74:75], v[60:61] op_sel:[0,0] op_sel_hi:[0,1]
	s_nop 0
	v_pk_fma_f32 v[74:75], v[74:75], v[60:61], v[78:79] op_sel:[1,1,0] op_sel_hi:[1,0,1] neg_lo:[0,1,0]
	v_pk_add_f32 v[78:79], v[66:67], v[70:71]
	v_pk_add_f32 v[66:67], v[66:67], v[70:71] neg_lo:[0,1] neg_hi:[0,1]
	s_nop 0
	v_pk_mul_f32 v[70:71], v[66:67], v[58:59] op_sel:[0,0] op_sel_hi:[0,1]
	s_nop 0
	v_pk_fma_f32 v[66:67], v[66:67], v[58:59], v[70:71] op_sel:[1,1,0] op_sel_hi:[1,0,1] neg_lo:[0,1,0]
	v_pk_add_f32 v[70:71], v[68:69], v[72:73]
	v_pk_add_f32 v[68:69], v[68:69], v[72:73] neg_lo:[0,1] neg_hi:[0,1]
	s_nop 0
	v_pk_mul_f32 v[72:73], v[68:69], v[60:61] op_sel:[0,0] op_sel_hi:[0,1]
	s_nop 0
	v_pk_fma_f32 v[68:69], v[68:69], v[60:61], v[72:73] op_sel:[1,1,0] op_sel_hi:[1,0,1] neg_lo:[0,1,0]
	v_pk_add_f32 v[72:73], v[80:81], v[130:131]
	v_pk_add_f32 v[80:81], v[80:81], v[130:131] neg_lo:[0,1] neg_hi:[0,1]
	s_nop 0
	v_pk_mul_f32 v[130:131], v[80:81], v[62:63] op_sel:[0,0] op_sel_hi:[0,1]
	s_nop 0
	v_pk_fma_f32 v[80:81], v[80:81], v[62:63], v[130:131] op_sel:[1,1,0] op_sel_hi:[1,0,1] neg_lo:[0,1,0]
	v_pk_add_f32 v[130:131], v[96:97], v[122:123]
	v_pk_add_f32 v[96:97], v[96:97], v[122:123] neg_lo:[0,1] neg_hi:[0,1]
	s_nop 0
	v_pk_mul_f32 v[122:123], v[96:97], v[62:63] op_sel:[0,0] op_sel_hi:[0,1]
	s_nop 0
	v_pk_fma_f32 v[96:97], v[96:97], v[62:63], v[122:123] op_sel:[1,1,0] op_sel_hi:[1,0,1] neg_lo:[0,1,0]
; __device__ __forceinline__ float2 cmul(float2 a, float2 b) { return make_float2(a.x * b.x - a.y * b.y, a.x * b.y + a.y * b.x); }
; template <int R, bool INV>
; __device__ __forceinline__ void butterflies(c32 (&v)[1 << R], float turns0) {
;     ...
;   for (int kk = 0; kk < R; ++kk) {
;     const int k = INV ? (R - 1 - kk) : kk;
;     const int hd = RAD >> (k + 1);
; #pragma unroll
;     for (int j = 0; j < RAD; ++j) {
;       if ((j & hd) == 0) {
;         const int m = (j & (hd - 1)) * (16 / hd);
;         const float2 c = make_float2(TC[m], INV ? TS[m] : -TS[m]);
;         const float2 twf = cmul(tbs[k], c);
;         const c32 tw = {twf.x, twf.y};
;         const c32 a = v[j], b = v[j + hd];
;         if (!INV) { v[j] = a + b; v[j + hd] = cmul_pk(a - b, tw); }
;         else { const c32 bt = cmul_pk(b, tw); v[j] = a + bt; v[j + hd] = a - bt; }
; template <int LOGN, int R, int DLOG, bool INV, int MODE, class F>
; __device__ __forceinline__ void fft_pass(float2* X, const F& f) {
;     ...
; #pragma unroll
;       for (int j = 0; j < RAD; ++j) Xc[(DLOG >= 5) ? pb + j * PSTEP : phys(base + (j << DLOG))] = v[j];
;     }
	v_pk_add_f32 v[122:123], v[128:129], v[118:119]
	v_pk_add_f32 v[118:119], v[128:129], v[118:119] neg_lo:[0,1] neg_hi:[0,1]
	s_nop 0
	v_pk_mul_f32 v[128:129], v[118:119], v[62:63] op_sel:[0,0] op_sel_hi:[0,1]
	s_nop 0
	v_pk_fma_f32 v[118:119], v[118:119], v[62:63], v[128:129] op_sel:[1,1,0] op_sel_hi:[1,0,1] neg_lo:[0,1,0]
	v_pk_add_f32 v[128:129], v[114:115], v[116:117]
	v_pk_add_f32 v[114:115], v[114:115], v[116:117] neg_lo:[0,1] neg_hi:[0,1]
	s_nop 0
	v_pk_mul_f32 v[116:117], v[114:115], v[62:63] op_sel:[0,0] op_sel_hi:[0,1]
	s_nop 0
	v_pk_fma_f32 v[114:115], v[114:115], v[62:63], v[116:117] op_sel:[1,1,0] op_sel_hi:[1,0,1] neg_lo:[0,1,0]
	v_pk_add_f32 v[116:117], v[120:121], v[124:125]
	v_pk_add_f32 v[120:121], v[120:121], v[124:125] neg_lo:[0,1] neg_hi:[0,1]
	s_nop 0
	v_pk_mul_f32 v[124:125], v[120:121], v[62:63] op_sel:[0,0] op_sel_hi:[0,1]
	s_nop 0
	v_pk_fma_f32 v[120:121], v[120:121], v[62:63], v[124:125] op_sel:[1,1,0] op_sel_hi:[1,0,1] neg_lo:[0,1,0]
	v_pk_add_f32 v[124:125], v[106:107], v[108:109]
	v_pk_add_f32 v[106:107], v[106:107], v[108:109] neg_lo:[0,1] neg_hi:[0,1]
	s_nop 0
	v_pk_mul_f32 v[108:109], v[106:107], v[62:63] op_sel:[0,0] op_sel_hi:[0,1]
	s_nop 0
	v_pk_fma_f32 v[106:107], v[106:107], v[62:63], v[108:109] op_sel:[1,1,0] op_sel_hi:[1,0,1] neg_lo:[0,1,0]
	v_pk_add_f32 v[108:109], v[112:113], v[104:105]
	v_pk_add_f32 v[104:105], v[112:113], v[104:105] neg_lo:[0,1] neg_hi:[0,1]
	s_nop 0
	v_pk_mul_f32 v[112:113], v[104:105], v[62:63] op_sel:[0,0] op_sel_hi:[0,1]
	s_nop 0
	v_pk_fma_f32 v[104:105], v[104:105], v[62:63], v[112:113] op_sel:[1,1,0] op_sel_hi:[1,0,1] neg_lo:[0,1,0]
	v_pk_add_f32 v[112:113], v[100:101], v[98:99]
	v_pk_add_f32 v[98:99], v[100:101], v[98:99] neg_lo:[0,1] neg_hi:[0,1]
	s_nop 0
	v_pk_mul_f32 v[100:101], v[98:99], v[62:63] op_sel:[0,0] op_sel_hi:[0,1]
	s_nop 0
	v_pk_fma_f32 v[98:99], v[98:99], v[62:63], v[100:101] op_sel:[1,1,0] op_sel_hi:[1,0,1] neg_lo:[0,1,0]
	v_pk_add_f32 v[100:101], v[102:103], v[110:111]
	v_pk_add_f32 v[102:103], v[102:103], v[110:111] neg_lo:[0,1] neg_hi:[0,1]
	s_nop 0
	v_pk_mul_f32 v[110:111], v[102:103], v[62:63] op_sel:[0,0] op_sel_hi:[0,1]
	s_nop 0
	v_pk_fma_f32 v[102:103], v[102:103], v[62:63], v[110:111] op_sel:[1,1,0] op_sel_hi:[1,0,1] neg_lo:[0,1,0]
	v_pk_add_f32 v[110:111], v[90:91], v[92:93]
	v_pk_add_f32 v[90:91], v[90:91], v[92:93] neg_lo:[0,1] neg_hi:[0,1]
	s_nop 0
	v_pk_mul_f32 v[92:93], v[90:91], v[62:63] op_sel:[0,0] op_sel_hi:[0,1]
	s_nop 0
	v_pk_fma_f32 v[90:91], v[90:91], v[62:63], v[92:93] op_sel:[1,1,0] op_sel_hi:[1,0,1] neg_lo:[0,1,0]
	v_pk_add_f32 v[92:93], v[126:127], v[88:89]
	v_pk_add_f32 v[88:89], v[126:127], v[88:89] neg_lo:[0,1] neg_hi:[0,1]
	s_nop 0
	v_pk_mul_f32 v[126:127], v[88:89], v[62:63] op_sel:[0,0] op_sel_hi:[0,1]
	s_nop 0
	v_pk_fma_f32 v[88:89], v[88:89], v[62:63], v[126:127] op_sel:[1,1,0] op_sel_hi:[1,0,1] neg_lo:[0,1,0]
	v_pk_add_f32 v[126:127], v[84:85], v[82:83]
	v_pk_add_f32 v[82:83], v[84:85], v[82:83] neg_lo:[0,1] neg_hi:[0,1]
	s_nop 0
	v_pk_mul_f32 v[84:85], v[82:83], v[62:63] op_sel:[0,0] op_sel_hi:[0,1]
	s_nop 0
	v_pk_fma_f32 v[82:83], v[82:83], v[62:63], v[84:85] op_sel:[1,1,0] op_sel_hi:[1,0,1] neg_lo:[0,1,0]
	v_pk_add_f32 v[84:85], v[86:87], v[94:95]
	v_pk_add_f32 v[86:87], v[86:87], v[94:95] neg_lo:[0,1] neg_hi:[0,1]
	s_nop 0
	v_pk_mul_f32 v[94:95], v[86:87], v[62:63] op_sel:[0,0] op_sel_hi:[0,1]
	s_nop 0
	v_pk_fma_f32 v[86:87], v[86:87], v[62:63], v[94:95] op_sel:[1,1,0] op_sel_hi:[1,0,1] neg_lo:[0,1,0]
	v_pk_add_f32 v[94:95], v[76:77], v[74:75]
	v_pk_add_f32 v[74:75], v[76:77], v[74:75] neg_lo:[0,1] neg_hi:[0,1]
	s_nop 0
	v_pk_mul_f32 v[76:77], v[74:75], v[62:63] op_sel:[0,0] op_sel_hi:[0,1]
	s_nop 0
	v_pk_fma_f32 v[74:75], v[74:75], v[62:63], v[76:77] op_sel:[1,1,0] op_sel_hi:[1,0,1] neg_lo:[0,1,0]
	v_pk_add_f32 v[76:77], v[78:79], v[70:71]
	v_pk_add_f32 v[70:71], v[78:79], v[70:71] neg_lo:[0,1] neg_hi:[0,1]
	s_nop 0
	v_pk_mul_f32 v[78:79], v[70:71], v[62:63] op_sel:[0,0] op_sel_hi:[0,1]
	s_nop 0
	v_pk_fma_f32 v[70:71], v[70:71], v[62:63], v[78:79] op_sel:[1,1,0] op_sel_hi:[1,0,1] neg_lo:[0,1,0]
	v_pk_add_f32 v[78:79], v[66:67], v[68:69]
	v_pk_add_f32 v[66:67], v[66:67], v[68:69] neg_lo:[0,1] neg_hi:[0,1]
	s_nop 0
	v_pk_mul_f32 v[68:69], v[66:67], v[62:63] op_sel:[0,0] op_sel_hi:[0,1]
	s_nop 0
	v_pk_fma_f32 v[66:67], v[66:67], v[62:63], v[68:69] op_sel:[1,1,0] op_sel_hi:[1,0,1] neg_lo:[0,1,0]
	ds_write2_b64 v132, v[72:73], v[80:81] offset1:33
	ds_write2_b64 v132, v[130:131], v[96:97] offset0:66 offset1:99
	ds_write2_b64 v132, v[122:123], v[118:119] offset0:132 offset1:165
	ds_write2_b64 v132, v[128:129], v[114:115] offset0:198 offset1:231
	ds_write2_b64 v133, v[116:117], v[120:121] offset0:8 offset1:41
	ds_write2_b64 v133, v[124:125], v[106:107] offset0:74 offset1:107
	ds_write2_b64 v133, v[108:109], v[104:105] offset0:140 offset1:173
	ds_write2_b64 v133, v[112:113], v[98:99] offset0:206 offset1:239
	ds_write2_b64 v134, v[100:101], v[102:103] offset0:16 offset1:49
	ds_write2_b64 v134, v[110:111], v[90:91] offset0:82 offset1:115
	ds_write2_b64 v134, v[92:93], v[88:89] offset0:148 offset1:181
	ds_write2_b64 v134, v[126:127], v[82:83] offset0:214 offset1:247
	ds_write2_b64 v135, v[84:85], v[86:87] offset0:24 offset1:57
	ds_write2_b64 v135, v[94:95], v[74:75] offset0:90 offset1:123
	ds_write2_b64 v135, v[76:77], v[70:71] offset0:156 offset1:189
	ds_write2_b64 v135, v[78:79], v[66:67] offset0:222 offset1:255
	s_andn2_b64 exec, exec, s[24:25]
	s_cbranch_execnz .LBB0_658
; __device__ __forceinline__ float2 cmul(float2 a, float2 b) { return make_float2(a.x * b.x - a.y * b.y, a.x * b.y + a.y * b.x); }
; template <int R, bool INV>
; __device__ __forceinline__ void butterflies(c32 (&v)[1 << R], float turns0) {
;     ...
;     for (int j = 0; j < RAD; ++j) {
;       if ((j & hd) == 0) {
;         const int m = (j & (hd - 1)) * (16 / hd);
;         const float2 c = make_float2(TC[m], INV ? TS[m] : -TS[m]);
;         const float2 twf = cmul(tbs[k], c);
;         const c32 tw = {twf.x, twf.y};
;         const c32 a = v[j], b = v[j + hd];
;         if (!INV) { v[j] = a + b; v[j + hd] = cmul_pk(a - b, tw); }
;         else { const c32 bt = cmul_pk(b, tw); v[j] = a + bt; v[j + hd] = a - bt; }
; template <int LOGN>
; __device__ __forceinline__ void fft_last_to_regs(const float2* X, c32 (&kf)[32]) {
;     ...
;   const int pb = tid0 * 33;
;   c32 v[32];
; #pragma unroll
;   for (int j = 0; j < 32; ++j) v[j] = Xc[pb + j];
;   butterflies<5, false>(v, 0.f);
.LBB0_659:
	s_or_b64 exec, exec, s[0:1]
	v_mov_b32_e32 v0, v196
	s_waitcnt lgkmcnt(0)
	s_barrier
	s_mov_b32 s7, s95
	v_mul_lo_u32 v0, v0, s56
	v_add_u32_e32 v32, 0, v0
	ds_read_b64 v[0:1], v32
	ds_read_b64 v[2:3], v32 offset:8
	ds_read_b64 v[4:5], v32 offset:16
	ds_read_b64 v[6:7], v32 offset:24
	ds_read_b64 v[8:9], v32 offset:32
	ds_read_b64 v[10:11], v32 offset:40
	ds_read_b64 v[12:13], v32 offset:48
	ds_read_b64 v[14:15], v32 offset:56
	ds_read_b64 v[16:17], v32 offset:64
	ds_read_b64 v[18:19], v32 offset:72
	ds_read_b64 v[20:21], v32 offset:80
	ds_read_b64 v[22:23], v32 offset:88
	ds_read_b64 v[24:25], v32 offset:96
	ds_read_b64 v[26:27], v32 offset:104
	ds_read_b64 v[28:29], v32 offset:112
	ds_read_b64 v[30:31], v32 offset:120
	ds_read_b64 v[34:35], v32 offset:128
	ds_read_b64 v[36:37], v32 offset:136
	ds_read_b64 v[38:39], v32 offset:144
	ds_read_b64 v[40:41], v32 offset:152
	ds_read_b64 v[42:43], v32 offset:160
	ds_read_b64 v[44:45], v32 offset:168
	ds_read_b64 v[46:47], v32 offset:176
	ds_read_b64 v[48:49], v32 offset:184
	ds_read_b64 v[50:51], v32 offset:192
	ds_read_b64 v[52:53], v32 offset:200
	ds_read_b64 v[54:55], v32 offset:208
	ds_read_b64 v[56:57], v32 offset:216
	ds_read_b64 v[58:59], v32 offset:224
	ds_read_b64 v[60:61], v32 offset:232
	ds_read_b64 v[62:63], v32 offset:240
	ds_read_b64 v[64:65], v32 offset:248
	s_waitcnt lgkmcnt(14)
	v_pk_add_f32 v[66:67], v[0:1], v[34:35]
	v_pk_add_f32 v[34:35], v[0:1], v[34:35] neg_lo:[0,1] neg_hi:[0,1]
	v_mov_b64_e32 v[0:1], s[6:7]
	v_pk_mul_f32 v[68:69], v[34:35], v[0:1] op_sel:[0,0] op_sel_hi:[0,1]
	s_mov_b32 s0, s19
	s_mov_b32 s1, s30
	v_pk_fma_f32 v[34:35], v[34:35], v[0:1], v[68:69] op_sel:[1,1,0] op_sel_hi:[1,0,1] neg_lo:[0,1,0]
	v_pk_add_f32 v[68:69], v[2:3], v[36:37]
	v_pk_add_f32 v[2:3], v[2:3], v[36:37] neg_lo:[0,1] neg_hi:[0,1]
	v_mov_b64_e32 v[36:37], s[0:1]
	v_pk_mul_f32 v[70:71], v[2:3], v[36:37] op_sel:[0,0] op_sel_hi:[0,1]
	s_mov_b32 s0, s9
	s_mov_b32 s1, s76
	v_pk_fma_f32 v[36:37], v[2:3], v[36:37], v[70:71] op_sel:[1,1,0] op_sel_hi:[1,0,1] neg_lo:[0,1,0]
	s_waitcnt lgkmcnt(12)
	v_pk_add_f32 v[70:71], v[4:5], v[38:39]
	v_pk_add_f32 v[2:3], v[4:5], v[38:39] neg_lo:[0,1] neg_hi:[0,1]
	v_mov_b64_e32 v[4:5], s[0:1]
	v_pk_mul_f32 v[38:39], v[2:3], v[4:5] op_sel:[0,0] op_sel_hi:[0,1]
	s_mov_b32 s0, s55
	s_mov_b32 s1, s68
	v_pk_fma_f32 v[38:39], v[2:3], v[4:5], v[38:39] op_sel:[1,1,0] op_sel_hi:[1,0,1] neg_lo:[0,1,0]
	v_pk_add_f32 v[72:73], v[6:7], v[40:41]
	v_pk_add_f32 v[2:3], v[6:7], v[40:41] neg_lo:[0,1] neg_hi:[0,1]
	v_mov_b64_e32 v[6:7], s[0:1]
	v_pk_mul_f32 v[40:41], v[2:3], v[6:7] op_sel:[0,0] op_sel_hi:[0,1]
	s_mov_b32 s0, s73
	s_mov_b32 s1, s72
	v_pk_fma_f32 v[6:7], v[2:3], v[6:7], v[40:41] op_sel:[1,1,0] op_sel_hi:[1,0,1] neg_lo:[0,1,0]
	s_waitcnt lgkmcnt(10)
	v_pk_add_f32 v[40:41], v[8:9], v[42:43]
	v_pk_add_f32 v[2:3], v[8:9], v[42:43] neg_lo:[0,1] neg_hi:[0,1]
	v_mov_b64_e32 v[8:9], s[0:1]
	v_pk_mul_f32 v[42:43], v[2:3], v[8:9] op_sel:[0,0] op_sel_hi:[0,1]
	s_mov_b32 s0, s54
	s_mov_b32 s1, s16
	v_pk_fma_f32 v[42:43], v[2:3], v[8:9], v[42:43] op_sel:[1,1,0] op_sel_hi:[1,0,1] neg_lo:[0,1,0]
	v_pk_add_f32 v[74:75], v[10:11], v[44:45]
	v_pk_add_f32 v[2:3], v[10:11], v[44:45] neg_lo:[0,1] neg_hi:[0,1]
	v_mov_b64_e32 v[10:11], s[0:1]
	v_pk_mul_f32 v[44:45], v[2:3], v[10:11] op_sel:[0,0] op_sel_hi:[0,1]
	s_mov_b32 s0, s8
	s_mov_b32 s1, s10
	v_pk_fma_f32 v[10:11], v[2:3], v[10:11], v[44:45] op_sel:[1,1,0] op_sel_hi:[1,0,1] neg_lo:[0,1,0]
	s_waitcnt lgkmcnt(8)
	v_pk_add_f32 v[44:45], v[12:13], v[46:47]
	v_pk_add_f32 v[2:3], v[12:13], v[46:47] neg_lo:[0,1] neg_hi:[0,1]
	v_mov_b64_e32 v[12:13], s[0:1]
	v_pk_mul_f32 v[46:47], v[2:3], v[12:13] op_sel:[0,0] op_sel_hi:[0,1]
	s_mov_b32 s0, s18
	s_mov_b32 s1, s4
	v_pk_fma_f32 v[46:47], v[2:3], v[12:13], v[46:47] op_sel:[1,1,0] op_sel_hi:[1,0,1] neg_lo:[0,1,0]
	v_pk_add_f32 v[76:77], v[14:15], v[48:49]
	v_pk_add_f32 v[2:3], v[14:15], v[48:49] neg_lo:[0,1] neg_hi:[0,1]
	v_mov_b64_e32 v[14:15], s[0:1]
	v_pk_mul_f32 v[48:49], v[2:3], v[14:15] op_sel:[0,0] op_sel_hi:[0,1]
	s_mov_b32 s88, s94
	v_pk_fma_f32 v[14:15], v[2:3], v[14:15], v[48:49] op_sel:[1,1,0] op_sel_hi:[1,0,1] neg_lo:[0,1,0]
	s_waitcnt lgkmcnt(6)
	v_pk_add_f32 v[48:49], v[16:17], v[50:51]
	v_pk_add_f32 v[16:17], v[16:17], v[50:51] neg_lo:[0,1] neg_hi:[0,1]
	v_mov_b64_e32 v[2:3], s[88:89]
	v_pk_mul_f32 v[50:51], v[16:17], v[2:3] op_sel:[0,0] op_sel_hi:[0,1]
	s_mov_b32 s31, s4
	v_pk_fma_f32 v[16:17], v[16:17], v[2:3], v[50:51] op_sel:[1,1,0] op_sel_hi:[1,0,1] neg_lo:[0,1,0]
	v_pk_add_f32 v[50:51], v[18:19], v[52:53]
	v_pk_add_f32 v[18:19], v[18:19], v[52:53] neg_lo:[0,1] neg_hi:[0,1]
	v_mov_b64_e32 v[52:53], s[30:31]
	v_pk_mul_f32 v[78:79], v[18:19], v[52:53] op_sel:[0,0] op_sel_hi:[0,1]
	s_mov_b32 s77, s10
	v_pk_fma_f32 v[18:19], v[18:19], v[52:53], v[78:79] op_sel:[1,1,0] op_sel_hi:[1,0,1] neg_lo:[0,1,0]
	s_waitcnt lgkmcnt(4)
	v_pk_add_f32 v[52:53], v[20:21], v[54:55]
	v_pk_add_f32 v[20:21], v[20:21], v[54:55] neg_lo:[0,1] neg_hi:[0,1]
	v_mov_b64_e32 v[54:55], s[76:77]
	v_pk_mul_f32 v[78:79], v[20:21], v[54:55] op_sel:[0,0] op_sel_hi:[0,1]
	s_mov_b32 s69, s16
	v_pk_fma_f32 v[20:21], v[20:21], v[54:55], v[78:79] op_sel:[1,1,0] op_sel_hi:[1,0,1] neg_lo:[0,1,0]
	v_pk_add_f32 v[78:79], v[22:23], v[56:57]
	v_pk_add_f32 v[22:23], v[22:23], v[56:57] neg_lo:[0,1] neg_hi:[0,1]
	v_mov_b64_e32 v[56:57], s[68:69]
	v_pk_mul_f32 v[80:81], v[22:23], v[56:57] op_sel:[0,0] op_sel_hi:[0,1]
	s_mov_b32 s0, s72
	s_mov_b32 s1, s72
	v_pk_fma_f32 v[22:23], v[22:23], v[56:57], v[80:81] op_sel:[1,1,0] op_sel_hi:[1,0,1] neg_lo:[0,1,0]
	s_waitcnt lgkmcnt(2)
; __device__ __forceinline__ float2 cmul(float2 a, float2 b) { return make_float2(a.x * b.x - a.y * b.y, a.x * b.y + a.y * b.x); }
; template <int R, bool INV>
; __device__ __forceinline__ void butterflies(c32 (&v)[1 << R], float turns0) {
;     ...
;   for (int kk = 0; kk < R; ++kk) {
;     const int k = INV ? (R - 1 - kk) : kk;
;     const int hd = RAD >> (k + 1);
; #pragma unroll
;     for (int j = 0; j < RAD; ++j) {
;       if ((j & hd) == 0) {
;         const int m = (j & (hd - 1)) * (16 / hd);
;         const float2 c = make_float2(TC[m], INV ? TS[m] : -TS[m]);
;         const float2 twf = cmul(tbs[k], c);
;         const c32 tw = {twf.x, twf.y};
;         const c32 a = v[j], b = v[j + hd];
;         if (!INV) { v[j] = a + b; v[j + hd] = cmul_pk(a - b, tw); }
;         else { const c32 bt = cmul_pk(b, tw); v[j] = a + bt; v[j + hd] = a - bt; }
;       }
;     }
;   }
; template <int LOGN>
; __device__ __forceinline__ void fft_last_to_regs(const float2* X, c32 (&kf)[32]) {
;   static_assert(LOGN == 14, "one radix-32 group per thread");
;   const c32* Xc = (const c32*)X;
;   int tid0 = threadIdx.x; asm volatile("" : "+v"(tid0));
;   const int pb = tid0 * 33;
;   c32 v[32];
; #pragma unroll
;   for (int j = 0; j < 32; ++j) v[j] = Xc[pb + j];
;   butterflies<5, false>(v, 0.f);
; #pragma unroll
;   for (int j = 0; j < 32; ++j) kf[j] = v[j];
;   __syncthreads();
; }
	v_pk_add_f32 v[56:57], v[24:25], v[58:59]
	v_pk_add_f32 v[24:25], v[24:25], v[58:59] neg_lo:[0,1] neg_hi:[0,1]
	v_mov_b64_e32 v[58:59], s[0:1]
	v_pk_mul_f32 v[80:81], v[24:25], v[58:59] op_sel:[0,0] op_sel_hi:[0,1]
	s_mov_b32 s17, s68
	v_pk_fma_f32 v[24:25], v[24:25], v[58:59], v[80:81] op_sel:[1,1,0] op_sel_hi:[1,0,1] neg_lo:[0,1,0]
	v_pk_add_f32 v[80:81], v[26:27], v[60:61]
	v_pk_add_f32 v[26:27], v[26:27], v[60:61] neg_lo:[0,1] neg_hi:[0,1]
	v_mov_b64_e32 v[60:61], s[16:17]
	v_pk_mul_f32 v[82:83], v[26:27], v[60:61] op_sel:[0,0] op_sel_hi:[0,1]
	s_mov_b32 s11, s76
	v_pk_fma_f32 v[26:27], v[26:27], v[60:61], v[82:83] op_sel:[1,1,0] op_sel_hi:[1,0,1] neg_lo:[0,1,0]
	s_waitcnt lgkmcnt(0)
	v_pk_add_f32 v[60:61], v[28:29], v[62:63]
	v_pk_add_f32 v[28:29], v[28:29], v[62:63] neg_lo:[0,1] neg_hi:[0,1]
	v_mov_b64_e32 v[62:63], s[10:11]
	v_pk_mul_f32 v[82:83], v[28:29], v[62:63] op_sel:[0,0] op_sel_hi:[0,1]
	s_mov_b32 s5, s30
	v_pk_fma_f32 v[28:29], v[28:29], v[62:63], v[82:83] op_sel:[1,1,0] op_sel_hi:[1,0,1] neg_lo:[0,1,0]
	v_pk_add_f32 v[82:83], v[30:31], v[64:65]
	v_pk_add_f32 v[30:31], v[30:31], v[64:65] neg_lo:[0,1] neg_hi:[0,1]
	v_mov_b64_e32 v[64:65], s[4:5]
	v_pk_mul_f32 v[84:85], v[30:31], v[64:65] op_sel:[0,0] op_sel_hi:[0,1]
	v_mov_b32_e32 v167, v196
	v_pk_fma_f32 v[30:31], v[30:31], v[64:65], v[84:85] op_sel:[1,1,0] op_sel_hi:[1,0,1] neg_lo:[0,1,0]
	v_pk_add_f32 v[64:65], v[66:67], v[48:49]
	v_pk_add_f32 v[48:49], v[66:67], v[48:49] neg_lo:[0,1] neg_hi:[0,1]
	s_nop 0
	v_pk_mul_f32 v[66:67], v[48:49], v[0:1] op_sel:[0,0] op_sel_hi:[0,1]
	s_barrier
	v_pk_fma_f32 v[48:49], v[48:49], v[0:1], v[66:67] op_sel:[1,1,0] op_sel_hi:[1,0,1] neg_lo:[0,1,0]
	v_pk_add_f32 v[66:67], v[68:69], v[50:51]
	v_pk_add_f32 v[50:51], v[68:69], v[50:51] neg_lo:[0,1] neg_hi:[0,1]
	s_nop 0
	v_pk_mul_f32 v[68:69], v[50:51], v[4:5] op_sel:[0,0] op_sel_hi:[0,1]
	s_and_b64 vcc, exec, s[40:41]
	v_pk_fma_f32 v[50:51], v[50:51], v[4:5], v[68:69] op_sel:[1,1,0] op_sel_hi:[1,0,1] neg_lo:[0,1,0]
	v_pk_add_f32 v[68:69], v[70:71], v[52:53]
	v_pk_add_f32 v[52:53], v[70:71], v[52:53] neg_lo:[0,1] neg_hi:[0,1]
	v_and_b32_e32 v124, 0x3ff, v167
	v_pk_mul_f32 v[70:71], v[52:53], v[8:9] op_sel:[0,0] op_sel_hi:[0,1]
	v_lshlrev_b32_e32 v32, 4, v167
	v_pk_fma_f32 v[52:53], v[52:53], v[8:9], v[70:71] op_sel:[1,1,0] op_sel_hi:[1,0,1] neg_lo:[0,1,0]
	v_pk_add_f32 v[70:71], v[72:73], v[78:79]
	v_pk_add_f32 v[72:73], v[72:73], v[78:79] neg_lo:[0,1] neg_hi:[0,1]
	s_nop 0
	v_pk_mul_f32 v[78:79], v[72:73], v[12:13] op_sel:[0,0] op_sel_hi:[0,1]
	s_nop 0
	v_pk_fma_f32 v[72:73], v[72:73], v[12:13], v[78:79] op_sel:[1,1,0] op_sel_hi:[1,0,1] neg_lo:[0,1,0]
	v_pk_add_f32 v[78:79], v[40:41], v[56:57]
	v_pk_add_f32 v[40:41], v[40:41], v[56:57] neg_lo:[0,1] neg_hi:[0,1]
	s_nop 0
	v_pk_mul_f32 v[56:57], v[40:41], v[2:3] op_sel:[0,0] op_sel_hi:[0,1]
	s_nop 0
	v_pk_fma_f32 v[40:41], v[40:41], v[2:3], v[56:57] op_sel:[1,1,0] op_sel_hi:[1,0,1] neg_lo:[0,1,0]
	v_pk_add_f32 v[56:57], v[74:75], v[80:81]
	v_pk_add_f32 v[74:75], v[74:75], v[80:81] neg_lo:[0,1] neg_hi:[0,1]
	s_nop 0
	v_pk_mul_f32 v[80:81], v[74:75], v[54:55] op_sel:[0,0] op_sel_hi:[0,1]
	s_nop 0
	v_pk_fma_f32 v[74:75], v[74:75], v[54:55], v[80:81] op_sel:[1,1,0] op_sel_hi:[1,0,1] neg_lo:[0,1,0]
	v_pk_add_f32 v[80:81], v[44:45], v[60:61]
	v_pk_add_f32 v[44:45], v[44:45], v[60:61] neg_lo:[0,1] neg_hi:[0,1]
	s_nop 0
	v_pk_mul_f32 v[60:61], v[44:45], v[58:59] op_sel:[0,0] op_sel_hi:[0,1]
	s_nop 0
	v_pk_fma_f32 v[44:45], v[44:45], v[58:59], v[60:61] op_sel:[1,1,0] op_sel_hi:[1,0,1] neg_lo:[0,1,0]
	v_pk_add_f32 v[60:61], v[76:77], v[82:83]
	v_pk_add_f32 v[76:77], v[76:77], v[82:83] neg_lo:[0,1] neg_hi:[0,1]
	s_nop 0
	v_pk_mul_f32 v[82:83], v[76:77], v[62:63] op_sel:[0,0] op_sel_hi:[0,1]
	s_nop 0
	v_pk_fma_f32 v[76:77], v[76:77], v[62:63], v[82:83] op_sel:[1,1,0] op_sel_hi:[1,0,1] neg_lo:[0,1,0]
	v_pk_add_f32 v[82:83], v[34:35], v[16:17]
	v_pk_add_f32 v[16:17], v[34:35], v[16:17] neg_lo:[0,1] neg_hi:[0,1]
	v_pk_add_f32 v[84:85], v[72:73], v[76:77]
	v_pk_mul_f32 v[34:35], v[16:17], v[0:1] op_sel:[0,0] op_sel_hi:[0,1]
	s_nop 0
	v_pk_fma_f32 v[16:17], v[16:17], v[0:1], v[34:35] op_sel:[1,1,0] op_sel_hi:[1,0,1] neg_lo:[0,1,0]
	v_pk_add_f32 v[34:35], v[36:37], v[18:19]
	v_pk_add_f32 v[18:19], v[36:37], v[18:19] neg_lo:[0,1] neg_hi:[0,1]
	s_nop 0
	v_pk_mul_f32 v[36:37], v[18:19], v[4:5] op_sel:[0,0] op_sel_hi:[0,1]
	s_nop 0
	v_pk_fma_f32 v[4:5], v[18:19], v[4:5], v[36:37] op_sel:[1,1,0] op_sel_hi:[1,0,1] neg_lo:[0,1,0]
	v_pk_add_f32 v[18:19], v[38:39], v[20:21]
	v_pk_add_f32 v[20:21], v[38:39], v[20:21] neg_lo:[0,1] neg_hi:[0,1]
	s_nop 0
	v_pk_mul_f32 v[36:37], v[20:21], v[8:9] op_sel:[0,0] op_sel_hi:[0,1]
	s_nop 0
	v_pk_fma_f32 v[20:21], v[20:21], v[8:9], v[36:37] op_sel:[1,1,0] op_sel_hi:[1,0,1] neg_lo:[0,1,0]
	v_pk_add_f32 v[36:37], v[6:7], v[22:23]
	v_pk_add_f32 v[6:7], v[6:7], v[22:23] neg_lo:[0,1] neg_hi:[0,1]
	s_nop 0
	v_pk_mul_f32 v[22:23], v[6:7], v[12:13] op_sel:[0,0] op_sel_hi:[0,1]
	s_nop 0
	v_pk_fma_f32 v[6:7], v[6:7], v[12:13], v[22:23] op_sel:[1,1,0] op_sel_hi:[1,0,1] neg_lo:[0,1,0]
	v_pk_add_f32 v[12:13], v[42:43], v[24:25]
	v_pk_add_f32 v[22:23], v[42:43], v[24:25] neg_lo:[0,1] neg_hi:[0,1]
	v_pk_add_f32 v[42:43], v[64:65], v[78:79] neg_lo:[0,1] neg_hi:[0,1]
	v_pk_mul_f32 v[24:25], v[22:23], v[2:3] op_sel:[0,0] op_sel_hi:[0,1]
	s_nop 0
	v_pk_fma_f32 v[22:23], v[22:23], v[2:3], v[24:25] op_sel:[1,1,0] op_sel_hi:[1,0,1] neg_lo:[0,1,0]
	v_pk_add_f32 v[24:25], v[10:11], v[26:27]
	v_pk_add_f32 v[10:11], v[10:11], v[26:27] neg_lo:[0,1] neg_hi:[0,1]
	v_pk_add_f32 v[90:91], v[16:17], v[22:23]
	v_pk_mul_f32 v[26:27], v[10:11], v[54:55] op_sel:[0,0] op_sel_hi:[0,1]
; __device__ __forceinline__ float2 cmul(float2 a, float2 b) { return make_float2(a.x * b.x - a.y * b.y, a.x * b.y + a.y * b.x); }
; template <int R, bool INV>
; __device__ __forceinline__ void butterflies(c32 (&v)[1 << R], float turns0) {
;     ...
;   for (int kk = 0; kk < R; ++kk) {
;     const int k = INV ? (R - 1 - kk) : kk;
;     const int hd = RAD >> (k + 1);
; #pragma unroll
;     for (int j = 0; j < RAD; ++j) {
;       if ((j & hd) == 0) {
;         const int m = (j & (hd - 1)) * (16 / hd);
;         const float2 c = make_float2(TC[m], INV ? TS[m] : -TS[m]);
;         const float2 twf = cmul(tbs[k], c);
;         const c32 tw = {twf.x, twf.y};
;         const c32 a = v[j], b = v[j + hd];
;         if (!INV) { v[j] = a + b; v[j + hd] = cmul_pk(a - b, tw); }
;         else { const c32 bt = cmul_pk(b, tw); v[j] = a + bt; v[j + hd] = a - bt; }
;       }
;     }
;   }
	v_pk_add_f32 v[16:17], v[16:17], v[22:23] neg_lo:[0,1] neg_hi:[0,1]
	v_pk_fma_f32 v[10:11], v[10:11], v[54:55], v[26:27] op_sel:[1,1,0] op_sel_hi:[1,0,1] neg_lo:[0,1,0]
	v_pk_add_f32 v[26:27], v[46:47], v[28:29]
	v_pk_add_f32 v[28:29], v[46:47], v[28:29] neg_lo:[0,1] neg_hi:[0,1]
	v_pk_mul_f32 v[46:47], v[42:43], v[0:1] op_sel:[0,0] op_sel_hi:[0,1]
	v_pk_add_f32 v[54:55], v[66:67], v[56:57] neg_lo:[0,1] neg_hi:[0,1]
	v_pk_mul_f32 v[38:39], v[28:29], v[58:59] op_sel:[0,0] op_sel_hi:[0,1]
	v_pk_fma_f32 v[46:47], v[42:43], v[0:1], v[46:47] op_sel:[1,1,0] op_sel_hi:[1,0,1] neg_lo:[0,1,0]
	v_pk_add_f32 v[42:43], v[66:67], v[56:57]
	v_pk_fma_f32 v[28:29], v[28:29], v[58:59], v[38:39] op_sel:[1,1,0] op_sel_hi:[1,0,1] neg_lo:[0,1,0]
	v_pk_add_f32 v[38:39], v[14:15], v[30:31]
	v_pk_add_f32 v[14:15], v[14:15], v[30:31] neg_lo:[0,1] neg_hi:[0,1]
	v_pk_mul_f32 v[56:57], v[54:55], v[8:9] op_sel:[0,0] op_sel_hi:[0,1]
	v_pk_mul_f32 v[22:23], v[16:17], v[0:1] op_sel:[0,0] op_sel_hi:[0,1]
	v_pk_add_f32 v[86:87], v[18:19], v[26:27]
	v_pk_mul_f32 v[30:31], v[14:15], v[62:63] op_sel:[0,0] op_sel_hi:[0,1]
	v_pk_fma_f32 v[54:55], v[54:55], v[8:9], v[56:57] op_sel:[1,1,0] op_sel_hi:[1,0,1] neg_lo:[0,1,0]
	v_pk_add_f32 v[56:57], v[68:69], v[80:81]
	v_pk_fma_f32 v[14:15], v[14:15], v[62:63], v[30:31] op_sel:[1,1,0] op_sel_hi:[1,0,1] neg_lo:[0,1,0]
	v_pk_add_f32 v[30:31], v[64:65], v[78:79]
	v_pk_add_f32 v[62:63], v[68:69], v[80:81] neg_lo:[0,1] neg_hi:[0,1]
	v_pk_add_f32 v[78:79], v[52:53], v[44:45]
	v_pk_mul_f32 v[64:65], v[62:63], v[2:3] op_sel:[0,0] op_sel_hi:[0,1]
	v_pk_fma_f32 v[16:17], v[16:17], v[0:1], v[22:23] op_sel:[1,1,0] op_sel_hi:[1,0,1] neg_lo:[0,1,0]
	v_pk_add_f32 v[22:23], v[4:5], v[10:11]
	v_pk_fma_f32 v[62:63], v[62:63], v[2:3], v[64:65] op_sel:[1,1,0] op_sel_hi:[1,0,1] neg_lo:[0,1,0]
	v_pk_add_f32 v[64:65], v[70:71], v[60:61]
	v_pk_add_f32 v[60:61], v[70:71], v[60:61] neg_lo:[0,1] neg_hi:[0,1]
	v_pk_add_f32 v[70:71], v[50:51], v[74:75]
	v_pk_mul_f32 v[66:67], v[60:61], v[58:59] op_sel:[0,0] op_sel_hi:[0,1]
	v_pk_add_f32 v[4:5], v[4:5], v[10:11] neg_lo:[0,1] neg_hi:[0,1]
	v_pk_fma_f32 v[60:61], v[60:61], v[58:59], v[66:67] op_sel:[1,1,0] op_sel_hi:[1,0,1] neg_lo:[0,1,0]
	v_pk_add_f32 v[66:67], v[48:49], v[40:41]
	v_pk_add_f32 v[40:41], v[48:49], v[40:41] neg_lo:[0,1] neg_hi:[0,1]
	v_pk_mul_f32 v[10:11], v[4:5], v[8:9] op_sel:[0,0] op_sel_hi:[0,1]
	v_pk_add_f32 v[18:19], v[18:19], v[26:27] neg_lo:[0,1] neg_hi:[0,1]
	v_pk_mul_f32 v[48:49], v[40:41], v[0:1] op_sel:[0,0] op_sel_hi:[0,1]
	v_pk_fma_f32 v[4:5], v[4:5], v[8:9], v[10:11] op_sel:[1,1,0] op_sel_hi:[1,0,1] neg_lo:[0,1,0]
	v_pk_add_f32 v[10:11], v[20:21], v[28:29] neg_lo:[0,1] neg_hi:[0,1]
	v_pk_fma_f32 v[68:69], v[40:41], v[0:1], v[48:49] op_sel:[1,1,0] op_sel_hi:[1,0,1] neg_lo:[0,1,0]
	v_pk_add_f32 v[40:41], v[50:51], v[74:75] neg_lo:[0,1] neg_hi:[0,1]
	v_pk_mul_f32 v[26:27], v[18:19], v[2:3] op_sel:[0,0] op_sel_hi:[0,1]
	s_nop 0
	v_pk_mul_f32 v[48:49], v[40:41], v[8:9] op_sel:[0,0] op_sel_hi:[0,1]
	v_pk_fma_f32 v[18:19], v[18:19], v[2:3], v[26:27] op_sel:[1,1,0] op_sel_hi:[1,0,1] neg_lo:[0,1,0]
	v_pk_add_f32 v[26:27], v[36:37], v[38:39]
	v_pk_fma_f32 v[74:75], v[40:41], v[8:9], v[48:49] op_sel:[1,1,0] op_sel_hi:[1,0,1] neg_lo:[0,1,0]
	v_pk_add_f32 v[40:41], v[52:53], v[44:45] neg_lo:[0,1] neg_hi:[0,1]
	v_pk_add_f32 v[48:49], v[66:67], v[78:79]
	v_pk_mul_f32 v[44:45], v[40:41], v[2:3] op_sel:[0,0] op_sel_hi:[0,1]
	s_nop 0
	v_pk_fma_f32 v[80:81], v[40:41], v[2:3], v[44:45] op_sel:[1,1,0] op_sel_hi:[1,0,1] neg_lo:[0,1,0]
	v_pk_add_f32 v[40:41], v[72:73], v[76:77] neg_lo:[0,1] neg_hi:[0,1]
	v_pk_add_f32 v[76:77], v[82:83], v[12:13]
	v_pk_add_f32 v[12:13], v[82:83], v[12:13] neg_lo:[0,1] neg_hi:[0,1]
	v_pk_add_f32 v[82:83], v[34:35], v[24:25]
	v_pk_add_f32 v[24:25], v[34:35], v[24:25] neg_lo:[0,1] neg_hi:[0,1]
	v_pk_mul_f32 v[44:45], v[40:41], v[58:59] op_sel:[0,0] op_sel_hi:[0,1]
	s_nop 0
	v_pk_mul_f32 v[34:35], v[24:25], v[8:9] op_sel:[0,0] op_sel_hi:[0,1]
	v_pk_fma_f32 v[72:73], v[40:41], v[58:59], v[44:45] op_sel:[1,1,0] op_sel_hi:[1,0,1] neg_lo:[0,1,0]
	v_pk_mul_f32 v[40:41], v[12:13], v[0:1] op_sel:[0,0] op_sel_hi:[0,1]
	s_nop 0
	v_pk_fma_f32 v[24:25], v[24:25], v[8:9], v[34:35] op_sel:[1,1,0] op_sel_hi:[1,0,1] neg_lo:[0,1,0]
	v_pk_add_f32 v[8:9], v[20:21], v[28:29]
	v_pk_mul_f32 v[20:21], v[10:11], v[2:3] op_sel:[0,0] op_sel_hi:[0,1]
	v_pk_add_f32 v[34:35], v[36:37], v[38:39] neg_lo:[0,1] neg_hi:[0,1]
	v_pk_fma_f32 v[10:11], v[10:11], v[2:3], v[20:21] op_sel:[1,1,0] op_sel_hi:[1,0,1] neg_lo:[0,1,0]
	v_pk_add_f32 v[20:21], v[6:7], v[14:15]
	v_pk_add_f32 v[6:7], v[6:7], v[14:15] neg_lo:[0,1] neg_hi:[0,1]
	v_pk_mul_f32 v[36:37], v[34:35], v[58:59] op_sel:[0,0] op_sel_hi:[0,1]
	v_pk_add_f32 v[38:39], v[42:43], v[64:65]
	v_pk_mul_f32 v[14:15], v[6:7], v[58:59] op_sel:[0,0] op_sel_hi:[0,1]
	v_pk_fma_f32 v[88:89], v[34:35], v[58:59], v[36:37] op_sel:[1,1,0] op_sel_hi:[1,0,1] neg_lo:[0,1,0]
	v_pk_fma_f32 v[12:13], v[12:13], v[0:1], v[40:41] op_sel:[1,1,0] op_sel_hi:[1,0,1] neg_lo:[0,1,0]
	v_pk_add_f32 v[40:41], v[46:47], v[62:63]
	v_pk_fma_f32 v[6:7], v[6:7], v[58:59], v[14:15] op_sel:[1,1,0] op_sel_hi:[1,0,1] neg_lo:[0,1,0]
	v_pk_add_f32 v[14:15], v[30:31], v[56:57] neg_lo:[0,1] neg_hi:[0,1]
	v_pk_add_f32 v[34:35], v[30:31], v[56:57]
	v_pk_mul_f32 v[28:29], v[14:15], v[0:1] op_sel:[0,0] op_sel_hi:[0,1]
	v_pk_add_f32 v[56:57], v[68:69], v[80:81]
	v_pk_fma_f32 v[36:37], v[14:15], v[0:1], v[28:29] op_sel:[1,1,0] op_sel_hi:[1,0,1] neg_lo:[0,1,0]
	v_pk_add_f32 v[14:15], v[42:43], v[64:65] neg_lo:[0,1] neg_hi:[0,1]
	v_pk_add_f32 v[64:65], v[76:77], v[86:87]
	v_pk_mul_f32 v[28:29], v[14:15], v[2:3] op_sel:[0,0] op_sel_hi:[0,1]
; __device__ __forceinline__ float2 cmul(float2 a, float2 b) { return make_float2(a.x * b.x - a.y * b.y, a.x * b.y + a.y * b.x); }
; template <int R, bool INV>
; __device__ __forceinline__ void butterflies(c32 (&v)[1 << R], float turns0) {
;     ...
;   for (int kk = 0; kk < R; ++kk) {
;     const int k = INV ? (R - 1 - kk) : kk;
;     const int hd = RAD >> (k + 1);
; #pragma unroll
;     for (int j = 0; j < RAD; ++j) {
;       if ((j & hd) == 0) {
;         const int m = (j & (hd - 1)) * (16 / hd);
;         const float2 c = make_float2(TC[m], INV ? TS[m] : -TS[m]);
;         const float2 twf = cmul(tbs[k], c);
;         const c32 tw = {twf.x, twf.y};
;         const c32 a = v[j], b = v[j + hd];
;         if (!INV) { v[j] = a + b; v[j + hd] = cmul_pk(a - b, tw); }
;         else { const c32 bt = cmul_pk(b, tw); v[j] = a + bt; v[j + hd] = a - bt; }
;       }
;     }
;   }
	v_pk_add_f32 v[94:95], v[4:5], v[6:7]
	v_pk_fma_f32 v[42:43], v[14:15], v[2:3], v[28:29] op_sel:[1,1,0] op_sel_hi:[1,0,1] neg_lo:[0,1,0]
	v_pk_add_f32 v[14:15], v[46:47], v[62:63] neg_lo:[0,1] neg_hi:[0,1]
	v_pk_add_f32 v[46:47], v[54:55], v[60:61]
	v_pk_mul_f32 v[28:29], v[14:15], v[0:1] op_sel:[0,0] op_sel_hi:[0,1]
	v_pk_add_f32 v[62:63], v[74:75], v[72:73]
	v_pk_fma_f32 v[44:45], v[14:15], v[0:1], v[28:29] op_sel:[1,1,0] op_sel_hi:[1,0,1] neg_lo:[0,1,0]
	v_pk_add_f32 v[14:15], v[54:55], v[60:61] neg_lo:[0,1] neg_hi:[0,1]
	v_pk_add_f32 v[54:55], v[70:71], v[84:85]
	v_pk_mul_f32 v[28:29], v[14:15], v[2:3] op_sel:[0,0] op_sel_hi:[0,1]
	v_pk_add_f32 v[4:5], v[4:5], v[6:7] neg_lo:[0,1] neg_hi:[0,1]
	v_pk_fma_f32 v[50:51], v[14:15], v[2:3], v[28:29] op_sel:[1,1,0] op_sel_hi:[1,0,1] neg_lo:[0,1,0]
	v_pk_add_f32 v[14:15], v[66:67], v[78:79] neg_lo:[0,1] neg_hi:[0,1]
	v_pk_mul_f32 v[6:7], v[4:5], v[2:3] op_sel:[0,0] op_sel_hi:[0,1]
	v_pk_add_f32 v[78:79], v[24:25], v[88:89]
	v_pk_mul_f32 v[28:29], v[14:15], v[0:1] op_sel:[0,0] op_sel_hi:[0,1]
	v_pk_fma_f32 v[96:97], v[4:5], v[2:3], v[6:7] op_sel:[1,1,0] op_sel_hi:[1,0,1] neg_lo:[0,1,0]
	s_nop 0
	v_pk_fma_f32 v[52:53], v[14:15], v[0:1], v[28:29] op_sel:[1,1,0] op_sel_hi:[1,0,1] neg_lo:[0,1,0]
	v_pk_add_f32 v[14:15], v[70:71], v[84:85] neg_lo:[0,1] neg_hi:[0,1]
	v_pk_add_f32 v[70:71], v[82:83], v[26:27]
	v_pk_mul_f32 v[28:29], v[14:15], v[2:3] op_sel:[0,0] op_sel_hi:[0,1]
	s_nop 0
	v_pk_fma_f32 v[58:59], v[14:15], v[2:3], v[28:29] op_sel:[1,1,0] op_sel_hi:[1,0,1] neg_lo:[0,1,0]
	v_pk_add_f32 v[14:15], v[68:69], v[80:81] neg_lo:[0,1] neg_hi:[0,1]
	v_pk_add_f32 v[80:81], v[90:91], v[8:9]
	v_pk_mul_f32 v[28:29], v[14:15], v[0:1] op_sel:[0,0] op_sel_hi:[0,1]
	v_pk_add_f32 v[8:9], v[90:91], v[8:9] neg_lo:[0,1] neg_hi:[0,1]
	v_pk_fma_f32 v[60:61], v[14:15], v[0:1], v[28:29] op_sel:[1,1,0] op_sel_hi:[1,0,1] neg_lo:[0,1,0]
	v_pk_add_f32 v[14:15], v[74:75], v[72:73] neg_lo:[0,1] neg_hi:[0,1]
	v_pk_add_f32 v[72:73], v[12:13], v[18:19]
	v_pk_mul_f32 v[28:29], v[14:15], v[2:3] op_sel:[0,0] op_sel_hi:[0,1]
	v_pk_add_f32 v[12:13], v[12:13], v[18:19] neg_lo:[0,1] neg_hi:[0,1]
	v_pk_fma_f32 v[66:67], v[14:15], v[2:3], v[28:29] op_sel:[1,1,0] op_sel_hi:[1,0,1] neg_lo:[0,1,0]
	v_pk_add_f32 v[14:15], v[76:77], v[86:87] neg_lo:[0,1] neg_hi:[0,1]
	v_pk_add_f32 v[86:87], v[22:23], v[20:21]
	v_pk_mul_f32 v[28:29], v[14:15], v[0:1] op_sel:[0,0] op_sel_hi:[0,1]
	s_nop 0
	v_pk_fma_f32 v[68:69], v[14:15], v[0:1], v[28:29] op_sel:[1,1,0] op_sel_hi:[1,0,1] neg_lo:[0,1,0]
	v_pk_add_f32 v[14:15], v[82:83], v[26:27] neg_lo:[0,1] neg_hi:[0,1]
	s_nop 0
	v_pk_mul_f32 v[26:27], v[14:15], v[2:3] op_sel:[0,0] op_sel_hi:[0,1]
	s_nop 0
	v_pk_fma_f32 v[74:75], v[14:15], v[2:3], v[26:27] op_sel:[1,1,0] op_sel_hi:[1,0,1] neg_lo:[0,1,0]
	v_pk_mul_f32 v[14:15], v[12:13], v[0:1] op_sel:[0,0] op_sel_hi:[0,1]
	s_nop 0
	v_pk_fma_f32 v[76:77], v[12:13], v[0:1], v[14:15] op_sel:[1,1,0] op_sel_hi:[1,0,1] neg_lo:[0,1,0]
	v_pk_add_f32 v[12:13], v[24:25], v[88:89] neg_lo:[0,1] neg_hi:[0,1]
	v_pk_add_f32 v[88:89], v[16:17], v[10:11]
	v_pk_mul_f32 v[14:15], v[12:13], v[2:3] op_sel:[0,0] op_sel_hi:[0,1]
	s_nop 0
	v_pk_fma_f32 v[82:83], v[12:13], v[2:3], v[14:15] op_sel:[1,1,0] op_sel_hi:[1,0,1] neg_lo:[0,1,0]
	v_pk_mul_f32 v[12:13], v[8:9], v[0:1] op_sel:[0,0] op_sel_hi:[0,1]
	s_nop 0
	v_pk_fma_f32 v[84:85], v[8:9], v[0:1], v[12:13] op_sel:[1,1,0] op_sel_hi:[1,0,1] neg_lo:[0,1,0]
	v_pk_add_f32 v[8:9], v[22:23], v[20:21] neg_lo:[0,1] neg_hi:[0,1]
	s_nop 0
	v_pk_mul_f32 v[12:13], v[8:9], v[2:3] op_sel:[0,0] op_sel_hi:[0,1]
	s_nop 0
	v_pk_fma_f32 v[90:91], v[8:9], v[2:3], v[12:13] op_sel:[1,1,0] op_sel_hi:[1,0,1] neg_lo:[0,1,0]
	v_pk_add_f32 v[2:3], v[34:35], v[38:39] neg_lo:[0,1] neg_hi:[0,1]
	v_pk_add_f32 v[8:9], v[16:17], v[10:11] neg_lo:[0,1] neg_hi:[0,1]
	v_pk_mul_f32 v[4:5], v[2:3], v[0:1] op_sel:[0,0] op_sel_hi:[0,1]
	s_nop 0
	v_pk_fma_f32 v[30:31], v[2:3], v[0:1], v[4:5] op_sel:[1,1,0] op_sel_hi:[1,0,1] neg_lo:[0,1,0]
	v_pk_add_f32 v[2:3], v[36:37], v[42:43] neg_lo:[0,1] neg_hi:[0,1]
	v_pk_mul_f32 v[10:11], v[8:9], v[0:1] op_sel:[0,0] op_sel_hi:[0,1]
	s_nop 0
	v_pk_mul_f32 v[4:5], v[2:3], v[0:1] op_sel:[0,0] op_sel_hi:[0,1]
	v_pk_fma_f32 v[92:93], v[8:9], v[0:1], v[10:11] op_sel:[1,1,0] op_sel_hi:[1,0,1] neg_lo:[0,1,0]
	s_nop 0
	v_pk_fma_f32 v[28:29], v[2:3], v[0:1], v[4:5] op_sel:[1,1,0] op_sel_hi:[1,0,1] neg_lo:[0,1,0]
	v_pk_add_f32 v[2:3], v[40:41], v[46:47] neg_lo:[0,1] neg_hi:[0,1]
	s_nop 0
	v_pk_mul_f32 v[4:5], v[2:3], v[0:1] op_sel:[0,0] op_sel_hi:[0,1]
	s_nop 0
	v_pk_fma_f32 v[26:27], v[2:3], v[0:1], v[4:5] op_sel:[1,1,0] op_sel_hi:[1,0,1] neg_lo:[0,1,0]
	v_pk_add_f32 v[2:3], v[44:45], v[50:51] neg_lo:[0,1] neg_hi:[0,1]
	s_nop 0
	v_pk_mul_f32 v[4:5], v[2:3], v[0:1] op_sel:[0,0] op_sel_hi:[0,1]
	s_nop 0
	v_pk_fma_f32 v[24:25], v[2:3], v[0:1], v[4:5] op_sel:[1,1,0] op_sel_hi:[1,0,1] neg_lo:[0,1,0]
; __device__ __forceinline__ float2 cmul(float2 a, float2 b) { return make_float2(a.x * b.x - a.y * b.y, a.x * b.y + a.y * b.x); }
; __device__ __forceinline__ float2 twid(float turns) { return make_float2(__builtin_amdgcn_cosf(turns), -__builtin_amdgcn_sinf(turns)); }
; __device__ __forceinline__ float2 unpk2(unsigned w) { return make_float2(bflo(w), bfhi(w)); }
; template <int R, bool INV>
; __device__ __forceinline__ void butterflies(c32 (&v)[1 << R], float turns0) {
;     ...
;   for (int kk = 0; kk < R; ++kk) {
;     const int k = INV ? (R - 1 - kk) : kk;
;     const int hd = RAD >> (k + 1);
; #pragma unroll
;     for (int j = 0; j < RAD; ++j) {
;       if ((j & hd) == 0) {
;         const int m = (j & (hd - 1)) * (16 / hd);
;         const float2 c = make_float2(TC[m], INV ? TS[m] : -TS[m]);
;         const float2 twf = cmul(tbs[k], c);
;         const c32 tw = {twf.x, twf.y};
;         const c32 a = v[j], b = v[j + hd];
;         if (!INV) { v[j] = a + b; v[j + hd] = cmul_pk(a - b, tw); }
;         else { const c32 bt = cmul_pk(b, tw); v[j] = a + bt; v[j + hd] = a - bt; }
;       }
;     }
;   }
; template <int LOGN, int R, int DLOG, bool INV, int MODE, class F>
; __device__ __forceinline__ void fft_pass(float2* X, const F& f) {
;     ...
;   auto fetch = [&](int g, c32 (&dst)[RAD]) {
;     const int base = gbase(g);
; #pragma unroll
;     for (int j = 0; j < RAD; ++j) { if constexpr (MODE == 1) { const float2 sv = f(base + (j << DLOG)); dst[j] = (c32){sv.x, sv.y}; } }
;   };
;   c32 nxt[RAD];
;   if constexpr (MODE == 1) fetch(tid0, nxt);
;   __device__ __forceinline__ float2 operator()(int i) const { const float2 wv = unpk2(Wd[i]); return half ? cmul(wv, twid((float)(i & (L - 1)) * invTurn)) : wv; }
	v_pk_add_f32 v[2:3], v[48:49], v[54:55] neg_lo:[0,1] neg_hi:[0,1]
	s_nop 0
	v_pk_mul_f32 v[4:5], v[2:3], v[0:1] op_sel:[0,0] op_sel_hi:[0,1]
	s_nop 0
	v_pk_fma_f32 v[22:23], v[2:3], v[0:1], v[4:5] op_sel:[1,1,0] op_sel_hi:[1,0,1] neg_lo:[0,1,0]
	v_pk_add_f32 v[2:3], v[52:53], v[58:59] neg_lo:[0,1] neg_hi:[0,1]
	s_nop 0
	v_pk_mul_f32 v[4:5], v[2:3], v[0:1] op_sel:[0,0] op_sel_hi:[0,1]
	s_nop 0
	v_pk_fma_f32 v[20:21], v[2:3], v[0:1], v[4:5] op_sel:[1,1,0] op_sel_hi:[1,0,1] neg_lo:[0,1,0]
	v_pk_add_f32 v[2:3], v[56:57], v[62:63] neg_lo:[0,1] neg_hi:[0,1]
	s_nop 0
	v_pk_mul_f32 v[4:5], v[2:3], v[0:1] op_sel:[0,0] op_sel_hi:[0,1]
	s_nop 0
	v_pk_fma_f32 v[18:19], v[2:3], v[0:1], v[4:5] op_sel:[1,1,0] op_sel_hi:[1,0,1] neg_lo:[0,1,0]
	v_pk_add_f32 v[2:3], v[60:61], v[66:67] neg_lo:[0,1] neg_hi:[0,1]
	s_nop 0
	v_pk_mul_f32 v[4:5], v[2:3], v[0:1] op_sel:[0,0] op_sel_hi:[0,1]
	s_nop 0
	v_pk_fma_f32 v[16:17], v[2:3], v[0:1], v[4:5] op_sel:[1,1,0] op_sel_hi:[1,0,1] neg_lo:[0,1,0]
	v_pk_add_f32 v[2:3], v[64:65], v[70:71] neg_lo:[0,1] neg_hi:[0,1]
	s_nop 0
	v_pk_mul_f32 v[4:5], v[2:3], v[0:1] op_sel:[0,0] op_sel_hi:[0,1]
	s_nop 0
	v_pk_fma_f32 v[14:15], v[2:3], v[0:1], v[4:5] op_sel:[1,1,0] op_sel_hi:[1,0,1] neg_lo:[0,1,0]
	v_pk_add_f32 v[2:3], v[68:69], v[74:75] neg_lo:[0,1] neg_hi:[0,1]
	s_nop 0
	v_pk_mul_f32 v[4:5], v[2:3], v[0:1] op_sel:[0,0] op_sel_hi:[0,1]
	s_nop 0
	v_pk_fma_f32 v[12:13], v[2:3], v[0:1], v[4:5] op_sel:[1,1,0] op_sel_hi:[1,0,1] neg_lo:[0,1,0]
	v_pk_add_f32 v[2:3], v[72:73], v[78:79] neg_lo:[0,1] neg_hi:[0,1]
	s_nop 0
	v_pk_mul_f32 v[4:5], v[2:3], v[0:1] op_sel:[0,0] op_sel_hi:[0,1]
	s_nop 0
	v_pk_fma_f32 v[10:11], v[2:3], v[0:1], v[4:5] op_sel:[1,1,0] op_sel_hi:[1,0,1] neg_lo:[0,1,0]
	v_pk_add_f32 v[2:3], v[76:77], v[82:83] neg_lo:[0,1] neg_hi:[0,1]
	s_nop 0
	v_pk_mul_f32 v[4:5], v[2:3], v[0:1] op_sel:[0,0] op_sel_hi:[0,1]
	s_nop 0
	v_pk_fma_f32 v[8:9], v[2:3], v[0:1], v[4:5] op_sel:[1,1,0] op_sel_hi:[1,0,1] neg_lo:[0,1,0]
	v_pk_add_f32 v[2:3], v[80:81], v[86:87] neg_lo:[0,1] neg_hi:[0,1]
	s_nop 0
	v_pk_mul_f32 v[4:5], v[2:3], v[0:1] op_sel:[0,0] op_sel_hi:[0,1]
	s_nop 0
	v_pk_fma_f32 v[6:7], v[2:3], v[0:1], v[4:5] op_sel:[1,1,0] op_sel_hi:[1,0,1] neg_lo:[0,1,0]
	v_pk_add_f32 v[2:3], v[84:85], v[90:91] neg_lo:[0,1] neg_hi:[0,1]
	s_nop 0
	v_pk_mul_f32 v[4:5], v[2:3], v[0:1] op_sel:[0,0] op_sel_hi:[0,1]
	s_nop 0
	v_pk_fma_f32 v[4:5], v[2:3], v[0:1], v[4:5] op_sel:[1,1,0] op_sel_hi:[1,0,1] neg_lo:[0,1,0]
	v_pk_add_f32 v[2:3], v[88:89], v[94:95] neg_lo:[0,1] neg_hi:[0,1]
	s_nop 0
	v_pk_mul_f32 v[98:99], v[2:3], v[0:1] op_sel:[0,0] op_sel_hi:[0,1]
	s_nop 0
	v_pk_fma_f32 v[2:3], v[2:3], v[0:1], v[98:99] op_sel:[1,1,0] op_sel_hi:[1,0,1] neg_lo:[0,1,0]
	v_pk_add_f32 v[98:99], v[92:93], v[96:97] neg_lo:[0,1] neg_hi:[0,1]
	s_nop 0
	v_pk_mul_f32 v[100:101], v[98:99], v[0:1] op_sel:[0,0] op_sel_hi:[0,1]
	s_nop 0
	v_pk_fma_f32 v[0:1], v[98:99], v[0:1], v[100:101] op_sel:[1,1,0] op_sel_hi:[1,0,1] neg_lo:[0,1,0]
	v_and_or_b32 v98, v32, s71, v124
	v_ashrrev_i32_e32 v99, 31, v98
	v_lshl_add_u64 v[120:121], v[98:99], 2, s[34:35]
	v_lshlrev_b32_e32 v207, 2, v98
	v_add_u32_e32 v208, 0x1000, v207
	v_add_u32_e32 v209, 0x2000, v207
	v_add_u32_e32 v210, 0x3000, v207
	v_add_u32_e32 v211, 0x4000, v207
	v_add_u32_e32 v212, 0x5000, v207
	v_add_u32_e32 v213, 0x6000, v207
	v_add_u32_e32 v214, 0x7000, v207
	v_add_u32_e32 v215, 0x8000, v207
	v_add_u32_e32 v216, 0x9000, v207
	v_add_u32_e32 v217, 0xa000, v207
	v_add_u32_e32 v218, 0xb000, v207
	v_add_u32_e32 v219, 0xc000, v207
	v_add_u32_e32 v220, 0xd000, v207
	v_add_u32_e32 v221, 0xe000, v207
	v_add_u32_e32 v222, 0xf000, v207
	global_load_dword v207, v207, s[34:35]
	global_load_dword v208, v208, s[34:35]
	global_load_dword v209, v209, s[34:35]
	global_load_dword v210, v210, s[34:35]
	global_load_dword v211, v211, s[34:35]
	global_load_dword v212, v212, s[34:35]
	global_load_dword v213, v213, s[34:35]
	global_load_dword v214, v214, s[34:35]
	global_load_dword v215, v215, s[34:35]
	global_load_dword v216, v216, s[34:35]
	global_load_dword v217, v217, s[34:35]
	global_load_dword v218, v218, s[34:35]
	global_load_dword v219, v219, s[34:35]
	global_load_dword v220, v220, s[34:35]
	global_load_dword v221, v221, s[34:35]
	global_load_dword v222, v222, s[34:35]
	s_waitcnt vmcnt(15)
	v_mov_b32_e32 v99, v207
	s_waitcnt vmcnt(0)
	v_lshlrev_b32_e32 v98, 16, v99
	v_and_b32_e32 v99, 0xffff0000, v99
	s_cbranch_vccnz .LBB0_661
	v_cvt_f32_u32_e32 v100, v124
	v_mul_f32_e32 v101, 0x38000000, v100
	v_sin_f32_e32 v100, v101
	v_cos_f32_e32 v102, v101
	v_pk_mul_f32 v[100:101], v[100:101], v[98:99] op_sel:[0,1] op_sel_hi:[0,0]
	v_pk_fma_f32 v[104:105], v[102:103], v[98:99], v[100:101]
	v_pk_fma_f32 v[98:99], v[102:103], v[98:99], v[100:101] op_sel_hi:[0,1,1] neg_lo:[0,0,1] neg_hi:[0,0,1]
	v_mov_b32_e32 v105, v99
	v_mov_b64_e32 v[98:99], v[104:105]

; __device__ __forceinline__ float2 cmul(float2 a, float2 b) { return make_float2(a.x * b.x - a.y * b.y, a.x * b.y + a.y * b.x); }
; template <int R, bool INV>
; __device__ __forceinline__ void butterflies(c32 (&v)[1 << R], float turns0) {
;     ...
;   for (int kk = 0; kk < R; ++kk) {
;     const int k = INV ? (R - 1 - kk) : kk;
;     const int hd = RAD >> (k + 1);
; #pragma unroll
;     for (int j = 0; j < RAD; ++j) {
;       if ((j & hd) == 0) {
;         const int m = (j & (hd - 1)) * (16 / hd);
;         const float2 c = make_float2(TC[m], INV ? TS[m] : -TS[m]);
;         const float2 twf = cmul(tbs[k], c);
;         const c32 tw = {twf.x, twf.y};
;         const c32 a = v[j], b = v[j + hd];
;         if (!INV) { v[j] = a + b; v[j + hd] = cmul_pk(a - b, tw); }
;         else { const c32 bt = cmul_pk(b, tw); v[j] = a + bt; v[j + hd] = a - bt; }
;       }
;     }
;   }
; template <int LOGN, int R, int DLOG, bool INV, int MODE, class F>
; __device__ __forceinline__ void fft_pass(float2* X, const F& f) {
;     ...
;   for (int g = tid0; g < NGR; g += 512) {
;     const int lo = g & (dmin - 1), base = gbase(g), pb = phys(base);
;     c32 v[RAD];
;     if constexpr (MODE == 1) {
; #pragma unroll
;       for (int j = 0; j < RAD; ++j) v[j] = nxt[j];
;       if (g + 512 < NGR) fetch(g + 512, nxt);
;     } else {
; #pragma unroll
;       for (int j = 0; j < RAD; ++j) v[j] = Xc[(DLOG >= 5) ? pb + j * PSTEP : phys(base + (j << DLOG))];
;     }
;     butterflies<R, INV>(v, (float)lo / (float)(RAD << DLOG));
.LBB0_731:
	v_and_b32_e32 v167, 0xfffffc00, v161
	v_ashrrev_i32_e32 v168, 2, v167
	v_add_u32_e32 v168, 0, v168
	v_lshlrev_b32_e32 v167, 3, v167
	v_lshlrev_b32_e32 v169, 3, v32
	v_add3_u32 v167, v168, v167, v169
	v_add_u32_e32 v197, 0x800, v167
	v_add_u32_e32 v207, 0x1000, v167
	ds_read_b64 v[168:169], v167
	ds_read_b64 v[170:171], v167 offset:264
	ds_read_b64 v[172:173], v167 offset:528
	ds_read_b64 v[174:175], v167 offset:792
	ds_read_b64 v[176:177], v167 offset:1056
	ds_read_b64 v[178:179], v167 offset:1320
	ds_read_b64 v[180:181], v167 offset:1584
	ds_read_b64 v[182:183], v167 offset:1848
	ds_read_b64 v[184:185], v197 offset:64
	ds_read_b64 v[186:187], v197 offset:328
	ds_read_b64 v[188:189], v197 offset:592
	ds_read_b64 v[190:191], v197 offset:856
	ds_read_b64 v[192:193], v197 offset:1120
	ds_read_b64 v[194:195], v197 offset:1384
	ds_read_b64 v[212:213], v197 offset:1648
	ds_read_b64 v[214:215], v197 offset:1912
	ds_read_b64 v[216:217], v207 offset:128
	ds_read_b64 v[218:219], v207 offset:392
	ds_read_b64 v[220:221], v207 offset:656
	ds_read_b64 v[222:223], v207 offset:920
	ds_read_b64 v[224:225], v207 offset:1184
	ds_read_b64 v[226:227], v207 offset:1448
	ds_read_b64 v[228:229], v207 offset:1712
	ds_read_b64 v[230:231], v207 offset:1976
	v_add_u32_e32 v248, 0x1800, v167
	s_waitcnt lgkmcnt(6)
	v_pk_add_f32 v[198:199], v[168:169], v[216:217]
	v_pk_add_f32 v[168:169], v[168:169], v[216:217] neg_lo:[0,1] neg_hi:[0,1]
	ds_read_b64 v[232:233], v248 offset:192
	ds_read_b64 v[234:235], v248 offset:456
	ds_read_b64 v[236:237], v248 offset:720
	ds_read_b64 v[238:239], v248 offset:984
	ds_read_b64 v[240:241], v248 offset:1248
	ds_read_b64 v[242:243], v248 offset:1512
	ds_read_b64 v[244:245], v248 offset:1776
	ds_read_b64 v[246:247], v248 offset:2040
	v_pk_mul_f32 v[208:209], v[168:169], v[98:99] op_sel:[0,0] op_sel_hi:[0,1]
	v_add_u32_e32 v160, 0x200, v160
	v_pk_fma_f32 v[168:169], v[168:169], v[98:99], v[208:209] op_sel:[1,1,0] op_sel_hi:[1,0,1] neg_lo:[0,1,0]
	v_pk_add_f32 v[208:209], v[170:171], v[218:219]
	v_pk_add_f32 v[170:171], v[170:171], v[218:219] neg_lo:[0,1] neg_hi:[0,1]
	v_cmp_lt_i32_e32 vcc, -1, v160
	v_pk_mul_f32 v[210:211], v[170:171], v[122:123] op_sel:[0,0] op_sel_hi:[0,1]
	v_add_u32_e32 v161, 0x4000, v161
	v_pk_fma_f32 v[170:171], v[170:171], v[122:123], v[210:211] op_sel:[1,1,0] op_sel_hi:[1,0,1] neg_lo:[0,1,0]
	s_waitcnt lgkmcnt(12)
	v_pk_add_f32 v[210:211], v[172:173], v[220:221]
	v_pk_add_f32 v[172:173], v[172:173], v[220:221] neg_lo:[0,1] neg_hi:[0,1]
	s_or_b64 s[24:25], vcc, s[24:25]
	v_pk_mul_f32 v[216:217], v[172:173], v[114:115] op_sel:[0,0] op_sel_hi:[0,1]
	s_nop 0
	v_pk_fma_f32 v[172:173], v[172:173], v[114:115], v[216:217] op_sel:[1,1,0] op_sel_hi:[1,0,1] neg_lo:[0,1,0]
	v_pk_add_f32 v[216:217], v[174:175], v[222:223]
	v_pk_add_f32 v[174:175], v[174:175], v[222:223] neg_lo:[0,1] neg_hi:[0,1]
	s_nop 0
	v_pk_mul_f32 v[218:219], v[174:175], v[106:107] op_sel:[0,0] op_sel_hi:[0,1]
	s_nop 0
	v_pk_fma_f32 v[174:175], v[174:175], v[106:107], v[218:219] op_sel:[1,1,0] op_sel_hi:[1,0,1] neg_lo:[0,1,0]
	s_waitcnt lgkmcnt(10)
	v_pk_add_f32 v[218:219], v[176:177], v[224:225]
	v_pk_add_f32 v[176:177], v[176:177], v[224:225] neg_lo:[0,1] neg_hi:[0,1]
	s_nop 0
	v_pk_mul_f32 v[220:221], v[176:177], v[102:103] op_sel:[0,0] op_sel_hi:[0,1]
	s_nop 0
	v_pk_fma_f32 v[176:177], v[176:177], v[102:103], v[220:221] op_sel:[1,1,0] op_sel_hi:[1,0,1] neg_lo:[0,1,0]
	v_pk_add_f32 v[220:221], v[178:179], v[226:227]
	v_pk_add_f32 v[178:179], v[178:179], v[226:227] neg_lo:[0,1] neg_hi:[0,1]
	s_nop 0
	v_pk_mul_f32 v[222:223], v[178:179], v[112:113] op_sel:[0,0] op_sel_hi:[0,1]
	s_nop 0
	v_pk_fma_f32 v[178:179], v[178:179], v[112:113], v[222:223] op_sel:[1,1,0] op_sel_hi:[1,0,1] neg_lo:[0,1,0]
	s_waitcnt lgkmcnt(8)
	v_pk_add_f32 v[222:223], v[180:181], v[228:229]
	v_pk_add_f32 v[180:181], v[180:181], v[228:229] neg_lo:[0,1] neg_hi:[0,1]
	s_nop 0
	v_pk_mul_f32 v[224:225], v[180:181], v[120:121] op_sel:[0,0] op_sel_hi:[0,1]
	s_nop 0
	v_pk_fma_f32 v[180:181], v[180:181], v[120:121], v[224:225] op_sel:[1,1,0] op_sel_hi:[1,0,1] neg_lo:[0,1,0]
	v_pk_add_f32 v[224:225], v[182:183], v[230:231]
	v_pk_add_f32 v[182:183], v[182:183], v[230:231] neg_lo:[0,1] neg_hi:[0,1]
	s_nop 0
	v_pk_mul_f32 v[226:227], v[182:183], v[128:129] op_sel:[0,0] op_sel_hi:[0,1]
	s_nop 0
	v_pk_fma_f32 v[182:183], v[182:183], v[128:129], v[226:227] op_sel:[1,1,0] op_sel_hi:[1,0,1] neg_lo:[0,1,0]
	s_waitcnt lgkmcnt(6)
	v_pk_add_f32 v[226:227], v[184:185], v[232:233]
	v_pk_add_f32 v[184:185], v[184:185], v[232:233] neg_lo:[0,1] neg_hi:[0,1]
	s_nop 0
	v_pk_mul_f32 v[228:229], v[184:185], v[100:101] op_sel:[0,0] op_sel_hi:[0,1]
	s_nop 0
	v_pk_fma_f32 v[184:185], v[184:185], v[100:101], v[228:229] op_sel:[1,1,0] op_sel_hi:[1,0,1] neg_lo:[0,1,0]
	v_pk_add_f32 v[228:229], v[186:187], v[234:235]
	v_pk_add_f32 v[186:187], v[186:187], v[234:235] neg_lo:[0,1] neg_hi:[0,1]
	s_nop 0
	v_pk_mul_f32 v[230:231], v[186:187], v[126:127] op_sel:[0,0] op_sel_hi:[0,1]
	s_nop 0
	v_pk_fma_f32 v[186:187], v[186:187], v[126:127], v[230:231] op_sel:[1,1,0] op_sel_hi:[1,0,1] neg_lo:[0,1,0]
	s_waitcnt lgkmcnt(4)
	v_pk_add_f32 v[230:231], v[188:189], v[236:237]
	v_pk_add_f32 v[188:189], v[188:189], v[236:237] neg_lo:[0,1] neg_hi:[0,1]
	s_nop 0
	v_pk_mul_f32 v[232:233], v[188:189], v[118:119] op_sel:[0,0] op_sel_hi:[0,1]
	s_nop 0
	v_pk_fma_f32 v[188:189], v[188:189], v[118:119], v[232:233] op_sel:[1,1,0] op_sel_hi:[1,0,1] neg_lo:[0,1,0]
	v_pk_add_f32 v[232:233], v[190:191], v[238:239]
	v_pk_add_f32 v[190:191], v[190:191], v[238:239] neg_lo:[0,1] neg_hi:[0,1]
	s_nop 0
	v_pk_mul_f32 v[234:235], v[190:191], v[110:111] op_sel:[0,0] op_sel_hi:[0,1]
	s_nop 0
	v_pk_fma_f32 v[190:191], v[190:191], v[110:111], v[234:235] op_sel:[1,1,0] op_sel_hi:[1,0,1] neg_lo:[0,1,0]
	s_waitcnt lgkmcnt(2)
; __device__ __forceinline__ float2 cmul(float2 a, float2 b) { return make_float2(a.x * b.x - a.y * b.y, a.x * b.y + a.y * b.x); }
; template <int R, bool INV>
; __device__ __forceinline__ void butterflies(c32 (&v)[1 << R], float turns0) {
;     ...
;   for (int kk = 0; kk < R; ++kk) {
;     const int k = INV ? (R - 1 - kk) : kk;
;     const int hd = RAD >> (k + 1);
; #pragma unroll
;     for (int j = 0; j < RAD; ++j) {
;       if ((j & hd) == 0) {
;         const int m = (j & (hd - 1)) * (16 / hd);
;         const float2 c = make_float2(TC[m], INV ? TS[m] : -TS[m]);
;         const float2 twf = cmul(tbs[k], c);
;         const c32 tw = {twf.x, twf.y};
;         const c32 a = v[j], b = v[j + hd];
;         if (!INV) { v[j] = a + b; v[j + hd] = cmul_pk(a - b, tw); }
;         else { const c32 bt = cmul_pk(b, tw); v[j] = a + bt; v[j + hd] = a - bt; }
;       }
;     }
;   }
	v_pk_add_f32 v[234:235], v[192:193], v[240:241]
	v_pk_add_f32 v[192:193], v[192:193], v[240:241] neg_lo:[0,1] neg_hi:[0,1]
	s_nop 0
	v_pk_mul_f32 v[236:237], v[192:193], v[104:105] op_sel:[0,0] op_sel_hi:[0,1]
	s_nop 0
	v_pk_fma_f32 v[192:193], v[192:193], v[104:105], v[236:237] op_sel:[1,1,0] op_sel_hi:[1,0,1] neg_lo:[0,1,0]
	v_pk_add_f32 v[236:237], v[194:195], v[242:243]
	v_pk_add_f32 v[194:195], v[194:195], v[242:243] neg_lo:[0,1] neg_hi:[0,1]
	s_nop 0
	v_pk_mul_f32 v[238:239], v[194:195], v[108:109] op_sel:[0,0] op_sel_hi:[0,1]
	s_nop 0
	v_pk_fma_f32 v[194:195], v[194:195], v[108:109], v[238:239] op_sel:[1,1,0] op_sel_hi:[1,0,1] neg_lo:[0,1,0]
	s_waitcnt lgkmcnt(0)
	v_pk_add_f32 v[238:239], v[212:213], v[244:245]
	v_pk_add_f32 v[212:213], v[212:213], v[244:245] neg_lo:[0,1] neg_hi:[0,1]
	s_nop 0
	v_pk_mul_f32 v[240:241], v[212:213], v[116:117] op_sel:[0,0] op_sel_hi:[0,1]
	s_nop 0
	v_pk_fma_f32 v[212:213], v[212:213], v[116:117], v[240:241] op_sel:[1,1,0] op_sel_hi:[1,0,1] neg_lo:[0,1,0]
	v_pk_add_f32 v[240:241], v[214:215], v[246:247]
	v_pk_add_f32 v[214:215], v[214:215], v[246:247] neg_lo:[0,1] neg_hi:[0,1]
	s_nop 0
	v_pk_mul_f32 v[242:243], v[214:215], v[124:125] op_sel:[0,0] op_sel_hi:[0,1]
	s_nop 0
	v_pk_fma_f32 v[214:215], v[214:215], v[124:125], v[242:243] op_sel:[1,1,0] op_sel_hi:[1,0,1] neg_lo:[0,1,0]
	v_pk_add_f32 v[242:243], v[198:199], v[226:227]
	v_pk_add_f32 v[198:199], v[198:199], v[226:227] neg_lo:[0,1] neg_hi:[0,1]
	s_nop 0
	v_pk_mul_f32 v[226:227], v[198:199], v[130:131] op_sel:[0,0] op_sel_hi:[0,1]
	s_nop 0
	v_pk_fma_f32 v[198:199], v[198:199], v[130:131], v[226:227] op_sel:[1,1,0] op_sel_hi:[1,0,1] neg_lo:[0,1,0]
	v_pk_add_f32 v[226:227], v[208:209], v[228:229]
	v_pk_add_f32 v[208:209], v[208:209], v[228:229] neg_lo:[0,1] neg_hi:[0,1]
	s_nop 0
	v_pk_mul_f32 v[228:229], v[208:209], v[138:139] op_sel:[0,0] op_sel_hi:[0,1]
	s_nop 0
	v_pk_fma_f32 v[208:209], v[208:209], v[138:139], v[228:229] op_sel:[1,1,0] op_sel_hi:[1,0,1] neg_lo:[0,1,0]
	v_pk_add_f32 v[228:229], v[210:211], v[230:231]
	v_pk_add_f32 v[210:211], v[210:211], v[230:231] neg_lo:[0,1] neg_hi:[0,1]
	s_nop 0
	v_pk_mul_f32 v[230:231], v[210:211], v[134:135] op_sel:[0,0] op_sel_hi:[0,1]
	s_nop 0
	v_pk_fma_f32 v[210:211], v[210:211], v[134:135], v[230:231] op_sel:[1,1,0] op_sel_hi:[1,0,1] neg_lo:[0,1,0]
	v_pk_add_f32 v[230:231], v[216:217], v[232:233]
	v_pk_add_f32 v[216:217], v[216:217], v[232:233] neg_lo:[0,1] neg_hi:[0,1]
	s_nop 0
	v_pk_mul_f32 v[232:233], v[216:217], v[144:145] op_sel:[0,0] op_sel_hi:[0,1]
	s_nop 0
	v_pk_fma_f32 v[216:217], v[216:217], v[144:145], v[232:233] op_sel:[1,1,0] op_sel_hi:[1,0,1] neg_lo:[0,1,0]
	v_pk_add_f32 v[232:233], v[218:219], v[234:235]
	v_pk_add_f32 v[218:219], v[218:219], v[234:235] neg_lo:[0,1] neg_hi:[0,1]
	s_nop 0
	v_pk_mul_f32 v[234:235], v[218:219], v[132:133] op_sel:[0,0] op_sel_hi:[0,1]
	s_nop 0
	v_pk_fma_f32 v[218:219], v[218:219], v[132:133], v[234:235] op_sel:[1,1,0] op_sel_hi:[1,0,1] neg_lo:[0,1,0]
	v_pk_add_f32 v[234:235], v[220:221], v[236:237]
	v_pk_add_f32 v[220:221], v[220:221], v[236:237] neg_lo:[0,1] neg_hi:[0,1]
	s_nop 0
	v_pk_mul_f32 v[236:237], v[220:221], v[142:143] op_sel:[0,0] op_sel_hi:[0,1]
	s_nop 0
	v_pk_fma_f32 v[220:221], v[220:221], v[142:143], v[236:237] op_sel:[1,1,0] op_sel_hi:[1,0,1] neg_lo:[0,1,0]
	v_pk_add_f32 v[236:237], v[222:223], v[238:239]
	v_pk_add_f32 v[222:223], v[222:223], v[238:239] neg_lo:[0,1] neg_hi:[0,1]
	s_nop 0
	v_pk_mul_f32 v[238:239], v[222:223], v[136:137] op_sel:[0,0] op_sel_hi:[0,1]
	s_nop 0
	v_pk_fma_f32 v[222:223], v[222:223], v[136:137], v[238:239] op_sel:[1,1,0] op_sel_hi:[1,0,1] neg_lo:[0,1,0]
	v_pk_add_f32 v[238:239], v[224:225], v[240:241]
	v_pk_add_f32 v[224:225], v[224:225], v[240:241] neg_lo:[0,1] neg_hi:[0,1]
	s_nop 0
	v_pk_mul_f32 v[240:241], v[224:225], v[140:141] op_sel:[0,0] op_sel_hi:[0,1]
	s_nop 0
	v_pk_fma_f32 v[224:225], v[224:225], v[140:141], v[240:241] op_sel:[1,1,0] op_sel_hi:[1,0,1] neg_lo:[0,1,0]
	v_pk_add_f32 v[240:241], v[168:169], v[184:185]
	v_pk_add_f32 v[168:169], v[168:169], v[184:185] neg_lo:[0,1] neg_hi:[0,1]
	s_nop 0
	v_pk_mul_f32 v[184:185], v[168:169], v[130:131] op_sel:[0,0] op_sel_hi:[0,1]
	s_nop 0
	v_pk_fma_f32 v[168:169], v[168:169], v[130:131], v[184:185] op_sel:[1,1,0] op_sel_hi:[1,0,1] neg_lo:[0,1,0]
	v_pk_add_f32 v[184:185], v[170:171], v[186:187]
	v_pk_add_f32 v[170:171], v[170:171], v[186:187] neg_lo:[0,1] neg_hi:[0,1]
	s_nop 0
	v_pk_mul_f32 v[186:187], v[170:171], v[138:139] op_sel:[0,0] op_sel_hi:[0,1]
	s_nop 0
	v_pk_fma_f32 v[170:171], v[170:171], v[138:139], v[186:187] op_sel:[1,1,0] op_sel_hi:[1,0,1] neg_lo:[0,1,0]
	v_pk_add_f32 v[186:187], v[172:173], v[188:189]
	v_pk_add_f32 v[172:173], v[172:173], v[188:189] neg_lo:[0,1] neg_hi:[0,1]
	s_nop 0
	v_pk_mul_f32 v[188:189], v[172:173], v[134:135] op_sel:[0,0] op_sel_hi:[0,1]
	s_nop 0
	v_pk_fma_f32 v[172:173], v[172:173], v[134:135], v[188:189] op_sel:[1,1,0] op_sel_hi:[1,0,1] neg_lo:[0,1,0]
	v_pk_add_f32 v[188:189], v[174:175], v[190:191]
	v_pk_add_f32 v[174:175], v[174:175], v[190:191] neg_lo:[0,1] neg_hi:[0,1]
	s_nop 0
	v_pk_mul_f32 v[190:191], v[174:175], v[144:145] op_sel:[0,0] op_sel_hi:[0,1]
	s_nop 0
	v_pk_fma_f32 v[174:175], v[174:175], v[144:145], v[190:191] op_sel:[1,1,0] op_sel_hi:[1,0,1] neg_lo:[0,1,0]
	v_pk_add_f32 v[190:191], v[176:177], v[192:193]
	v_pk_add_f32 v[176:177], v[176:177], v[192:193] neg_lo:[0,1] neg_hi:[0,1]
	s_nop 0
	v_pk_mul_f32 v[192:193], v[176:177], v[132:133] op_sel:[0,0] op_sel_hi:[0,1]
	s_nop 0
	v_pk_fma_f32 v[176:177], v[176:177], v[132:133], v[192:193] op_sel:[1,1,0] op_sel_hi:[1,0,1] neg_lo:[0,1,0]
	v_pk_add_f32 v[192:193], v[178:179], v[194:195]
; __device__ __forceinline__ float2 cmul(float2 a, float2 b) { return make_float2(a.x * b.x - a.y * b.y, a.x * b.y + a.y * b.x); }
; template <int R, bool INV>
; __device__ __forceinline__ void butterflies(c32 (&v)[1 << R], float turns0) {
;     ...
;   for (int kk = 0; kk < R; ++kk) {
;     const int k = INV ? (R - 1 - kk) : kk;
;     const int hd = RAD >> (k + 1);
; #pragma unroll
;     for (int j = 0; j < RAD; ++j) {
;       if ((j & hd) == 0) {
;         const int m = (j & (hd - 1)) * (16 / hd);
;         const float2 c = make_float2(TC[m], INV ? TS[m] : -TS[m]);
;         const float2 twf = cmul(tbs[k], c);
;         const c32 tw = {twf.x, twf.y};
;         const c32 a = v[j], b = v[j + hd];
;         if (!INV) { v[j] = a + b; v[j + hd] = cmul_pk(a - b, tw); }
;         else { const c32 bt = cmul_pk(b, tw); v[j] = a + bt; v[j + hd] = a - bt; }
;       }
;     }
;   }
	v_pk_add_f32 v[178:179], v[178:179], v[194:195] neg_lo:[0,1] neg_hi:[0,1]
	s_nop 0
	v_pk_mul_f32 v[194:195], v[178:179], v[142:143] op_sel:[0,0] op_sel_hi:[0,1]
	s_nop 0
	v_pk_fma_f32 v[178:179], v[178:179], v[142:143], v[194:195] op_sel:[1,1,0] op_sel_hi:[1,0,1] neg_lo:[0,1,0]
	v_pk_add_f32 v[194:195], v[180:181], v[212:213]
	v_pk_add_f32 v[180:181], v[180:181], v[212:213] neg_lo:[0,1] neg_hi:[0,1]
	s_nop 0
	v_pk_mul_f32 v[212:213], v[180:181], v[136:137] op_sel:[0,0] op_sel_hi:[0,1]
	s_nop 0
	v_pk_fma_f32 v[180:181], v[180:181], v[136:137], v[212:213] op_sel:[1,1,0] op_sel_hi:[1,0,1] neg_lo:[0,1,0]
	v_pk_add_f32 v[212:213], v[182:183], v[214:215]
	v_pk_add_f32 v[182:183], v[182:183], v[214:215] neg_lo:[0,1] neg_hi:[0,1]
	s_nop 0
	v_pk_mul_f32 v[214:215], v[182:183], v[140:141] op_sel:[0,0] op_sel_hi:[0,1]
	s_nop 0
	v_pk_fma_f32 v[182:183], v[182:183], v[140:141], v[214:215] op_sel:[1,1,0] op_sel_hi:[1,0,1] neg_lo:[0,1,0]
	v_pk_add_f32 v[214:215], v[242:243], v[232:233]
	v_pk_add_f32 v[232:233], v[242:243], v[232:233] neg_lo:[0,1] neg_hi:[0,1]
	s_nop 0
	v_pk_mul_f32 v[242:243], v[232:233], v[146:147] op_sel:[0,0] op_sel_hi:[0,1]
	s_nop 0
	v_pk_fma_f32 v[232:233], v[232:233], v[146:147], v[242:243] op_sel:[1,1,0] op_sel_hi:[1,0,1] neg_lo:[0,1,0]
	v_pk_add_f32 v[242:243], v[226:227], v[234:235]
	v_pk_add_f32 v[226:227], v[226:227], v[234:235] neg_lo:[0,1] neg_hi:[0,1]
	s_nop 0
	v_pk_mul_f32 v[234:235], v[226:227], v[150:151] op_sel:[0,0] op_sel_hi:[0,1]
	s_nop 0
	v_pk_fma_f32 v[226:227], v[226:227], v[150:151], v[234:235] op_sel:[1,1,0] op_sel_hi:[1,0,1] neg_lo:[0,1,0]
	v_pk_add_f32 v[234:235], v[228:229], v[236:237]
	v_pk_add_f32 v[228:229], v[228:229], v[236:237] neg_lo:[0,1] neg_hi:[0,1]
	s_nop 0
	v_pk_mul_f32 v[236:237], v[228:229], v[148:149] op_sel:[0,0] op_sel_hi:[0,1]
	s_nop 0
	v_pk_fma_f32 v[228:229], v[228:229], v[148:149], v[236:237] op_sel:[1,1,0] op_sel_hi:[1,0,1] neg_lo:[0,1,0]
	v_pk_add_f32 v[236:237], v[230:231], v[238:239]
	v_pk_add_f32 v[230:231], v[230:231], v[238:239] neg_lo:[0,1] neg_hi:[0,1]
	s_nop 0
	v_pk_mul_f32 v[238:239], v[230:231], v[152:153] op_sel:[0,0] op_sel_hi:[0,1]
	s_nop 0
	v_pk_fma_f32 v[230:231], v[230:231], v[152:153], v[238:239] op_sel:[1,1,0] op_sel_hi:[1,0,1] neg_lo:[0,1,0]
	v_pk_add_f32 v[238:239], v[198:199], v[218:219]
	v_pk_add_f32 v[198:199], v[198:199], v[218:219] neg_lo:[0,1] neg_hi:[0,1]
	s_nop 0
	v_pk_mul_f32 v[218:219], v[198:199], v[146:147] op_sel:[0,0] op_sel_hi:[0,1]
	s_nop 0
	v_pk_fma_f32 v[198:199], v[198:199], v[146:147], v[218:219] op_sel:[1,1,0] op_sel_hi:[1,0,1] neg_lo:[0,1,0]
	v_pk_add_f32 v[218:219], v[208:209], v[220:221]
	v_pk_add_f32 v[208:209], v[208:209], v[220:221] neg_lo:[0,1] neg_hi:[0,1]
	s_nop 0
	v_pk_mul_f32 v[220:221], v[208:209], v[150:151] op_sel:[0,0] op_sel_hi:[0,1]
	s_nop 0
	v_pk_fma_f32 v[208:209], v[208:209], v[150:151], v[220:221] op_sel:[1,1,0] op_sel_hi:[1,0,1] neg_lo:[0,1,0]
	v_pk_add_f32 v[220:221], v[210:211], v[222:223]
	v_pk_add_f32 v[210:211], v[210:211], v[222:223] neg_lo:[0,1] neg_hi:[0,1]
	s_nop 0
	v_pk_mul_f32 v[222:223], v[210:211], v[148:149] op_sel:[0,0] op_sel_hi:[0,1]
	s_nop 0
	v_pk_fma_f32 v[210:211], v[210:211], v[148:149], v[222:223] op_sel:[1,1,0] op_sel_hi:[1,0,1] neg_lo:[0,1,0]
	v_pk_add_f32 v[222:223], v[216:217], v[224:225]
	v_pk_add_f32 v[216:217], v[216:217], v[224:225] neg_lo:[0,1] neg_hi:[0,1]
	s_nop 0
	v_pk_mul_f32 v[224:225], v[216:217], v[152:153] op_sel:[0,0] op_sel_hi:[0,1]
	s_nop 0
	v_pk_fma_f32 v[216:217], v[216:217], v[152:153], v[224:225] op_sel:[1,1,0] op_sel_hi:[1,0,1] neg_lo:[0,1,0]
	v_pk_add_f32 v[224:225], v[240:241], v[190:191]
	v_pk_add_f32 v[190:191], v[240:241], v[190:191] neg_lo:[0,1] neg_hi:[0,1]
	s_nop 0
	v_pk_mul_f32 v[240:241], v[190:191], v[146:147] op_sel:[0,0] op_sel_hi:[0,1]
	s_nop 0
	v_pk_fma_f32 v[190:191], v[190:191], v[146:147], v[240:241] op_sel:[1,1,0] op_sel_hi:[1,0,1] neg_lo:[0,1,0]
	v_pk_add_f32 v[240:241], v[184:185], v[192:193]
	v_pk_add_f32 v[184:185], v[184:185], v[192:193] neg_lo:[0,1] neg_hi:[0,1]
	s_nop 0
	v_pk_mul_f32 v[192:193], v[184:185], v[150:151] op_sel:[0,0] op_sel_hi:[0,1]
	s_nop 0
	v_pk_fma_f32 v[184:185], v[184:185], v[150:151], v[192:193] op_sel:[1,1,0] op_sel_hi:[1,0,1] neg_lo:[0,1,0]
	v_pk_add_f32 v[192:193], v[186:187], v[194:195]
	v_pk_add_f32 v[186:187], v[186:187], v[194:195] neg_lo:[0,1] neg_hi:[0,1]
	s_nop 0
	v_pk_mul_f32 v[194:195], v[186:187], v[148:149] op_sel:[0,0] op_sel_hi:[0,1]
	s_nop 0
	v_pk_fma_f32 v[186:187], v[186:187], v[148:149], v[194:195] op_sel:[1,1,0] op_sel_hi:[1,0,1] neg_lo:[0,1,0]
	v_pk_add_f32 v[194:195], v[188:189], v[212:213]
	v_pk_add_f32 v[188:189], v[188:189], v[212:213] neg_lo:[0,1] neg_hi:[0,1]
	s_nop 0
	v_pk_mul_f32 v[212:213], v[188:189], v[152:153] op_sel:[0,0] op_sel_hi:[0,1]
	s_nop 0
	v_pk_fma_f32 v[188:189], v[188:189], v[152:153], v[212:213] op_sel:[1,1,0] op_sel_hi:[1,0,1] neg_lo:[0,1,0]
	v_pk_add_f32 v[212:213], v[168:169], v[176:177]
	v_pk_add_f32 v[168:169], v[168:169], v[176:177] neg_lo:[0,1] neg_hi:[0,1]
	s_nop 0
	v_pk_mul_f32 v[176:177], v[168:169], v[146:147] op_sel:[0,0] op_sel_hi:[0,1]
	s_nop 0
	v_pk_fma_f32 v[168:169], v[168:169], v[146:147], v[176:177] op_sel:[1,1,0] op_sel_hi:[1,0,1] neg_lo:[0,1,0]
	v_pk_add_f32 v[176:177], v[170:171], v[178:179]
	v_pk_add_f32 v[170:171], v[170:171], v[178:179] neg_lo:[0,1] neg_hi:[0,1]
	s_nop 0
	v_pk_mul_f32 v[178:179], v[170:171], v[150:151] op_sel:[0,0] op_sel_hi:[0,1]
	s_nop 0
	v_pk_fma_f32 v[170:171], v[170:171], v[150:151], v[178:179] op_sel:[1,1,0] op_sel_hi:[1,0,1] neg_lo:[0,1,0]
	v_pk_add_f32 v[178:179], v[172:173], v[180:181]
	v_pk_add_f32 v[172:173], v[172:173], v[180:181] neg_lo:[0,1] neg_hi:[0,1]
; __device__ __forceinline__ float2 cmul(float2 a, float2 b) { return make_float2(a.x * b.x - a.y * b.y, a.x * b.y + a.y * b.x); }
; template <int R, bool INV>
; __device__ __forceinline__ void butterflies(c32 (&v)[1 << R], float turns0) {
;     ...
;   for (int kk = 0; kk < R; ++kk) {
;     const int k = INV ? (R - 1 - kk) : kk;
;     const int hd = RAD >> (k + 1);
; #pragma unroll
;     for (int j = 0; j < RAD; ++j) {
;       if ((j & hd) == 0) {
;         const int m = (j & (hd - 1)) * (16 / hd);
;         const float2 c = make_float2(TC[m], INV ? TS[m] : -TS[m]);
;         const float2 twf = cmul(tbs[k], c);
;         const c32 tw = {twf.x, twf.y};
;         const c32 a = v[j], b = v[j + hd];
;         if (!INV) { v[j] = a + b; v[j + hd] = cmul_pk(a - b, tw); }
;         else { const c32 bt = cmul_pk(b, tw); v[j] = a + bt; v[j + hd] = a - bt; }
;       }
;     }
;   }
	s_nop 0
	v_pk_mul_f32 v[180:181], v[172:173], v[148:149] op_sel:[0,0] op_sel_hi:[0,1]
	s_nop 0
	v_pk_fma_f32 v[172:173], v[172:173], v[148:149], v[180:181] op_sel:[1,1,0] op_sel_hi:[1,0,1] neg_lo:[0,1,0]
	v_pk_add_f32 v[180:181], v[174:175], v[182:183]
	v_pk_add_f32 v[174:175], v[174:175], v[182:183] neg_lo:[0,1] neg_hi:[0,1]
	s_nop 0
	v_pk_mul_f32 v[182:183], v[174:175], v[152:153] op_sel:[0,0] op_sel_hi:[0,1]
	s_nop 0
	v_pk_fma_f32 v[174:175], v[174:175], v[152:153], v[182:183] op_sel:[1,1,0] op_sel_hi:[1,0,1] neg_lo:[0,1,0]
	v_pk_add_f32 v[182:183], v[214:215], v[234:235]
	v_pk_add_f32 v[214:215], v[214:215], v[234:235] neg_lo:[0,1] neg_hi:[0,1]
	s_nop 0
	v_pk_mul_f32 v[234:235], v[214:215], v[154:155] op_sel:[0,0] op_sel_hi:[0,1]
	s_nop 0
	v_pk_fma_f32 v[214:215], v[214:215], v[154:155], v[234:235] op_sel:[1,1,0] op_sel_hi:[1,0,1] neg_lo:[0,1,0]
	v_pk_add_f32 v[234:235], v[242:243], v[236:237]
	v_pk_add_f32 v[236:237], v[242:243], v[236:237] neg_lo:[0,1] neg_hi:[0,1]
	s_nop 0
	v_pk_mul_f32 v[242:243], v[236:237], v[156:157] op_sel:[0,0] op_sel_hi:[0,1]
	s_nop 0
	v_pk_fma_f32 v[236:237], v[236:237], v[156:157], v[242:243] op_sel:[1,1,0] op_sel_hi:[1,0,1] neg_lo:[0,1,0]
	v_pk_add_f32 v[242:243], v[232:233], v[228:229]
	v_pk_add_f32 v[228:229], v[232:233], v[228:229] neg_lo:[0,1] neg_hi:[0,1]
	s_nop 0
	v_pk_mul_f32 v[232:233], v[228:229], v[154:155] op_sel:[0,0] op_sel_hi:[0,1]
	s_nop 0
	v_pk_fma_f32 v[228:229], v[228:229], v[154:155], v[232:233] op_sel:[1,1,0] op_sel_hi:[1,0,1] neg_lo:[0,1,0]
	v_pk_add_f32 v[232:233], v[226:227], v[230:231]
	v_pk_add_f32 v[226:227], v[226:227], v[230:231] neg_lo:[0,1] neg_hi:[0,1]
	s_nop 0
	v_pk_mul_f32 v[230:231], v[226:227], v[156:157] op_sel:[0,0] op_sel_hi:[0,1]
	s_nop 0
	v_pk_fma_f32 v[226:227], v[226:227], v[156:157], v[230:231] op_sel:[1,1,0] op_sel_hi:[1,0,1] neg_lo:[0,1,0]
	v_pk_add_f32 v[230:231], v[238:239], v[220:221]
	v_pk_add_f32 v[220:221], v[238:239], v[220:221] neg_lo:[0,1] neg_hi:[0,1]
	s_nop 0
	v_pk_mul_f32 v[238:239], v[220:221], v[154:155] op_sel:[0,0] op_sel_hi:[0,1]
	s_nop 0
	v_pk_fma_f32 v[220:221], v[220:221], v[154:155], v[238:239] op_sel:[1,1,0] op_sel_hi:[1,0,1] neg_lo:[0,1,0]
	v_pk_add_f32 v[238:239], v[218:219], v[222:223]
	v_pk_add_f32 v[218:219], v[218:219], v[222:223] neg_lo:[0,1] neg_hi:[0,1]
	s_nop 0
	v_pk_mul_f32 v[222:223], v[218:219], v[156:157] op_sel:[0,0] op_sel_hi:[0,1]
	s_nop 0
	v_pk_fma_f32 v[218:219], v[218:219], v[156:157], v[222:223] op_sel:[1,1,0] op_sel_hi:[1,0,1] neg_lo:[0,1,0]
	v_pk_add_f32 v[222:223], v[198:199], v[210:211]
	v_pk_add_f32 v[198:199], v[198:199], v[210:211] neg_lo:[0,1] neg_hi:[0,1]
	s_nop 0
	v_pk_mul_f32 v[210:211], v[198:199], v[154:155] op_sel:[0,0] op_sel_hi:[0,1]
	s_nop 0
	v_pk_fma_f32 v[198:199], v[198:199], v[154:155], v[210:211] op_sel:[1,1,0] op_sel_hi:[1,0,1] neg_lo:[0,1,0]
	v_pk_add_f32 v[210:211], v[208:209], v[216:217]
	v_pk_add_f32 v[208:209], v[208:209], v[216:217] neg_lo:[0,1] neg_hi:[0,1]
	s_nop 0
	v_pk_mul_f32 v[216:217], v[208:209], v[156:157] op_sel:[0,0] op_sel_hi:[0,1]
	s_nop 0
	v_pk_fma_f32 v[208:209], v[208:209], v[156:157], v[216:217] op_sel:[1,1,0] op_sel_hi:[1,0,1] neg_lo:[0,1,0]
	v_pk_add_f32 v[216:217], v[224:225], v[192:193]
	v_pk_add_f32 v[192:193], v[224:225], v[192:193] neg_lo:[0,1] neg_hi:[0,1]
	s_nop 0
	v_pk_mul_f32 v[224:225], v[192:193], v[154:155] op_sel:[0,0] op_sel_hi:[0,1]
	s_nop 0
	v_pk_fma_f32 v[192:193], v[192:193], v[154:155], v[224:225] op_sel:[1,1,0] op_sel_hi:[1,0,1] neg_lo:[0,1,0]
	v_pk_add_f32 v[224:225], v[240:241], v[194:195]
	v_pk_add_f32 v[194:195], v[240:241], v[194:195] neg_lo:[0,1] neg_hi:[0,1]
	s_nop 0
	v_pk_mul_f32 v[240:241], v[194:195], v[156:157] op_sel:[0,0] op_sel_hi:[0,1]
	s_nop 0
	v_pk_fma_f32 v[194:195], v[194:195], v[156:157], v[240:241] op_sel:[1,1,0] op_sel_hi:[1,0,1] neg_lo:[0,1,0]
	v_pk_add_f32 v[240:241], v[190:191], v[186:187]
	v_pk_add_f32 v[186:187], v[190:191], v[186:187] neg_lo:[0,1] neg_hi:[0,1]
	s_nop 0
	v_pk_mul_f32 v[190:191], v[186:187], v[154:155] op_sel:[0,0] op_sel_hi:[0,1]
	s_nop 0
	v_pk_fma_f32 v[186:187], v[186:187], v[154:155], v[190:191] op_sel:[1,1,0] op_sel_hi:[1,0,1] neg_lo:[0,1,0]
	v_pk_add_f32 v[190:191], v[184:185], v[188:189]
	v_pk_add_f32 v[184:185], v[184:185], v[188:189] neg_lo:[0,1] neg_hi:[0,1]
	s_nop 0
	v_pk_mul_f32 v[188:189], v[184:185], v[156:157] op_sel:[0,0] op_sel_hi:[0,1]
	s_nop 0
	v_pk_fma_f32 v[184:185], v[184:185], v[156:157], v[188:189] op_sel:[1,1,0] op_sel_hi:[1,0,1] neg_lo:[0,1,0]
	v_pk_add_f32 v[188:189], v[212:213], v[178:179]
	v_pk_add_f32 v[178:179], v[212:213], v[178:179] neg_lo:[0,1] neg_hi:[0,1]
	s_nop 0
	v_pk_mul_f32 v[212:213], v[178:179], v[154:155] op_sel:[0,0] op_sel_hi:[0,1]
	s_nop 0
	v_pk_fma_f32 v[178:179], v[178:179], v[154:155], v[212:213] op_sel:[1,1,0] op_sel_hi:[1,0,1] neg_lo:[0,1,0]
	v_pk_add_f32 v[212:213], v[176:177], v[180:181]
	v_pk_add_f32 v[176:177], v[176:177], v[180:181] neg_lo:[0,1] neg_hi:[0,1]
	s_nop 0
	v_pk_mul_f32 v[180:181], v[176:177], v[156:157] op_sel:[0,0] op_sel_hi:[0,1]
	s_nop 0
	v_pk_fma_f32 v[176:177], v[176:177], v[156:157], v[180:181] op_sel:[1,1,0] op_sel_hi:[1,0,1] neg_lo:[0,1,0]
	v_pk_add_f32 v[180:181], v[168:169], v[172:173]
	v_pk_add_f32 v[168:169], v[168:169], v[172:173] neg_lo:[0,1] neg_hi:[0,1]
	s_nop 0
	v_pk_mul_f32 v[172:173], v[168:169], v[154:155] op_sel:[0,0] op_sel_hi:[0,1]
	s_nop 0
	v_pk_fma_f32 v[168:169], v[168:169], v[154:155], v[172:173] op_sel:[1,1,0] op_sel_hi:[1,0,1] neg_lo:[0,1,0]
	v_pk_add_f32 v[172:173], v[170:171], v[174:175]
	v_pk_add_f32 v[170:171], v[170:171], v[174:175] neg_lo:[0,1] neg_hi:[0,1]
	s_nop 0
; __device__ __forceinline__ float2 cmul(float2 a, float2 b) { return make_float2(a.x * b.x - a.y * b.y, a.x * b.y + a.y * b.x); }
; template <int R, bool INV>
; __device__ __forceinline__ void butterflies(c32 (&v)[1 << R], float turns0) {
;     ...
;   for (int kk = 0; kk < R; ++kk) {
;     const int k = INV ? (R - 1 - kk) : kk;
;     const int hd = RAD >> (k + 1);
; #pragma unroll
;     for (int j = 0; j < RAD; ++j) {
;       if ((j & hd) == 0) {
;         const int m = (j & (hd - 1)) * (16 / hd);
;         const float2 c = make_float2(TC[m], INV ? TS[m] : -TS[m]);
;         const float2 twf = cmul(tbs[k], c);
;         const c32 tw = {twf.x, twf.y};
;         const c32 a = v[j], b = v[j + hd];
;         if (!INV) { v[j] = a + b; v[j + hd] = cmul_pk(a - b, tw); }
;         else { const c32 bt = cmul_pk(b, tw); v[j] = a + bt; v[j + hd] = a - bt; }
;       }
;     }
;   }
; template <int LOGN, int R, int DLOG, bool INV, int MODE, class F>
; __device__ __forceinline__ void fft_pass(float2* X, const F& f) {
;     ...
; #pragma unroll
;       for (int j = 0; j < RAD; ++j) Xc[(DLOG >= 5) ? pb + j * PSTEP : phys(base + (j << DLOG))] = v[j];
;     }
;   }
;   __syncthreads();
	v_pk_mul_f32 v[174:175], v[170:171], v[156:157] op_sel:[0,0] op_sel_hi:[0,1]
	s_nop 0
	v_pk_fma_f32 v[170:171], v[170:171], v[156:157], v[174:175] op_sel:[1,1,0] op_sel_hi:[1,0,1] neg_lo:[0,1,0]
	v_pk_add_f32 v[174:175], v[182:183], v[234:235]
	v_pk_add_f32 v[182:183], v[182:183], v[234:235] neg_lo:[0,1] neg_hi:[0,1]
	s_nop 0
	v_pk_mul_f32 v[234:235], v[182:183], v[158:159] op_sel:[0,0] op_sel_hi:[0,1]
	s_nop 0
	v_pk_fma_f32 v[182:183], v[182:183], v[158:159], v[234:235] op_sel:[1,1,0] op_sel_hi:[1,0,1] neg_lo:[0,1,0]
	v_pk_add_f32 v[234:235], v[214:215], v[236:237]
	v_pk_add_f32 v[214:215], v[214:215], v[236:237] neg_lo:[0,1] neg_hi:[0,1]
	s_nop 0
	v_pk_mul_f32 v[236:237], v[214:215], v[158:159] op_sel:[0,0] op_sel_hi:[0,1]
	s_nop 0
	v_pk_fma_f32 v[214:215], v[214:215], v[158:159], v[236:237] op_sel:[1,1,0] op_sel_hi:[1,0,1] neg_lo:[0,1,0]
	v_pk_add_f32 v[236:237], v[242:243], v[232:233]
	v_pk_add_f32 v[232:233], v[242:243], v[232:233] neg_lo:[0,1] neg_hi:[0,1]
	s_nop 0
	v_pk_mul_f32 v[242:243], v[232:233], v[158:159] op_sel:[0,0] op_sel_hi:[0,1]
	s_nop 0
	v_pk_fma_f32 v[232:233], v[232:233], v[158:159], v[242:243] op_sel:[1,1,0] op_sel_hi:[1,0,1] neg_lo:[0,1,0]
	v_pk_add_f32 v[242:243], v[228:229], v[226:227]
	v_pk_add_f32 v[226:227], v[228:229], v[226:227] neg_lo:[0,1] neg_hi:[0,1]
	s_nop 0
	v_pk_mul_f32 v[228:229], v[226:227], v[158:159] op_sel:[0,0] op_sel_hi:[0,1]
	s_nop 0
	v_pk_fma_f32 v[226:227], v[226:227], v[158:159], v[228:229] op_sel:[1,1,0] op_sel_hi:[1,0,1] neg_lo:[0,1,0]
	v_pk_add_f32 v[228:229], v[230:231], v[238:239]
	v_pk_add_f32 v[230:231], v[230:231], v[238:239] neg_lo:[0,1] neg_hi:[0,1]
	s_nop 0
	v_pk_mul_f32 v[238:239], v[230:231], v[158:159] op_sel:[0,0] op_sel_hi:[0,1]
	s_nop 0
	v_pk_fma_f32 v[230:231], v[230:231], v[158:159], v[238:239] op_sel:[1,1,0] op_sel_hi:[1,0,1] neg_lo:[0,1,0]
	v_pk_add_f32 v[238:239], v[220:221], v[218:219]
	v_pk_add_f32 v[218:219], v[220:221], v[218:219] neg_lo:[0,1] neg_hi:[0,1]
	s_nop 0
	v_pk_mul_f32 v[220:221], v[218:219], v[158:159] op_sel:[0,0] op_sel_hi:[0,1]
	s_nop 0
	v_pk_fma_f32 v[218:219], v[218:219], v[158:159], v[220:221] op_sel:[1,1,0] op_sel_hi:[1,0,1] neg_lo:[0,1,0]
	v_pk_add_f32 v[220:221], v[222:223], v[210:211]
	v_pk_add_f32 v[210:211], v[222:223], v[210:211] neg_lo:[0,1] neg_hi:[0,1]
	s_nop 0
	v_pk_mul_f32 v[222:223], v[210:211], v[158:159] op_sel:[0,0] op_sel_hi:[0,1]
	s_nop 0
	v_pk_fma_f32 v[210:211], v[210:211], v[158:159], v[222:223] op_sel:[1,1,0] op_sel_hi:[1,0,1] neg_lo:[0,1,0]
	v_pk_add_f32 v[222:223], v[198:199], v[208:209]
	v_pk_add_f32 v[198:199], v[198:199], v[208:209] neg_lo:[0,1] neg_hi:[0,1]
	s_nop 0
	v_pk_mul_f32 v[208:209], v[198:199], v[158:159] op_sel:[0,0] op_sel_hi:[0,1]
	s_nop 0
	v_pk_fma_f32 v[198:199], v[198:199], v[158:159], v[208:209] op_sel:[1,1,0] op_sel_hi:[1,0,1] neg_lo:[0,1,0]
	v_pk_add_f32 v[208:209], v[216:217], v[224:225]
	v_pk_add_f32 v[216:217], v[216:217], v[224:225] neg_lo:[0,1] neg_hi:[0,1]
	s_nop 0
	v_pk_mul_f32 v[224:225], v[216:217], v[158:159] op_sel:[0,0] op_sel_hi:[0,1]
	s_nop 0
	v_pk_fma_f32 v[216:217], v[216:217], v[158:159], v[224:225] op_sel:[1,1,0] op_sel_hi:[1,0,1] neg_lo:[0,1,0]
	v_pk_add_f32 v[224:225], v[192:193], v[194:195]
	v_pk_add_f32 v[192:193], v[192:193], v[194:195] neg_lo:[0,1] neg_hi:[0,1]
	s_nop 0
	v_pk_mul_f32 v[194:195], v[192:193], v[158:159] op_sel:[0,0] op_sel_hi:[0,1]
	s_nop 0
	v_pk_fma_f32 v[192:193], v[192:193], v[158:159], v[194:195] op_sel:[1,1,0] op_sel_hi:[1,0,1] neg_lo:[0,1,0]
	v_pk_add_f32 v[194:195], v[240:241], v[190:191]
	v_pk_add_f32 v[190:191], v[240:241], v[190:191] neg_lo:[0,1] neg_hi:[0,1]
	s_nop 0
	v_pk_mul_f32 v[240:241], v[190:191], v[158:159] op_sel:[0,0] op_sel_hi:[0,1]
	s_nop 0
	v_pk_fma_f32 v[190:191], v[190:191], v[158:159], v[240:241] op_sel:[1,1,0] op_sel_hi:[1,0,1] neg_lo:[0,1,0]
	v_pk_add_f32 v[240:241], v[186:187], v[184:185]
	v_pk_add_f32 v[184:185], v[186:187], v[184:185] neg_lo:[0,1] neg_hi:[0,1]
	s_nop 0
	v_pk_mul_f32 v[186:187], v[184:185], v[158:159] op_sel:[0,0] op_sel_hi:[0,1]
	s_nop 0
	v_pk_fma_f32 v[184:185], v[184:185], v[158:159], v[186:187] op_sel:[1,1,0] op_sel_hi:[1,0,1] neg_lo:[0,1,0]
	v_pk_add_f32 v[186:187], v[188:189], v[212:213]
	v_pk_add_f32 v[188:189], v[188:189], v[212:213] neg_lo:[0,1] neg_hi:[0,1]
	s_nop 0
	v_pk_mul_f32 v[212:213], v[188:189], v[158:159] op_sel:[0,0] op_sel_hi:[0,1]
	s_nop 0
	v_pk_fma_f32 v[188:189], v[188:189], v[158:159], v[212:213] op_sel:[1,1,0] op_sel_hi:[1,0,1] neg_lo:[0,1,0]
	v_pk_add_f32 v[212:213], v[178:179], v[176:177]
	v_pk_add_f32 v[176:177], v[178:179], v[176:177] neg_lo:[0,1] neg_hi:[0,1]
	s_nop 0
	v_pk_mul_f32 v[178:179], v[176:177], v[158:159] op_sel:[0,0] op_sel_hi:[0,1]
	s_nop 0
	v_pk_fma_f32 v[176:177], v[176:177], v[158:159], v[178:179] op_sel:[1,1,0] op_sel_hi:[1,0,1] neg_lo:[0,1,0]
	v_pk_add_f32 v[178:179], v[180:181], v[172:173]
	v_pk_add_f32 v[172:173], v[180:181], v[172:173] neg_lo:[0,1] neg_hi:[0,1]
	s_nop 0
	v_pk_mul_f32 v[180:181], v[172:173], v[158:159] op_sel:[0,0] op_sel_hi:[0,1]
	s_nop 0
	v_pk_fma_f32 v[172:173], v[172:173], v[158:159], v[180:181] op_sel:[1,1,0] op_sel_hi:[1,0,1] neg_lo:[0,1,0]
	v_pk_add_f32 v[180:181], v[168:169], v[170:171]
	v_pk_add_f32 v[168:169], v[168:169], v[170:171] neg_lo:[0,1] neg_hi:[0,1]
	s_nop 0
	v_pk_mul_f32 v[170:171], v[168:169], v[158:159] op_sel:[0,0] op_sel_hi:[0,1]
	s_nop 0
	v_pk_fma_f32 v[168:169], v[168:169], v[158:159], v[170:171] op_sel:[1,1,0] op_sel_hi:[1,0,1] neg_lo:[0,1,0]
	ds_write2_b64 v167, v[174:175], v[182:183] offset1:33
	ds_write2_b64 v167, v[234:235], v[214:215] offset0:66 offset1:99
	ds_write2_b64 v167, v[236:237], v[232:233] offset0:132 offset1:165
	ds_write2_b64 v167, v[242:243], v[226:227] offset0:198 offset1:231
	ds_write2_b64 v197, v[228:229], v[230:231] offset0:8 offset1:41
	ds_write2_b64 v197, v[238:239], v[218:219] offset0:74 offset1:107
	ds_write2_b64 v197, v[220:221], v[210:211] offset0:140 offset1:173
	ds_write2_b64 v197, v[222:223], v[198:199] offset0:206 offset1:239
	ds_write2_b64 v207, v[208:209], v[216:217] offset0:16 offset1:49
	ds_write2_b64 v207, v[224:225], v[192:193] offset0:82 offset1:115
	ds_write2_b64 v207, v[194:195], v[190:191] offset0:148 offset1:181
	ds_write2_b64 v207, v[240:241], v[184:185] offset0:214 offset1:247
	ds_write2_b64 v248, v[186:187], v[188:189] offset0:24 offset1:57
	ds_write2_b64 v248, v[212:213], v[176:177] offset0:90 offset1:123
	ds_write2_b64 v248, v[178:179], v[172:173] offset0:156 offset1:189
	ds_write2_b64 v248, v[180:181], v[168:169] offset0:222 offset1:255
	s_andn2_b64 exec, exec, s[24:25]
	s_cbranch_execnz .LBB0_731
; __device__ __forceinline__ float2 cmul(float2 a, float2 b) { return make_float2(a.x * b.x - a.y * b.y, a.x * b.y + a.y * b.x); }
; template <int R, bool INV>
; __device__ __forceinline__ void butterflies(c32 (&v)[1 << R], float turns0) {
;     ...
;   for (int kk = 0; kk < R; ++kk) {
;     const int k = INV ? (R - 1 - kk) : kk;
;     const int hd = RAD >> (k + 1);
; #pragma unroll
;     for (int j = 0; j < RAD; ++j) {
;       if ((j & hd) == 0) {
;         const int m = (j & (hd - 1)) * (16 / hd);
;         const float2 c = make_float2(TC[m], INV ? TS[m] : -TS[m]);
;         const float2 twf = cmul(tbs[k], c);
;         const c32 tw = {twf.x, twf.y};
;         const c32 a = v[j], b = v[j + hd];
;         if (!INV) { v[j] = a + b; v[j + hd] = cmul_pk(a - b, tw); }
;         else { const c32 bt = cmul_pk(b, tw); v[j] = a + bt; v[j + hd] = a - bt; }
;       }
;     }
;   }
; template <int LOGN>
; __device__ __forceinline__ void fft_fused_mul(float2* X, const c32 (&kf)[32]) {
;   static_assert(LOGN == 14, "one radix-32 group per thread");
;   c32* Xc = (c32*)X;
;   int tid0 = threadIdx.x; asm volatile("" : "+v"(tid0));
;   const int pb = tid0 * 33;
;   c32 v[32];
; #pragma unroll
;   for (int j = 0; j < 32; ++j) v[j] = Xc[pb + j];
;   butterflies<5, false>(v, 0.f);
.LBB0_732:
	s_or_b64 exec, exec, s[0:1]
	v_mov_b32_e32 v32, v196
	s_waitcnt lgkmcnt(0)
	s_barrier
	v_pk_add_f32 v[106:107], v[34:35], v[38:39]
	v_mul_lo_u32 v32, v32, s56
	v_add_u32_e32 v32, 0, v32
	v_pk_add_f32 v[104:105], v[36:37], v[42:43]
	v_pk_add_f32 v[102:103], v[40:41], v[46:47]
	v_pk_add_f32 v[100:101], v[44:45], v[50:51]
	v_pk_add_f32 v[98:99], v[48:49], v[54:55]
	v_pk_add_f32 v[54:55], v[52:53], v[58:59]
	v_pk_add_f32 v[52:53], v[56:57], v[62:63]
	v_pk_add_f32 v[50:51], v[60:61], v[66:67]
	v_pk_add_f32 v[48:49], v[64:65], v[70:71]
	v_pk_add_f32 v[46:47], v[68:69], v[74:75]
	v_pk_add_f32 v[44:45], v[72:73], v[78:79]
	v_pk_add_f32 v[42:43], v[76:77], v[82:83]
	v_pk_add_f32 v[40:41], v[80:81], v[86:87]
	v_pk_add_f32 v[38:39], v[84:85], v[90:91]
	v_pk_add_f32 v[36:37], v[88:89], v[94:95]
	v_pk_add_f32 v[34:35], v[92:93], v[96:97]
	ds_read_b64 v[56:57], v32
	ds_read_b64 v[58:59], v32 offset:8
	ds_read_b64 v[60:61], v32 offset:16
	ds_read_b64 v[62:63], v32 offset:24
	ds_read_b64 v[64:65], v32 offset:32
	ds_read_b64 v[66:67], v32 offset:40
	ds_read_b64 v[68:69], v32 offset:48
	ds_read_b64 v[70:71], v32 offset:56
	ds_read_b64 v[72:73], v32 offset:64
	ds_read_b64 v[74:75], v32 offset:72
	ds_read_b64 v[76:77], v32 offset:80
	ds_read_b64 v[78:79], v32 offset:88
	ds_read_b64 v[80:81], v32 offset:96
	ds_read_b64 v[82:83], v32 offset:104
	ds_read_b64 v[84:85], v32 offset:112
	ds_read_b64 v[86:87], v32 offset:120
	ds_read_b64 v[88:89], v32 offset:128
	ds_read_b64 v[90:91], v32 offset:136
	ds_read_b64 v[92:93], v32 offset:144
	ds_read_b64 v[94:95], v32 offset:152
	ds_read_b64 v[108:109], v32 offset:160
	ds_read_b64 v[110:111], v32 offset:168
	ds_read_b64 v[112:113], v32 offset:176
	ds_read_b64 v[114:115], v32 offset:184
	ds_read_b64 v[116:117], v32 offset:192
	ds_read_b64 v[118:119], v32 offset:200
	ds_read_b64 v[120:121], v32 offset:208
	ds_read_b64 v[122:123], v32 offset:216
	ds_read_b64 v[124:125], v32 offset:224
	ds_read_b64 v[126:127], v32 offset:232
	ds_read_b64 v[128:129], v32 offset:240
	ds_read_b64 v[130:131], v32 offset:248
	s_mov_b32 s7, s95
	s_waitcnt lgkmcnt(14)
	v_pk_add_f32 v[96:97], v[56:57], v[88:89]
	v_pk_add_f32 v[88:89], v[56:57], v[88:89] neg_lo:[0,1] neg_hi:[0,1]
	v_mov_b64_e32 v[56:57], s[6:7]
	v_pk_mul_f32 v[132:133], v[88:89], v[56:57] op_sel:[0,0] op_sel_hi:[0,1]
	s_mov_b32 s0, s19
	s_mov_b32 s1, s30
	v_pk_fma_f32 v[88:89], v[88:89], v[56:57], v[132:133] op_sel:[1,1,0] op_sel_hi:[1,0,1] neg_lo:[0,1,0]
	v_pk_add_f32 v[132:133], v[58:59], v[90:91]
	v_pk_add_f32 v[58:59], v[58:59], v[90:91] neg_lo:[0,1] neg_hi:[0,1]
	v_mov_b64_e32 v[90:91], s[0:1]
	v_pk_mul_f32 v[134:135], v[58:59], v[90:91] op_sel:[0,0] op_sel_hi:[0,1]
	s_mov_b32 s0, s9
	s_mov_b32 s1, s76
	v_pk_fma_f32 v[90:91], v[58:59], v[90:91], v[134:135] op_sel:[1,1,0] op_sel_hi:[1,0,1] neg_lo:[0,1,0]
	s_waitcnt lgkmcnt(12)
	v_pk_add_f32 v[134:135], v[60:61], v[92:93]
	v_pk_add_f32 v[58:59], v[60:61], v[92:93] neg_lo:[0,1] neg_hi:[0,1]
	v_mov_b64_e32 v[60:61], s[0:1]
	v_pk_mul_f32 v[92:93], v[58:59], v[60:61] op_sel:[0,0] op_sel_hi:[0,1]
	s_mov_b32 s0, s55
	s_mov_b32 s1, s68
	v_pk_fma_f32 v[92:93], v[58:59], v[60:61], v[92:93] op_sel:[1,1,0] op_sel_hi:[1,0,1] neg_lo:[0,1,0]
	v_pk_add_f32 v[136:137], v[62:63], v[94:95]
	v_pk_add_f32 v[58:59], v[62:63], v[94:95] neg_lo:[0,1] neg_hi:[0,1]
	v_mov_b64_e32 v[62:63], s[0:1]
	v_pk_mul_f32 v[94:95], v[58:59], v[62:63] op_sel:[0,0] op_sel_hi:[0,1]
	s_mov_b32 s0, s73
	s_mov_b32 s1, s72
	v_pk_fma_f32 v[62:63], v[58:59], v[62:63], v[94:95] op_sel:[1,1,0] op_sel_hi:[1,0,1] neg_lo:[0,1,0]
	s_waitcnt lgkmcnt(10)
	v_pk_add_f32 v[94:95], v[64:65], v[108:109]
	v_pk_add_f32 v[58:59], v[64:65], v[108:109] neg_lo:[0,1] neg_hi:[0,1]
	v_mov_b64_e32 v[64:65], s[0:1]
	v_pk_mul_f32 v[108:109], v[58:59], v[64:65] op_sel:[0,0] op_sel_hi:[0,1]
	s_mov_b32 s0, s54
	s_mov_b32 s1, s16
	v_pk_fma_f32 v[108:109], v[58:59], v[64:65], v[108:109] op_sel:[1,1,0] op_sel_hi:[1,0,1] neg_lo:[0,1,0]
	v_pk_add_f32 v[138:139], v[66:67], v[110:111]
	v_pk_add_f32 v[58:59], v[66:67], v[110:111] neg_lo:[0,1] neg_hi:[0,1]
	v_mov_b64_e32 v[66:67], s[0:1]
	v_pk_mul_f32 v[110:111], v[58:59], v[66:67] op_sel:[0,0] op_sel_hi:[0,1]
	s_mov_b32 s0, s8
	s_mov_b32 s1, s10
	v_pk_fma_f32 v[66:67], v[58:59], v[66:67], v[110:111] op_sel:[1,1,0] op_sel_hi:[1,0,1] neg_lo:[0,1,0]
	s_waitcnt lgkmcnt(8)
	v_pk_add_f32 v[110:111], v[68:69], v[112:113]
	v_pk_add_f32 v[58:59], v[68:69], v[112:113] neg_lo:[0,1] neg_hi:[0,1]
	v_mov_b64_e32 v[68:69], s[0:1]
	v_pk_mul_f32 v[112:113], v[58:59], v[68:69] op_sel:[0,0] op_sel_hi:[0,1]
	s_mov_b32 s0, s18
	s_mov_b32 s1, s4
	v_pk_fma_f32 v[112:113], v[58:59], v[68:69], v[112:113] op_sel:[1,1,0] op_sel_hi:[1,0,1] neg_lo:[0,1,0]
	v_pk_add_f32 v[140:141], v[70:71], v[114:115]
	v_pk_add_f32 v[58:59], v[70:71], v[114:115] neg_lo:[0,1] neg_hi:[0,1]
	v_mov_b64_e32 v[70:71], s[0:1]
	v_pk_mul_f32 v[114:115], v[58:59], v[70:71] op_sel:[0,0] op_sel_hi:[0,1]
	s_mov_b32 s88, s94
	v_pk_fma_f32 v[70:71], v[58:59], v[70:71], v[114:115] op_sel:[1,1,0] op_sel_hi:[1,0,1] neg_lo:[0,1,0]
	s_waitcnt lgkmcnt(6)
	v_pk_add_f32 v[114:115], v[72:73], v[116:117]
	v_pk_add_f32 v[72:73], v[72:73], v[116:117] neg_lo:[0,1] neg_hi:[0,1]
	v_mov_b64_e32 v[58:59], s[88:89]
	v_pk_mul_f32 v[116:117], v[72:73], v[58:59] op_sel:[0,0] op_sel_hi:[0,1]
	s_mov_b32 s31, s4
	v_pk_fma_f32 v[72:73], v[72:73], v[58:59], v[116:117] op_sel:[1,1,0] op_sel_hi:[1,0,1] neg_lo:[0,1,0]
	v_pk_add_f32 v[116:117], v[74:75], v[118:119]
	v_pk_add_f32 v[74:75], v[74:75], v[118:119] neg_lo:[0,1] neg_hi:[0,1]
	v_mov_b64_e32 v[118:119], s[30:31]
	v_pk_mul_f32 v[142:143], v[74:75], v[118:119] op_sel:[0,0] op_sel_hi:[0,1]
	s_mov_b32 s77, s10
	v_pk_fma_f32 v[74:75], v[74:75], v[118:119], v[142:143] op_sel:[1,1,0] op_sel_hi:[1,0,1] neg_lo:[0,1,0]
	s_waitcnt lgkmcnt(4)
; __device__ __forceinline__ float2 cmul(float2 a, float2 b) { return make_float2(a.x * b.x - a.y * b.y, a.x * b.y + a.y * b.x); }
; template <int R, bool INV>
; __device__ __forceinline__ void butterflies(c32 (&v)[1 << R], float turns0) {
;     ...
;   for (int kk = 0; kk < R; ++kk) {
;     const int k = INV ? (R - 1 - kk) : kk;
;     const int hd = RAD >> (k + 1);
; #pragma unroll
;     for (int j = 0; j < RAD; ++j) {
;       if ((j & hd) == 0) {
;         const int m = (j & (hd - 1)) * (16 / hd);
;         const float2 c = make_float2(TC[m], INV ? TS[m] : -TS[m]);
;         const float2 twf = cmul(tbs[k], c);
;         const c32 tw = {twf.x, twf.y};
;         const c32 a = v[j], b = v[j + hd];
;         if (!INV) { v[j] = a + b; v[j + hd] = cmul_pk(a - b, tw); }
;         else { const c32 bt = cmul_pk(b, tw); v[j] = a + bt; v[j + hd] = a - bt; }
;       }
;     }
;   }
	v_pk_add_f32 v[118:119], v[76:77], v[120:121]
	v_pk_add_f32 v[76:77], v[76:77], v[120:121] neg_lo:[0,1] neg_hi:[0,1]
	v_mov_b64_e32 v[120:121], s[76:77]
	v_pk_mul_f32 v[142:143], v[76:77], v[120:121] op_sel:[0,0] op_sel_hi:[0,1]
	s_mov_b32 s69, s16
	v_pk_fma_f32 v[76:77], v[76:77], v[120:121], v[142:143] op_sel:[1,1,0] op_sel_hi:[1,0,1] neg_lo:[0,1,0]
	v_pk_add_f32 v[142:143], v[78:79], v[122:123]
	v_pk_add_f32 v[78:79], v[78:79], v[122:123] neg_lo:[0,1] neg_hi:[0,1]
	v_mov_b64_e32 v[122:123], s[68:69]
	v_pk_mul_f32 v[144:145], v[78:79], v[122:123] op_sel:[0,0] op_sel_hi:[0,1]
	s_mov_b32 s0, s72
	s_mov_b32 s1, s72
	v_pk_fma_f32 v[78:79], v[78:79], v[122:123], v[144:145] op_sel:[1,1,0] op_sel_hi:[1,0,1] neg_lo:[0,1,0]
	s_waitcnt lgkmcnt(2)
	v_pk_add_f32 v[122:123], v[80:81], v[124:125]
	v_pk_add_f32 v[80:81], v[80:81], v[124:125] neg_lo:[0,1] neg_hi:[0,1]
	v_mov_b64_e32 v[124:125], s[0:1]
	v_pk_mul_f32 v[144:145], v[80:81], v[124:125] op_sel:[0,0] op_sel_hi:[0,1]
	s_mov_b32 s17, s68
	v_pk_fma_f32 v[80:81], v[80:81], v[124:125], v[144:145] op_sel:[1,1,0] op_sel_hi:[1,0,1] neg_lo:[0,1,0]
	v_pk_add_f32 v[144:145], v[82:83], v[126:127]
	v_pk_add_f32 v[82:83], v[82:83], v[126:127] neg_lo:[0,1] neg_hi:[0,1]
	v_mov_b64_e32 v[126:127], s[16:17]
	v_pk_mul_f32 v[146:147], v[82:83], v[126:127] op_sel:[0,0] op_sel_hi:[0,1]
	s_mov_b32 s11, s76
	v_pk_fma_f32 v[82:83], v[82:83], v[126:127], v[146:147] op_sel:[1,1,0] op_sel_hi:[1,0,1] neg_lo:[0,1,0]
	s_waitcnt lgkmcnt(0)
	v_pk_add_f32 v[126:127], v[84:85], v[128:129]
	v_pk_add_f32 v[84:85], v[84:85], v[128:129] neg_lo:[0,1] neg_hi:[0,1]
	v_mov_b64_e32 v[128:129], s[10:11]
	v_pk_mul_f32 v[146:147], v[84:85], v[128:129] op_sel:[0,0] op_sel_hi:[0,1]
	s_mov_b32 s5, s30
	v_pk_fma_f32 v[84:85], v[84:85], v[128:129], v[146:147] op_sel:[1,1,0] op_sel_hi:[1,0,1] neg_lo:[0,1,0]
	v_pk_add_f32 v[146:147], v[86:87], v[130:131]
	v_pk_add_f32 v[86:87], v[86:87], v[130:131] neg_lo:[0,1] neg_hi:[0,1]
	v_mov_b64_e32 v[130:131], s[4:5]
	v_pk_mul_f32 v[148:149], v[86:87], v[130:131] op_sel:[0,0] op_sel_hi:[0,1]
	s_mov_b32 s7, s94
	v_pk_fma_f32 v[86:87], v[86:87], v[130:131], v[148:149] op_sel:[1,1,0] op_sel_hi:[1,0,1] neg_lo:[0,1,0]
	v_pk_add_f32 v[130:131], v[96:97], v[114:115]
	v_pk_add_f32 v[96:97], v[96:97], v[114:115] neg_lo:[0,1] neg_hi:[0,1]
	s_mov_b32 s0, s94
	v_pk_mul_f32 v[114:115], v[96:97], v[56:57] op_sel:[0,0] op_sel_hi:[0,1]
	s_mov_b32 s1, s6
	v_pk_fma_f32 v[96:97], v[96:97], v[56:57], v[114:115] op_sel:[1,1,0] op_sel_hi:[1,0,1] neg_lo:[0,1,0]
	v_pk_add_f32 v[114:115], v[132:133], v[116:117]
	v_pk_add_f32 v[116:117], v[132:133], v[116:117] neg_lo:[0,1] neg_hi:[0,1]
	s_mov_b32 s77, s9
	v_pk_mul_f32 v[132:133], v[116:117], v[60:61] op_sel:[0,0] op_sel_hi:[0,1]
	s_mov_b32 s11, s8
	v_pk_fma_f32 v[116:117], v[116:117], v[60:61], v[132:133] op_sel:[1,1,0] op_sel_hi:[1,0,1] neg_lo:[0,1,0]
	v_pk_add_f32 v[132:133], v[134:135], v[118:119]
	v_pk_add_f32 v[118:119], v[134:135], v[118:119] neg_lo:[0,1] neg_hi:[0,1]
	s_mov_b32 s31, s19
	v_pk_mul_f32 v[134:135], v[118:119], v[64:65] op_sel:[0,0] op_sel_hi:[0,1]
	s_mov_b32 s69, s55
	v_pk_fma_f32 v[118:119], v[118:119], v[64:65], v[134:135] op_sel:[1,1,0] op_sel_hi:[1,0,1] neg_lo:[0,1,0]
	v_pk_add_f32 v[134:135], v[136:137], v[142:143]
	v_pk_add_f32 v[136:137], v[136:137], v[142:143] neg_lo:[0,1] neg_hi:[0,1]
	s_mov_b32 s17, s54
	v_pk_mul_f32 v[142:143], v[136:137], v[68:69] op_sel:[0,0] op_sel_hi:[0,1]
	s_mov_b32 s5, s18
	v_pk_fma_f32 v[136:137], v[136:137], v[68:69], v[142:143] op_sel:[1,1,0] op_sel_hi:[1,0,1] neg_lo:[0,1,0]
	v_pk_add_f32 v[142:143], v[94:95], v[122:123]
	v_pk_add_f32 v[94:95], v[94:95], v[122:123] neg_lo:[0,1] neg_hi:[0,1]
	s_nop 0
	v_pk_mul_f32 v[122:123], v[94:95], v[58:59] op_sel:[0,0] op_sel_hi:[0,1]
	s_nop 0
	v_pk_fma_f32 v[94:95], v[94:95], v[58:59], v[122:123] op_sel:[1,1,0] op_sel_hi:[1,0,1] neg_lo:[0,1,0]
	v_pk_add_f32 v[122:123], v[138:139], v[144:145]
	v_pk_add_f32 v[138:139], v[138:139], v[144:145] neg_lo:[0,1] neg_hi:[0,1]
	s_nop 0
	v_pk_mul_f32 v[144:145], v[138:139], v[120:121] op_sel:[0,0] op_sel_hi:[0,1]
	s_nop 0
	v_pk_fma_f32 v[138:139], v[138:139], v[120:121], v[144:145] op_sel:[1,1,0] op_sel_hi:[1,0,1] neg_lo:[0,1,0]
	v_pk_add_f32 v[144:145], v[110:111], v[126:127]
	v_pk_add_f32 v[110:111], v[110:111], v[126:127] neg_lo:[0,1] neg_hi:[0,1]
	s_nop 0
	v_pk_mul_f32 v[126:127], v[110:111], v[124:125] op_sel:[0,0] op_sel_hi:[0,1]
	s_nop 0
	v_pk_fma_f32 v[110:111], v[110:111], v[124:125], v[126:127] op_sel:[1,1,0] op_sel_hi:[1,0,1] neg_lo:[0,1,0]
	v_pk_add_f32 v[126:127], v[140:141], v[146:147]
	v_pk_add_f32 v[140:141], v[140:141], v[146:147] neg_lo:[0,1] neg_hi:[0,1]
	s_nop 0
	v_pk_mul_f32 v[146:147], v[140:141], v[128:129] op_sel:[0,0] op_sel_hi:[0,1]
	s_nop 0
	v_pk_fma_f32 v[140:141], v[140:141], v[128:129], v[146:147] op_sel:[1,1,0] op_sel_hi:[1,0,1] neg_lo:[0,1,0]
	v_pk_add_f32 v[146:147], v[88:89], v[72:73]
	v_pk_add_f32 v[72:73], v[88:89], v[72:73] neg_lo:[0,1] neg_hi:[0,1]
	s_nop 0
	v_pk_mul_f32 v[88:89], v[72:73], v[56:57] op_sel:[0,0] op_sel_hi:[0,1]
	s_nop 0
	v_pk_fma_f32 v[72:73], v[72:73], v[56:57], v[88:89] op_sel:[1,1,0] op_sel_hi:[1,0,1] neg_lo:[0,1,0]
	v_pk_add_f32 v[88:89], v[90:91], v[74:75]
	v_pk_add_f32 v[74:75], v[90:91], v[74:75] neg_lo:[0,1] neg_hi:[0,1]
	s_nop 0
	v_pk_mul_f32 v[90:91], v[74:75], v[60:61] op_sel:[0,0] op_sel_hi:[0,1]
	s_nop 0
	v_pk_fma_f32 v[60:61], v[74:75], v[60:61], v[90:91] op_sel:[1,1,0] op_sel_hi:[1,0,1] neg_lo:[0,1,0]
	v_pk_add_f32 v[74:75], v[92:93], v[76:77]
	v_pk_add_f32 v[76:77], v[92:93], v[76:77] neg_lo:[0,1] neg_hi:[0,1]
	s_nop 0
	v_pk_mul_f32 v[90:91], v[76:77], v[64:65] op_sel:[0,0] op_sel_hi:[0,1]
; __device__ __forceinline__ float2 cmul(float2 a, float2 b) { return make_float2(a.x * b.x - a.y * b.y, a.x * b.y + a.y * b.x); }
; template <int R, bool INV>
; __device__ __forceinline__ void butterflies(c32 (&v)[1 << R], float turns0) {
;     ...
;   for (int kk = 0; kk < R; ++kk) {
;     const int k = INV ? (R - 1 - kk) : kk;
;     const int hd = RAD >> (k + 1);
; #pragma unroll
;     for (int j = 0; j < RAD; ++j) {
;       if ((j & hd) == 0) {
;         const int m = (j & (hd - 1)) * (16 / hd);
;         const float2 c = make_float2(TC[m], INV ? TS[m] : -TS[m]);
;         const float2 twf = cmul(tbs[k], c);
;         const c32 tw = {twf.x, twf.y};
;         const c32 a = v[j], b = v[j + hd];
;         if (!INV) { v[j] = a + b; v[j + hd] = cmul_pk(a - b, tw); }
;         else { const c32 bt = cmul_pk(b, tw); v[j] = a + bt; v[j + hd] = a - bt; }
;       }
;     }
;   }
	s_nop 0
	v_pk_fma_f32 v[76:77], v[76:77], v[64:65], v[90:91] op_sel:[1,1,0] op_sel_hi:[1,0,1] neg_lo:[0,1,0]
	v_pk_add_f32 v[90:91], v[62:63], v[78:79]
	v_pk_add_f32 v[62:63], v[62:63], v[78:79] neg_lo:[0,1] neg_hi:[0,1]
	s_nop 0
	v_pk_mul_f32 v[78:79], v[62:63], v[68:69] op_sel:[0,0] op_sel_hi:[0,1]
	s_nop 0
	v_pk_fma_f32 v[62:63], v[62:63], v[68:69], v[78:79] op_sel:[1,1,0] op_sel_hi:[1,0,1] neg_lo:[0,1,0]
	v_pk_add_f32 v[68:69], v[108:109], v[80:81]
	v_pk_add_f32 v[78:79], v[108:109], v[80:81] neg_lo:[0,1] neg_hi:[0,1]
	v_pk_add_f32 v[108:109], v[130:131], v[142:143] neg_lo:[0,1] neg_hi:[0,1]
	v_pk_mul_f32 v[80:81], v[78:79], v[58:59] op_sel:[0,0] op_sel_hi:[0,1]
	s_nop 0
	v_pk_fma_f32 v[78:79], v[78:79], v[58:59], v[80:81] op_sel:[1,1,0] op_sel_hi:[1,0,1] neg_lo:[0,1,0]
	v_pk_add_f32 v[80:81], v[66:67], v[82:83]
	v_pk_add_f32 v[66:67], v[66:67], v[82:83] neg_lo:[0,1] neg_hi:[0,1]
	s_nop 0
	v_pk_mul_f32 v[82:83], v[66:67], v[120:121] op_sel:[0,0] op_sel_hi:[0,1]
	s_nop 0
	v_pk_fma_f32 v[66:67], v[66:67], v[120:121], v[82:83] op_sel:[1,1,0] op_sel_hi:[1,0,1] neg_lo:[0,1,0]
	v_pk_add_f32 v[82:83], v[112:113], v[84:85]
	v_pk_add_f32 v[84:85], v[112:113], v[84:85] neg_lo:[0,1] neg_hi:[0,1]
	v_pk_mul_f32 v[112:113], v[108:109], v[56:57] op_sel:[0,0] op_sel_hi:[0,1]
	s_nop 0
	v_pk_mul_f32 v[92:93], v[84:85], v[124:125] op_sel:[0,0] op_sel_hi:[0,1]
	v_pk_fma_f32 v[108:109], v[108:109], v[56:57], v[112:113] op_sel:[1,1,0] op_sel_hi:[1,0,1] neg_lo:[0,1,0]
	v_pk_add_f32 v[112:113], v[114:115], v[122:123]
	v_pk_fma_f32 v[84:85], v[84:85], v[124:125], v[92:93] op_sel:[1,1,0] op_sel_hi:[1,0,1] neg_lo:[0,1,0]
	v_pk_add_f32 v[92:93], v[70:71], v[86:87]
	v_pk_add_f32 v[70:71], v[70:71], v[86:87] neg_lo:[0,1] neg_hi:[0,1]
	v_pk_add_f32 v[114:115], v[114:115], v[122:123] neg_lo:[0,1] neg_hi:[0,1]
	v_pk_mul_f32 v[86:87], v[70:71], v[128:129] op_sel:[0,0] op_sel_hi:[0,1]
	v_pk_add_f32 v[122:123], v[132:133], v[144:145] neg_lo:[0,1] neg_hi:[0,1]
	v_pk_fma_f32 v[70:71], v[70:71], v[128:129], v[86:87] op_sel:[1,1,0] op_sel_hi:[1,0,1] neg_lo:[0,1,0]
	v_pk_add_f32 v[86:87], v[130:131], v[142:143]
	v_pk_mul_f32 v[128:129], v[122:123], v[58:59] op_sel:[0,0] op_sel_hi:[0,1]
	v_pk_mul_f32 v[120:121], v[114:115], v[64:65] op_sel:[0,0] op_sel_hi:[0,1]
	s_nop 0
	v_pk_fma_f32 v[122:123], v[122:123], v[58:59], v[128:129] op_sel:[1,1,0] op_sel_hi:[1,0,1] neg_lo:[0,1,0]
	v_pk_add_f32 v[128:129], v[134:135], v[126:127]
	v_pk_add_f32 v[126:127], v[134:135], v[126:127] neg_lo:[0,1] neg_hi:[0,1]
	v_pk_fma_f32 v[114:115], v[114:115], v[64:65], v[120:121] op_sel:[1,1,0] op_sel_hi:[1,0,1] neg_lo:[0,1,0]
	v_pk_add_f32 v[120:121], v[132:133], v[144:145]
	v_pk_mul_f32 v[130:131], v[126:127], v[124:125] op_sel:[0,0] op_sel_hi:[0,1]
	v_pk_add_f32 v[134:135], v[136:137], v[140:141] neg_lo:[0,1] neg_hi:[0,1]
	v_pk_fma_f32 v[126:127], v[126:127], v[124:125], v[130:131] op_sel:[1,1,0] op_sel_hi:[1,0,1] neg_lo:[0,1,0]
	v_pk_add_f32 v[130:131], v[96:97], v[94:95]
	v_pk_add_f32 v[94:95], v[96:97], v[94:95] neg_lo:[0,1] neg_hi:[0,1]
	s_nop 0
	v_pk_mul_f32 v[96:97], v[94:95], v[56:57] op_sel:[0,0] op_sel_hi:[0,1]
	s_nop 0
	v_pk_fma_f32 v[94:95], v[94:95], v[56:57], v[96:97] op_sel:[1,1,0] op_sel_hi:[1,0,1] neg_lo:[0,1,0]
	v_pk_add_f32 v[96:97], v[116:117], v[138:139]
	v_pk_add_f32 v[116:117], v[116:117], v[138:139] neg_lo:[0,1] neg_hi:[0,1]
	s_nop 0
	v_pk_mul_f32 v[132:133], v[116:117], v[64:65] op_sel:[0,0] op_sel_hi:[0,1]
	s_nop 0
	v_pk_fma_f32 v[116:117], v[116:117], v[64:65], v[132:133] op_sel:[1,1,0] op_sel_hi:[1,0,1] neg_lo:[0,1,0]
	v_pk_add_f32 v[132:133], v[118:119], v[110:111]
	v_pk_add_f32 v[110:111], v[118:119], v[110:111] neg_lo:[0,1] neg_hi:[0,1]
	s_nop 0
	v_pk_mul_f32 v[118:119], v[110:111], v[58:59] op_sel:[0,0] op_sel_hi:[0,1]
	s_nop 0
	v_pk_fma_f32 v[110:111], v[110:111], v[58:59], v[118:119] op_sel:[1,1,0] op_sel_hi:[1,0,1] neg_lo:[0,1,0]
	v_pk_add_f32 v[118:119], v[136:137], v[140:141]
	v_pk_mul_f32 v[136:137], v[134:135], v[124:125] op_sel:[0,0] op_sel_hi:[0,1]
	s_nop 0
	v_pk_fma_f32 v[134:135], v[134:135], v[124:125], v[136:137] op_sel:[1,1,0] op_sel_hi:[1,0,1] neg_lo:[0,1,0]
	v_pk_add_f32 v[136:137], v[146:147], v[68:69]
	v_pk_add_f32 v[68:69], v[146:147], v[68:69] neg_lo:[0,1] neg_hi:[0,1]
	s_nop 0
	v_pk_mul_f32 v[138:139], v[68:69], v[56:57] op_sel:[0,0] op_sel_hi:[0,1]
	s_nop 0
	v_pk_fma_f32 v[68:69], v[68:69], v[56:57], v[138:139] op_sel:[1,1,0] op_sel_hi:[1,0,1] neg_lo:[0,1,0]
	v_pk_add_f32 v[138:139], v[88:89], v[80:81]
	v_pk_add_f32 v[80:81], v[88:89], v[80:81] neg_lo:[0,1] neg_hi:[0,1]
	s_nop 0
	v_pk_mul_f32 v[88:89], v[80:81], v[64:65] op_sel:[0,0] op_sel_hi:[0,1]
	s_nop 0
	v_pk_fma_f32 v[80:81], v[80:81], v[64:65], v[88:89] op_sel:[1,1,0] op_sel_hi:[1,0,1] neg_lo:[0,1,0]
	v_pk_add_f32 v[88:89], v[74:75], v[82:83]
	v_pk_add_f32 v[74:75], v[74:75], v[82:83] neg_lo:[0,1] neg_hi:[0,1]
	s_nop 0
	v_pk_mul_f32 v[82:83], v[74:75], v[58:59] op_sel:[0,0] op_sel_hi:[0,1]
	s_nop 0
	v_pk_fma_f32 v[74:75], v[74:75], v[58:59], v[82:83] op_sel:[1,1,0] op_sel_hi:[1,0,1] neg_lo:[0,1,0]
	v_pk_add_f32 v[82:83], v[90:91], v[92:93]
	v_pk_add_f32 v[90:91], v[90:91], v[92:93] neg_lo:[0,1] neg_hi:[0,1]
	s_nop 0
	v_pk_mul_f32 v[92:93], v[90:91], v[124:125] op_sel:[0,0] op_sel_hi:[0,1]
	s_nop 0
	v_pk_fma_f32 v[90:91], v[90:91], v[124:125], v[92:93] op_sel:[1,1,0] op_sel_hi:[1,0,1] neg_lo:[0,1,0]
	v_pk_add_f32 v[92:93], v[72:73], v[78:79]
	v_pk_add_f32 v[72:73], v[72:73], v[78:79] neg_lo:[0,1] neg_hi:[0,1]
	s_nop 0
	v_pk_mul_f32 v[78:79], v[72:73], v[56:57] op_sel:[0,0] op_sel_hi:[0,1]
	s_nop 0
	v_pk_fma_f32 v[72:73], v[72:73], v[56:57], v[78:79] op_sel:[1,1,0] op_sel_hi:[1,0,1] neg_lo:[0,1,0]
; __device__ __forceinline__ float2 cmul(float2 a, float2 b) { return make_float2(a.x * b.x - a.y * b.y, a.x * b.y + a.y * b.x); }
; template <int R, bool INV>
; __device__ __forceinline__ void butterflies(c32 (&v)[1 << R], float turns0) {
;     ...
;   for (int kk = 0; kk < R; ++kk) {
;     const int k = INV ? (R - 1 - kk) : kk;
;     const int hd = RAD >> (k + 1);
; #pragma unroll
;     for (int j = 0; j < RAD; ++j) {
;       if ((j & hd) == 0) {
;         const int m = (j & (hd - 1)) * (16 / hd);
;         const float2 c = make_float2(TC[m], INV ? TS[m] : -TS[m]);
;         const float2 twf = cmul(tbs[k], c);
;         const c32 tw = {twf.x, twf.y};
;         const c32 a = v[j], b = v[j + hd];
;         if (!INV) { v[j] = a + b; v[j + hd] = cmul_pk(a - b, tw); }
;         else { const c32 bt = cmul_pk(b, tw); v[j] = a + bt; v[j + hd] = a - bt; }
;       }
;     }
;   }
	v_pk_add_f32 v[78:79], v[60:61], v[66:67]
	v_pk_add_f32 v[60:61], v[60:61], v[66:67] neg_lo:[0,1] neg_hi:[0,1]
	s_nop 0
	v_pk_mul_f32 v[66:67], v[60:61], v[64:65] op_sel:[0,0] op_sel_hi:[0,1]
	s_nop 0
	v_pk_fma_f32 v[60:61], v[60:61], v[64:65], v[66:67] op_sel:[1,1,0] op_sel_hi:[1,0,1] neg_lo:[0,1,0]
	v_pk_add_f32 v[64:65], v[76:77], v[84:85]
	v_pk_add_f32 v[66:67], v[76:77], v[84:85] neg_lo:[0,1] neg_hi:[0,1]
	v_pk_add_f32 v[84:85], v[86:87], v[120:121] neg_lo:[0,1] neg_hi:[0,1]
	v_pk_mul_f32 v[76:77], v[66:67], v[58:59] op_sel:[0,0] op_sel_hi:[0,1]
	s_nop 0
	v_pk_fma_f32 v[66:67], v[66:67], v[58:59], v[76:77] op_sel:[1,1,0] op_sel_hi:[1,0,1] neg_lo:[0,1,0]
	v_pk_add_f32 v[76:77], v[62:63], v[70:71]
	v_pk_add_f32 v[62:63], v[62:63], v[70:71] neg_lo:[0,1] neg_hi:[0,1]
	s_nop 0
	v_pk_mul_f32 v[70:71], v[62:63], v[124:125] op_sel:[0,0] op_sel_hi:[0,1]
	s_nop 0
	v_pk_fma_f32 v[62:63], v[62:63], v[124:125], v[70:71] op_sel:[1,1,0] op_sel_hi:[1,0,1] neg_lo:[0,1,0]
	v_pk_add_f32 v[70:71], v[86:87], v[120:121]
	v_pk_mul_f32 v[86:87], v[84:85], v[56:57] op_sel:[0,0] op_sel_hi:[0,1]
	s_nop 0
	v_pk_fma_f32 v[84:85], v[84:85], v[56:57], v[86:87] op_sel:[1,1,0] op_sel_hi:[1,0,1] neg_lo:[0,1,0]
	v_pk_add_f32 v[86:87], v[112:113], v[128:129]
	v_pk_add_f32 v[112:113], v[112:113], v[128:129] neg_lo:[0,1] neg_hi:[0,1]
	s_nop 0
	v_pk_mul_f32 v[120:121], v[112:113], v[58:59] op_sel:[0,0] op_sel_hi:[0,1]
	s_nop 0
	v_pk_fma_f32 v[112:113], v[112:113], v[58:59], v[120:121] op_sel:[1,1,0] op_sel_hi:[1,0,1] neg_lo:[0,1,0]
	v_pk_add_f32 v[120:121], v[108:109], v[122:123]
	v_pk_add_f32 v[108:109], v[108:109], v[122:123] neg_lo:[0,1] neg_hi:[0,1]
	s_nop 0
	v_pk_mul_f32 v[122:123], v[108:109], v[56:57] op_sel:[0,0] op_sel_hi:[0,1]
	s_nop 0
	v_pk_fma_f32 v[108:109], v[108:109], v[56:57], v[122:123] op_sel:[1,1,0] op_sel_hi:[1,0,1] neg_lo:[0,1,0]
	v_pk_add_f32 v[122:123], v[114:115], v[126:127]
	v_pk_add_f32 v[114:115], v[114:115], v[126:127] neg_lo:[0,1] neg_hi:[0,1]
	v_pk_add_f32 v[126:127], v[130:131], v[132:133] neg_lo:[0,1] neg_hi:[0,1]
	v_pk_mul_f32 v[124:125], v[114:115], v[58:59] op_sel:[0,0] op_sel_hi:[0,1]
	s_nop 0
	v_pk_mul_f32 v[128:129], v[126:127], v[56:57] op_sel:[0,0] op_sel_hi:[0,1]
	v_pk_fma_f32 v[114:115], v[114:115], v[58:59], v[124:125] op_sel:[1,1,0] op_sel_hi:[1,0,1] neg_lo:[0,1,0]
	v_pk_add_f32 v[124:125], v[130:131], v[132:133]
	v_pk_fma_f32 v[126:127], v[126:127], v[56:57], v[128:129] op_sel:[1,1,0] op_sel_hi:[1,0,1] neg_lo:[0,1,0]
	v_pk_add_f32 v[128:129], v[96:97], v[118:119]
	v_pk_add_f32 v[96:97], v[96:97], v[118:119] neg_lo:[0,1] neg_hi:[0,1]
	s_nop 0
	v_pk_mul_f32 v[118:119], v[96:97], v[58:59] op_sel:[0,0] op_sel_hi:[0,1]
	s_nop 0
	v_pk_fma_f32 v[96:97], v[96:97], v[58:59], v[118:119] op_sel:[1,1,0] op_sel_hi:[1,0,1] neg_lo:[0,1,0]
	v_pk_add_f32 v[118:119], v[94:95], v[110:111]
	v_pk_add_f32 v[94:95], v[94:95], v[110:111] neg_lo:[0,1] neg_hi:[0,1]
	s_nop 0
	v_pk_mul_f32 v[110:111], v[94:95], v[56:57] op_sel:[0,0] op_sel_hi:[0,1]
	s_nop 0
	v_pk_fma_f32 v[94:95], v[94:95], v[56:57], v[110:111] op_sel:[1,1,0] op_sel_hi:[1,0,1] neg_lo:[0,1,0]
	v_pk_add_f32 v[110:111], v[116:117], v[134:135]
	v_pk_add_f32 v[116:117], v[116:117], v[134:135] neg_lo:[0,1] neg_hi:[0,1]
	s_nop 0
	v_pk_mul_f32 v[130:131], v[116:117], v[58:59] op_sel:[0,0] op_sel_hi:[0,1]
	s_nop 0
	v_pk_fma_f32 v[116:117], v[116:117], v[58:59], v[130:131] op_sel:[1,1,0] op_sel_hi:[1,0,1] neg_lo:[0,1,0]
	v_pk_add_f32 v[130:131], v[136:137], v[88:89]
	v_pk_add_f32 v[88:89], v[136:137], v[88:89] neg_lo:[0,1] neg_hi:[0,1]
	s_nop 0
	v_pk_mul_f32 v[132:133], v[88:89], v[56:57] op_sel:[0,0] op_sel_hi:[0,1]
	s_nop 0
	v_pk_fma_f32 v[88:89], v[88:89], v[56:57], v[132:133] op_sel:[1,1,0] op_sel_hi:[1,0,1] neg_lo:[0,1,0]
	v_pk_add_f32 v[132:133], v[138:139], v[82:83]
	v_pk_add_f32 v[82:83], v[138:139], v[82:83] neg_lo:[0,1] neg_hi:[0,1]
	s_nop 0
	v_pk_mul_f32 v[134:135], v[82:83], v[58:59] op_sel:[0,0] op_sel_hi:[0,1]
	s_nop 0
	v_pk_fma_f32 v[82:83], v[82:83], v[58:59], v[134:135] op_sel:[1,1,0] op_sel_hi:[1,0,1] neg_lo:[0,1,0]
	v_pk_add_f32 v[134:135], v[68:69], v[74:75]
	v_pk_add_f32 v[68:69], v[68:69], v[74:75] neg_lo:[0,1] neg_hi:[0,1]
	s_nop 0
	v_pk_mul_f32 v[74:75], v[68:69], v[56:57] op_sel:[0,0] op_sel_hi:[0,1]
	s_nop 0
	v_pk_fma_f32 v[68:69], v[68:69], v[56:57], v[74:75] op_sel:[1,1,0] op_sel_hi:[1,0,1] neg_lo:[0,1,0]
	v_pk_add_f32 v[74:75], v[80:81], v[90:91]
	v_pk_add_f32 v[80:81], v[80:81], v[90:91] neg_lo:[0,1] neg_hi:[0,1]
	s_nop 0
	v_pk_mul_f32 v[90:91], v[80:81], v[58:59] op_sel:[0,0] op_sel_hi:[0,1]
	s_nop 0
	v_pk_fma_f32 v[80:81], v[80:81], v[58:59], v[90:91] op_sel:[1,1,0] op_sel_hi:[1,0,1] neg_lo:[0,1,0]
	v_pk_add_f32 v[90:91], v[92:93], v[64:65]
	v_pk_add_f32 v[64:65], v[92:93], v[64:65] neg_lo:[0,1] neg_hi:[0,1]
	s_nop 0
	v_pk_mul_f32 v[92:93], v[64:65], v[56:57] op_sel:[0,0] op_sel_hi:[0,1]
	s_nop 0
	v_pk_fma_f32 v[64:65], v[64:65], v[56:57], v[92:93] op_sel:[1,1,0] op_sel_hi:[1,0,1] neg_lo:[0,1,0]
	v_pk_add_f32 v[92:93], v[78:79], v[76:77]
	v_pk_add_f32 v[76:77], v[78:79], v[76:77] neg_lo:[0,1] neg_hi:[0,1]
	s_nop 0
	v_pk_mul_f32 v[78:79], v[76:77], v[58:59] op_sel:[0,0] op_sel_hi:[0,1]
	s_nop 0
	v_pk_fma_f32 v[76:77], v[76:77], v[58:59], v[78:79] op_sel:[1,1,0] op_sel_hi:[1,0,1] neg_lo:[0,1,0]
	v_pk_add_f32 v[78:79], v[72:73], v[66:67]
	v_pk_add_f32 v[66:67], v[72:73], v[66:67] neg_lo:[0,1] neg_hi:[0,1]
	s_nop 0
	v_pk_mul_f32 v[72:73], v[66:67], v[56:57] op_sel:[0,0] op_sel_hi:[0,1]
	s_nop 0
	v_pk_fma_f32 v[66:67], v[66:67], v[56:57], v[72:73] op_sel:[1,1,0] op_sel_hi:[1,0,1] neg_lo:[0,1,0]
	v_pk_add_f32 v[72:73], v[60:61], v[62:63]
; __device__ __forceinline__ float2 cmul(float2 a, float2 b) { return make_float2(a.x * b.x - a.y * b.y, a.x * b.y + a.y * b.x); }
; template <int R, bool INV>
; __device__ __forceinline__ void butterflies(c32 (&v)[1 << R], float turns0) {
;     ...
;   for (int kk = 0; kk < R; ++kk) {
;     const int k = INV ? (R - 1 - kk) : kk;
;     const int hd = RAD >> (k + 1);
; #pragma unroll
;     for (int j = 0; j < RAD; ++j) {
;       if ((j & hd) == 0) {
;         const int m = (j & (hd - 1)) * (16 / hd);
;         const float2 c = make_float2(TC[m], INV ? TS[m] : -TS[m]);
;         const float2 twf = cmul(tbs[k], c);
;         const c32 tw = {twf.x, twf.y};
;         const c32 a = v[j], b = v[j + hd];
;         if (!INV) { v[j] = a + b; v[j + hd] = cmul_pk(a - b, tw); }
;         else { const c32 bt = cmul_pk(b, tw); v[j] = a + bt; v[j + hd] = a - bt; }
;       }
;     }
;   }
; template <int LOGN>
; __device__ __forceinline__ void fft_fused_mul(float2* X, const c32 (&kf)[32]) {
;     ...
; #pragma unroll
;   for (int j = 0; j < 32; ++j) v[j] = cmul_pk(v[j], kf[j]);
	v_pk_add_f32 v[60:61], v[60:61], v[62:63] neg_lo:[0,1] neg_hi:[0,1]
	s_nop 0
	v_pk_mul_f32 v[62:63], v[60:61], v[58:59] op_sel:[0,0] op_sel_hi:[0,1]
	s_nop 0
	v_pk_fma_f32 v[58:59], v[60:61], v[58:59], v[62:63] op_sel:[1,1,0] op_sel_hi:[1,0,1] neg_lo:[0,1,0]
	v_pk_add_f32 v[60:61], v[70:71], v[86:87]
	v_pk_add_f32 v[62:63], v[70:71], v[86:87] neg_lo:[0,1] neg_hi:[0,1]
	s_nop 0
	v_pk_mul_f32 v[70:71], v[62:63], v[56:57] op_sel:[0,0] op_sel_hi:[0,1]
	s_nop 0
	v_pk_fma_f32 v[62:63], v[62:63], v[56:57], v[70:71] op_sel:[1,1,0] op_sel_hi:[1,0,1] neg_lo:[0,1,0]
	v_pk_add_f32 v[70:71], v[84:85], v[112:113]
	v_pk_add_f32 v[84:85], v[84:85], v[112:113] neg_lo:[0,1] neg_hi:[0,1]
	v_pk_add_f32 v[112:113], v[120:121], v[122:123] neg_lo:[0,1] neg_hi:[0,1]
	v_pk_mul_f32 v[86:87], v[84:85], v[56:57] op_sel:[0,0] op_sel_hi:[0,1]
	s_nop 0
	v_pk_fma_f32 v[84:85], v[84:85], v[56:57], v[86:87] op_sel:[1,1,0] op_sel_hi:[1,0,1] neg_lo:[0,1,0]
	v_pk_add_f32 v[86:87], v[120:121], v[122:123]
	v_pk_mul_f32 v[120:121], v[112:113], v[56:57] op_sel:[0,0] op_sel_hi:[0,1]
	v_pk_add_f32 v[122:123], v[124:125], v[128:129] neg_lo:[0,1] neg_hi:[0,1]
	v_pk_fma_f32 v[112:113], v[112:113], v[56:57], v[120:121] op_sel:[1,1,0] op_sel_hi:[1,0,1] neg_lo:[0,1,0]
	v_pk_add_f32 v[120:121], v[108:109], v[114:115]
	v_pk_add_f32 v[108:109], v[108:109], v[114:115] neg_lo:[0,1] neg_hi:[0,1]
	s_nop 0
	v_pk_mul_f32 v[114:115], v[108:109], v[56:57] op_sel:[0,0] op_sel_hi:[0,1]
	s_nop 0
	v_pk_fma_f32 v[108:109], v[108:109], v[56:57], v[114:115] op_sel:[1,1,0] op_sel_hi:[1,0,1] neg_lo:[0,1,0]
	v_pk_add_f32 v[114:115], v[124:125], v[128:129]
	v_pk_mul_f32 v[124:125], v[122:123], v[56:57] op_sel:[0,0] op_sel_hi:[0,1]
	v_pk_add_f32 v[128:129], v[130:131], v[132:133] neg_lo:[0,1] neg_hi:[0,1]
	v_pk_fma_f32 v[122:123], v[122:123], v[56:57], v[124:125] op_sel:[1,1,0] op_sel_hi:[1,0,1] neg_lo:[0,1,0]
	v_pk_add_f32 v[124:125], v[126:127], v[96:97]
	v_pk_add_f32 v[96:97], v[126:127], v[96:97] neg_lo:[0,1] neg_hi:[0,1]
	s_nop 0
	v_pk_mul_f32 v[126:127], v[96:97], v[56:57] op_sel:[0,0] op_sel_hi:[0,1]
	s_nop 0
	v_pk_fma_f32 v[96:97], v[96:97], v[56:57], v[126:127] op_sel:[1,1,0] op_sel_hi:[1,0,1] neg_lo:[0,1,0]
	v_pk_add_f32 v[126:127], v[118:119], v[110:111]
	v_pk_add_f32 v[110:111], v[118:119], v[110:111] neg_lo:[0,1] neg_hi:[0,1]
	s_nop 0
	v_pk_mul_f32 v[118:119], v[110:111], v[56:57] op_sel:[0,0] op_sel_hi:[0,1]
	s_nop 0
	v_pk_fma_f32 v[110:111], v[110:111], v[56:57], v[118:119] op_sel:[1,1,0] op_sel_hi:[1,0,1] neg_lo:[0,1,0]
	v_pk_add_f32 v[118:119], v[94:95], v[116:117]
	v_pk_add_f32 v[94:95], v[94:95], v[116:117] neg_lo:[0,1] neg_hi:[0,1]
	s_nop 0
	v_pk_mul_f32 v[116:117], v[94:95], v[56:57] op_sel:[0,0] op_sel_hi:[0,1]
	s_nop 0
	v_pk_fma_f32 v[94:95], v[94:95], v[56:57], v[116:117] op_sel:[1,1,0] op_sel_hi:[1,0,1] neg_lo:[0,1,0]
	v_pk_add_f32 v[116:117], v[130:131], v[132:133]
	v_pk_mul_f32 v[130:131], v[128:129], v[56:57] op_sel:[0,0] op_sel_hi:[0,1]
	s_nop 0
	v_pk_fma_f32 v[128:129], v[128:129], v[56:57], v[130:131] op_sel:[1,1,0] op_sel_hi:[1,0,1] neg_lo:[0,1,0]
	v_pk_add_f32 v[130:131], v[88:89], v[82:83]
	v_pk_add_f32 v[82:83], v[88:89], v[82:83] neg_lo:[0,1] neg_hi:[0,1]
	s_nop 0
	v_pk_mul_f32 v[88:89], v[82:83], v[56:57] op_sel:[0,0] op_sel_hi:[0,1]
	s_nop 0
	v_pk_fma_f32 v[82:83], v[82:83], v[56:57], v[88:89] op_sel:[1,1,0] op_sel_hi:[1,0,1] neg_lo:[0,1,0]
	v_pk_add_f32 v[88:89], v[134:135], v[74:75]
	v_pk_add_f32 v[74:75], v[134:135], v[74:75] neg_lo:[0,1] neg_hi:[0,1]
	s_nop 0
	v_pk_mul_f32 v[132:133], v[74:75], v[56:57] op_sel:[0,0] op_sel_hi:[0,1]
	s_nop 0
	v_pk_fma_f32 v[74:75], v[74:75], v[56:57], v[132:133] op_sel:[1,1,0] op_sel_hi:[1,0,1] neg_lo:[0,1,0]
	v_pk_add_f32 v[132:133], v[68:69], v[80:81]
	v_pk_add_f32 v[68:69], v[68:69], v[80:81] neg_lo:[0,1] neg_hi:[0,1]
	s_nop 0
	v_pk_mul_f32 v[80:81], v[68:69], v[56:57] op_sel:[0,0] op_sel_hi:[0,1]
	s_nop 0
	v_pk_fma_f32 v[68:69], v[68:69], v[56:57], v[80:81] op_sel:[1,1,0] op_sel_hi:[1,0,1] neg_lo:[0,1,0]
	v_pk_add_f32 v[80:81], v[90:91], v[92:93]
	v_pk_add_f32 v[90:91], v[90:91], v[92:93] neg_lo:[0,1] neg_hi:[0,1]
	s_nop 0
	v_pk_mul_f32 v[92:93], v[90:91], v[56:57] op_sel:[0,0] op_sel_hi:[0,1]
	s_nop 0
	v_pk_fma_f32 v[90:91], v[90:91], v[56:57], v[92:93] op_sel:[1,1,0] op_sel_hi:[1,0,1] neg_lo:[0,1,0]
	v_pk_add_f32 v[92:93], v[64:65], v[76:77]
	v_pk_add_f32 v[64:65], v[64:65], v[76:77] neg_lo:[0,1] neg_hi:[0,1]
	s_nop 0
	v_pk_mul_f32 v[76:77], v[64:65], v[56:57] op_sel:[0,0] op_sel_hi:[0,1]
	s_nop 0
	v_pk_fma_f32 v[64:65], v[64:65], v[56:57], v[76:77] op_sel:[1,1,0] op_sel_hi:[1,0,1] neg_lo:[0,1,0]
	v_pk_add_f32 v[76:77], v[78:79], v[72:73]
	v_pk_add_f32 v[72:73], v[78:79], v[72:73] neg_lo:[0,1] neg_hi:[0,1]
	s_nop 0
	v_pk_mul_f32 v[78:79], v[72:73], v[56:57] op_sel:[0,0] op_sel_hi:[0,1]
	s_nop 0
	v_pk_fma_f32 v[72:73], v[72:73], v[56:57], v[78:79] op_sel:[1,1,0] op_sel_hi:[1,0,1] neg_lo:[0,1,0]
	v_pk_add_f32 v[78:79], v[66:67], v[58:59]
	v_pk_add_f32 v[58:59], v[66:67], v[58:59] neg_lo:[0,1] neg_hi:[0,1]
	s_nop 0
	v_pk_mul_f32 v[66:67], v[58:59], v[56:57] op_sel:[0,0] op_sel_hi:[0,1]
	s_nop 0
	v_pk_fma_f32 v[56:57], v[58:59], v[56:57], v[66:67] op_sel:[1,1,0] op_sel_hi:[1,0,1] neg_lo:[0,1,0]
	v_pk_mul_f32 v[58:59], v[60:61], v[106:107] op_sel:[0,0] op_sel_hi:[0,1]
	v_pk_mul_f32 v[66:67], v[112:113], v[26:27] op_sel:[0,0] op_sel_hi:[0,1]
	s_nop 0
	v_pk_fma_f32 v[58:59], v[60:61], v[106:107], v[58:59] op_sel:[1,1,0] op_sel_hi:[1,0,1] neg_lo:[0,1,0]
	v_pk_mul_f32 v[60:61], v[62:63], v[30:31] op_sel:[0,0] op_sel_hi:[0,1]
	v_pk_fma_f32 v[26:27], v[112:113], v[26:27], v[66:67] op_sel:[1,1,0] op_sel_hi:[1,0,1] neg_lo:[0,1,0]
; __device__ __forceinline__ float2 cmul(float2 a, float2 b) { return make_float2(a.x * b.x - a.y * b.y, a.x * b.y + a.y * b.x); }
; template <int R, bool INV>
; __device__ __forceinline__ void butterflies(c32 (&v)[1 << R], float turns0) {
;     ...
;   for (int kk = 0; kk < R; ++kk) {
;     const int k = INV ? (R - 1 - kk) : kk;
;     const int hd = RAD >> (k + 1);
; #pragma unroll
;     for (int j = 0; j < RAD; ++j) {
;       if ((j & hd) == 0) {
;         const int m = (j & (hd - 1)) * (16 / hd);
;         const float2 c = make_float2(TC[m], INV ? TS[m] : -TS[m]);
;         const float2 twf = cmul(tbs[k], c);
;         const c32 tw = {twf.x, twf.y};
;         const c32 a = v[j], b = v[j + hd];
;         if (!INV) { v[j] = a + b; v[j + hd] = cmul_pk(a - b, tw); }
;         else { const c32 bt = cmul_pk(b, tw); v[j] = a + bt; v[j + hd] = a - bt; }
;       }
;     }
;   }
; template <int LOGN>
; __device__ __forceinline__ void fft_fused_mul(float2* X, const c32 (&kf)[32]) {
;     ...
; #pragma unroll
;   for (int j = 0; j < 32; ++j) v[j] = cmul_pk(v[j], kf[j]);
;   butterflies<5, true>(v, 0.f);
	v_pk_mul_f32 v[66:67], v[120:121], v[100:101] op_sel:[0,0] op_sel_hi:[0,1]
	s_nop 0
	v_pk_fma_f32 v[30:31], v[62:63], v[30:31], v[60:61] op_sel:[1,1,0] op_sel_hi:[1,0,1] neg_lo:[0,1,0]
	v_pk_mul_f32 v[62:63], v[84:85], v[28:29] op_sel:[0,0] op_sel_hi:[0,1]
	v_pk_mul_f32 v[60:61], v[70:71], v[104:105] op_sel:[0,0] op_sel_hi:[0,1]
	v_pk_fma_f32 v[66:67], v[120:121], v[100:101], v[66:67] op_sel:[1,1,0] op_sel_hi:[1,0,1] neg_lo:[0,1,0]
	s_nop 0
	v_pk_fma_f32 v[28:29], v[84:85], v[28:29], v[62:63] op_sel:[1,1,0] op_sel_hi:[1,0,1] neg_lo:[0,1,0]
	v_pk_mul_f32 v[84:85], v[122:123], v[22:23] op_sel:[0,0] op_sel_hi:[0,1]
	v_pk_fma_f32 v[60:61], v[70:71], v[104:105], v[60:61] op_sel:[1,1,0] op_sel_hi:[1,0,1] neg_lo:[0,1,0]
	v_pk_mul_f32 v[62:63], v[86:87], v[102:103] op_sel:[0,0] op_sel_hi:[0,1]
	v_pk_mul_f32 v[70:71], v[108:109], v[24:25] op_sel:[0,0] op_sel_hi:[0,1]
	s_nop 0
	v_pk_fma_f32 v[22:23], v[122:123], v[22:23], v[84:85] op_sel:[1,1,0] op_sel_hi:[1,0,1] neg_lo:[0,1,0]
	v_pk_mul_f32 v[84:85], v[124:125], v[54:55] op_sel:[0,0] op_sel_hi:[0,1]
	v_pk_fma_f32 v[62:63], v[86:87], v[102:103], v[62:63] op_sel:[1,1,0] op_sel_hi:[1,0,1] neg_lo:[0,1,0]
	v_pk_fma_f32 v[24:25], v[108:109], v[24:25], v[70:71] op_sel:[1,1,0] op_sel_hi:[1,0,1] neg_lo:[0,1,0]
	v_pk_mul_f32 v[70:71], v[114:115], v[98:99] op_sel:[0,0] op_sel_hi:[0,1]
	s_nop 0
	v_pk_fma_f32 v[54:55], v[124:125], v[54:55], v[84:85] op_sel:[1,1,0] op_sel_hi:[1,0,1] neg_lo:[0,1,0]
	v_pk_mul_f32 v[84:85], v[96:97], v[20:21] op_sel:[0,0] op_sel_hi:[0,1]
	v_pk_fma_f32 v[70:71], v[114:115], v[98:99], v[70:71] op_sel:[1,1,0] op_sel_hi:[1,0,1] neg_lo:[0,1,0]
	s_nop 0
	v_pk_fma_f32 v[20:21], v[96:97], v[20:21], v[84:85] op_sel:[1,1,0] op_sel_hi:[1,0,1] neg_lo:[0,1,0]
	v_pk_mul_f32 v[84:85], v[126:127], v[52:53] op_sel:[0,0] op_sel_hi:[0,1]
	s_nop 0
	v_pk_fma_f32 v[52:53], v[126:127], v[52:53], v[84:85] op_sel:[1,1,0] op_sel_hi:[1,0,1] neg_lo:[0,1,0]
	v_pk_mul_f32 v[84:85], v[110:111], v[18:19] op_sel:[0,0] op_sel_hi:[0,1]
	s_nop 0
	v_pk_fma_f32 v[18:19], v[110:111], v[18:19], v[84:85] op_sel:[1,1,0] op_sel_hi:[1,0,1] neg_lo:[0,1,0]
	v_pk_mul_f32 v[84:85], v[118:119], v[50:51] op_sel:[0,0] op_sel_hi:[0,1]
	s_nop 0
	v_pk_fma_f32 v[50:51], v[118:119], v[50:51], v[84:85] op_sel:[1,1,0] op_sel_hi:[1,0,1] neg_lo:[0,1,0]
	v_pk_mul_f32 v[84:85], v[94:95], v[16:17] op_sel:[0,0] op_sel_hi:[0,1]
	s_nop 0
	v_pk_fma_f32 v[16:17], v[94:95], v[16:17], v[84:85] op_sel:[1,1,0] op_sel_hi:[1,0,1] neg_lo:[0,1,0]
	v_pk_mul_f32 v[84:85], v[116:117], v[48:49] op_sel:[0,0] op_sel_hi:[0,1]
	s_nop 0
	v_pk_fma_f32 v[48:49], v[116:117], v[48:49], v[84:85] op_sel:[1,1,0] op_sel_hi:[1,0,1] neg_lo:[0,1,0]
	v_pk_mul_f32 v[84:85], v[128:129], v[14:15] op_sel:[0,0] op_sel_hi:[0,1]
	s_nop 0
	v_pk_fma_f32 v[14:15], v[128:129], v[14:15], v[84:85] op_sel:[1,1,0] op_sel_hi:[1,0,1] neg_lo:[0,1,0]
	v_pk_mul_f32 v[84:85], v[130:131], v[46:47] op_sel:[0,0] op_sel_hi:[0,1]
	s_nop 0
	v_pk_fma_f32 v[46:47], v[130:131], v[46:47], v[84:85] op_sel:[1,1,0] op_sel_hi:[1,0,1] neg_lo:[0,1,0]
	v_pk_mul_f32 v[84:85], v[82:83], v[12:13] op_sel:[0,0] op_sel_hi:[0,1]
	s_nop 0
	v_pk_fma_f32 v[12:13], v[82:83], v[12:13], v[84:85] op_sel:[1,1,0] op_sel_hi:[1,0,1] neg_lo:[0,1,0]
	v_pk_mul_f32 v[82:83], v[88:89], v[44:45] op_sel:[0,0] op_sel_hi:[0,1]
	s_nop 0
	v_pk_fma_f32 v[44:45], v[88:89], v[44:45], v[82:83] op_sel:[1,1,0] op_sel_hi:[1,0,1] neg_lo:[0,1,0]
	v_pk_mul_f32 v[82:83], v[74:75], v[10:11] op_sel:[0,0] op_sel_hi:[0,1]
	s_nop 0
	v_pk_fma_f32 v[10:11], v[74:75], v[10:11], v[82:83] op_sel:[1,1,0] op_sel_hi:[1,0,1] neg_lo:[0,1,0]
	v_pk_mul_f32 v[74:75], v[132:133], v[42:43] op_sel:[0,0] op_sel_hi:[0,1]
	s_nop 0
	v_pk_fma_f32 v[42:43], v[132:133], v[42:43], v[74:75] op_sel:[1,1,0] op_sel_hi:[1,0,1] neg_lo:[0,1,0]
	v_pk_mul_f32 v[74:75], v[68:69], v[8:9] op_sel:[0,0] op_sel_hi:[0,1]
	s_nop 0
	v_pk_fma_f32 v[8:9], v[68:69], v[8:9], v[74:75] op_sel:[1,1,0] op_sel_hi:[1,0,1] neg_lo:[0,1,0]
	v_pk_mul_f32 v[68:69], v[80:81], v[40:41] op_sel:[0,0] op_sel_hi:[0,1]
	s_nop 0
	v_pk_fma_f32 v[40:41], v[80:81], v[40:41], v[68:69] op_sel:[1,1,0] op_sel_hi:[1,0,1] neg_lo:[0,1,0]
	v_pk_mul_f32 v[68:69], v[90:91], v[6:7] op_sel:[0,0] op_sel_hi:[0,1]
	s_nop 0
	v_pk_fma_f32 v[6:7], v[90:91], v[6:7], v[68:69] op_sel:[1,1,0] op_sel_hi:[1,0,1] neg_lo:[0,1,0]
	v_pk_mul_f32 v[68:69], v[92:93], v[38:39] op_sel:[0,0] op_sel_hi:[0,1]
	s_nop 0
	v_pk_fma_f32 v[38:39], v[92:93], v[38:39], v[68:69] op_sel:[1,1,0] op_sel_hi:[1,0,1] neg_lo:[0,1,0]
	v_pk_mul_f32 v[68:69], v[64:65], v[4:5] op_sel:[0,0] op_sel_hi:[0,1]
	s_nop 0
	v_pk_fma_f32 v[4:5], v[64:65], v[4:5], v[68:69] op_sel:[1,1,0] op_sel_hi:[1,0,1] neg_lo:[0,1,0]
	v_pk_mul_f32 v[64:65], v[76:77], v[36:37] op_sel:[0,0] op_sel_hi:[0,1]
	s_nop 0
	v_pk_fma_f32 v[36:37], v[76:77], v[36:37], v[64:65] op_sel:[1,1,0] op_sel_hi:[1,0,1] neg_lo:[0,1,0]
	v_pk_mul_f32 v[64:65], v[72:73], v[2:3] op_sel:[0,0] op_sel_hi:[0,1]
	s_nop 0
	v_pk_fma_f32 v[2:3], v[72:73], v[2:3], v[64:65] op_sel:[1,1,0] op_sel_hi:[1,0,1] neg_lo:[0,1,0]
	v_pk_mul_f32 v[64:65], v[78:79], v[34:35] op_sel:[0,0] op_sel_hi:[0,1]
	s_nop 0
	v_pk_fma_f32 v[34:35], v[78:79], v[34:35], v[64:65] op_sel:[1,1,0] op_sel_hi:[1,0,1] neg_lo:[0,1,0]
	v_pk_mul_f32 v[64:65], v[56:57], v[0:1] op_sel:[0,0] op_sel_hi:[0,1]
	s_nop 0
	v_pk_fma_f32 v[56:57], v[56:57], v[0:1], v[64:65] op_sel:[1,1,0] op_sel_hi:[1,0,1] neg_lo:[0,1,0]
	v_mov_b64_e32 v[0:1], s[6:7]
	v_pk_mul_f32 v[68:69], v[20:21], v[0:1] op_sel:[0,0] op_sel_hi:[0,1]
	v_pk_mul_f32 v[64:65], v[30:31], v[0:1] op_sel:[0,0] op_sel_hi:[0,1]
	s_nop 0
	v_pk_fma_f32 v[20:21], v[20:21], v[0:1], v[68:69] op_sel:[1,1,0] op_sel_hi:[1,0,1] neg_lo:[0,1,0]
; __device__ __forceinline__ float2 cmul(float2 a, float2 b) { return make_float2(a.x * b.x - a.y * b.y, a.x * b.y + a.y * b.x); }
; template <int R, bool INV>
; __device__ __forceinline__ void butterflies(c32 (&v)[1 << R], float turns0) {
;     ...
;   for (int kk = 0; kk < R; ++kk) {
;     const int k = INV ? (R - 1 - kk) : kk;
;     const int hd = RAD >> (k + 1);
; #pragma unroll
;     for (int j = 0; j < RAD; ++j) {
;       if ((j & hd) == 0) {
;         const int m = (j & (hd - 1)) * (16 / hd);
;         const float2 c = make_float2(TC[m], INV ? TS[m] : -TS[m]);
;         const float2 twf = cmul(tbs[k], c);
;         const c32 tw = {twf.x, twf.y};
;         const c32 a = v[j], b = v[j + hd];
;         if (!INV) { v[j] = a + b; v[j + hd] = cmul_pk(a - b, tw); }
;         else { const c32 bt = cmul_pk(b, tw); v[j] = a + bt; v[j + hd] = a - bt; }
;       }
;     }
;   }
	v_pk_fma_f32 v[30:31], v[30:31], v[0:1], v[64:65] op_sel:[1,1,0] op_sel_hi:[1,0,1] neg_lo:[0,1,0]
	s_nop 0
	v_pk_add_f32 v[68:69], v[54:55], v[20:21]
	v_pk_add_f32 v[20:21], v[54:55], v[20:21] neg_lo:[0,1] neg_hi:[0,1]
	v_pk_mul_f32 v[54:55], v[18:19], v[0:1] op_sel:[0,0] op_sel_hi:[0,1]
	v_pk_add_f32 v[64:65], v[58:59], v[30:31]
	v_pk_fma_f32 v[18:19], v[18:19], v[0:1], v[54:55] op_sel:[1,1,0] op_sel_hi:[1,0,1] neg_lo:[0,1,0]
	v_pk_add_f32 v[30:31], v[58:59], v[30:31] neg_lo:[0,1] neg_hi:[0,1]
	v_pk_add_f32 v[54:55], v[52:53], v[18:19]
	v_pk_add_f32 v[18:19], v[52:53], v[18:19] neg_lo:[0,1] neg_hi:[0,1]
	v_pk_mul_f32 v[52:53], v[16:17], v[0:1] op_sel:[0,0] op_sel_hi:[0,1]
	v_pk_mul_f32 v[58:59], v[28:29], v[0:1] op_sel:[0,0] op_sel_hi:[0,1]
	s_nop 0
	v_pk_fma_f32 v[16:17], v[16:17], v[0:1], v[52:53] op_sel:[1,1,0] op_sel_hi:[1,0,1] neg_lo:[0,1,0]
	v_pk_fma_f32 v[28:29], v[28:29], v[0:1], v[58:59] op_sel:[1,1,0] op_sel_hi:[1,0,1] neg_lo:[0,1,0]
	s_nop 0
	v_pk_add_f32 v[52:53], v[50:51], v[16:17]
	v_pk_add_f32 v[16:17], v[50:51], v[16:17] neg_lo:[0,1] neg_hi:[0,1]
	v_pk_mul_f32 v[50:51], v[14:15], v[0:1] op_sel:[0,0] op_sel_hi:[0,1]
	v_pk_add_f32 v[58:59], v[60:61], v[28:29]
	v_pk_fma_f32 v[14:15], v[14:15], v[0:1], v[50:51] op_sel:[1,1,0] op_sel_hi:[1,0,1] neg_lo:[0,1,0]
	v_pk_add_f32 v[28:29], v[60:61], v[28:29] neg_lo:[0,1] neg_hi:[0,1]
	v_pk_add_f32 v[50:51], v[48:49], v[14:15]
	v_pk_add_f32 v[14:15], v[48:49], v[14:15] neg_lo:[0,1] neg_hi:[0,1]
	v_pk_mul_f32 v[48:49], v[12:13], v[0:1] op_sel:[0,0] op_sel_hi:[0,1]
	v_pk_mul_f32 v[60:61], v[26:27], v[0:1] op_sel:[0,0] op_sel_hi:[0,1]
	s_nop 0
	v_pk_fma_f32 v[12:13], v[12:13], v[0:1], v[48:49] op_sel:[1,1,0] op_sel_hi:[1,0,1] neg_lo:[0,1,0]
	v_pk_fma_f32 v[26:27], v[26:27], v[0:1], v[60:61] op_sel:[1,1,0] op_sel_hi:[1,0,1] neg_lo:[0,1,0]
	s_nop 0
	v_pk_add_f32 v[48:49], v[46:47], v[12:13]
	v_pk_add_f32 v[12:13], v[46:47], v[12:13] neg_lo:[0,1] neg_hi:[0,1]
	v_pk_mul_f32 v[46:47], v[10:11], v[0:1] op_sel:[0,0] op_sel_hi:[0,1]
	v_pk_add_f32 v[60:61], v[62:63], v[26:27]
	v_pk_fma_f32 v[10:11], v[10:11], v[0:1], v[46:47] op_sel:[1,1,0] op_sel_hi:[1,0,1] neg_lo:[0,1,0]
	v_pk_add_f32 v[26:27], v[62:63], v[26:27] neg_lo:[0,1] neg_hi:[0,1]
	v_pk_add_f32 v[46:47], v[44:45], v[10:11]
	v_pk_add_f32 v[10:11], v[44:45], v[10:11] neg_lo:[0,1] neg_hi:[0,1]
	v_pk_mul_f32 v[44:45], v[8:9], v[0:1] op_sel:[0,0] op_sel_hi:[0,1]
	v_pk_mul_f32 v[62:63], v[24:25], v[0:1] op_sel:[0,0] op_sel_hi:[0,1]
	s_nop 0
	v_pk_fma_f32 v[8:9], v[8:9], v[0:1], v[44:45] op_sel:[1,1,0] op_sel_hi:[1,0,1] neg_lo:[0,1,0]
	v_pk_fma_f32 v[24:25], v[24:25], v[0:1], v[62:63] op_sel:[1,1,0] op_sel_hi:[1,0,1] neg_lo:[0,1,0]
	s_nop 0
	v_pk_add_f32 v[44:45], v[42:43], v[8:9]
	v_pk_add_f32 v[8:9], v[42:43], v[8:9] neg_lo:[0,1] neg_hi:[0,1]
	v_pk_mul_f32 v[42:43], v[6:7], v[0:1] op_sel:[0,0] op_sel_hi:[0,1]
	v_pk_add_f32 v[62:63], v[66:67], v[24:25]
	v_pk_fma_f32 v[6:7], v[6:7], v[0:1], v[42:43] op_sel:[1,1,0] op_sel_hi:[1,0,1] neg_lo:[0,1,0]
	v_pk_add_f32 v[24:25], v[66:67], v[24:25] neg_lo:[0,1] neg_hi:[0,1]
	v_pk_add_f32 v[42:43], v[40:41], v[6:7]
	v_pk_add_f32 v[6:7], v[40:41], v[6:7] neg_lo:[0,1] neg_hi:[0,1]
	v_pk_mul_f32 v[40:41], v[4:5], v[0:1] op_sel:[0,0] op_sel_hi:[0,1]
	v_pk_mul_f32 v[66:67], v[22:23], v[0:1] op_sel:[0,0] op_sel_hi:[0,1]
	s_nop 0
	v_pk_fma_f32 v[4:5], v[4:5], v[0:1], v[40:41] op_sel:[1,1,0] op_sel_hi:[1,0,1] neg_lo:[0,1,0]
	v_pk_fma_f32 v[22:23], v[22:23], v[0:1], v[66:67] op_sel:[1,1,0] op_sel_hi:[1,0,1] neg_lo:[0,1,0]
	s_nop 0
	v_pk_add_f32 v[40:41], v[38:39], v[4:5]
	v_pk_add_f32 v[4:5], v[38:39], v[4:5] neg_lo:[0,1] neg_hi:[0,1]
	v_pk_mul_f32 v[38:39], v[2:3], v[0:1] op_sel:[0,0] op_sel_hi:[0,1]
	v_pk_add_f32 v[66:67], v[70:71], v[22:23]
	v_pk_fma_f32 v[2:3], v[2:3], v[0:1], v[38:39] op_sel:[1,1,0] op_sel_hi:[1,0,1] neg_lo:[0,1,0]
	v_pk_add_f32 v[22:23], v[70:71], v[22:23] neg_lo:[0,1] neg_hi:[0,1]
	v_pk_add_f32 v[38:39], v[36:37], v[2:3]
	v_pk_add_f32 v[36:37], v[36:37], v[2:3] neg_lo:[0,1] neg_hi:[0,1]
	v_pk_mul_f32 v[2:3], v[56:57], v[0:1] op_sel:[0,0] op_sel_hi:[0,1]
	s_nop 0
	v_pk_fma_f32 v[2:3], v[56:57], v[0:1], v[2:3] op_sel:[1,1,0] op_sel_hi:[1,0,1] neg_lo:[0,1,0]
	s_nop 0
	v_pk_add_f32 v[56:57], v[34:35], v[2:3]
	v_pk_add_f32 v[34:35], v[34:35], v[2:3] neg_lo:[0,1] neg_hi:[0,1]
	v_pk_mul_f32 v[2:3], v[58:59], v[0:1] op_sel:[0,0] op_sel_hi:[0,1]
	s_nop 0
	v_pk_fma_f32 v[2:3], v[58:59], v[0:1], v[2:3] op_sel:[1,1,0] op_sel_hi:[1,0,1] neg_lo:[0,1,0]
	s_nop 0
	v_pk_add_f32 v[58:59], v[64:65], v[2:3]
	v_pk_add_f32 v[64:65], v[64:65], v[2:3] neg_lo:[0,1] neg_hi:[0,1]
	v_mov_b64_e32 v[2:3], s[0:1]
	v_pk_mul_f32 v[70:71], v[28:29], v[2:3] op_sel:[0,0] op_sel_hi:[0,1]
	s_mov_b32 s0, s73
	v_pk_fma_f32 v[28:29], v[28:29], v[2:3], v[70:71] op_sel:[1,1,0] op_sel_hi:[1,0,1] neg_lo:[0,1,0]
	s_mov_b32 s1, s73
	v_pk_add_f32 v[70:71], v[30:31], v[28:29]
	v_pk_add_f32 v[28:29], v[30:31], v[28:29] neg_lo:[0,1] neg_hi:[0,1]
	v_pk_mul_f32 v[30:31], v[62:63], v[0:1] op_sel:[0,0] op_sel_hi:[0,1]
	s_nop 0
	v_pk_fma_f32 v[30:31], v[62:63], v[0:1], v[30:31] op_sel:[1,1,0] op_sel_hi:[1,0,1] neg_lo:[0,1,0]
	s_nop 0
	v_pk_add_f32 v[62:63], v[60:61], v[30:31]
	v_pk_add_f32 v[30:31], v[60:61], v[30:31] neg_lo:[0,1] neg_hi:[0,1]
	v_pk_mul_f32 v[60:61], v[24:25], v[2:3] op_sel:[0,0] op_sel_hi:[0,1]
	s_nop 0
	v_pk_fma_f32 v[24:25], v[24:25], v[2:3], v[60:61] op_sel:[1,1,0] op_sel_hi:[1,0,1] neg_lo:[0,1,0]
	s_nop 0
	v_pk_add_f32 v[60:61], v[26:27], v[24:25]
	v_pk_add_f32 v[24:25], v[26:27], v[24:25] neg_lo:[0,1] neg_hi:[0,1]
	v_pk_mul_f32 v[26:27], v[68:69], v[0:1] op_sel:[0,0] op_sel_hi:[0,1]
	s_nop 0
; __device__ __forceinline__ float2 cmul(float2 a, float2 b) { return make_float2(a.x * b.x - a.y * b.y, a.x * b.y + a.y * b.x); }
; template <int R, bool INV>
; __device__ __forceinline__ void butterflies(c32 (&v)[1 << R], float turns0) {
;     ...
;   for (int kk = 0; kk < R; ++kk) {
;     const int k = INV ? (R - 1 - kk) : kk;
;     const int hd = RAD >> (k + 1);
; #pragma unroll
;     for (int j = 0; j < RAD; ++j) {
;       if ((j & hd) == 0) {
;         const int m = (j & (hd - 1)) * (16 / hd);
;         const float2 c = make_float2(TC[m], INV ? TS[m] : -TS[m]);
;         const float2 twf = cmul(tbs[k], c);
;         const c32 tw = {twf.x, twf.y};
;         const c32 a = v[j], b = v[j + hd];
;         if (!INV) { v[j] = a + b; v[j + hd] = cmul_pk(a - b, tw); }
;         else { const c32 bt = cmul_pk(b, tw); v[j] = a + bt; v[j + hd] = a - bt; }
;       }
;     }
;   }
	v_pk_fma_f32 v[26:27], v[68:69], v[0:1], v[26:27] op_sel:[1,1,0] op_sel_hi:[1,0,1] neg_lo:[0,1,0]
	s_nop 0
	v_pk_add_f32 v[68:69], v[66:67], v[26:27]
	v_pk_add_f32 v[26:27], v[66:67], v[26:27] neg_lo:[0,1] neg_hi:[0,1]
	v_pk_mul_f32 v[66:67], v[20:21], v[2:3] op_sel:[0,0] op_sel_hi:[0,1]
	s_nop 0
	v_pk_fma_f32 v[20:21], v[20:21], v[2:3], v[66:67] op_sel:[1,1,0] op_sel_hi:[1,0,1] neg_lo:[0,1,0]
	s_nop 0
	v_pk_add_f32 v[66:67], v[22:23], v[20:21]
	v_pk_add_f32 v[20:21], v[22:23], v[20:21] neg_lo:[0,1] neg_hi:[0,1]
	v_pk_mul_f32 v[22:23], v[52:53], v[0:1] op_sel:[0,0] op_sel_hi:[0,1]
	s_nop 0
	v_pk_fma_f32 v[22:23], v[52:53], v[0:1], v[22:23] op_sel:[1,1,0] op_sel_hi:[1,0,1] neg_lo:[0,1,0]
	s_nop 0
	v_pk_add_f32 v[52:53], v[54:55], v[22:23]
	v_pk_add_f32 v[22:23], v[54:55], v[22:23] neg_lo:[0,1] neg_hi:[0,1]
	v_pk_mul_f32 v[54:55], v[16:17], v[2:3] op_sel:[0,0] op_sel_hi:[0,1]
	s_nop 0
	v_pk_fma_f32 v[16:17], v[16:17], v[2:3], v[54:55] op_sel:[1,1,0] op_sel_hi:[1,0,1] neg_lo:[0,1,0]
	s_nop 0
	v_pk_add_f32 v[54:55], v[18:19], v[16:17]
	v_pk_add_f32 v[16:17], v[18:19], v[16:17] neg_lo:[0,1] neg_hi:[0,1]
	v_pk_mul_f32 v[18:19], v[48:49], v[0:1] op_sel:[0,0] op_sel_hi:[0,1]
	s_nop 0
	v_pk_fma_f32 v[18:19], v[48:49], v[0:1], v[18:19] op_sel:[1,1,0] op_sel_hi:[1,0,1] neg_lo:[0,1,0]
	s_nop 0
	v_pk_add_f32 v[48:49], v[50:51], v[18:19]
	v_pk_add_f32 v[18:19], v[50:51], v[18:19] neg_lo:[0,1] neg_hi:[0,1]
	v_pk_mul_f32 v[50:51], v[12:13], v[2:3] op_sel:[0,0] op_sel_hi:[0,1]
	s_nop 0
	v_pk_fma_f32 v[12:13], v[12:13], v[2:3], v[50:51] op_sel:[1,1,0] op_sel_hi:[1,0,1] neg_lo:[0,1,0]
	s_nop 0
	v_pk_add_f32 v[50:51], v[14:15], v[12:13]
	v_pk_add_f32 v[12:13], v[14:15], v[12:13] neg_lo:[0,1] neg_hi:[0,1]
	v_pk_mul_f32 v[14:15], v[44:45], v[0:1] op_sel:[0,0] op_sel_hi:[0,1]
	s_nop 0
	v_pk_fma_f32 v[14:15], v[44:45], v[0:1], v[14:15] op_sel:[1,1,0] op_sel_hi:[1,0,1] neg_lo:[0,1,0]
	s_nop 0
	v_pk_add_f32 v[44:45], v[46:47], v[14:15]
	v_pk_add_f32 v[14:15], v[46:47], v[14:15] neg_lo:[0,1] neg_hi:[0,1]
	v_pk_mul_f32 v[46:47], v[8:9], v[2:3] op_sel:[0,0] op_sel_hi:[0,1]
	s_nop 0
	v_pk_fma_f32 v[8:9], v[8:9], v[2:3], v[46:47] op_sel:[1,1,0] op_sel_hi:[1,0,1] neg_lo:[0,1,0]
	s_nop 0
	v_pk_add_f32 v[46:47], v[10:11], v[8:9]
	v_pk_add_f32 v[8:9], v[10:11], v[8:9] neg_lo:[0,1] neg_hi:[0,1]
	v_pk_mul_f32 v[10:11], v[40:41], v[0:1] op_sel:[0,0] op_sel_hi:[0,1]
	s_nop 0
	v_pk_fma_f32 v[10:11], v[40:41], v[0:1], v[10:11] op_sel:[1,1,0] op_sel_hi:[1,0,1] neg_lo:[0,1,0]
	s_nop 0
	v_pk_add_f32 v[40:41], v[42:43], v[10:11]
	v_pk_add_f32 v[10:11], v[42:43], v[10:11] neg_lo:[0,1] neg_hi:[0,1]
	v_pk_mul_f32 v[42:43], v[4:5], v[2:3] op_sel:[0,0] op_sel_hi:[0,1]
	s_nop 0
	v_pk_fma_f32 v[4:5], v[4:5], v[2:3], v[42:43] op_sel:[1,1,0] op_sel_hi:[1,0,1] neg_lo:[0,1,0]
	s_nop 0
	v_pk_add_f32 v[42:43], v[6:7], v[4:5]
	v_pk_add_f32 v[4:5], v[6:7], v[4:5] neg_lo:[0,1] neg_hi:[0,1]
	v_pk_mul_f32 v[6:7], v[56:57], v[0:1] op_sel:[0,0] op_sel_hi:[0,1]
	s_nop 0
	v_pk_fma_f32 v[6:7], v[56:57], v[0:1], v[6:7] op_sel:[1,1,0] op_sel_hi:[1,0,1] neg_lo:[0,1,0]
	s_nop 0
	v_pk_add_f32 v[56:57], v[38:39], v[6:7]
	v_pk_add_f32 v[6:7], v[38:39], v[6:7] neg_lo:[0,1] neg_hi:[0,1]
	v_pk_mul_f32 v[38:39], v[34:35], v[2:3] op_sel:[0,0] op_sel_hi:[0,1]
	s_nop 0
	v_pk_fma_f32 v[34:35], v[34:35], v[2:3], v[38:39] op_sel:[1,1,0] op_sel_hi:[1,0,1] neg_lo:[0,1,0]
	s_nop 0
	v_pk_add_f32 v[38:39], v[36:37], v[34:35]
	v_pk_add_f32 v[34:35], v[36:37], v[34:35] neg_lo:[0,1] neg_hi:[0,1]
	v_pk_mul_f32 v[36:37], v[62:63], v[0:1] op_sel:[0,0] op_sel_hi:[0,1]
	s_nop 0
	v_pk_fma_f32 v[36:37], v[62:63], v[0:1], v[36:37] op_sel:[1,1,0] op_sel_hi:[1,0,1] neg_lo:[0,1,0]
	s_nop 0
	v_pk_add_f32 v[62:63], v[58:59], v[36:37]
	v_pk_add_f32 v[36:37], v[58:59], v[36:37] neg_lo:[0,1] neg_hi:[0,1]
	v_mov_b64_e32 v[58:59], s[0:1]
	v_pk_mul_f32 v[72:73], v[60:61], v[58:59] op_sel:[0,0] op_sel_hi:[0,1]
	s_mov_b32 s0, s9
	v_pk_fma_f32 v[60:61], v[60:61], v[58:59], v[72:73] op_sel:[1,1,0] op_sel_hi:[1,0,1] neg_lo:[0,1,0]
	s_mov_b32 s1, s8
	v_pk_add_f32 v[72:73], v[70:71], v[60:61]
	v_pk_add_f32 v[60:61], v[70:71], v[60:61] neg_lo:[0,1] neg_hi:[0,1]
	v_pk_mul_f32 v[70:71], v[30:31], v[2:3] op_sel:[0,0] op_sel_hi:[0,1]
	s_nop 0
	v_pk_fma_f32 v[30:31], v[30:31], v[2:3], v[70:71] op_sel:[1,1,0] op_sel_hi:[1,0,1] neg_lo:[0,1,0]
	s_nop 0
	v_pk_add_f32 v[70:71], v[64:65], v[30:31]
	v_pk_add_f32 v[30:31], v[64:65], v[30:31] neg_lo:[0,1] neg_hi:[0,1]
	v_mov_b64_e32 v[64:65], s[72:73]
	v_pk_mul_f32 v[74:75], v[24:25], v[64:65] op_sel:[0,0] op_sel_hi:[0,1]
	s_nop 0
	v_pk_fma_f32 v[24:25], v[24:25], v[64:65], v[74:75] op_sel:[1,1,0] op_sel_hi:[1,0,1] neg_lo:[0,1,0]
	s_nop 0
	v_pk_add_f32 v[74:75], v[28:29], v[24:25]
	v_pk_add_f32 v[24:25], v[28:29], v[24:25] neg_lo:[0,1] neg_hi:[0,1]
	v_pk_mul_f32 v[28:29], v[52:53], v[0:1] op_sel:[0,0] op_sel_hi:[0,1]
	s_nop 0
	v_pk_fma_f32 v[28:29], v[52:53], v[0:1], v[28:29] op_sel:[1,1,0] op_sel_hi:[1,0,1] neg_lo:[0,1,0]
	s_nop 0
	v_pk_add_f32 v[52:53], v[68:69], v[28:29]
	v_pk_add_f32 v[28:29], v[68:69], v[28:29] neg_lo:[0,1] neg_hi:[0,1]
	v_pk_mul_f32 v[68:69], v[54:55], v[58:59] op_sel:[0,0] op_sel_hi:[0,1]
	s_nop 0
	v_pk_fma_f32 v[54:55], v[54:55], v[58:59], v[68:69] op_sel:[1,1,0] op_sel_hi:[1,0,1] neg_lo:[0,1,0]
	s_nop 0
	v_pk_add_f32 v[68:69], v[66:67], v[54:55]
	v_pk_add_f32 v[54:55], v[66:67], v[54:55] neg_lo:[0,1] neg_hi:[0,1]
	v_pk_mul_f32 v[66:67], v[22:23], v[2:3] op_sel:[0,0] op_sel_hi:[0,1]
	s_nop 0
	v_pk_fma_f32 v[22:23], v[22:23], v[2:3], v[66:67] op_sel:[1,1,0] op_sel_hi:[1,0,1] neg_lo:[0,1,0]
	s_nop 0
	v_pk_add_f32 v[66:67], v[26:27], v[22:23]
	v_pk_add_f32 v[22:23], v[26:27], v[22:23] neg_lo:[0,1] neg_hi:[0,1]
; __device__ __forceinline__ float2 cmul(float2 a, float2 b) { return make_float2(a.x * b.x - a.y * b.y, a.x * b.y + a.y * b.x); }
; template <int R, bool INV>
; __device__ __forceinline__ void butterflies(c32 (&v)[1 << R], float turns0) {
;     ...
;   for (int kk = 0; kk < R; ++kk) {
;     const int k = INV ? (R - 1 - kk) : kk;
;     const int hd = RAD >> (k + 1);
; #pragma unroll
;     for (int j = 0; j < RAD; ++j) {
;       if ((j & hd) == 0) {
;         const int m = (j & (hd - 1)) * (16 / hd);
;         const float2 c = make_float2(TC[m], INV ? TS[m] : -TS[m]);
;         const float2 twf = cmul(tbs[k], c);
;         const c32 tw = {twf.x, twf.y};
;         const c32 a = v[j], b = v[j + hd];
;         if (!INV) { v[j] = a + b; v[j + hd] = cmul_pk(a - b, tw); }
;         else { const c32 bt = cmul_pk(b, tw); v[j] = a + bt; v[j + hd] = a - bt; }
;       }
;     }
;   }
	v_pk_mul_f32 v[26:27], v[16:17], v[64:65] op_sel:[0,0] op_sel_hi:[0,1]
	s_nop 0
	v_pk_fma_f32 v[16:17], v[16:17], v[64:65], v[26:27] op_sel:[1,1,0] op_sel_hi:[1,0,1] neg_lo:[0,1,0]
	s_nop 0
	v_pk_add_f32 v[26:27], v[20:21], v[16:17]
	v_pk_add_f32 v[16:17], v[20:21], v[16:17] neg_lo:[0,1] neg_hi:[0,1]
	v_pk_mul_f32 v[20:21], v[44:45], v[0:1] op_sel:[0,0] op_sel_hi:[0,1]
	s_nop 0
	v_pk_fma_f32 v[20:21], v[44:45], v[0:1], v[20:21] op_sel:[1,1,0] op_sel_hi:[1,0,1] neg_lo:[0,1,0]
	s_nop 0
	v_pk_add_f32 v[44:45], v[48:49], v[20:21]
	v_pk_add_f32 v[20:21], v[48:49], v[20:21] neg_lo:[0,1] neg_hi:[0,1]
	v_pk_mul_f32 v[48:49], v[46:47], v[58:59] op_sel:[0,0] op_sel_hi:[0,1]
	s_nop 0
	v_pk_fma_f32 v[46:47], v[46:47], v[58:59], v[48:49] op_sel:[1,1,0] op_sel_hi:[1,0,1] neg_lo:[0,1,0]
	s_nop 0
	v_pk_add_f32 v[48:49], v[50:51], v[46:47]
	v_pk_add_f32 v[46:47], v[50:51], v[46:47] neg_lo:[0,1] neg_hi:[0,1]
	v_pk_mul_f32 v[50:51], v[14:15], v[2:3] op_sel:[0,0] op_sel_hi:[0,1]
	s_nop 0
	v_pk_fma_f32 v[14:15], v[14:15], v[2:3], v[50:51] op_sel:[1,1,0] op_sel_hi:[1,0,1] neg_lo:[0,1,0]
	s_nop 0
	v_pk_add_f32 v[50:51], v[18:19], v[14:15]
	v_pk_add_f32 v[14:15], v[18:19], v[14:15] neg_lo:[0,1] neg_hi:[0,1]
	v_pk_mul_f32 v[18:19], v[8:9], v[64:65] op_sel:[0,0] op_sel_hi:[0,1]
	s_nop 0
	v_pk_fma_f32 v[8:9], v[8:9], v[64:65], v[18:19] op_sel:[1,1,0] op_sel_hi:[1,0,1] neg_lo:[0,1,0]
	s_nop 0
	v_pk_add_f32 v[18:19], v[12:13], v[8:9]
	v_pk_add_f32 v[8:9], v[12:13], v[8:9] neg_lo:[0,1] neg_hi:[0,1]
	v_pk_mul_f32 v[12:13], v[56:57], v[0:1] op_sel:[0,0] op_sel_hi:[0,1]
	s_nop 0
	v_pk_fma_f32 v[12:13], v[56:57], v[0:1], v[12:13] op_sel:[1,1,0] op_sel_hi:[1,0,1] neg_lo:[0,1,0]
	s_nop 0
	v_pk_add_f32 v[56:57], v[40:41], v[12:13]
	v_pk_add_f32 v[12:13], v[40:41], v[12:13] neg_lo:[0,1] neg_hi:[0,1]
	v_pk_mul_f32 v[40:41], v[38:39], v[58:59] op_sel:[0,0] op_sel_hi:[0,1]
	s_nop 0
	v_pk_fma_f32 v[38:39], v[38:39], v[58:59], v[40:41] op_sel:[1,1,0] op_sel_hi:[1,0,1] neg_lo:[0,1,0]
	s_nop 0
	v_pk_add_f32 v[40:41], v[42:43], v[38:39]
	v_pk_add_f32 v[38:39], v[42:43], v[38:39] neg_lo:[0,1] neg_hi:[0,1]
	v_pk_mul_f32 v[42:43], v[6:7], v[2:3] op_sel:[0,0] op_sel_hi:[0,1]
	s_nop 0
	v_pk_fma_f32 v[6:7], v[6:7], v[2:3], v[42:43] op_sel:[1,1,0] op_sel_hi:[1,0,1] neg_lo:[0,1,0]
	s_nop 0
	v_pk_add_f32 v[42:43], v[10:11], v[6:7]
	v_pk_add_f32 v[6:7], v[10:11], v[6:7] neg_lo:[0,1] neg_hi:[0,1]
	v_pk_mul_f32 v[10:11], v[34:35], v[64:65] op_sel:[0,0] op_sel_hi:[0,1]
	s_nop 0
	v_pk_fma_f32 v[10:11], v[34:35], v[64:65], v[10:11] op_sel:[1,1,0] op_sel_hi:[1,0,1] neg_lo:[0,1,0]
	s_nop 0
	v_pk_add_f32 v[34:35], v[4:5], v[10:11]
	v_pk_add_f32 v[4:5], v[4:5], v[10:11] neg_lo:[0,1] neg_hi:[0,1]
	v_pk_mul_f32 v[10:11], v[52:53], v[0:1] op_sel:[0,0] op_sel_hi:[0,1]
	s_nop 0
	v_pk_fma_f32 v[10:11], v[52:53], v[0:1], v[10:11] op_sel:[1,1,0] op_sel_hi:[1,0,1] neg_lo:[0,1,0]
	s_nop 0
	v_pk_add_f32 v[52:53], v[62:63], v[10:11]
	v_pk_add_f32 v[10:11], v[62:63], v[10:11] neg_lo:[0,1] neg_hi:[0,1]
	v_mov_b64_e32 v[62:63], s[0:1]
	v_pk_mul_f32 v[76:77], v[68:69], v[62:63] op_sel:[0,0] op_sel_hi:[0,1]
	s_mov_b32 s0, s19
	v_pk_fma_f32 v[68:69], v[68:69], v[62:63], v[76:77] op_sel:[1,1,0] op_sel_hi:[1,0,1] neg_lo:[0,1,0]
	s_mov_b32 s1, s18
	v_pk_add_f32 v[76:77], v[72:73], v[68:69]
	v_pk_add_f32 v[68:69], v[72:73], v[68:69] neg_lo:[0,1] neg_hi:[0,1]
	v_pk_mul_f32 v[72:73], v[66:67], v[58:59] op_sel:[0,0] op_sel_hi:[0,1]
	s_nop 0
	v_pk_fma_f32 v[66:67], v[66:67], v[58:59], v[72:73] op_sel:[1,1,0] op_sel_hi:[1,0,1] neg_lo:[0,1,0]
	s_nop 0
	v_pk_add_f32 v[72:73], v[70:71], v[66:67]
	v_pk_add_f32 v[66:67], v[70:71], v[66:67] neg_lo:[0,1] neg_hi:[0,1]
	v_mov_b64_e32 v[70:71], s[8:9]
	v_pk_mul_f32 v[78:79], v[26:27], v[70:71] op_sel:[0,0] op_sel_hi:[0,1]
	s_nop 0
	v_pk_fma_f32 v[26:27], v[26:27], v[70:71], v[78:79] op_sel:[1,1,0] op_sel_hi:[1,0,1] neg_lo:[0,1,0]
	s_nop 0
	v_pk_add_f32 v[78:79], v[74:75], v[26:27]
	v_pk_add_f32 v[26:27], v[74:75], v[26:27] neg_lo:[0,1] neg_hi:[0,1]
	v_pk_mul_f32 v[74:75], v[28:29], v[2:3] op_sel:[0,0] op_sel_hi:[0,1]
	s_nop 0
	v_pk_fma_f32 v[28:29], v[28:29], v[2:3], v[74:75] op_sel:[1,1,0] op_sel_hi:[1,0,1] neg_lo:[0,1,0]
	s_nop 0
	v_pk_add_f32 v[74:75], v[36:37], v[28:29]
	v_pk_add_f32 v[28:29], v[36:37], v[28:29] neg_lo:[0,1] neg_hi:[0,1]
	v_mov_b64_e32 v[36:37], s[76:77]
	v_pk_mul_f32 v[80:81], v[54:55], v[36:37] op_sel:[0,0] op_sel_hi:[0,1]
	s_nop 0
	v_pk_fma_f32 v[54:55], v[54:55], v[36:37], v[80:81] op_sel:[1,1,0] op_sel_hi:[1,0,1] neg_lo:[0,1,0]
	s_nop 0
	v_pk_add_f32 v[80:81], v[60:61], v[54:55]
	v_pk_add_f32 v[54:55], v[60:61], v[54:55] neg_lo:[0,1] neg_hi:[0,1]
	v_pk_mul_f32 v[60:61], v[22:23], v[64:65] op_sel:[0,0] op_sel_hi:[0,1]
	s_nop 0
	v_pk_fma_f32 v[22:23], v[22:23], v[64:65], v[60:61] op_sel:[1,1,0] op_sel_hi:[1,0,1] neg_lo:[0,1,0]
	s_nop 0
	v_pk_add_f32 v[60:61], v[30:31], v[22:23]
	v_pk_add_f32 v[22:23], v[30:31], v[22:23] neg_lo:[0,1] neg_hi:[0,1]
	v_mov_b64_e32 v[30:31], s[10:11]
	v_pk_mul_f32 v[82:83], v[16:17], v[30:31] op_sel:[0,0] op_sel_hi:[0,1]
	s_nop 0
	v_pk_fma_f32 v[16:17], v[16:17], v[30:31], v[82:83] op_sel:[1,1,0] op_sel_hi:[1,0,1] neg_lo:[0,1,0]
	s_nop 0
	v_pk_add_f32 v[82:83], v[24:25], v[16:17]
	v_pk_add_f32 v[16:17], v[24:25], v[16:17] neg_lo:[0,1] neg_hi:[0,1]
	v_pk_mul_f32 v[24:25], v[56:57], v[0:1] op_sel:[0,0] op_sel_hi:[0,1]
	s_nop 0
	v_pk_fma_f32 v[24:25], v[56:57], v[0:1], v[24:25] op_sel:[1,1,0] op_sel_hi:[1,0,1] neg_lo:[0,1,0]
	s_nop 0
	v_pk_add_f32 v[56:57], v[44:45], v[24:25]
	v_pk_add_f32 v[24:25], v[44:45], v[24:25] neg_lo:[0,1] neg_hi:[0,1]
	v_pk_mul_f32 v[44:45], v[40:41], v[62:63] op_sel:[0,0] op_sel_hi:[0,1]
	s_nop 0
; __device__ __forceinline__ float2 cmul(float2 a, float2 b) { return make_float2(a.x * b.x - a.y * b.y, a.x * b.y + a.y * b.x); }
; template <int R, bool INV>
; __device__ __forceinline__ void butterflies(c32 (&v)[1 << R], float turns0) {
;     ...
;   for (int kk = 0; kk < R; ++kk) {
;     const int k = INV ? (R - 1 - kk) : kk;
;     const int hd = RAD >> (k + 1);
; #pragma unroll
;     for (int j = 0; j < RAD; ++j) {
;       if ((j & hd) == 0) {
;         const int m = (j & (hd - 1)) * (16 / hd);
;         const float2 c = make_float2(TC[m], INV ? TS[m] : -TS[m]);
;         const float2 twf = cmul(tbs[k], c);
;         const c32 tw = {twf.x, twf.y};
;         const c32 a = v[j], b = v[j + hd];
;         if (!INV) { v[j] = a + b; v[j + hd] = cmul_pk(a - b, tw); }
;         else { const c32 bt = cmul_pk(b, tw); v[j] = a + bt; v[j + hd] = a - bt; }
;       }
;     }
;   }
	v_pk_fma_f32 v[40:41], v[40:41], v[62:63], v[44:45] op_sel:[1,1,0] op_sel_hi:[1,0,1] neg_lo:[0,1,0]
	s_nop 0
	v_pk_add_f32 v[44:45], v[48:49], v[40:41]
	v_pk_add_f32 v[40:41], v[48:49], v[40:41] neg_lo:[0,1] neg_hi:[0,1]
	v_pk_mul_f32 v[48:49], v[42:43], v[58:59] op_sel:[0,0] op_sel_hi:[0,1]
	s_nop 0
	v_pk_fma_f32 v[42:43], v[42:43], v[58:59], v[48:49] op_sel:[1,1,0] op_sel_hi:[1,0,1] neg_lo:[0,1,0]
	s_nop 0
	v_pk_add_f32 v[48:49], v[50:51], v[42:43]
	v_pk_add_f32 v[42:43], v[50:51], v[42:43] neg_lo:[0,1] neg_hi:[0,1]
	v_pk_mul_f32 v[50:51], v[34:35], v[70:71] op_sel:[0,0] op_sel_hi:[0,1]
	s_nop 0
	v_pk_fma_f32 v[34:35], v[34:35], v[70:71], v[50:51] op_sel:[1,1,0] op_sel_hi:[1,0,1] neg_lo:[0,1,0]
	s_nop 0
	v_pk_add_f32 v[50:51], v[18:19], v[34:35]
	v_pk_add_f32 v[18:19], v[18:19], v[34:35] neg_lo:[0,1] neg_hi:[0,1]
	v_pk_mul_f32 v[34:35], v[12:13], v[2:3] op_sel:[0,0] op_sel_hi:[0,1]
	s_nop 0
	v_pk_fma_f32 v[12:13], v[12:13], v[2:3], v[34:35] op_sel:[1,1,0] op_sel_hi:[1,0,1] neg_lo:[0,1,0]
	s_nop 0
	v_pk_add_f32 v[34:35], v[20:21], v[12:13]
	v_pk_add_f32 v[12:13], v[20:21], v[12:13] neg_lo:[0,1] neg_hi:[0,1]
	v_pk_mul_f32 v[20:21], v[38:39], v[36:37] op_sel:[0,0] op_sel_hi:[0,1]
	s_nop 0
	v_pk_fma_f32 v[20:21], v[38:39], v[36:37], v[20:21] op_sel:[1,1,0] op_sel_hi:[1,0,1] neg_lo:[0,1,0]
	s_nop 0
	v_pk_add_f32 v[38:39], v[46:47], v[20:21]
	v_pk_add_f32 v[20:21], v[46:47], v[20:21] neg_lo:[0,1] neg_hi:[0,1]
	v_pk_mul_f32 v[46:47], v[6:7], v[64:65] op_sel:[0,0] op_sel_hi:[0,1]
	s_nop 0
	v_pk_fma_f32 v[6:7], v[6:7], v[64:65], v[46:47] op_sel:[1,1,0] op_sel_hi:[1,0,1] neg_lo:[0,1,0]
	s_nop 0
	v_pk_add_f32 v[46:47], v[14:15], v[6:7]
	v_pk_add_f32 v[6:7], v[14:15], v[6:7] neg_lo:[0,1] neg_hi:[0,1]
	v_pk_mul_f32 v[14:15], v[4:5], v[30:31] op_sel:[0,0] op_sel_hi:[0,1]
	s_nop 0
	v_pk_fma_f32 v[4:5], v[4:5], v[30:31], v[14:15] op_sel:[1,1,0] op_sel_hi:[1,0,1] neg_lo:[0,1,0]
	s_nop 0
	v_pk_add_f32 v[14:15], v[8:9], v[4:5]
	v_pk_add_f32 v[4:5], v[8:9], v[4:5] neg_lo:[0,1] neg_hi:[0,1]
	v_pk_mul_f32 v[8:9], v[56:57], v[0:1] op_sel:[0,0] op_sel_hi:[0,1]
	s_nop 0
	v_pk_fma_f32 v[0:1], v[56:57], v[0:1], v[8:9] op_sel:[1,1,0] op_sel_hi:[1,0,1] neg_lo:[0,1,0]
	s_nop 0
	v_pk_add_f32 v[8:9], v[52:53], v[0:1]
	v_pk_add_f32 v[0:1], v[52:53], v[0:1] neg_lo:[0,1] neg_hi:[0,1]
	v_mov_b64_e32 v[52:53], s[0:1]
	v_pk_mul_f32 v[56:57], v[44:45], v[52:53] op_sel:[0,0] op_sel_hi:[0,1]
	s_mov_b32 s0, s55
	v_pk_fma_f32 v[44:45], v[44:45], v[52:53], v[56:57] op_sel:[1,1,0] op_sel_hi:[1,0,1] neg_lo:[0,1,0]
	v_pk_mul_f32 v[56:57], v[48:49], v[62:63] op_sel:[0,0] op_sel_hi:[0,1]
	s_mov_b32 s1, s54
	v_pk_fma_f32 v[48:49], v[48:49], v[62:63], v[56:57] op_sel:[1,1,0] op_sel_hi:[1,0,1] neg_lo:[0,1,0]
	v_mov_b64_e32 v[62:63], s[0:1]
	v_pk_add_f32 v[56:57], v[72:73], v[48:49]
	v_pk_add_f32 v[48:49], v[72:73], v[48:49] neg_lo:[0,1] neg_hi:[0,1]
	v_pk_mul_f32 v[72:73], v[50:51], v[62:63] op_sel:[0,0] op_sel_hi:[0,1]
	v_pk_add_f32 v[52:53], v[76:77], v[44:45]
	v_pk_fma_f32 v[50:51], v[50:51], v[62:63], v[72:73] op_sel:[1,1,0] op_sel_hi:[1,0,1] neg_lo:[0,1,0]
	v_pk_mul_f32 v[72:73], v[34:35], v[58:59] op_sel:[0,0] op_sel_hi:[0,1]
	v_pk_add_f32 v[44:45], v[76:77], v[44:45] neg_lo:[0,1] neg_hi:[0,1]
	v_pk_fma_f32 v[34:35], v[34:35], v[58:59], v[72:73] op_sel:[1,1,0] op_sel_hi:[1,0,1] neg_lo:[0,1,0]
	v_mov_b64_e32 v[72:73], s[54:55]
	v_pk_add_f32 v[58:59], v[74:75], v[34:35]
	v_pk_add_f32 v[34:35], v[74:75], v[34:35] neg_lo:[0,1] neg_hi:[0,1]
	v_pk_mul_f32 v[74:75], v[38:39], v[72:73] op_sel:[0,0] op_sel_hi:[0,1]
	v_pk_add_f32 v[62:63], v[78:79], v[50:51]
	v_pk_fma_f32 v[38:39], v[38:39], v[72:73], v[74:75] op_sel:[1,1,0] op_sel_hi:[1,0,1] neg_lo:[0,1,0]
	v_pk_mul_f32 v[74:75], v[46:47], v[70:71] op_sel:[0,0] op_sel_hi:[0,1]
	v_pk_add_f32 v[50:51], v[78:79], v[50:51] neg_lo:[0,1] neg_hi:[0,1]
	v_pk_fma_f32 v[46:47], v[46:47], v[70:71], v[74:75] op_sel:[1,1,0] op_sel_hi:[1,0,1] neg_lo:[0,1,0]
	v_pk_add_f32 v[72:73], v[80:81], v[38:39]
	v_pk_add_f32 v[70:71], v[60:61], v[46:47]
	v_pk_add_f32 v[46:47], v[60:61], v[46:47] neg_lo:[0,1] neg_hi:[0,1]
	v_mov_b64_e32 v[60:61], s[18:19]
	v_pk_mul_f32 v[74:75], v[14:15], v[60:61] op_sel:[0,0] op_sel_hi:[0,1]
	v_pk_add_f32 v[38:39], v[80:81], v[38:39] neg_lo:[0,1] neg_hi:[0,1]
	v_pk_fma_f32 v[14:15], v[14:15], v[60:61], v[74:75] op_sel:[1,1,0] op_sel_hi:[1,0,1] neg_lo:[0,1,0]
	v_pk_mul_f32 v[74:75], v[24:25], v[2:3] op_sel:[0,0] op_sel_hi:[0,1]
	s_nop 0
	v_pk_fma_f32 v[2:3], v[24:25], v[2:3], v[74:75] op_sel:[1,1,0] op_sel_hi:[1,0,1] neg_lo:[0,1,0]
	v_pk_add_f32 v[60:61], v[82:83], v[14:15]
	v_pk_add_f32 v[24:25], v[10:11], v[2:3]
	v_pk_add_f32 v[2:3], v[10:11], v[2:3] neg_lo:[0,1] neg_hi:[0,1]
	v_mov_b64_e32 v[10:11], s[30:31]
	v_pk_mul_f32 v[74:75], v[40:41], v[10:11] op_sel:[0,0] op_sel_hi:[0,1]
	v_pk_add_f32 v[14:15], v[82:83], v[14:15] neg_lo:[0,1] neg_hi:[0,1]
	v_pk_fma_f32 v[10:11], v[40:41], v[10:11], v[74:75] op_sel:[1,1,0] op_sel_hi:[1,0,1] neg_lo:[0,1,0]
	s_nop 0
	v_pk_add_f32 v[40:41], v[68:69], v[10:11]
	v_pk_add_f32 v[10:11], v[68:69], v[10:11] neg_lo:[0,1] neg_hi:[0,1]
	v_pk_mul_f32 v[68:69], v[42:43], v[36:37] op_sel:[0,0] op_sel_hi:[0,1]
	s_nop 0
	v_pk_fma_f32 v[36:37], v[42:43], v[36:37], v[68:69] op_sel:[1,1,0] op_sel_hi:[1,0,1] neg_lo:[0,1,0]
	s_nop 0
	v_pk_add_f32 v[42:43], v[66:67], v[36:37]
	v_pk_add_f32 v[36:37], v[66:67], v[36:37] neg_lo:[0,1] neg_hi:[0,1]
	v_mov_b64_e32 v[66:67], s[68:69]
	v_pk_mul_f32 v[68:69], v[18:19], v[66:67] op_sel:[0,0] op_sel_hi:[0,1]
	s_nop 0
	v_pk_fma_f32 v[18:19], v[18:19], v[66:67], v[68:69] op_sel:[1,1,0] op_sel_hi:[1,0,1] neg_lo:[0,1,0]
	s_nop 0
	v_pk_add_f32 v[66:67], v[26:27], v[18:19]
; __device__ __forceinline__ float2 cmul(float2 a, float2 b) { return make_float2(a.x * b.x - a.y * b.y, a.x * b.y + a.y * b.x); }
; __device__ __forceinline__ float2 twid(float turns) { return make_float2(__builtin_amdgcn_cosf(turns), -__builtin_amdgcn_sinf(turns)); }
; template <int R, bool INV>
; __device__ __forceinline__ void butterflies(c32 (&v)[1 << R], float turns0) {
;     ...
;   float2 tbs[R];
;   tbs[0] = twid(turns0);
;   if (INV) tbs[0].y = -tbs[0].y;
; #pragma unroll
;   for (int k = 1; k < R; ++k) tbs[k] = cmul(tbs[k - 1], tbs[k - 1]);
; template <int LOGN>
; __device__ __forceinline__ void fft_fused_mul(float2* X, const c32 (&kf)[32]) {
;     ...
;   butterflies<5, true>(v, 0.f);
; #pragma unroll
;   for (int j = 0; j < 32; ++j) Xc[pb + j] = v[j];
;   __syncthreads();
	v_pk_add_f32 v[18:19], v[26:27], v[18:19] neg_lo:[0,1] neg_hi:[0,1]
	v_pk_mul_f32 v[26:27], v[12:13], v[64:65] op_sel:[0,0] op_sel_hi:[0,1]
	s_nop 0
	v_pk_fma_f32 v[12:13], v[12:13], v[64:65], v[26:27] op_sel:[1,1,0] op_sel_hi:[1,0,1] neg_lo:[0,1,0]
	s_nop 0
	v_pk_add_f32 v[26:27], v[28:29], v[12:13]
	v_pk_add_f32 v[12:13], v[28:29], v[12:13] neg_lo:[0,1] neg_hi:[0,1]
	v_mov_b64_e32 v[28:29], s[16:17]
	v_pk_mul_f32 v[64:65], v[20:21], v[28:29] op_sel:[0,0] op_sel_hi:[0,1]
	s_nop 0
	v_pk_fma_f32 v[20:21], v[20:21], v[28:29], v[64:65] op_sel:[1,1,0] op_sel_hi:[1,0,1] neg_lo:[0,1,0]
	v_mov_b32_e32 v65, v196
	v_pk_add_f32 v[28:29], v[54:55], v[20:21]
	v_pk_add_f32 v[20:21], v[54:55], v[20:21] neg_lo:[0,1] neg_hi:[0,1]
	v_pk_mul_f32 v[54:55], v[6:7], v[30:31] op_sel:[0,0] op_sel_hi:[0,1]
	s_nop 0
	v_pk_fma_f32 v[6:7], v[6:7], v[30:31], v[54:55] op_sel:[1,1,0] op_sel_hi:[1,0,1] neg_lo:[0,1,0]
	s_nop 0
	v_pk_add_f32 v[30:31], v[22:23], v[6:7]
	v_pk_add_f32 v[6:7], v[22:23], v[6:7] neg_lo:[0,1] neg_hi:[0,1]
	v_mov_b64_e32 v[22:23], s[4:5]
	v_pk_mul_f32 v[54:55], v[4:5], v[22:23] op_sel:[0,0] op_sel_hi:[0,1]
	s_nop 0
	v_pk_fma_f32 v[4:5], v[4:5], v[22:23], v[54:55] op_sel:[1,1,0] op_sel_hi:[1,0,1] neg_lo:[0,1,0]
	s_nop 0
	v_pk_add_f32 v[22:23], v[16:17], v[4:5]
	v_pk_add_f32 v[4:5], v[16:17], v[4:5] neg_lo:[0,1] neg_hi:[0,1]
	ds_write2_b64 v32, v[8:9], v[52:53] offset1:1
	ds_write2_b64 v32, v[56:57], v[62:63] offset0:2 offset1:3
	ds_write2_b64 v32, v[58:59], v[72:73] offset0:4 offset1:5
	ds_write2_b64 v32, v[70:71], v[60:61] offset0:6 offset1:7
	ds_write2_b64 v32, v[24:25], v[40:41] offset0:8 offset1:9
	ds_write2_b64 v32, v[42:43], v[66:67] offset0:10 offset1:11
	ds_write2_b64 v32, v[26:27], v[28:29] offset0:12 offset1:13
	ds_write2_b64 v32, v[30:31], v[22:23] offset0:14 offset1:15
	ds_write2_b64 v32, v[0:1], v[44:45] offset0:16 offset1:17
	ds_write2_b64 v32, v[48:49], v[50:51] offset0:18 offset1:19
	ds_write2_b64 v32, v[34:35], v[38:39] offset0:20 offset1:21
	ds_write2_b64 v32, v[46:47], v[14:15] offset0:22 offset1:23
	ds_write2_b64 v32, v[2:3], v[10:11] offset0:24 offset1:25
	ds_write2_b64 v32, v[36:37], v[18:19] offset0:26 offset1:27
	ds_write2_b64 v32, v[12:13], v[20:21] offset0:28 offset1:29
	ds_write2_b64 v32, v[6:7], v[4:5] offset0:30 offset1:31
	s_waitcnt lgkmcnt(0)
	s_barrier
	s_nop 0
	v_cmp_gt_i32_e32 vcc, s33, v65
	s_and_saveexec_b64 s[0:1], vcc
	s_cbranch_execz .LBB0_735
	v_and_b32_e32 v32, 31, v65
	v_cvt_f32_ubyte0_e32 v0, v32
	v_mul_f32_e32 v0, 0x3a800000, v0
	v_cos_f32_e32 v62, v0
	v_sin_f32_e32 v63, v0
	v_add_u32_e32 v64, 0xfffffe00, v65
	v_lshlrev_b32_e32 v65, 5, v65
	v_mul_f32_e32 v37, 0x3f3504f3, v62
	v_pk_mul_f32 v[0:1], v[62:63], v[62:63] op_sel:[1,1] op_sel_hi:[0,1]
	v_pk_fma_f32 v[28:29], v[62:63], v[62:63], v[0:1] op_sel_hi:[0,1,1] neg_lo:[0,0,1] neg_hi:[0,0,1]
	v_pk_fma_f32 v[22:23], v[62:63], v[62:63], v[0:1] op_sel_hi:[0,1,1]
	v_mov_b32_e32 v18, v28
	v_mov_b32_e32 v19, v23
	v_pk_mul_f32 v[0:1], v[18:19], v[22:23] op_sel:[0,1]
	v_pk_mul_f32 v[30:31], v[22:23], s[8:9] op_sel:[1,0]
	v_pk_fma_f32 v[12:13], v[28:29], v[18:19], v[0:1] op_sel:[0,0,1] op_sel_hi:[0,1,0] neg_lo:[0,0,1] neg_hi:[0,0,1]
	v_pk_fma_f32 v[14:15], v[28:29], v[18:19], v[0:1] op_sel:[0,0,1] op_sel_hi:[0,1,0]
	v_pk_mov_b32 v[16:17], v[14:15], v[12:13] op_sel:[1,0]
	v_mov_b32_e32 v10, v12
	v_mov_b32_e32 v11, v15
	v_pk_mul_f32 v[0:1], v[16:17], v[14:15] op_sel:[0,1]
	v_pk_mul_f32 v[34:35], v[62:63], 0 op_sel_hi:[1,0]
	v_pk_fma_f32 v[2:3], v[12:13], v[10:11], v[0:1] op_sel_hi:[0,1,1] neg_lo:[0,0,1] neg_hi:[0,0,1]
	v_pk_fma_f32 v[4:5], v[12:13], v[10:11], v[0:1] op_sel_hi:[0,1,1]
	v_pk_mov_b32 v[8:9], v[4:5], v[2:3] op_sel:[1,0]
	v_mov_b32_e32 v6, v2
	v_mov_b32_e32 v7, v5
	v_pk_mul_f32 v[0:1], v[8:9], v[4:5] op_sel:[0,1]
	v_mov_b32_e32 v56, v63
	v_pk_fma_f32 v[20:21], v[2:3], v[6:7], v[0:1] op_sel_hi:[0,1,1] neg_lo:[0,0,1] neg_hi:[0,0,1]
	v_pk_fma_f32 v[24:25], v[2:3], v[6:7], v[0:1] op_sel_hi:[0,1,1]
	v_pk_mov_b32 v[26:27], v[24:25], v[20:21] op_sel:[1,0]
	v_mul_f32_e32 v36, 0x3f3504f3, v63
	v_pk_fma_f32 v[0:1], v[26:27], 0, v[20:21] op_sel_hi:[1,0,1] neg_lo:[1,0,0] neg_hi:[1,0,0]
	v_pk_fma_f32 v[20:21], v[26:27], 0, v[24:25] op_sel_hi:[1,0,1]
	v_pk_mov_b32 v[24:25], v[22:23], v[28:29] op_sel:[1,0]
	v_mov_b32_e32 v1, v21
	v_pk_mul_f32 v[20:21], v[6:7], 0 op_sel_hi:[1,0]
	v_pk_fma_f32 v[26:27], v[28:29], s[76:77], v[30:31] op_sel:[0,0,1] op_sel_hi:[0,1,0] neg_lo:[0,0,1] neg_hi:[0,0,1]
	v_pk_add_f32 v[2:3], v[2:3], v[20:21] op_sel:[0,1] op_sel_hi:[1,0] neg_lo:[0,1] neg_hi:[0,1]
	v_pk_add_f32 v[4:5], v[4:5], v[20:21] op_sel_hi:[1,0]
	v_mul_f32_e32 v20, 0x3f3504f3, v23
	v_mov_b32_e32 v3, v5
	v_pk_fma_f32 v[4:5], v[6:7], 0, v[8:9] op_sel_hi:[1,0,1] neg_lo:[0,0,1] neg_hi:[0,0,1]
	v_pk_fma_f32 v[6:7], v[6:7], 0, v[8:9] op_sel_hi:[1,0,1]
	v_pk_mul_f32 v[8:9], v[10:11], 0 op_sel_hi:[1,0]
	v_mov_b32_e32 v5, v7
	v_pk_add_f32 v[6:7], v[12:13], v[8:9] op_sel:[0,1] op_sel_hi:[1,0] neg_lo:[0,1] neg_hi:[0,1]
	v_pk_add_f32 v[8:9], v[14:15], v[8:9] op_sel_hi:[1,0]
	v_mul_f32_e32 v14, 0x3f3504f3, v15
	v_mov_b32_e32 v7, v9
	v_pk_fma_f32 v[8:9], v[10:11], 0, v[16:17] op_sel_hi:[1,0,1] neg_lo:[0,0,1] neg_hi:[0,0,1]
	v_pk_fma_f32 v[10:11], v[10:11], 0, v[16:17] op_sel_hi:[1,0,1]
	v_pk_mul_f32 v[16:17], v[18:19], 0 op_sel_hi:[1,0]
	v_mov_b32_e32 v9, v11
	v_mul_f32_e32 v11, 0x3f3504f3, v12
	v_fmac_f32_e32 v11, 0x3f3504f3, v15
	v_pk_fma_f32 v[12:13], v[12:13], s[72:73], v[14:15] op_sel_hi:[0,1,0] neg_lo:[0,0,1] neg_hi:[0,0,1]
	v_pk_add_f32 v[14:15], v[28:29], v[16:17] op_sel:[0,1] op_sel_hi:[1,0] neg_lo:[0,1] neg_hi:[0,1]
	v_pk_add_f32 v[16:17], v[22:23], v[16:17] op_sel_hi:[1,0]
; __device__ __forceinline__ float2 cmul(float2 a, float2 b) { return make_float2(a.x * b.x - a.y * b.y, a.x * b.y + a.y * b.x); }
; __device__ __forceinline__ float2 twid(float turns) { return make_float2(__builtin_amdgcn_cosf(turns), -__builtin_amdgcn_sinf(turns)); }
; template <int R, bool INV>
; __device__ __forceinline__ void butterflies(c32 (&v)[1 << R], float turns0) {
;     ...
;   float2 tbs[R];
;   tbs[0] = twid(turns0);
;   if (INV) tbs[0].y = -tbs[0].y;
; #pragma unroll
;   for (int k = 1; k < R; ++k) tbs[k] = cmul(tbs[k - 1], tbs[k - 1]);
; template <int LOGN, int R, int DLOG, bool INV, int MODE, class F>
; __device__ __forceinline__ void fft_pass(float2* X, const F& f) {
;     ...
;   for (int g = tid0; g < NGR; g += 512) {
;     const int lo = g & (dmin - 1), base = gbase(g), pb = phys(base);
;     c32 v[RAD];
;     if constexpr (MODE == 1) {
; #pragma unroll
;       for (int j = 0; j < RAD; ++j) v[j] = nxt[j];
;       if (g + 512 < NGR) fetch(g + 512, nxt);
;     } else {
; #pragma unroll
;       for (int j = 0; j < RAD; ++j) v[j] = Xc[(DLOG >= 5) ? pb + j * PSTEP : phys(base + (j << DLOG))];
;     }
;     butterflies<R, INV>(v, (float)lo / (float)(RAD << DLOG));
	v_pk_fma_f32 v[20:21], v[28:29], s[72:73], v[20:21] op_sel_hi:[0,1,0] neg_lo:[0,0,1] neg_hi:[0,0,1]
	v_mov_b32_e32 v15, v17
	v_pk_fma_f32 v[16:17], v[18:19], 0, v[24:25] op_sel_hi:[1,0,1] neg_lo:[0,0,1] neg_hi:[0,0,1]
	v_pk_fma_f32 v[18:19], v[18:19], 0, v[24:25] op_sel_hi:[1,0,1]
	v_pk_fma_f32 v[24:25], v[28:29], s[10:11], v[30:31] op_sel_hi:[0,1,1] neg_lo:[0,0,1] neg_hi:[0,0,1]
	v_mov_b32_e32 v17, v19
	v_mul_f32_e32 v19, 0x3f3504f3, v28
	v_fmac_f32_e32 v19, 0x3f3504f3, v23
	v_pk_fma_f32 v[22:23], v[28:29], s[10:11], v[30:31] op_sel_hi:[0,1,1]
	v_pk_fma_f32 v[28:29], v[28:29], s[76:77], v[30:31] op_sel_hi:[0,1,0]
	v_sub_f32_e32 v30, v62, v35
	v_add_f32_e32 v31, v63, v34
	v_pk_fma_f32 v[34:35], v[62:63], 0, v[62:63] op_sel:[0,0,1] op_sel_hi:[1,0,0] neg_lo:[0,0,1] neg_hi:[0,0,1]
	v_pk_fma_f32 v[38:39], v[62:63], 0, v[62:63] op_sel:[0,0,1] op_sel_hi:[1,0,0]
	v_fmac_f32_e32 v37, 0x3f3504f3, v63
	v_pk_mul_f32 v[46:47], v[56:57], s[54:55] op_sel_hi:[0,1]
	v_pk_mul_f32 v[54:55], v[56:57], s[8:9] op_sel_hi:[0,1]
	v_pk_mul_f32 v[66:67], v[56:57], s[18:19] op_sel_hi:[0,1]
	v_mov_b32_e32 v35, v39
	v_pk_fma_f32 v[38:39], v[62:63], s[72:73], v[36:37] op_sel_hi:[0,1,0] neg_lo:[0,0,1] neg_hi:[0,0,1]
	v_pk_fma_f32 v[40:41], v[62:63], s[16:17], v[46:47] op_sel_hi:[0,1,1]
	v_pk_fma_f32 v[42:43], v[62:63], s[16:17], v[46:47] op_sel_hi:[0,1,1] neg_lo:[0,0,1] neg_hi:[0,0,1]
	v_pk_fma_f32 v[44:45], v[62:63], s[68:69], v[46:47] op_sel:[0,0,1] op_sel_hi:[0,1,0] neg_lo:[0,0,1] neg_hi:[0,0,1]
	v_pk_fma_f32 v[46:47], v[62:63], s[68:69], v[46:47] op_sel_hi:[0,1,0]
	v_pk_fma_f32 v[48:49], v[62:63], s[10:11], v[54:55] op_sel_hi:[0,1,1]
	v_pk_fma_f32 v[50:51], v[62:63], s[10:11], v[54:55] op_sel_hi:[0,1,1] neg_lo:[0,0,1] neg_hi:[0,0,1]
	v_pk_fma_f32 v[52:53], v[62:63], s[76:77], v[54:55] op_sel:[0,0,1] op_sel_hi:[0,1,0] neg_lo:[0,0,1] neg_hi:[0,0,1]
	v_pk_fma_f32 v[54:55], v[62:63], s[76:77], v[54:55] op_sel_hi:[0,1,0]
	v_pk_fma_f32 v[56:57], v[62:63], s[4:5], v[66:67] op_sel_hi:[0,1,1]
	v_pk_fma_f32 v[58:59], v[62:63], s[4:5], v[66:67] op_sel_hi:[0,1,1] neg_lo:[0,0,1] neg_hi:[0,0,1]
	v_pk_fma_f32 v[60:61], v[62:63], s[30:31], v[66:67] op_sel:[0,0,1] op_sel_hi:[0,1,0] neg_lo:[0,0,1] neg_hi:[0,0,1]
	v_pk_fma_f32 v[62:63], v[62:63], s[30:31], v[66:67] op_sel_hi:[0,1,0]
	v_mov_b32_e32 v10, v13
	v_mov_b32_e32 v18, v21
	v_mov_b32_e32 v22, v27
	v_mov_b32_e32 v28, v25
	v_mov_b32_e32 v36, v39
	v_mov_b32_e32 v40, v45
	v_mov_b32_e32 v46, v43
	v_mov_b32_e32 v48, v53
	v_mov_b32_e32 v54, v51
	v_mov_b32_e32 v56, v61
	v_mov_b32_e32 v62, v59
	s_mov_b64 s[24:25], 0
.LBB0_734:
	v_and_b32_e32 v66, 0xfffffc00, v65
	v_ashrrev_i32_e32 v67, 2, v66
	v_add_u32_e32 v67, 0, v67
	v_lshlrev_b32_e32 v66, 3, v66
	v_lshlrev_b32_e32 v68, 3, v32
	v_add3_u32 v132, v67, v66, v68
	ds_read_b64 v[66:67], v132
	ds_read_b64 v[68:69], v132 offset:264
	ds_read_b64 v[70:71], v132 offset:528
	ds_read_b64 v[72:73], v132 offset:792
	ds_read_b64 v[74:75], v132 offset:1056
	ds_read_b64 v[76:77], v132 offset:1320
	ds_read_b64 v[78:79], v132 offset:1584
	ds_read_b64 v[80:81], v132 offset:1848
	s_waitcnt lgkmcnt(6)
	v_pk_mul_f32 v[130:131], v[68:69], v[0:1] op_sel:[0,0] op_sel_hi:[0,1]
	s_nop 0
	v_pk_fma_f32 v[68:69], v[68:69], v[0:1], v[130:131] op_sel:[1,1,0] op_sel_hi:[1,0,1] neg_lo:[0,1,0]
	v_add_u32_e32 v133, 0x800, v132
	v_pk_add_f32 v[130:131], v[66:67], v[68:69]
	v_pk_add_f32 v[66:67], v[66:67], v[68:69] neg_lo:[0,1] neg_hi:[0,1]
	s_waitcnt lgkmcnt(4)
	v_pk_mul_f32 v[68:69], v[72:73], v[0:1] op_sel:[0,0] op_sel_hi:[0,1]
	ds_read_b64 v[82:83], v133 offset:64
	ds_read_b64 v[84:85], v133 offset:328
	ds_read_b64 v[86:87], v133 offset:592
	ds_read_b64 v[88:89], v133 offset:856
	ds_read_b64 v[90:91], v133 offset:1120
	ds_read_b64 v[92:93], v133 offset:1384
	ds_read_b64 v[94:95], v133 offset:1648
	ds_read_b64 v[96:97], v133 offset:1912
	v_pk_fma_f32 v[68:69], v[72:73], v[0:1], v[68:69] op_sel:[1,1,0] op_sel_hi:[1,0,1] neg_lo:[0,1,0]
	v_add_u32_e32 v134, 0x1000, v132
	v_pk_add_f32 v[72:73], v[70:71], v[68:69]
	v_pk_add_f32 v[68:69], v[70:71], v[68:69] neg_lo:[0,1] neg_hi:[0,1]
	s_waitcnt lgkmcnt(10)
	v_pk_mul_f32 v[70:71], v[76:77], v[0:1] op_sel:[0,0] op_sel_hi:[0,1]
	ds_read_b64 v[98:99], v134 offset:128
	ds_read_b64 v[100:101], v134 offset:392
	ds_read_b64 v[102:103], v134 offset:656
	ds_read_b64 v[104:105], v134 offset:920
	ds_read_b64 v[106:107], v134 offset:1184
	ds_read_b64 v[108:109], v134 offset:1448
	ds_read_b64 v[110:111], v134 offset:1712
	ds_read_b64 v[112:113], v134 offset:1976
	v_pk_fma_f32 v[70:71], v[76:77], v[0:1], v[70:71] op_sel:[1,1,0] op_sel_hi:[1,0,1] neg_lo:[0,1,0]
	v_add_u32_e32 v135, 0x1800, v132
	v_pk_add_f32 v[76:77], v[74:75], v[70:71]
	v_pk_add_f32 v[70:71], v[74:75], v[70:71] neg_lo:[0,1] neg_hi:[0,1]
	s_waitcnt lgkmcnt(15)
	v_pk_mul_f32 v[74:75], v[80:81], v[0:1] op_sel:[0,0] op_sel_hi:[0,1]
	ds_read_b64 v[114:115], v135 offset:192
	ds_read_b64 v[116:117], v135 offset:456
	ds_read_b64 v[118:119], v135 offset:720
	ds_read_b64 v[120:121], v135 offset:984
	ds_read_b64 v[122:123], v135 offset:1248
	ds_read_b64 v[124:125], v135 offset:1512
	ds_read_b64 v[126:127], v135 offset:1776
	ds_read_b64 v[128:129], v135 offset:2040
	v_pk_fma_f32 v[74:75], v[80:81], v[0:1], v[74:75] op_sel:[1,1,0] op_sel_hi:[1,0,1] neg_lo:[0,1,0]
	v_add_u32_e32 v64, 0x200, v64
	v_pk_add_f32 v[80:81], v[78:79], v[74:75]
	v_pk_add_f32 v[74:75], v[78:79], v[74:75] neg_lo:[0,1] neg_hi:[0,1]
	s_waitcnt lgkmcnt(15)
	v_pk_mul_f32 v[78:79], v[84:85], v[0:1] op_sel:[0,0] op_sel_hi:[0,1]
	v_cmp_lt_i32_e32 vcc, -1, v64
	v_pk_fma_f32 v[78:79], v[84:85], v[0:1], v[78:79] op_sel:[1,1,0] op_sel_hi:[1,0,1] neg_lo:[0,1,0]
	v_add_u32_e32 v65, 0x4000, v65
	v_pk_add_f32 v[84:85], v[82:83], v[78:79]
	v_pk_add_f32 v[78:79], v[82:83], v[78:79] neg_lo:[0,1] neg_hi:[0,1]
	s_waitcnt lgkmcnt(15)
; __device__ __forceinline__ float2 cmul(float2 a, float2 b) { return make_float2(a.x * b.x - a.y * b.y, a.x * b.y + a.y * b.x); }
; __device__ __forceinline__ c32 cmul_pk(c32 a, c32 b) {
;   c32 t, r;
;   asm("v_pk_mul_f32 %0, %1, %2 op_sel:[0,0] op_sel_hi:[0,1]" : "=v"(t) : "v"(a), "v"(b));
;   asm("v_pk_fma_f32 %0, %1, %2, %3 op_sel:[1,1,0] op_sel_hi:[1,0,1] neg_lo:[0,1,0]" : "=v"(r) : "v"(a), "v"(b), "v"(t));
;   return r;
; }
; template <int R, bool INV>
; __device__ __forceinline__ void butterflies(c32 (&v)[1 << R], float turns0) {
;     ...
;   for (int kk = 0; kk < R; ++kk) {
;     const int k = INV ? (R - 1 - kk) : kk;
;     const int hd = RAD >> (k + 1);
; #pragma unroll
;     for (int j = 0; j < RAD; ++j) {
;       if ((j & hd) == 0) {
;         const int m = (j & (hd - 1)) * (16 / hd);
;         const float2 c = make_float2(TC[m], INV ? TS[m] : -TS[m]);
;         const float2 twf = cmul(tbs[k], c);
;         const c32 tw = {twf.x, twf.y};
;         const c32 a = v[j], b = v[j + hd];
;         if (!INV) { v[j] = a + b; v[j + hd] = cmul_pk(a - b, tw); }
;         else { const c32 bt = cmul_pk(b, tw); v[j] = a + bt; v[j + hd] = a - bt; }
;       }
;     }
;   }
	v_pk_mul_f32 v[82:83], v[88:89], v[0:1] op_sel:[0,0] op_sel_hi:[0,1]
	s_or_b64 s[24:25], vcc, s[24:25]
	v_pk_fma_f32 v[82:83], v[88:89], v[0:1], v[82:83] op_sel:[1,1,0] op_sel_hi:[1,0,1] neg_lo:[0,1,0]
	s_nop 0
	v_pk_add_f32 v[88:89], v[86:87], v[82:83]
	v_pk_add_f32 v[82:83], v[86:87], v[82:83] neg_lo:[0,1] neg_hi:[0,1]
	s_waitcnt lgkmcnt(15)
	v_pk_mul_f32 v[86:87], v[92:93], v[0:1] op_sel:[0,0] op_sel_hi:[0,1]
	s_nop 0
	v_pk_fma_f32 v[86:87], v[92:93], v[0:1], v[86:87] op_sel:[1,1,0] op_sel_hi:[1,0,1] neg_lo:[0,1,0]
	s_nop 0
	v_pk_add_f32 v[92:93], v[90:91], v[86:87]
	v_pk_add_f32 v[86:87], v[90:91], v[86:87] neg_lo:[0,1] neg_hi:[0,1]
	s_waitcnt lgkmcnt(15)
	v_pk_mul_f32 v[90:91], v[96:97], v[0:1] op_sel:[0,0] op_sel_hi:[0,1]
	s_nop 0
	v_pk_fma_f32 v[90:91], v[96:97], v[0:1], v[90:91] op_sel:[1,1,0] op_sel_hi:[1,0,1] neg_lo:[0,1,0]
	s_nop 0
	v_pk_add_f32 v[96:97], v[94:95], v[90:91]
	v_pk_add_f32 v[90:91], v[94:95], v[90:91] neg_lo:[0,1] neg_hi:[0,1]
	s_waitcnt lgkmcnt(14)
	v_pk_mul_f32 v[94:95], v[100:101], v[0:1] op_sel:[0,0] op_sel_hi:[0,1]
	s_nop 0
	v_pk_fma_f32 v[94:95], v[100:101], v[0:1], v[94:95] op_sel:[1,1,0] op_sel_hi:[1,0,1] neg_lo:[0,1,0]
	s_nop 0
	v_pk_add_f32 v[100:101], v[98:99], v[94:95]
	v_pk_add_f32 v[94:95], v[98:99], v[94:95] neg_lo:[0,1] neg_hi:[0,1]
	s_waitcnt lgkmcnt(12)
	v_pk_mul_f32 v[98:99], v[104:105], v[0:1] op_sel:[0,0] op_sel_hi:[0,1]
	s_nop 0
	v_pk_fma_f32 v[98:99], v[104:105], v[0:1], v[98:99] op_sel:[1,1,0] op_sel_hi:[1,0,1] neg_lo:[0,1,0]
	s_nop 0
	v_pk_add_f32 v[104:105], v[102:103], v[98:99]
	v_pk_add_f32 v[98:99], v[102:103], v[98:99] neg_lo:[0,1] neg_hi:[0,1]
	s_waitcnt lgkmcnt(10)
	v_pk_mul_f32 v[102:103], v[108:109], v[0:1] op_sel:[0,0] op_sel_hi:[0,1]
	s_nop 0
	v_pk_fma_f32 v[102:103], v[108:109], v[0:1], v[102:103] op_sel:[1,1,0] op_sel_hi:[1,0,1] neg_lo:[0,1,0]
	s_nop 0
	v_pk_add_f32 v[108:109], v[106:107], v[102:103]
	v_pk_add_f32 v[102:103], v[106:107], v[102:103] neg_lo:[0,1] neg_hi:[0,1]
	s_waitcnt lgkmcnt(8)
	v_pk_mul_f32 v[106:107], v[112:113], v[0:1] op_sel:[0,0] op_sel_hi:[0,1]
	s_nop 0
	v_pk_fma_f32 v[106:107], v[112:113], v[0:1], v[106:107] op_sel:[1,1,0] op_sel_hi:[1,0,1] neg_lo:[0,1,0]
	s_nop 0
	v_pk_add_f32 v[112:113], v[110:111], v[106:107]
	v_pk_add_f32 v[106:107], v[110:111], v[106:107] neg_lo:[0,1] neg_hi:[0,1]
	s_waitcnt lgkmcnt(6)
	v_pk_mul_f32 v[110:111], v[116:117], v[0:1] op_sel:[0,0] op_sel_hi:[0,1]
	s_nop 0
	v_pk_fma_f32 v[110:111], v[116:117], v[0:1], v[110:111] op_sel:[1,1,0] op_sel_hi:[1,0,1] neg_lo:[0,1,0]
	s_nop 0
	v_pk_add_f32 v[116:117], v[114:115], v[110:111]
	v_pk_add_f32 v[110:111], v[114:115], v[110:111] neg_lo:[0,1] neg_hi:[0,1]
	s_waitcnt lgkmcnt(4)
	v_pk_mul_f32 v[114:115], v[120:121], v[0:1] op_sel:[0,0] op_sel_hi:[0,1]
	s_nop 0
	v_pk_fma_f32 v[114:115], v[120:121], v[0:1], v[114:115] op_sel:[1,1,0] op_sel_hi:[1,0,1] neg_lo:[0,1,0]
	s_nop 0
	v_pk_add_f32 v[120:121], v[118:119], v[114:115]
	v_pk_add_f32 v[114:115], v[118:119], v[114:115] neg_lo:[0,1] neg_hi:[0,1]
	s_waitcnt lgkmcnt(2)
	v_pk_mul_f32 v[118:119], v[124:125], v[0:1] op_sel:[0,0] op_sel_hi:[0,1]
	s_nop 0
	v_pk_fma_f32 v[118:119], v[124:125], v[0:1], v[118:119] op_sel:[1,1,0] op_sel_hi:[1,0,1] neg_lo:[0,1,0]
	s_nop 0
	v_pk_add_f32 v[124:125], v[122:123], v[118:119]
	v_pk_add_f32 v[118:119], v[122:123], v[118:119] neg_lo:[0,1] neg_hi:[0,1]
	s_waitcnt lgkmcnt(0)
	v_pk_mul_f32 v[122:123], v[128:129], v[0:1] op_sel:[0,0] op_sel_hi:[0,1]
	s_nop 0
	v_pk_fma_f32 v[122:123], v[128:129], v[0:1], v[122:123] op_sel:[1,1,0] op_sel_hi:[1,0,1] neg_lo:[0,1,0]
	s_nop 0
	v_pk_add_f32 v[128:129], v[126:127], v[122:123]
	v_pk_add_f32 v[122:123], v[126:127], v[122:123] neg_lo:[0,1] neg_hi:[0,1]
	v_pk_mul_f32 v[126:127], v[72:73], v[2:3] op_sel:[0,0] op_sel_hi:[0,1]
	s_nop 0
	v_pk_fma_f32 v[72:73], v[72:73], v[2:3], v[126:127] op_sel:[1,1,0] op_sel_hi:[1,0,1] neg_lo:[0,1,0]
	s_nop 0
	v_pk_add_f32 v[126:127], v[130:131], v[72:73]
	v_pk_add_f32 v[72:73], v[130:131], v[72:73] neg_lo:[0,1] neg_hi:[0,1]
	v_pk_mul_f32 v[130:131], v[68:69], v[4:5] op_sel:[0,0] op_sel_hi:[0,1]
	s_nop 0
	v_pk_fma_f32 v[68:69], v[68:69], v[4:5], v[130:131] op_sel:[1,1,0] op_sel_hi:[1,0,1] neg_lo:[0,1,0]
	s_nop 0
	v_pk_add_f32 v[130:131], v[66:67], v[68:69]
	v_pk_add_f32 v[66:67], v[66:67], v[68:69] neg_lo:[0,1] neg_hi:[0,1]
	v_pk_mul_f32 v[68:69], v[80:81], v[2:3] op_sel:[0,0] op_sel_hi:[0,1]
	s_nop 0
	v_pk_fma_f32 v[68:69], v[80:81], v[2:3], v[68:69] op_sel:[1,1,0] op_sel_hi:[1,0,1] neg_lo:[0,1,0]
	s_nop 0
	v_pk_add_f32 v[80:81], v[76:77], v[68:69]
	v_pk_add_f32 v[68:69], v[76:77], v[68:69] neg_lo:[0,1] neg_hi:[0,1]
	v_pk_mul_f32 v[76:77], v[74:75], v[4:5] op_sel:[0,0] op_sel_hi:[0,1]
	s_nop 0
	v_pk_fma_f32 v[74:75], v[74:75], v[4:5], v[76:77] op_sel:[1,1,0] op_sel_hi:[1,0,1] neg_lo:[0,1,0]
	s_nop 0
	v_pk_add_f32 v[76:77], v[70:71], v[74:75]
	v_pk_add_f32 v[70:71], v[70:71], v[74:75] neg_lo:[0,1] neg_hi:[0,1]
	v_pk_mul_f32 v[74:75], v[88:89], v[2:3] op_sel:[0,0] op_sel_hi:[0,1]
	s_nop 0
	v_pk_fma_f32 v[74:75], v[88:89], v[2:3], v[74:75] op_sel:[1,1,0] op_sel_hi:[1,0,1] neg_lo:[0,1,0]
	s_nop 0
	v_pk_add_f32 v[88:89], v[84:85], v[74:75]
	v_pk_add_f32 v[74:75], v[84:85], v[74:75] neg_lo:[0,1] neg_hi:[0,1]
	v_pk_mul_f32 v[84:85], v[82:83], v[4:5] op_sel:[0,0] op_sel_hi:[0,1]
	s_nop 0
	v_pk_fma_f32 v[82:83], v[82:83], v[4:5], v[84:85] op_sel:[1,1,0] op_sel_hi:[1,0,1] neg_lo:[0,1,0]
	s_nop 0
	v_pk_add_f32 v[84:85], v[78:79], v[82:83]
	v_pk_add_f32 v[78:79], v[78:79], v[82:83] neg_lo:[0,1] neg_hi:[0,1]
	v_pk_mul_f32 v[82:83], v[96:97], v[2:3] op_sel:[0,0] op_sel_hi:[0,1]
	s_nop 0
	v_pk_fma_f32 v[82:83], v[96:97], v[2:3], v[82:83] op_sel:[1,1,0] op_sel_hi:[1,0,1] neg_lo:[0,1,0]
; __device__ __forceinline__ float2 cmul(float2 a, float2 b) { return make_float2(a.x * b.x - a.y * b.y, a.x * b.y + a.y * b.x); }
; __device__ __forceinline__ c32 cmul_pk(c32 a, c32 b) {
;   c32 t, r;
;   asm("v_pk_mul_f32 %0, %1, %2 op_sel:[0,0] op_sel_hi:[0,1]" : "=v"(t) : "v"(a), "v"(b));
;   asm("v_pk_fma_f32 %0, %1, %2, %3 op_sel:[1,1,0] op_sel_hi:[1,0,1] neg_lo:[0,1,0]" : "=v"(r) : "v"(a), "v"(b), "v"(t));
;   return r;
; }
; template <int R, bool INV>
; __device__ __forceinline__ void butterflies(c32 (&v)[1 << R], float turns0) {
;     ...
;   for (int kk = 0; kk < R; ++kk) {
;     const int k = INV ? (R - 1 - kk) : kk;
;     const int hd = RAD >> (k + 1);
; #pragma unroll
;     for (int j = 0; j < RAD; ++j) {
;       if ((j & hd) == 0) {
;         const int m = (j & (hd - 1)) * (16 / hd);
;         const float2 c = make_float2(TC[m], INV ? TS[m] : -TS[m]);
;         const float2 twf = cmul(tbs[k], c);
;         const c32 tw = {twf.x, twf.y};
;         const c32 a = v[j], b = v[j + hd];
;         if (!INV) { v[j] = a + b; v[j + hd] = cmul_pk(a - b, tw); }
;         else { const c32 bt = cmul_pk(b, tw); v[j] = a + bt; v[j + hd] = a - bt; }
;       }
;     }
;   }
	s_nop 0
	v_pk_add_f32 v[96:97], v[92:93], v[82:83]
	v_pk_add_f32 v[82:83], v[92:93], v[82:83] neg_lo:[0,1] neg_hi:[0,1]
	v_pk_mul_f32 v[92:93], v[90:91], v[4:5] op_sel:[0,0] op_sel_hi:[0,1]
	s_nop 0
	v_pk_fma_f32 v[90:91], v[90:91], v[4:5], v[92:93] op_sel:[1,1,0] op_sel_hi:[1,0,1] neg_lo:[0,1,0]
	s_nop 0
	v_pk_add_f32 v[92:93], v[86:87], v[90:91]
	v_pk_add_f32 v[86:87], v[86:87], v[90:91] neg_lo:[0,1] neg_hi:[0,1]
	v_pk_mul_f32 v[90:91], v[104:105], v[2:3] op_sel:[0,0] op_sel_hi:[0,1]
	s_nop 0
	v_pk_fma_f32 v[90:91], v[104:105], v[2:3], v[90:91] op_sel:[1,1,0] op_sel_hi:[1,0,1] neg_lo:[0,1,0]
	s_nop 0
	v_pk_add_f32 v[104:105], v[100:101], v[90:91]
	v_pk_add_f32 v[90:91], v[100:101], v[90:91] neg_lo:[0,1] neg_hi:[0,1]
	v_pk_mul_f32 v[100:101], v[98:99], v[4:5] op_sel:[0,0] op_sel_hi:[0,1]
	s_nop 0
	v_pk_fma_f32 v[98:99], v[98:99], v[4:5], v[100:101] op_sel:[1,1,0] op_sel_hi:[1,0,1] neg_lo:[0,1,0]
	s_nop 0
	v_pk_add_f32 v[100:101], v[94:95], v[98:99]
	v_pk_add_f32 v[94:95], v[94:95], v[98:99] neg_lo:[0,1] neg_hi:[0,1]
	v_pk_mul_f32 v[98:99], v[112:113], v[2:3] op_sel:[0,0] op_sel_hi:[0,1]
	s_nop 0
	v_pk_fma_f32 v[98:99], v[112:113], v[2:3], v[98:99] op_sel:[1,1,0] op_sel_hi:[1,0,1] neg_lo:[0,1,0]
	s_nop 0
	v_pk_add_f32 v[112:113], v[108:109], v[98:99]
	v_pk_add_f32 v[98:99], v[108:109], v[98:99] neg_lo:[0,1] neg_hi:[0,1]
	v_pk_mul_f32 v[108:109], v[106:107], v[4:5] op_sel:[0,0] op_sel_hi:[0,1]
	s_nop 0
	v_pk_fma_f32 v[106:107], v[106:107], v[4:5], v[108:109] op_sel:[1,1,0] op_sel_hi:[1,0,1] neg_lo:[0,1,0]
	s_nop 0
	v_pk_add_f32 v[108:109], v[102:103], v[106:107]
	v_pk_add_f32 v[102:103], v[102:103], v[106:107] neg_lo:[0,1] neg_hi:[0,1]
	v_pk_mul_f32 v[106:107], v[120:121], v[2:3] op_sel:[0,0] op_sel_hi:[0,1]
	s_nop 0
	v_pk_fma_f32 v[106:107], v[120:121], v[2:3], v[106:107] op_sel:[1,1,0] op_sel_hi:[1,0,1] neg_lo:[0,1,0]
	s_nop 0
	v_pk_add_f32 v[120:121], v[116:117], v[106:107]
	v_pk_add_f32 v[106:107], v[116:117], v[106:107] neg_lo:[0,1] neg_hi:[0,1]
	v_pk_mul_f32 v[116:117], v[114:115], v[4:5] op_sel:[0,0] op_sel_hi:[0,1]
	s_nop 0
	v_pk_fma_f32 v[114:115], v[114:115], v[4:5], v[116:117] op_sel:[1,1,0] op_sel_hi:[1,0,1] neg_lo:[0,1,0]
	s_nop 0
	v_pk_add_f32 v[116:117], v[110:111], v[114:115]
	v_pk_add_f32 v[110:111], v[110:111], v[114:115] neg_lo:[0,1] neg_hi:[0,1]
	v_pk_mul_f32 v[114:115], v[128:129], v[2:3] op_sel:[0,0] op_sel_hi:[0,1]
	s_nop 0
	v_pk_fma_f32 v[114:115], v[128:129], v[2:3], v[114:115] op_sel:[1,1,0] op_sel_hi:[1,0,1] neg_lo:[0,1,0]
	s_nop 0
	v_pk_add_f32 v[128:129], v[124:125], v[114:115]
	v_pk_add_f32 v[114:115], v[124:125], v[114:115] neg_lo:[0,1] neg_hi:[0,1]
	v_pk_mul_f32 v[124:125], v[122:123], v[4:5] op_sel:[0,0] op_sel_hi:[0,1]
	s_nop 0
	v_pk_fma_f32 v[122:123], v[122:123], v[4:5], v[124:125] op_sel:[1,1,0] op_sel_hi:[1,0,1] neg_lo:[0,1,0]
	s_nop 0
	v_pk_add_f32 v[124:125], v[118:119], v[122:123]
	v_pk_add_f32 v[118:119], v[118:119], v[122:123] neg_lo:[0,1] neg_hi:[0,1]
	v_pk_mul_f32 v[122:123], v[80:81], v[6:7] op_sel:[0,0] op_sel_hi:[0,1]
	s_nop 0
	v_pk_fma_f32 v[80:81], v[80:81], v[6:7], v[122:123] op_sel:[1,1,0] op_sel_hi:[1,0,1] neg_lo:[0,1,0]
	s_nop 0
	v_pk_add_f32 v[122:123], v[126:127], v[80:81]
	v_pk_add_f32 v[80:81], v[126:127], v[80:81] neg_lo:[0,1] neg_hi:[0,1]
	v_pk_mul_f32 v[126:127], v[76:77], v[10:11] op_sel:[0,0] op_sel_hi:[0,1]
	s_nop 0
	v_pk_fma_f32 v[76:77], v[76:77], v[10:11], v[126:127] op_sel:[1,1,0] op_sel_hi:[1,0,1] neg_lo:[0,1,0]
	s_nop 0
	v_pk_add_f32 v[126:127], v[130:131], v[76:77]
	v_pk_add_f32 v[76:77], v[130:131], v[76:77] neg_lo:[0,1] neg_hi:[0,1]
	v_pk_mul_f32 v[130:131], v[68:69], v[8:9] op_sel:[0,0] op_sel_hi:[0,1]
	s_nop 0
	v_pk_fma_f32 v[68:69], v[68:69], v[8:9], v[130:131] op_sel:[1,1,0] op_sel_hi:[1,0,1] neg_lo:[0,1,0]
	s_nop 0
	v_pk_add_f32 v[130:131], v[72:73], v[68:69]
	v_pk_add_f32 v[68:69], v[72:73], v[68:69] neg_lo:[0,1] neg_hi:[0,1]
	v_pk_mul_f32 v[72:73], v[70:71], v[12:13] op_sel:[0,0] op_sel_hi:[0,1]
	s_nop 0
	v_pk_fma_f32 v[70:71], v[70:71], v[12:13], v[72:73] op_sel:[1,1,0] op_sel_hi:[1,0,1] neg_lo:[0,1,0]
	s_nop 0
	v_pk_add_f32 v[72:73], v[66:67], v[70:71]
	v_pk_add_f32 v[66:67], v[66:67], v[70:71] neg_lo:[0,1] neg_hi:[0,1]
	v_pk_mul_f32 v[70:71], v[96:97], v[6:7] op_sel:[0,0] op_sel_hi:[0,1]
	s_nop 0
	v_pk_fma_f32 v[70:71], v[96:97], v[6:7], v[70:71] op_sel:[1,1,0] op_sel_hi:[1,0,1] neg_lo:[0,1,0]
	s_nop 0
	v_pk_add_f32 v[96:97], v[88:89], v[70:71]
	v_pk_add_f32 v[70:71], v[88:89], v[70:71] neg_lo:[0,1] neg_hi:[0,1]
	v_pk_mul_f32 v[88:89], v[92:93], v[10:11] op_sel:[0,0] op_sel_hi:[0,1]
	s_nop 0
	v_pk_fma_f32 v[88:89], v[92:93], v[10:11], v[88:89] op_sel:[1,1,0] op_sel_hi:[1,0,1] neg_lo:[0,1,0]
	s_nop 0
	v_pk_add_f32 v[92:93], v[84:85], v[88:89]
	v_pk_add_f32 v[84:85], v[84:85], v[88:89] neg_lo:[0,1] neg_hi:[0,1]
	v_pk_mul_f32 v[88:89], v[82:83], v[8:9] op_sel:[0,0] op_sel_hi:[0,1]
	s_nop 0
	v_pk_fma_f32 v[82:83], v[82:83], v[8:9], v[88:89] op_sel:[1,1,0] op_sel_hi:[1,0,1] neg_lo:[0,1,0]
	s_nop 0
	v_pk_add_f32 v[88:89], v[74:75], v[82:83]
	v_pk_add_f32 v[74:75], v[74:75], v[82:83] neg_lo:[0,1] neg_hi:[0,1]
	v_pk_mul_f32 v[82:83], v[86:87], v[12:13] op_sel:[0,0] op_sel_hi:[0,1]
	s_nop 0
	v_pk_fma_f32 v[82:83], v[86:87], v[12:13], v[82:83] op_sel:[1,1,0] op_sel_hi:[1,0,1] neg_lo:[0,1,0]
	s_nop 0
	v_pk_add_f32 v[86:87], v[78:79], v[82:83]
	v_pk_add_f32 v[78:79], v[78:79], v[82:83] neg_lo:[0,1] neg_hi:[0,1]
	v_pk_mul_f32 v[82:83], v[112:113], v[6:7] op_sel:[0,0] op_sel_hi:[0,1]
	s_nop 0
	v_pk_fma_f32 v[82:83], v[112:113], v[6:7], v[82:83] op_sel:[1,1,0] op_sel_hi:[1,0,1] neg_lo:[0,1,0]
	s_nop 0
	v_pk_add_f32 v[112:113], v[104:105], v[82:83]
; __device__ __forceinline__ float2 cmul(float2 a, float2 b) { return make_float2(a.x * b.x - a.y * b.y, a.x * b.y + a.y * b.x); }
; __device__ __forceinline__ c32 cmul_pk(c32 a, c32 b) {
;   c32 t, r;
;   asm("v_pk_mul_f32 %0, %1, %2 op_sel:[0,0] op_sel_hi:[0,1]" : "=v"(t) : "v"(a), "v"(b));
;   asm("v_pk_fma_f32 %0, %1, %2, %3 op_sel:[1,1,0] op_sel_hi:[1,0,1] neg_lo:[0,1,0]" : "=v"(r) : "v"(a), "v"(b), "v"(t));
;   return r;
; }
; template <int R, bool INV>
; __device__ __forceinline__ void butterflies(c32 (&v)[1 << R], float turns0) {
;     ...
;   for (int kk = 0; kk < R; ++kk) {
;     const int k = INV ? (R - 1 - kk) : kk;
;     const int hd = RAD >> (k + 1);
; #pragma unroll
;     for (int j = 0; j < RAD; ++j) {
;       if ((j & hd) == 0) {
;         const int m = (j & (hd - 1)) * (16 / hd);
;         const float2 c = make_float2(TC[m], INV ? TS[m] : -TS[m]);
;         const float2 twf = cmul(tbs[k], c);
;         const c32 tw = {twf.x, twf.y};
;         const c32 a = v[j], b = v[j + hd];
;         if (!INV) { v[j] = a + b; v[j + hd] = cmul_pk(a - b, tw); }
;         else { const c32 bt = cmul_pk(b, tw); v[j] = a + bt; v[j + hd] = a - bt; }
;       }
;     }
;   }
	v_pk_add_f32 v[82:83], v[104:105], v[82:83] neg_lo:[0,1] neg_hi:[0,1]
	v_pk_mul_f32 v[104:105], v[108:109], v[10:11] op_sel:[0,0] op_sel_hi:[0,1]
	s_nop 0
	v_pk_fma_f32 v[104:105], v[108:109], v[10:11], v[104:105] op_sel:[1,1,0] op_sel_hi:[1,0,1] neg_lo:[0,1,0]
	s_nop 0
	v_pk_add_f32 v[108:109], v[100:101], v[104:105]
	v_pk_add_f32 v[100:101], v[100:101], v[104:105] neg_lo:[0,1] neg_hi:[0,1]
	v_pk_mul_f32 v[104:105], v[98:99], v[8:9] op_sel:[0,0] op_sel_hi:[0,1]
	s_nop 0
	v_pk_fma_f32 v[98:99], v[98:99], v[8:9], v[104:105] op_sel:[1,1,0] op_sel_hi:[1,0,1] neg_lo:[0,1,0]
	s_nop 0
	v_pk_add_f32 v[104:105], v[90:91], v[98:99]
	v_pk_add_f32 v[90:91], v[90:91], v[98:99] neg_lo:[0,1] neg_hi:[0,1]
	v_pk_mul_f32 v[98:99], v[102:103], v[12:13] op_sel:[0,0] op_sel_hi:[0,1]
	s_nop 0
	v_pk_fma_f32 v[98:99], v[102:103], v[12:13], v[98:99] op_sel:[1,1,0] op_sel_hi:[1,0,1] neg_lo:[0,1,0]
	s_nop 0
	v_pk_add_f32 v[102:103], v[94:95], v[98:99]
	v_pk_add_f32 v[94:95], v[94:95], v[98:99] neg_lo:[0,1] neg_hi:[0,1]
	v_pk_mul_f32 v[98:99], v[128:129], v[6:7] op_sel:[0,0] op_sel_hi:[0,1]
	s_nop 0
	v_pk_fma_f32 v[98:99], v[128:129], v[6:7], v[98:99] op_sel:[1,1,0] op_sel_hi:[1,0,1] neg_lo:[0,1,0]
	s_nop 0
	v_pk_add_f32 v[128:129], v[120:121], v[98:99]
	v_pk_add_f32 v[98:99], v[120:121], v[98:99] neg_lo:[0,1] neg_hi:[0,1]
	v_pk_mul_f32 v[120:121], v[124:125], v[10:11] op_sel:[0,0] op_sel_hi:[0,1]
	s_nop 0
	v_pk_fma_f32 v[120:121], v[124:125], v[10:11], v[120:121] op_sel:[1,1,0] op_sel_hi:[1,0,1] neg_lo:[0,1,0]
	s_nop 0
	v_pk_add_f32 v[124:125], v[116:117], v[120:121]
	v_pk_add_f32 v[116:117], v[116:117], v[120:121] neg_lo:[0,1] neg_hi:[0,1]
	v_pk_mul_f32 v[120:121], v[114:115], v[8:9] op_sel:[0,0] op_sel_hi:[0,1]
	s_nop 0
	v_pk_fma_f32 v[114:115], v[114:115], v[8:9], v[120:121] op_sel:[1,1,0] op_sel_hi:[1,0,1] neg_lo:[0,1,0]
	s_nop 0
	v_pk_add_f32 v[120:121], v[106:107], v[114:115]
	v_pk_add_f32 v[106:107], v[106:107], v[114:115] neg_lo:[0,1] neg_hi:[0,1]
	v_pk_mul_f32 v[114:115], v[118:119], v[12:13] op_sel:[0,0] op_sel_hi:[0,1]
	s_nop 0
	v_pk_fma_f32 v[114:115], v[118:119], v[12:13], v[114:115] op_sel:[1,1,0] op_sel_hi:[1,0,1] neg_lo:[0,1,0]
	s_nop 0
	v_pk_add_f32 v[118:119], v[110:111], v[114:115]
	v_pk_add_f32 v[110:111], v[110:111], v[114:115] neg_lo:[0,1] neg_hi:[0,1]
	v_pk_mul_f32 v[114:115], v[96:97], v[14:15] op_sel:[0,0] op_sel_hi:[0,1]
	s_nop 0
	v_pk_fma_f32 v[96:97], v[96:97], v[14:15], v[114:115] op_sel:[1,1,0] op_sel_hi:[1,0,1] neg_lo:[0,1,0]
	s_nop 0
	v_pk_add_f32 v[114:115], v[122:123], v[96:97]
	v_pk_add_f32 v[96:97], v[122:123], v[96:97] neg_lo:[0,1] neg_hi:[0,1]
	v_pk_mul_f32 v[122:123], v[92:93], v[22:23] op_sel:[0,0] op_sel_hi:[0,1]
	s_nop 0
	v_pk_fma_f32 v[92:93], v[92:93], v[22:23], v[122:123] op_sel:[1,1,0] op_sel_hi:[1,0,1] neg_lo:[0,1,0]
	s_nop 0
	v_pk_add_f32 v[122:123], v[126:127], v[92:93]
	v_pk_add_f32 v[92:93], v[126:127], v[92:93] neg_lo:[0,1] neg_hi:[0,1]
	v_pk_mul_f32 v[126:127], v[88:89], v[18:19] op_sel:[0,0] op_sel_hi:[0,1]
	s_nop 0
	v_pk_fma_f32 v[88:89], v[88:89], v[18:19], v[126:127] op_sel:[1,1,0] op_sel_hi:[1,0,1] neg_lo:[0,1,0]
	s_nop 0
	v_pk_add_f32 v[126:127], v[130:131], v[88:89]
	v_pk_add_f32 v[88:89], v[130:131], v[88:89] neg_lo:[0,1] neg_hi:[0,1]
	v_pk_mul_f32 v[130:131], v[86:87], v[28:29] op_sel:[0,0] op_sel_hi:[0,1]
	s_nop 0
	v_pk_fma_f32 v[86:87], v[86:87], v[28:29], v[130:131] op_sel:[1,1,0] op_sel_hi:[1,0,1] neg_lo:[0,1,0]
	s_nop 0
	v_pk_add_f32 v[130:131], v[72:73], v[86:87]
	v_pk_add_f32 v[72:73], v[72:73], v[86:87] neg_lo:[0,1] neg_hi:[0,1]
	v_pk_mul_f32 v[86:87], v[70:71], v[16:17] op_sel:[0,0] op_sel_hi:[0,1]
	s_nop 0
	v_pk_fma_f32 v[70:71], v[70:71], v[16:17], v[86:87] op_sel:[1,1,0] op_sel_hi:[1,0,1] neg_lo:[0,1,0]
	s_nop 0
	v_pk_add_f32 v[86:87], v[80:81], v[70:71]
	v_pk_add_f32 v[70:71], v[80:81], v[70:71] neg_lo:[0,1] neg_hi:[0,1]
	v_pk_mul_f32 v[80:81], v[84:85], v[26:27] op_sel:[0,0] op_sel_hi:[0,1]
	s_nop 0
	v_pk_fma_f32 v[80:81], v[84:85], v[26:27], v[80:81] op_sel:[1,1,0] op_sel_hi:[1,0,1] neg_lo:[0,1,0]
	s_nop 0
	v_pk_add_f32 v[84:85], v[76:77], v[80:81]
	v_pk_add_f32 v[76:77], v[76:77], v[80:81] neg_lo:[0,1] neg_hi:[0,1]
	v_pk_mul_f32 v[80:81], v[74:75], v[20:21] op_sel:[0,0] op_sel_hi:[0,1]
	s_nop 0
	v_pk_fma_f32 v[74:75], v[74:75], v[20:21], v[80:81] op_sel:[1,1,0] op_sel_hi:[1,0,1] neg_lo:[0,1,0]
	s_nop 0
	v_pk_add_f32 v[80:81], v[68:69], v[74:75]
	v_pk_add_f32 v[68:69], v[68:69], v[74:75] neg_lo:[0,1] neg_hi:[0,1]
	v_pk_mul_f32 v[74:75], v[78:79], v[24:25] op_sel:[0,0] op_sel_hi:[0,1]
	s_nop 0
	v_pk_fma_f32 v[74:75], v[78:79], v[24:25], v[74:75] op_sel:[1,1,0] op_sel_hi:[1,0,1] neg_lo:[0,1,0]
	s_nop 0
	v_pk_add_f32 v[78:79], v[66:67], v[74:75]
	v_pk_add_f32 v[66:67], v[66:67], v[74:75] neg_lo:[0,1] neg_hi:[0,1]
	v_pk_mul_f32 v[74:75], v[128:129], v[14:15] op_sel:[0,0] op_sel_hi:[0,1]
	s_nop 0
	v_pk_fma_f32 v[74:75], v[128:129], v[14:15], v[74:75] op_sel:[1,1,0] op_sel_hi:[1,0,1] neg_lo:[0,1,0]
	s_nop 0
	v_pk_add_f32 v[128:129], v[112:113], v[74:75]
	v_pk_add_f32 v[74:75], v[112:113], v[74:75] neg_lo:[0,1] neg_hi:[0,1]
	v_pk_mul_f32 v[112:113], v[124:125], v[22:23] op_sel:[0,0] op_sel_hi:[0,1]
	s_nop 0
	v_pk_fma_f32 v[112:113], v[124:125], v[22:23], v[112:113] op_sel:[1,1,0] op_sel_hi:[1,0,1] neg_lo:[0,1,0]
	s_nop 0
	v_pk_add_f32 v[124:125], v[108:109], v[112:113]
	v_pk_add_f32 v[108:109], v[108:109], v[112:113] neg_lo:[0,1] neg_hi:[0,1]
	v_pk_mul_f32 v[112:113], v[120:121], v[18:19] op_sel:[0,0] op_sel_hi:[0,1]
	s_nop 0
	v_pk_fma_f32 v[112:113], v[120:121], v[18:19], v[112:113] op_sel:[1,1,0] op_sel_hi:[1,0,1] neg_lo:[0,1,0]
	s_nop 0
	v_pk_add_f32 v[120:121], v[104:105], v[112:113]
; __device__ __forceinline__ float2 cmul(float2 a, float2 b) { return make_float2(a.x * b.x - a.y * b.y, a.x * b.y + a.y * b.x); }
; __device__ __forceinline__ c32 cmul_pk(c32 a, c32 b) {
;   c32 t, r;
;   asm("v_pk_mul_f32 %0, %1, %2 op_sel:[0,0] op_sel_hi:[0,1]" : "=v"(t) : "v"(a), "v"(b));
;   asm("v_pk_fma_f32 %0, %1, %2, %3 op_sel:[1,1,0] op_sel_hi:[1,0,1] neg_lo:[0,1,0]" : "=v"(r) : "v"(a), "v"(b), "v"(t));
;   return r;
; }
; template <int R, bool INV>
; __device__ __forceinline__ void butterflies(c32 (&v)[1 << R], float turns0) {
;     ...
;   for (int kk = 0; kk < R; ++kk) {
;     const int k = INV ? (R - 1 - kk) : kk;
;     const int hd = RAD >> (k + 1);
; #pragma unroll
;     for (int j = 0; j < RAD; ++j) {
;       if ((j & hd) == 0) {
;         const int m = (j & (hd - 1)) * (16 / hd);
;         const float2 c = make_float2(TC[m], INV ? TS[m] : -TS[m]);
;         const float2 twf = cmul(tbs[k], c);
;         const c32 tw = {twf.x, twf.y};
;         const c32 a = v[j], b = v[j + hd];
;         if (!INV) { v[j] = a + b; v[j + hd] = cmul_pk(a - b, tw); }
;         else { const c32 bt = cmul_pk(b, tw); v[j] = a + bt; v[j + hd] = a - bt; }
;       }
;     }
;   }
	v_pk_add_f32 v[104:105], v[104:105], v[112:113] neg_lo:[0,1] neg_hi:[0,1]
	v_pk_mul_f32 v[112:113], v[118:119], v[28:29] op_sel:[0,0] op_sel_hi:[0,1]
	s_nop 0
	v_pk_fma_f32 v[112:113], v[118:119], v[28:29], v[112:113] op_sel:[1,1,0] op_sel_hi:[1,0,1] neg_lo:[0,1,0]
	s_nop 0
	v_pk_add_f32 v[118:119], v[102:103], v[112:113]
	v_pk_add_f32 v[102:103], v[102:103], v[112:113] neg_lo:[0,1] neg_hi:[0,1]
	v_pk_mul_f32 v[112:113], v[98:99], v[16:17] op_sel:[0,0] op_sel_hi:[0,1]
	s_nop 0
	v_pk_fma_f32 v[98:99], v[98:99], v[16:17], v[112:113] op_sel:[1,1,0] op_sel_hi:[1,0,1] neg_lo:[0,1,0]
	s_nop 0
	v_pk_add_f32 v[112:113], v[82:83], v[98:99]
	v_pk_add_f32 v[82:83], v[82:83], v[98:99] neg_lo:[0,1] neg_hi:[0,1]
	v_pk_mul_f32 v[98:99], v[116:117], v[26:27] op_sel:[0,0] op_sel_hi:[0,1]
	s_nop 0
	v_pk_fma_f32 v[98:99], v[116:117], v[26:27], v[98:99] op_sel:[1,1,0] op_sel_hi:[1,0,1] neg_lo:[0,1,0]
	s_nop 0
	v_pk_add_f32 v[116:117], v[100:101], v[98:99]
	v_pk_add_f32 v[98:99], v[100:101], v[98:99] neg_lo:[0,1] neg_hi:[0,1]
	v_pk_mul_f32 v[100:101], v[106:107], v[20:21] op_sel:[0,0] op_sel_hi:[0,1]
	s_nop 0
	v_pk_fma_f32 v[100:101], v[106:107], v[20:21], v[100:101] op_sel:[1,1,0] op_sel_hi:[1,0,1] neg_lo:[0,1,0]
	s_nop 0
	v_pk_add_f32 v[106:107], v[90:91], v[100:101]
	v_pk_add_f32 v[90:91], v[90:91], v[100:101] neg_lo:[0,1] neg_hi:[0,1]
	v_pk_mul_f32 v[100:101], v[110:111], v[24:25] op_sel:[0,0] op_sel_hi:[0,1]
	s_nop 0
	v_pk_fma_f32 v[100:101], v[110:111], v[24:25], v[100:101] op_sel:[1,1,0] op_sel_hi:[1,0,1] neg_lo:[0,1,0]
	s_nop 0
	v_pk_add_f32 v[110:111], v[94:95], v[100:101]
	v_pk_add_f32 v[94:95], v[94:95], v[100:101] neg_lo:[0,1] neg_hi:[0,1]
	v_pk_mul_f32 v[100:101], v[128:129], v[30:31] op_sel:[0,0] op_sel_hi:[0,1]
	s_nop 0
	v_pk_fma_f32 v[100:101], v[128:129], v[30:31], v[100:101] op_sel:[1,1,0] op_sel_hi:[1,0,1] neg_lo:[0,1,0]
	s_nop 0
	v_pk_add_f32 v[128:129], v[114:115], v[100:101]
	v_pk_add_f32 v[100:101], v[114:115], v[100:101] neg_lo:[0,1] neg_hi:[0,1]
	v_pk_mul_f32 v[114:115], v[124:125], v[56:57] op_sel:[0,0] op_sel_hi:[0,1]
	s_nop 0
	v_pk_fma_f32 v[114:115], v[124:125], v[56:57], v[114:115] op_sel:[1,1,0] op_sel_hi:[1,0,1] neg_lo:[0,1,0]
	s_nop 0
	v_pk_add_f32 v[124:125], v[122:123], v[114:115]
	v_pk_add_f32 v[114:115], v[122:123], v[114:115] neg_lo:[0,1] neg_hi:[0,1]
	v_pk_mul_f32 v[122:123], v[120:121], v[48:49] op_sel:[0,0] op_sel_hi:[0,1]
	s_nop 0
	v_pk_fma_f32 v[120:121], v[120:121], v[48:49], v[122:123] op_sel:[1,1,0] op_sel_hi:[1,0,1] neg_lo:[0,1,0]
	s_nop 0
	v_pk_add_f32 v[122:123], v[126:127], v[120:121]
	v_pk_add_f32 v[120:121], v[126:127], v[120:121] neg_lo:[0,1] neg_hi:[0,1]
	v_pk_mul_f32 v[126:127], v[118:119], v[40:41] op_sel:[0,0] op_sel_hi:[0,1]
	s_nop 0
	v_pk_fma_f32 v[118:119], v[118:119], v[40:41], v[126:127] op_sel:[1,1,0] op_sel_hi:[1,0,1] neg_lo:[0,1,0]
	s_nop 0
	v_pk_add_f32 v[126:127], v[130:131], v[118:119]
	v_pk_add_f32 v[118:119], v[130:131], v[118:119] neg_lo:[0,1] neg_hi:[0,1]
	v_pk_mul_f32 v[130:131], v[112:113], v[36:37] op_sel:[0,0] op_sel_hi:[0,1]
	s_nop 0
	v_pk_fma_f32 v[112:113], v[112:113], v[36:37], v[130:131] op_sel:[1,1,0] op_sel_hi:[1,0,1] neg_lo:[0,1,0]
	s_nop 0
	v_pk_add_f32 v[130:131], v[86:87], v[112:113]
	v_pk_add_f32 v[86:87], v[86:87], v[112:113] neg_lo:[0,1] neg_hi:[0,1]
	v_pk_mul_f32 v[112:113], v[116:117], v[46:47] op_sel:[0,0] op_sel_hi:[0,1]
	s_nop 0
	v_pk_fma_f32 v[112:113], v[116:117], v[46:47], v[112:113] op_sel:[1,1,0] op_sel_hi:[1,0,1] neg_lo:[0,1,0]
	s_nop 0
	v_pk_add_f32 v[116:117], v[84:85], v[112:113]
	v_pk_add_f32 v[84:85], v[84:85], v[112:113] neg_lo:[0,1] neg_hi:[0,1]
	v_pk_mul_f32 v[112:113], v[106:107], v[54:55] op_sel:[0,0] op_sel_hi:[0,1]
	s_nop 0
	v_pk_fma_f32 v[106:107], v[106:107], v[54:55], v[112:113] op_sel:[1,1,0] op_sel_hi:[1,0,1] neg_lo:[0,1,0]
	s_nop 0
	v_pk_add_f32 v[112:113], v[80:81], v[106:107]
	v_pk_add_f32 v[80:81], v[80:81], v[106:107] neg_lo:[0,1] neg_hi:[0,1]
; __device__ __forceinline__ float2 cmul(float2 a, float2 b) { return make_float2(a.x * b.x - a.y * b.y, a.x * b.y + a.y * b.x); }
; template <int R, bool INV>
; __device__ __forceinline__ void butterflies(c32 (&v)[1 << R], float turns0) {
;     ...
;   for (int kk = 0; kk < R; ++kk) {
;     const int k = INV ? (R - 1 - kk) : kk;
;     const int hd = RAD >> (k + 1);
; #pragma unroll
;     for (int j = 0; j < RAD; ++j) {
;       if ((j & hd) == 0) {
;         const int m = (j & (hd - 1)) * (16 / hd);
;         const float2 c = make_float2(TC[m], INV ? TS[m] : -TS[m]);
;         const float2 twf = cmul(tbs[k], c);
;         const c32 tw = {twf.x, twf.y};
;         const c32 a = v[j], b = v[j + hd];
;         if (!INV) { v[j] = a + b; v[j + hd] = cmul_pk(a - b, tw); }
;         else { const c32 bt = cmul_pk(b, tw); v[j] = a + bt; v[j + hd] = a - bt; }
;       }
;     }
;   }
; template <int LOGN, int R, int DLOG, bool INV, int MODE, class F>
; __device__ __forceinline__ void fft_pass(float2* X, const F& f) {
;     ...
;       for (int j = 0; j < RAD; ++j) Xc[(DLOG >= 5) ? pb + j * PSTEP : phys(base + (j << DLOG))] = v[j];
	v_pk_mul_f32 v[106:107], v[110:111], v[62:63] op_sel:[0,0] op_sel_hi:[0,1]
	s_nop 0
	v_pk_fma_f32 v[106:107], v[110:111], v[62:63], v[106:107] op_sel:[1,1,0] op_sel_hi:[1,0,1] neg_lo:[0,1,0]
	s_nop 0
	v_pk_add_f32 v[110:111], v[78:79], v[106:107]
	v_pk_add_f32 v[78:79], v[78:79], v[106:107] neg_lo:[0,1] neg_hi:[0,1]
	v_pk_mul_f32 v[106:107], v[74:75], v[34:35] op_sel:[0,0] op_sel_hi:[0,1]
	s_nop 0
	v_pk_fma_f32 v[74:75], v[74:75], v[34:35], v[106:107] op_sel:[1,1,0] op_sel_hi:[1,0,1] neg_lo:[0,1,0]
	s_nop 0
	v_pk_add_f32 v[106:107], v[96:97], v[74:75]
	v_pk_add_f32 v[74:75], v[96:97], v[74:75] neg_lo:[0,1] neg_hi:[0,1]
	v_pk_mul_f32 v[96:97], v[108:109], v[60:61] op_sel:[0,0] op_sel_hi:[0,1]
	s_nop 0
	v_pk_fma_f32 v[96:97], v[108:109], v[60:61], v[96:97] op_sel:[1,1,0] op_sel_hi:[1,0,1] neg_lo:[0,1,0]
	s_nop 0
	v_pk_add_f32 v[108:109], v[92:93], v[96:97]
	v_pk_add_f32 v[92:93], v[92:93], v[96:97] neg_lo:[0,1] neg_hi:[0,1]
	v_pk_mul_f32 v[96:97], v[104:105], v[52:53] op_sel:[0,0] op_sel_hi:[0,1]
	s_nop 0
	v_pk_fma_f32 v[96:97], v[104:105], v[52:53], v[96:97] op_sel:[1,1,0] op_sel_hi:[1,0,1] neg_lo:[0,1,0]
	s_nop 0
	v_pk_add_f32 v[104:105], v[88:89], v[96:97]
	v_pk_add_f32 v[88:89], v[88:89], v[96:97] neg_lo:[0,1] neg_hi:[0,1]
	v_pk_mul_f32 v[96:97], v[102:103], v[44:45] op_sel:[0,0] op_sel_hi:[0,1]
	s_nop 0
	v_pk_fma_f32 v[96:97], v[102:103], v[44:45], v[96:97] op_sel:[1,1,0] op_sel_hi:[1,0,1] neg_lo:[0,1,0]
	s_nop 0
	v_pk_add_f32 v[102:103], v[72:73], v[96:97]
	v_pk_add_f32 v[72:73], v[72:73], v[96:97] neg_lo:[0,1] neg_hi:[0,1]
	v_pk_mul_f32 v[96:97], v[82:83], v[38:39] op_sel:[0,0] op_sel_hi:[0,1]
	s_nop 0
	v_pk_fma_f32 v[82:83], v[82:83], v[38:39], v[96:97] op_sel:[1,1,0] op_sel_hi:[1,0,1] neg_lo:[0,1,0]
	s_nop 0
	v_pk_add_f32 v[96:97], v[70:71], v[82:83]
	v_pk_add_f32 v[70:71], v[70:71], v[82:83] neg_lo:[0,1] neg_hi:[0,1]
	v_pk_mul_f32 v[82:83], v[98:99], v[42:43] op_sel:[0,0] op_sel_hi:[0,1]
	s_nop 0
	v_pk_fma_f32 v[82:83], v[98:99], v[42:43], v[82:83] op_sel:[1,1,0] op_sel_hi:[1,0,1] neg_lo:[0,1,0]
	s_nop 0
	v_pk_add_f32 v[98:99], v[76:77], v[82:83]
	v_pk_add_f32 v[76:77], v[76:77], v[82:83] neg_lo:[0,1] neg_hi:[0,1]
	v_pk_mul_f32 v[82:83], v[90:91], v[50:51] op_sel:[0,0] op_sel_hi:[0,1]
	s_nop 0
	v_pk_fma_f32 v[82:83], v[90:91], v[50:51], v[82:83] op_sel:[1,1,0] op_sel_hi:[1,0,1] neg_lo:[0,1,0]
	s_nop 0
	v_pk_add_f32 v[90:91], v[68:69], v[82:83]
	v_pk_add_f32 v[68:69], v[68:69], v[82:83] neg_lo:[0,1] neg_hi:[0,1]
	v_pk_mul_f32 v[82:83], v[94:95], v[58:59] op_sel:[0,0] op_sel_hi:[0,1]
	s_nop 0
	v_pk_fma_f32 v[82:83], v[94:95], v[58:59], v[82:83] op_sel:[1,1,0] op_sel_hi:[1,0,1] neg_lo:[0,1,0]
	s_nop 0
	v_pk_add_f32 v[94:95], v[66:67], v[82:83]
	v_pk_add_f32 v[66:67], v[66:67], v[82:83] neg_lo:[0,1] neg_hi:[0,1]
	ds_write2_b64 v132, v[128:129], v[124:125] offset1:33
	ds_write2_b64 v132, v[122:123], v[126:127] offset0:66 offset1:99
	ds_write2_b64 v132, v[130:131], v[116:117] offset0:132 offset1:165
	ds_write2_b64 v132, v[112:113], v[110:111] offset0:198 offset1:231
	ds_write2_b64 v133, v[106:107], v[108:109] offset0:8 offset1:41
	ds_write2_b64 v133, v[104:105], v[102:103] offset0:74 offset1:107
	ds_write2_b64 v133, v[96:97], v[98:99] offset0:140 offset1:173
	ds_write2_b64 v133, v[90:91], v[94:95] offset0:206 offset1:239
	ds_write2_b64 v134, v[100:101], v[114:115] offset0:16 offset1:49
	ds_write2_b64 v134, v[120:121], v[118:119] offset0:82 offset1:115
	ds_write2_b64 v134, v[86:87], v[84:85] offset0:148 offset1:181
	ds_write2_b64 v134, v[80:81], v[78:79] offset0:214 offset1:247
	ds_write2_b64 v135, v[74:75], v[92:93] offset0:24 offset1:57
	ds_write2_b64 v135, v[88:89], v[72:73] offset0:90 offset1:123
	ds_write2_b64 v135, v[70:71], v[76:77] offset0:156 offset1:189
	ds_write2_b64 v135, v[68:69], v[66:67] offset0:222 offset1:255
	s_andn2_b64 exec, exec, s[24:25]
	s_cbranch_execnz .LBB0_734

; __device__ __forceinline__ float2 cmul(float2 a, float2 b) { return make_float2(a.x * b.x - a.y * b.y, a.x * b.y + a.y * b.x); }
; template <int R, bool INV>
; __device__ __forceinline__ void butterflies(c32 (&v)[1 << R], float turns0) {
;     ...
;   for (int kk = 0; kk < R; ++kk) {
;     const int k = INV ? (R - 1 - kk) : kk;
;     const int hd = RAD >> (k + 1);
; #pragma unroll
;     for (int j = 0; j < RAD; ++j) {
;       if ((j & hd) == 0) {
;         const int m = (j & (hd - 1)) * (16 / hd);
;         const float2 c = make_float2(TC[m], INV ? TS[m] : -TS[m]);
;         const float2 twf = cmul(tbs[k], c);
;         const c32 tw = {twf.x, twf.y};
;         const c32 a = v[j], b = v[j + hd];
;         if (!INV) { v[j] = a + b; v[j + hd] = cmul_pk(a - b, tw); }
;         else { const c32 bt = cmul_pk(b, tw); v[j] = a + bt; v[j + hd] = a - bt; }
;       }
;     }
;   }
; template <int LOGN, int R, int DLOG, bool INV, int MODE, class F>
; __device__ __forceinline__ void fft_pass(float2* X, const F& f) {
;     ...
;   for (int g = tid0; g < NGR; g += 512) {
;     const int lo = g & (dmin - 1), base = gbase(g), pb = phys(base);
;     c32 v[RAD];
;     if constexpr (MODE == 1) {
; #pragma unroll
;       for (int j = 0; j < RAD; ++j) v[j] = nxt[j];
;       if (g + 512 < NGR) fetch(g + 512, nxt);
;     } else {
; #pragma unroll
;       for (int j = 0; j < RAD; ++j) v[j] = Xc[(DLOG >= 5) ? pb + j * PSTEP : phys(base + (j << DLOG))];
;     }
;     butterflies<R, INV>(v, (float)lo / (float)(RAD << DLOG));
.LBB0_1022:
	v_and_b32_e32 v66, 0xfffffc00, v65
	v_ashrrev_i32_e32 v67, 2, v66
	v_add_u32_e32 v67, 0, v67
	v_lshlrev_b32_e32 v66, 3, v66
	v_lshlrev_b32_e32 v68, 3, v32
	v_add3_u32 v132, v67, v66, v68
	v_add_u32_e32 v133, 0x800, v132
	v_add_u32_e32 v134, 0x1000, v132
	ds_read_b64 v[66:67], v132
	ds_read_b64 v[68:69], v132 offset:264
	ds_read_b64 v[70:71], v132 offset:528
	ds_read_b64 v[72:73], v132 offset:792
	ds_read_b64 v[74:75], v132 offset:1056
	ds_read_b64 v[76:77], v132 offset:1320
	ds_read_b64 v[78:79], v132 offset:1584
	ds_read_b64 v[80:81], v132 offset:1848
	ds_read_b64 v[82:83], v133 offset:64
	ds_read_b64 v[84:85], v133 offset:328
	ds_read_b64 v[86:87], v133 offset:592
	ds_read_b64 v[88:89], v133 offset:856
	ds_read_b64 v[90:91], v133 offset:1120
	ds_read_b64 v[92:93], v133 offset:1384
	ds_read_b64 v[94:95], v133 offset:1648
	ds_read_b64 v[96:97], v133 offset:1912
	ds_read_b64 v[98:99], v134 offset:128
	ds_read_b64 v[100:101], v134 offset:392
	ds_read_b64 v[102:103], v134 offset:656
	ds_read_b64 v[104:105], v134 offset:920
	ds_read_b64 v[106:107], v134 offset:1184
	ds_read_b64 v[108:109], v134 offset:1448
	ds_read_b64 v[110:111], v134 offset:1712
	ds_read_b64 v[112:113], v134 offset:1976
	v_add_u32_e32 v135, 0x1800, v132
	s_waitcnt lgkmcnt(6)
	v_pk_add_f32 v[130:131], v[66:67], v[98:99]
	v_pk_add_f32 v[66:67], v[66:67], v[98:99] neg_lo:[0,1] neg_hi:[0,1]
	ds_read_b64 v[114:115], v135 offset:192
	ds_read_b64 v[116:117], v135 offset:456
	ds_read_b64 v[118:119], v135 offset:720
	ds_read_b64 v[120:121], v135 offset:984
	ds_read_b64 v[122:123], v135 offset:1248
	ds_read_b64 v[124:125], v135 offset:1512
	ds_read_b64 v[126:127], v135 offset:1776
	ds_read_b64 v[128:129], v135 offset:2040
	v_pk_mul_f32 v[98:99], v[66:67], v[0:1] op_sel:[0,0] op_sel_hi:[0,1]
	v_add_u32_e32 v64, 0x200, v64
	v_pk_fma_f32 v[66:67], v[66:67], v[0:1], v[98:99] op_sel:[1,1,0] op_sel_hi:[1,0,1] neg_lo:[0,1,0]
	v_pk_add_f32 v[98:99], v[68:69], v[100:101]
	v_pk_add_f32 v[68:69], v[68:69], v[100:101] neg_lo:[0,1] neg_hi:[0,1]
	v_cmp_lt_i32_e32 vcc, -1, v64
	v_pk_mul_f32 v[100:101], v[68:69], v[24:25] op_sel:[0,0] op_sel_hi:[0,1]
	v_add_u32_e32 v65, 0x4000, v65
	v_pk_fma_f32 v[68:69], v[68:69], v[24:25], v[100:101] op_sel:[1,1,0] op_sel_hi:[1,0,1] neg_lo:[0,1,0]
	s_waitcnt lgkmcnt(12)
	v_pk_add_f32 v[100:101], v[70:71], v[102:103]
	v_pk_add_f32 v[70:71], v[70:71], v[102:103] neg_lo:[0,1] neg_hi:[0,1]
	s_or_b64 s[14:15], vcc, s[14:15]
	v_pk_mul_f32 v[102:103], v[70:71], v[16:17] op_sel:[0,0] op_sel_hi:[0,1]
	s_nop 0
	v_pk_fma_f32 v[70:71], v[70:71], v[16:17], v[102:103] op_sel:[1,1,0] op_sel_hi:[1,0,1] neg_lo:[0,1,0]
	v_pk_add_f32 v[102:103], v[72:73], v[104:105]
	v_pk_add_f32 v[72:73], v[72:73], v[104:105] neg_lo:[0,1] neg_hi:[0,1]
	s_nop 0
	v_pk_mul_f32 v[104:105], v[72:73], v[8:9] op_sel:[0,0] op_sel_hi:[0,1]
	s_nop 0
	v_pk_fma_f32 v[72:73], v[72:73], v[8:9], v[104:105] op_sel:[1,1,0] op_sel_hi:[1,0,1] neg_lo:[0,1,0]
	s_waitcnt lgkmcnt(10)
	v_pk_add_f32 v[104:105], v[74:75], v[106:107]
	v_pk_add_f32 v[74:75], v[74:75], v[106:107] neg_lo:[0,1] neg_hi:[0,1]
	s_nop 0
	v_pk_mul_f32 v[106:107], v[74:75], v[4:5] op_sel:[0,0] op_sel_hi:[0,1]
	s_nop 0
	v_pk_fma_f32 v[74:75], v[74:75], v[4:5], v[106:107] op_sel:[1,1,0] op_sel_hi:[1,0,1] neg_lo:[0,1,0]
	v_pk_add_f32 v[106:107], v[76:77], v[108:109]
	v_pk_add_f32 v[76:77], v[76:77], v[108:109] neg_lo:[0,1] neg_hi:[0,1]
	s_nop 0
	v_pk_mul_f32 v[108:109], v[76:77], v[14:15] op_sel:[0,0] op_sel_hi:[0,1]
	s_nop 0
	v_pk_fma_f32 v[76:77], v[76:77], v[14:15], v[108:109] op_sel:[1,1,0] op_sel_hi:[1,0,1] neg_lo:[0,1,0]
	s_waitcnt lgkmcnt(8)
	v_pk_add_f32 v[108:109], v[78:79], v[110:111]
	v_pk_add_f32 v[78:79], v[78:79], v[110:111] neg_lo:[0,1] neg_hi:[0,1]
	s_nop 0
	v_pk_mul_f32 v[110:111], v[78:79], v[22:23] op_sel:[0,0] op_sel_hi:[0,1]
	s_nop 0
	v_pk_fma_f32 v[78:79], v[78:79], v[22:23], v[110:111] op_sel:[1,1,0] op_sel_hi:[1,0,1] neg_lo:[0,1,0]
	v_pk_add_f32 v[110:111], v[80:81], v[112:113]
	v_pk_add_f32 v[80:81], v[80:81], v[112:113] neg_lo:[0,1] neg_hi:[0,1]
	s_nop 0
	v_pk_mul_f32 v[112:113], v[80:81], v[30:31] op_sel:[0,0] op_sel_hi:[0,1]
	s_nop 0
	v_pk_fma_f32 v[80:81], v[80:81], v[30:31], v[112:113] op_sel:[1,1,0] op_sel_hi:[1,0,1] neg_lo:[0,1,0]
	s_waitcnt lgkmcnt(6)
	v_pk_add_f32 v[112:113], v[82:83], v[114:115]
	v_pk_add_f32 v[82:83], v[82:83], v[114:115] neg_lo:[0,1] neg_hi:[0,1]
	s_nop 0
	v_pk_mul_f32 v[114:115], v[82:83], v[2:3] op_sel:[0,0] op_sel_hi:[0,1]
	s_nop 0
	v_pk_fma_f32 v[82:83], v[82:83], v[2:3], v[114:115] op_sel:[1,1,0] op_sel_hi:[1,0,1] neg_lo:[0,1,0]
	v_pk_add_f32 v[114:115], v[84:85], v[116:117]
	v_pk_add_f32 v[84:85], v[84:85], v[116:117] neg_lo:[0,1] neg_hi:[0,1]
	s_nop 0
	v_pk_mul_f32 v[116:117], v[84:85], v[28:29] op_sel:[0,0] op_sel_hi:[0,1]
	s_nop 0
	v_pk_fma_f32 v[84:85], v[84:85], v[28:29], v[116:117] op_sel:[1,1,0] op_sel_hi:[1,0,1] neg_lo:[0,1,0]
	s_waitcnt lgkmcnt(4)
	v_pk_add_f32 v[116:117], v[86:87], v[118:119]
	v_pk_add_f32 v[86:87], v[86:87], v[118:119] neg_lo:[0,1] neg_hi:[0,1]
	s_nop 0
	v_pk_mul_f32 v[118:119], v[86:87], v[20:21] op_sel:[0,0] op_sel_hi:[0,1]
	s_nop 0
	v_pk_fma_f32 v[86:87], v[86:87], v[20:21], v[118:119] op_sel:[1,1,0] op_sel_hi:[1,0,1] neg_lo:[0,1,0]
	v_pk_add_f32 v[118:119], v[88:89], v[120:121]
	v_pk_add_f32 v[88:89], v[88:89], v[120:121] neg_lo:[0,1] neg_hi:[0,1]
	s_nop 0
	v_pk_mul_f32 v[120:121], v[88:89], v[12:13] op_sel:[0,0] op_sel_hi:[0,1]
	s_nop 0
	v_pk_fma_f32 v[88:89], v[88:89], v[12:13], v[120:121] op_sel:[1,1,0] op_sel_hi:[1,0,1] neg_lo:[0,1,0]
	s_waitcnt lgkmcnt(2)
; __device__ __forceinline__ float2 cmul(float2 a, float2 b) { return make_float2(a.x * b.x - a.y * b.y, a.x * b.y + a.y * b.x); }
; __device__ __forceinline__ c32 cmul_pk(c32 a, c32 b) {
;   c32 t, r;
;   asm("v_pk_mul_f32 %0, %1, %2 op_sel:[0,0] op_sel_hi:[0,1]" : "=v"(t) : "v"(a), "v"(b));
;   asm("v_pk_fma_f32 %0, %1, %2, %3 op_sel:[1,1,0] op_sel_hi:[1,0,1] neg_lo:[0,1,0]" : "=v"(r) : "v"(a), "v"(b), "v"(t));
;   return r;
; }
; template <int R, bool INV>
; __device__ __forceinline__ void butterflies(c32 (&v)[1 << R], float turns0) {
;     ...
;   for (int kk = 0; kk < R; ++kk) {
;     const int k = INV ? (R - 1 - kk) : kk;
;     const int hd = RAD >> (k + 1);
; #pragma unroll
;     for (int j = 0; j < RAD; ++j) {
;       if ((j & hd) == 0) {
;         const int m = (j & (hd - 1)) * (16 / hd);
;         const float2 c = make_float2(TC[m], INV ? TS[m] : -TS[m]);
;         const float2 twf = cmul(tbs[k], c);
;         const c32 tw = {twf.x, twf.y};
;         const c32 a = v[j], b = v[j + hd];
;         if (!INV) { v[j] = a + b; v[j + hd] = cmul_pk(a - b, tw); }
;         else { const c32 bt = cmul_pk(b, tw); v[j] = a + bt; v[j + hd] = a - bt; }
;       }
;     }
;   }
	v_pk_add_f32 v[120:121], v[90:91], v[122:123]
	v_pk_add_f32 v[90:91], v[90:91], v[122:123] neg_lo:[0,1] neg_hi:[0,1]
	s_nop 0
	v_pk_mul_f32 v[122:123], v[90:91], v[6:7] op_sel:[0,0] op_sel_hi:[0,1]
	s_nop 0
	v_pk_fma_f32 v[90:91], v[90:91], v[6:7], v[122:123] op_sel:[1,1,0] op_sel_hi:[1,0,1] neg_lo:[0,1,0]
	v_pk_add_f32 v[122:123], v[92:93], v[124:125]
	v_pk_add_f32 v[92:93], v[92:93], v[124:125] neg_lo:[0,1] neg_hi:[0,1]
	s_nop 0
	v_pk_mul_f32 v[124:125], v[92:93], v[10:11] op_sel:[0,0] op_sel_hi:[0,1]
	s_nop 0
	v_pk_fma_f32 v[92:93], v[92:93], v[10:11], v[124:125] op_sel:[1,1,0] op_sel_hi:[1,0,1] neg_lo:[0,1,0]
	s_waitcnt lgkmcnt(0)
	v_pk_add_f32 v[124:125], v[94:95], v[126:127]
	v_pk_add_f32 v[94:95], v[94:95], v[126:127] neg_lo:[0,1] neg_hi:[0,1]
	s_nop 0
	v_pk_mul_f32 v[126:127], v[94:95], v[18:19] op_sel:[0,0] op_sel_hi:[0,1]
	s_nop 0
	v_pk_fma_f32 v[94:95], v[94:95], v[18:19], v[126:127] op_sel:[1,1,0] op_sel_hi:[1,0,1] neg_lo:[0,1,0]
	v_pk_add_f32 v[126:127], v[96:97], v[128:129]
	v_pk_add_f32 v[96:97], v[96:97], v[128:129] neg_lo:[0,1] neg_hi:[0,1]
	s_nop 0
	v_pk_mul_f32 v[128:129], v[96:97], v[26:27] op_sel:[0,0] op_sel_hi:[0,1]
	s_nop 0
	v_pk_fma_f32 v[96:97], v[96:97], v[26:27], v[128:129] op_sel:[1,1,0] op_sel_hi:[1,0,1] neg_lo:[0,1,0]
	v_pk_add_f32 v[128:129], v[130:131], v[112:113]
	v_pk_add_f32 v[112:113], v[130:131], v[112:113] neg_lo:[0,1] neg_hi:[0,1]
	s_nop 0
	v_pk_mul_f32 v[130:131], v[112:113], v[34:35] op_sel:[0,0] op_sel_hi:[0,1]
	s_nop 0
	v_pk_fma_f32 v[112:113], v[112:113], v[34:35], v[130:131] op_sel:[1,1,0] op_sel_hi:[1,0,1] neg_lo:[0,1,0]
	v_pk_add_f32 v[130:131], v[98:99], v[114:115]
	v_pk_add_f32 v[98:99], v[98:99], v[114:115] neg_lo:[0,1] neg_hi:[0,1]
	s_nop 0
	v_pk_mul_f32 v[114:115], v[98:99], v[42:43] op_sel:[0,0] op_sel_hi:[0,1]
	s_nop 0
	v_pk_fma_f32 v[98:99], v[98:99], v[42:43], v[114:115] op_sel:[1,1,0] op_sel_hi:[1,0,1] neg_lo:[0,1,0]
	v_pk_add_f32 v[114:115], v[100:101], v[116:117]
	v_pk_add_f32 v[100:101], v[100:101], v[116:117] neg_lo:[0,1] neg_hi:[0,1]
	s_nop 0
	v_pk_mul_f32 v[116:117], v[100:101], v[38:39] op_sel:[0,0] op_sel_hi:[0,1]
	s_nop 0
	v_pk_fma_f32 v[100:101], v[100:101], v[38:39], v[116:117] op_sel:[1,1,0] op_sel_hi:[1,0,1] neg_lo:[0,1,0]
	v_pk_add_f32 v[116:117], v[102:103], v[118:119]
	v_pk_add_f32 v[102:103], v[102:103], v[118:119] neg_lo:[0,1] neg_hi:[0,1]
	s_nop 0
	v_pk_mul_f32 v[118:119], v[102:103], v[48:49] op_sel:[0,0] op_sel_hi:[0,1]
	s_nop 0
	v_pk_fma_f32 v[102:103], v[102:103], v[48:49], v[118:119] op_sel:[1,1,0] op_sel_hi:[1,0,1] neg_lo:[0,1,0]
	v_pk_add_f32 v[118:119], v[104:105], v[120:121]
	v_pk_add_f32 v[104:105], v[104:105], v[120:121] neg_lo:[0,1] neg_hi:[0,1]
	s_nop 0
	v_pk_mul_f32 v[120:121], v[104:105], v[36:37] op_sel:[0,0] op_sel_hi:[0,1]
	s_nop 0
	v_pk_fma_f32 v[104:105], v[104:105], v[36:37], v[120:121] op_sel:[1,1,0] op_sel_hi:[1,0,1] neg_lo:[0,1,0]
	v_pk_add_f32 v[120:121], v[106:107], v[122:123]
	v_pk_add_f32 v[106:107], v[106:107], v[122:123] neg_lo:[0,1] neg_hi:[0,1]
	s_nop 0
	v_pk_mul_f32 v[122:123], v[106:107], v[46:47] op_sel:[0,0] op_sel_hi:[0,1]
	s_nop 0
	v_pk_fma_f32 v[106:107], v[106:107], v[46:47], v[122:123] op_sel:[1,1,0] op_sel_hi:[1,0,1] neg_lo:[0,1,0]
	v_pk_add_f32 v[122:123], v[108:109], v[124:125]
	v_pk_add_f32 v[108:109], v[108:109], v[124:125] neg_lo:[0,1] neg_hi:[0,1]
	s_nop 0
	v_pk_mul_f32 v[124:125], v[108:109], v[40:41] op_sel:[0,0] op_sel_hi:[0,1]
	s_nop 0
	v_pk_fma_f32 v[108:109], v[108:109], v[40:41], v[124:125] op_sel:[1,1,0] op_sel_hi:[1,0,1] neg_lo:[0,1,0]
	v_pk_add_f32 v[124:125], v[110:111], v[126:127]
	v_pk_add_f32 v[110:111], v[110:111], v[126:127] neg_lo:[0,1] neg_hi:[0,1]
	s_nop 0
	v_pk_mul_f32 v[126:127], v[110:111], v[44:45] op_sel:[0,0] op_sel_hi:[0,1]
	s_nop 0
	v_pk_fma_f32 v[110:111], v[110:111], v[44:45], v[126:127] op_sel:[1,1,0] op_sel_hi:[1,0,1] neg_lo:[0,1,0]
	v_pk_add_f32 v[126:127], v[66:67], v[82:83]
	v_pk_add_f32 v[66:67], v[66:67], v[82:83] neg_lo:[0,1] neg_hi:[0,1]
	s_nop 0
	v_pk_mul_f32 v[82:83], v[66:67], v[34:35] op_sel:[0,0] op_sel_hi:[0,1]
	s_nop 0
	v_pk_fma_f32 v[66:67], v[66:67], v[34:35], v[82:83] op_sel:[1,1,0] op_sel_hi:[1,0,1] neg_lo:[0,1,0]
	v_pk_add_f32 v[82:83], v[68:69], v[84:85]
	v_pk_add_f32 v[68:69], v[68:69], v[84:85] neg_lo:[0,1] neg_hi:[0,1]
	s_nop 0
	v_pk_mul_f32 v[84:85], v[68:69], v[42:43] op_sel:[0,0] op_sel_hi:[0,1]
	s_nop 0
	v_pk_fma_f32 v[68:69], v[68:69], v[42:43], v[84:85] op_sel:[1,1,0] op_sel_hi:[1,0,1] neg_lo:[0,1,0]
	v_pk_add_f32 v[84:85], v[70:71], v[86:87]
	v_pk_add_f32 v[70:71], v[70:71], v[86:87] neg_lo:[0,1] neg_hi:[0,1]
	s_nop 0
	v_pk_mul_f32 v[86:87], v[70:71], v[38:39] op_sel:[0,0] op_sel_hi:[0,1]
	s_nop 0
	v_pk_fma_f32 v[70:71], v[70:71], v[38:39], v[86:87] op_sel:[1,1,0] op_sel_hi:[1,0,1] neg_lo:[0,1,0]
	v_pk_add_f32 v[86:87], v[72:73], v[88:89]
	v_pk_add_f32 v[72:73], v[72:73], v[88:89] neg_lo:[0,1] neg_hi:[0,1]
	s_nop 0
	v_pk_mul_f32 v[88:89], v[72:73], v[48:49] op_sel:[0,0] op_sel_hi:[0,1]
	s_nop 0
	v_pk_fma_f32 v[72:73], v[72:73], v[48:49], v[88:89] op_sel:[1,1,0] op_sel_hi:[1,0,1] neg_lo:[0,1,0]
	v_pk_add_f32 v[88:89], v[74:75], v[90:91]
	v_pk_add_f32 v[74:75], v[74:75], v[90:91] neg_lo:[0,1] neg_hi:[0,1]
	s_nop 0
	v_pk_mul_f32 v[90:91], v[74:75], v[36:37] op_sel:[0,0] op_sel_hi:[0,1]
	s_nop 0
	v_pk_fma_f32 v[74:75], v[74:75], v[36:37], v[90:91] op_sel:[1,1,0] op_sel_hi:[1,0,1] neg_lo:[0,1,0]
	v_pk_add_f32 v[90:91], v[76:77], v[92:93]
	v_pk_add_f32 v[76:77], v[76:77], v[92:93] neg_lo:[0,1] neg_hi:[0,1]
	s_nop 0
	v_pk_mul_f32 v[92:93], v[76:77], v[46:47] op_sel:[0,0] op_sel_hi:[0,1]
	s_nop 0
	v_pk_fma_f32 v[76:77], v[76:77], v[46:47], v[92:93] op_sel:[1,1,0] op_sel_hi:[1,0,1] neg_lo:[0,1,0]
; __device__ __forceinline__ float2 cmul(float2 a, float2 b) { return make_float2(a.x * b.x - a.y * b.y, a.x * b.y + a.y * b.x); }
; __device__ __forceinline__ c32 cmul_pk(c32 a, c32 b) {
;   c32 t, r;
;   asm("v_pk_mul_f32 %0, %1, %2 op_sel:[0,0] op_sel_hi:[0,1]" : "=v"(t) : "v"(a), "v"(b));
;   asm("v_pk_fma_f32 %0, %1, %2, %3 op_sel:[1,1,0] op_sel_hi:[1,0,1] neg_lo:[0,1,0]" : "=v"(r) : "v"(a), "v"(b), "v"(t));
;   return r;
; }
; template <int R, bool INV>
; __device__ __forceinline__ void butterflies(c32 (&v)[1 << R], float turns0) {
;     ...
;   for (int kk = 0; kk < R; ++kk) {
;     const int k = INV ? (R - 1 - kk) : kk;
;     const int hd = RAD >> (k + 1);
; #pragma unroll
;     for (int j = 0; j < RAD; ++j) {
;       if ((j & hd) == 0) {
;         const int m = (j & (hd - 1)) * (16 / hd);
;         const float2 c = make_float2(TC[m], INV ? TS[m] : -TS[m]);
;         const float2 twf = cmul(tbs[k], c);
;         const c32 tw = {twf.x, twf.y};
;         const c32 a = v[j], b = v[j + hd];
;         if (!INV) { v[j] = a + b; v[j + hd] = cmul_pk(a - b, tw); }
;         else { const c32 bt = cmul_pk(b, tw); v[j] = a + bt; v[j + hd] = a - bt; }
;       }
;     }
;   }
	v_pk_add_f32 v[92:93], v[78:79], v[94:95]
	v_pk_add_f32 v[78:79], v[78:79], v[94:95] neg_lo:[0,1] neg_hi:[0,1]
	s_nop 0
	v_pk_mul_f32 v[94:95], v[78:79], v[40:41] op_sel:[0,0] op_sel_hi:[0,1]
	s_nop 0
	v_pk_fma_f32 v[78:79], v[78:79], v[40:41], v[94:95] op_sel:[1,1,0] op_sel_hi:[1,0,1] neg_lo:[0,1,0]
	v_pk_add_f32 v[94:95], v[80:81], v[96:97]
	v_pk_add_f32 v[80:81], v[80:81], v[96:97] neg_lo:[0,1] neg_hi:[0,1]
	s_nop 0
	v_pk_mul_f32 v[96:97], v[80:81], v[44:45] op_sel:[0,0] op_sel_hi:[0,1]
	s_nop 0
	v_pk_fma_f32 v[80:81], v[80:81], v[44:45], v[96:97] op_sel:[1,1,0] op_sel_hi:[1,0,1] neg_lo:[0,1,0]
	v_pk_add_f32 v[96:97], v[128:129], v[118:119]
	v_pk_add_f32 v[118:119], v[128:129], v[118:119] neg_lo:[0,1] neg_hi:[0,1]
	s_nop 0
	v_pk_mul_f32 v[128:129], v[118:119], v[50:51] op_sel:[0,0] op_sel_hi:[0,1]
	s_nop 0
	v_pk_fma_f32 v[118:119], v[118:119], v[50:51], v[128:129] op_sel:[1,1,0] op_sel_hi:[1,0,1] neg_lo:[0,1,0]
	v_pk_add_f32 v[128:129], v[130:131], v[120:121]
	v_pk_add_f32 v[120:121], v[130:131], v[120:121] neg_lo:[0,1] neg_hi:[0,1]
	s_nop 0
	v_pk_mul_f32 v[130:131], v[120:121], v[54:55] op_sel:[0,0] op_sel_hi:[0,1]
	s_nop 0
	v_pk_fma_f32 v[120:121], v[120:121], v[54:55], v[130:131] op_sel:[1,1,0] op_sel_hi:[1,0,1] neg_lo:[0,1,0]
	v_pk_add_f32 v[130:131], v[114:115], v[122:123]
	v_pk_add_f32 v[114:115], v[114:115], v[122:123] neg_lo:[0,1] neg_hi:[0,1]
	s_nop 0
	v_pk_mul_f32 v[122:123], v[114:115], v[52:53] op_sel:[0,0] op_sel_hi:[0,1]
	s_nop 0
	v_pk_fma_f32 v[114:115], v[114:115], v[52:53], v[122:123] op_sel:[1,1,0] op_sel_hi:[1,0,1] neg_lo:[0,1,0]
	v_pk_add_f32 v[122:123], v[116:117], v[124:125]
	v_pk_add_f32 v[116:117], v[116:117], v[124:125] neg_lo:[0,1] neg_hi:[0,1]
	s_nop 0
	v_pk_mul_f32 v[124:125], v[116:117], v[56:57] op_sel:[0,0] op_sel_hi:[0,1]
	s_nop 0
	v_pk_fma_f32 v[116:117], v[116:117], v[56:57], v[124:125] op_sel:[1,1,0] op_sel_hi:[1,0,1] neg_lo:[0,1,0]
	v_pk_add_f32 v[124:125], v[112:113], v[104:105]
	v_pk_add_f32 v[104:105], v[112:113], v[104:105] neg_lo:[0,1] neg_hi:[0,1]
	s_nop 0
	v_pk_mul_f32 v[112:113], v[104:105], v[50:51] op_sel:[0,0] op_sel_hi:[0,1]
	s_nop 0
	v_pk_fma_f32 v[104:105], v[104:105], v[50:51], v[112:113] op_sel:[1,1,0] op_sel_hi:[1,0,1] neg_lo:[0,1,0]
	v_pk_add_f32 v[112:113], v[98:99], v[106:107]
	v_pk_add_f32 v[98:99], v[98:99], v[106:107] neg_lo:[0,1] neg_hi:[0,1]
	s_nop 0
	v_pk_mul_f32 v[106:107], v[98:99], v[54:55] op_sel:[0,0] op_sel_hi:[0,1]
	s_nop 0
	v_pk_fma_f32 v[98:99], v[98:99], v[54:55], v[106:107] op_sel:[1,1,0] op_sel_hi:[1,0,1] neg_lo:[0,1,0]
	v_pk_add_f32 v[106:107], v[100:101], v[108:109]
	v_pk_add_f32 v[100:101], v[100:101], v[108:109] neg_lo:[0,1] neg_hi:[0,1]
	s_nop 0
	v_pk_mul_f32 v[108:109], v[100:101], v[52:53] op_sel:[0,0] op_sel_hi:[0,1]
	s_nop 0
	v_pk_fma_f32 v[100:101], v[100:101], v[52:53], v[108:109] op_sel:[1,1,0] op_sel_hi:[1,0,1] neg_lo:[0,1,0]
	v_pk_add_f32 v[108:109], v[102:103], v[110:111]
	v_pk_add_f32 v[102:103], v[102:103], v[110:111] neg_lo:[0,1] neg_hi:[0,1]
	s_nop 0
	v_pk_mul_f32 v[110:111], v[102:103], v[56:57] op_sel:[0,0] op_sel_hi:[0,1]
	s_nop 0
	v_pk_fma_f32 v[102:103], v[102:103], v[56:57], v[110:111] op_sel:[1,1,0] op_sel_hi:[1,0,1] neg_lo:[0,1,0]
	v_pk_add_f32 v[110:111], v[126:127], v[88:89]
	v_pk_add_f32 v[88:89], v[126:127], v[88:89] neg_lo:[0,1] neg_hi:[0,1]
	s_nop 0
	v_pk_mul_f32 v[126:127], v[88:89], v[50:51] op_sel:[0,0] op_sel_hi:[0,1]
	s_nop 0
	v_pk_fma_f32 v[88:89], v[88:89], v[50:51], v[126:127] op_sel:[1,1,0] op_sel_hi:[1,0,1] neg_lo:[0,1,0]
	v_pk_add_f32 v[126:127], v[82:83], v[90:91]
	v_pk_add_f32 v[82:83], v[82:83], v[90:91] neg_lo:[0,1] neg_hi:[0,1]
	s_nop 0
	v_pk_mul_f32 v[90:91], v[82:83], v[54:55] op_sel:[0,0] op_sel_hi:[0,1]
	s_nop 0
	v_pk_fma_f32 v[82:83], v[82:83], v[54:55], v[90:91] op_sel:[1,1,0] op_sel_hi:[1,0,1] neg_lo:[0,1,0]
	v_pk_add_f32 v[90:91], v[84:85], v[92:93]
	v_pk_add_f32 v[84:85], v[84:85], v[92:93] neg_lo:[0,1] neg_hi:[0,1]
	s_nop 0
	v_pk_mul_f32 v[92:93], v[84:85], v[52:53] op_sel:[0,0] op_sel_hi:[0,1]
	s_nop 0
	v_pk_fma_f32 v[84:85], v[84:85], v[52:53], v[92:93] op_sel:[1,1,0] op_sel_hi:[1,0,1] neg_lo:[0,1,0]
	v_pk_add_f32 v[92:93], v[86:87], v[94:95]
	v_pk_add_f32 v[86:87], v[86:87], v[94:95] neg_lo:[0,1] neg_hi:[0,1]
	s_nop 0
	v_pk_mul_f32 v[94:95], v[86:87], v[56:57] op_sel:[0,0] op_sel_hi:[0,1]
	s_nop 0
	v_pk_fma_f32 v[86:87], v[86:87], v[56:57], v[94:95] op_sel:[1,1,0] op_sel_hi:[1,0,1] neg_lo:[0,1,0]
	v_pk_add_f32 v[94:95], v[66:67], v[74:75]
	v_pk_add_f32 v[66:67], v[66:67], v[74:75] neg_lo:[0,1] neg_hi:[0,1]
	s_nop 0
	v_pk_mul_f32 v[74:75], v[66:67], v[50:51] op_sel:[0,0] op_sel_hi:[0,1]
	s_nop 0
	v_pk_fma_f32 v[66:67], v[66:67], v[50:51], v[74:75] op_sel:[1,1,0] op_sel_hi:[1,0,1] neg_lo:[0,1,0]
	v_pk_add_f32 v[74:75], v[68:69], v[76:77]
	v_pk_add_f32 v[68:69], v[68:69], v[76:77] neg_lo:[0,1] neg_hi:[0,1]
	s_nop 0
	v_pk_mul_f32 v[76:77], v[68:69], v[54:55] op_sel:[0,0] op_sel_hi:[0,1]
	s_nop 0
	v_pk_fma_f32 v[68:69], v[68:69], v[54:55], v[76:77] op_sel:[1,1,0] op_sel_hi:[1,0,1] neg_lo:[0,1,0]
	v_pk_add_f32 v[76:77], v[70:71], v[78:79]
	v_pk_add_f32 v[70:71], v[70:71], v[78:79] neg_lo:[0,1] neg_hi:[0,1]
	s_nop 0
	v_pk_mul_f32 v[78:79], v[70:71], v[52:53] op_sel:[0,0] op_sel_hi:[0,1]
	s_nop 0
	v_pk_fma_f32 v[70:71], v[70:71], v[52:53], v[78:79] op_sel:[1,1,0] op_sel_hi:[1,0,1] neg_lo:[0,1,0]
	v_pk_add_f32 v[78:79], v[72:73], v[80:81]
	v_pk_add_f32 v[72:73], v[72:73], v[80:81] neg_lo:[0,1] neg_hi:[0,1]
	s_nop 0
	v_pk_mul_f32 v[80:81], v[72:73], v[56:57] op_sel:[0,0] op_sel_hi:[0,1]
	s_nop 0
	v_pk_fma_f32 v[72:73], v[72:73], v[56:57], v[80:81] op_sel:[1,1,0] op_sel_hi:[1,0,1] neg_lo:[0,1,0]
; __device__ __forceinline__ float2 cmul(float2 a, float2 b) { return make_float2(a.x * b.x - a.y * b.y, a.x * b.y + a.y * b.x); }
; __device__ __forceinline__ c32 cmul_pk(c32 a, c32 b) {
;   c32 t, r;
;   asm("v_pk_mul_f32 %0, %1, %2 op_sel:[0,0] op_sel_hi:[0,1]" : "=v"(t) : "v"(a), "v"(b));
;   asm("v_pk_fma_f32 %0, %1, %2, %3 op_sel:[1,1,0] op_sel_hi:[1,0,1] neg_lo:[0,1,0]" : "=v"(r) : "v"(a), "v"(b), "v"(t));
;   return r;
; }
; template <int R, bool INV>
; __device__ __forceinline__ void butterflies(c32 (&v)[1 << R], float turns0) {
;     ...
;   for (int kk = 0; kk < R; ++kk) {
;     const int k = INV ? (R - 1 - kk) : kk;
;     const int hd = RAD >> (k + 1);
; #pragma unroll
;     for (int j = 0; j < RAD; ++j) {
;       if ((j & hd) == 0) {
;         const int m = (j & (hd - 1)) * (16 / hd);
;         const float2 c = make_float2(TC[m], INV ? TS[m] : -TS[m]);
;         const float2 twf = cmul(tbs[k], c);
;         const c32 tw = {twf.x, twf.y};
;         const c32 a = v[j], b = v[j + hd];
;         if (!INV) { v[j] = a + b; v[j + hd] = cmul_pk(a - b, tw); }
;         else { const c32 bt = cmul_pk(b, tw); v[j] = a + bt; v[j + hd] = a - bt; }
;       }
;     }
;   }
	v_pk_add_f32 v[80:81], v[96:97], v[130:131]
	v_pk_add_f32 v[96:97], v[96:97], v[130:131] neg_lo:[0,1] neg_hi:[0,1]
	s_nop 0
	v_pk_mul_f32 v[130:131], v[96:97], v[58:59] op_sel:[0,0] op_sel_hi:[0,1]
	s_nop 0
	v_pk_fma_f32 v[96:97], v[96:97], v[58:59], v[130:131] op_sel:[1,1,0] op_sel_hi:[1,0,1] neg_lo:[0,1,0]
	v_pk_add_f32 v[130:131], v[128:129], v[122:123]
	v_pk_add_f32 v[122:123], v[128:129], v[122:123] neg_lo:[0,1] neg_hi:[0,1]
	s_nop 0
	v_pk_mul_f32 v[128:129], v[122:123], v[60:61] op_sel:[0,0] op_sel_hi:[0,1]
	s_nop 0
	v_pk_fma_f32 v[122:123], v[122:123], v[60:61], v[128:129] op_sel:[1,1,0] op_sel_hi:[1,0,1] neg_lo:[0,1,0]
	v_pk_add_f32 v[128:129], v[118:119], v[114:115]
	v_pk_add_f32 v[114:115], v[118:119], v[114:115] neg_lo:[0,1] neg_hi:[0,1]
	s_nop 0
	v_pk_mul_f32 v[118:119], v[114:115], v[58:59] op_sel:[0,0] op_sel_hi:[0,1]
	s_nop 0
	v_pk_fma_f32 v[114:115], v[114:115], v[58:59], v[118:119] op_sel:[1,1,0] op_sel_hi:[1,0,1] neg_lo:[0,1,0]
	v_pk_add_f32 v[118:119], v[120:121], v[116:117]
	v_pk_add_f32 v[116:117], v[120:121], v[116:117] neg_lo:[0,1] neg_hi:[0,1]
	s_nop 0
	v_pk_mul_f32 v[120:121], v[116:117], v[60:61] op_sel:[0,0] op_sel_hi:[0,1]
	s_nop 0
	v_pk_fma_f32 v[116:117], v[116:117], v[60:61], v[120:121] op_sel:[1,1,0] op_sel_hi:[1,0,1] neg_lo:[0,1,0]
	v_pk_add_f32 v[120:121], v[124:125], v[106:107]
	v_pk_add_f32 v[106:107], v[124:125], v[106:107] neg_lo:[0,1] neg_hi:[0,1]
	s_nop 0
	v_pk_mul_f32 v[124:125], v[106:107], v[58:59] op_sel:[0,0] op_sel_hi:[0,1]
	s_nop 0
	v_pk_fma_f32 v[106:107], v[106:107], v[58:59], v[124:125] op_sel:[1,1,0] op_sel_hi:[1,0,1] neg_lo:[0,1,0]
	v_pk_add_f32 v[124:125], v[112:113], v[108:109]
	v_pk_add_f32 v[108:109], v[112:113], v[108:109] neg_lo:[0,1] neg_hi:[0,1]
	s_nop 0
	v_pk_mul_f32 v[112:113], v[108:109], v[60:61] op_sel:[0,0] op_sel_hi:[0,1]
	s_nop 0
	v_pk_fma_f32 v[108:109], v[108:109], v[60:61], v[112:113] op_sel:[1,1,0] op_sel_hi:[1,0,1] neg_lo:[0,1,0]
	v_pk_add_f32 v[112:113], v[104:105], v[100:101]
	v_pk_add_f32 v[100:101], v[104:105], v[100:101] neg_lo:[0,1] neg_hi:[0,1]
	s_nop 0
	v_pk_mul_f32 v[104:105], v[100:101], v[58:59] op_sel:[0,0] op_sel_hi:[0,1]
	s_nop 0
	v_pk_fma_f32 v[100:101], v[100:101], v[58:59], v[104:105] op_sel:[1,1,0] op_sel_hi:[1,0,1] neg_lo:[0,1,0]
	v_pk_add_f32 v[104:105], v[98:99], v[102:103]
	v_pk_add_f32 v[98:99], v[98:99], v[102:103] neg_lo:[0,1] neg_hi:[0,1]
	s_nop 0
	v_pk_mul_f32 v[102:103], v[98:99], v[60:61] op_sel:[0,0] op_sel_hi:[0,1]
	s_nop 0
	v_pk_fma_f32 v[98:99], v[98:99], v[60:61], v[102:103] op_sel:[1,1,0] op_sel_hi:[1,0,1] neg_lo:[0,1,0]
	v_pk_add_f32 v[102:103], v[110:111], v[90:91]
	v_pk_add_f32 v[90:91], v[110:111], v[90:91] neg_lo:[0,1] neg_hi:[0,1]
	s_nop 0
	v_pk_mul_f32 v[110:111], v[90:91], v[58:59] op_sel:[0,0] op_sel_hi:[0,1]
	s_nop 0
	v_pk_fma_f32 v[90:91], v[90:91], v[58:59], v[110:111] op_sel:[1,1,0] op_sel_hi:[1,0,1] neg_lo:[0,1,0]
	v_pk_add_f32 v[110:111], v[126:127], v[92:93]
	v_pk_add_f32 v[92:93], v[126:127], v[92:93] neg_lo:[0,1] neg_hi:[0,1]
	s_nop 0
	v_pk_mul_f32 v[126:127], v[92:93], v[60:61] op_sel:[0,0] op_sel_hi:[0,1]
	s_nop 0
	v_pk_fma_f32 v[92:93], v[92:93], v[60:61], v[126:127] op_sel:[1,1,0] op_sel_hi:[1,0,1] neg_lo:[0,1,0]
	v_pk_add_f32 v[126:127], v[88:89], v[84:85]
	v_pk_add_f32 v[84:85], v[88:89], v[84:85] neg_lo:[0,1] neg_hi:[0,1]
	s_nop 0
	v_pk_mul_f32 v[88:89], v[84:85], v[58:59] op_sel:[0,0] op_sel_hi:[0,1]
	s_nop 0
	v_pk_fma_f32 v[84:85], v[84:85], v[58:59], v[88:89] op_sel:[1,1,0] op_sel_hi:[1,0,1] neg_lo:[0,1,0]
	v_pk_add_f32 v[88:89], v[82:83], v[86:87]
	v_pk_add_f32 v[82:83], v[82:83], v[86:87] neg_lo:[0,1] neg_hi:[0,1]
	s_nop 0
	v_pk_mul_f32 v[86:87], v[82:83], v[60:61] op_sel:[0,0] op_sel_hi:[0,1]
	s_nop 0
	v_pk_fma_f32 v[82:83], v[82:83], v[60:61], v[86:87] op_sel:[1,1,0] op_sel_hi:[1,0,1] neg_lo:[0,1,0]
	v_pk_add_f32 v[86:87], v[94:95], v[76:77]
	v_pk_add_f32 v[76:77], v[94:95], v[76:77] neg_lo:[0,1] neg_hi:[0,1]
	s_nop 0
	v_pk_mul_f32 v[94:95], v[76:77], v[58:59] op_sel:[0,0] op_sel_hi:[0,1]
	s_nop 0
	v_pk_fma_f32 v[76:77], v[76:77], v[58:59], v[94:95] op_sel:[1,1,0] op_sel_hi:[1,0,1] neg_lo:[0,1,0]
	v_pk_add_f32 v[94:95], v[74:75], v[78:79]
	v_pk_add_f32 v[74:75], v[74:75], v[78:79] neg_lo:[0,1] neg_hi:[0,1]
	s_nop 0
	v_pk_mul_f32 v[78:79], v[74:75], v[60:61] op_sel:[0,0] op_sel_hi:[0,1]
	s_nop 0
	v_pk_fma_f32 v[74:75], v[74:75], v[60:61], v[78:79] op_sel:[1,1,0] op_sel_hi:[1,0,1] neg_lo:[0,1,0]
	v_pk_add_f32 v[78:79], v[66:67], v[70:71]
	v_pk_add_f32 v[66:67], v[66:67], v[70:71] neg_lo:[0,1] neg_hi:[0,1]
	s_nop 0
	v_pk_mul_f32 v[70:71], v[66:67], v[58:59] op_sel:[0,0] op_sel_hi:[0,1]
	s_nop 0
	v_pk_fma_f32 v[66:67], v[66:67], v[58:59], v[70:71] op_sel:[1,1,0] op_sel_hi:[1,0,1] neg_lo:[0,1,0]
	v_pk_add_f32 v[70:71], v[68:69], v[72:73]
	v_pk_add_f32 v[68:69], v[68:69], v[72:73] neg_lo:[0,1] neg_hi:[0,1]
	s_nop 0
	v_pk_mul_f32 v[72:73], v[68:69], v[60:61] op_sel:[0,0] op_sel_hi:[0,1]
	s_nop 0
	v_pk_fma_f32 v[68:69], v[68:69], v[60:61], v[72:73] op_sel:[1,1,0] op_sel_hi:[1,0,1] neg_lo:[0,1,0]
	v_pk_add_f32 v[72:73], v[80:81], v[130:131]
	v_pk_add_f32 v[80:81], v[80:81], v[130:131] neg_lo:[0,1] neg_hi:[0,1]
	s_nop 0
	v_pk_mul_f32 v[130:131], v[80:81], v[62:63] op_sel:[0,0] op_sel_hi:[0,1]
	s_nop 0
	v_pk_fma_f32 v[80:81], v[80:81], v[62:63], v[130:131] op_sel:[1,1,0] op_sel_hi:[1,0,1] neg_lo:[0,1,0]
	v_pk_add_f32 v[130:131], v[96:97], v[122:123]
	v_pk_add_f32 v[96:97], v[96:97], v[122:123] neg_lo:[0,1] neg_hi:[0,1]
	s_nop 0
	v_pk_mul_f32 v[122:123], v[96:97], v[62:63] op_sel:[0,0] op_sel_hi:[0,1]
	s_nop 0
	v_pk_fma_f32 v[96:97], v[96:97], v[62:63], v[122:123] op_sel:[1,1,0] op_sel_hi:[1,0,1] neg_lo:[0,1,0]
; __device__ __forceinline__ float2 cmul(float2 a, float2 b) { return make_float2(a.x * b.x - a.y * b.y, a.x * b.y + a.y * b.x); }
; template <int R, bool INV>
; __device__ __forceinline__ void butterflies(c32 (&v)[1 << R], float turns0) {
;     ...
;   for (int kk = 0; kk < R; ++kk) {
;     const int k = INV ? (R - 1 - kk) : kk;
;     const int hd = RAD >> (k + 1);
; #pragma unroll
;     for (int j = 0; j < RAD; ++j) {
;       if ((j & hd) == 0) {
;         const int m = (j & (hd - 1)) * (16 / hd);
;         const float2 c = make_float2(TC[m], INV ? TS[m] : -TS[m]);
;         const float2 twf = cmul(tbs[k], c);
;         const c32 tw = {twf.x, twf.y};
;         const c32 a = v[j], b = v[j + hd];
;         if (!INV) { v[j] = a + b; v[j + hd] = cmul_pk(a - b, tw); }
;         else { const c32 bt = cmul_pk(b, tw); v[j] = a + bt; v[j + hd] = a - bt; }
;       }
;     }
;   }
; template <int LOGN, int R, int DLOG, bool INV, int MODE, class F>
; __device__ __forceinline__ void fft_pass(float2* X, const F& f) {
;     ...
;       for (int j = 0; j < RAD; ++j) Xc[(DLOG >= 5) ? pb + j * PSTEP : phys(base + (j << DLOG))] = v[j];
	v_pk_add_f32 v[122:123], v[128:129], v[118:119]
	v_pk_add_f32 v[118:119], v[128:129], v[118:119] neg_lo:[0,1] neg_hi:[0,1]
	s_nop 0
	v_pk_mul_f32 v[128:129], v[118:119], v[62:63] op_sel:[0,0] op_sel_hi:[0,1]
	s_nop 0
	v_pk_fma_f32 v[118:119], v[118:119], v[62:63], v[128:129] op_sel:[1,1,0] op_sel_hi:[1,0,1] neg_lo:[0,1,0]
	v_pk_add_f32 v[128:129], v[114:115], v[116:117]
	v_pk_add_f32 v[114:115], v[114:115], v[116:117] neg_lo:[0,1] neg_hi:[0,1]
	s_nop 0
	v_pk_mul_f32 v[116:117], v[114:115], v[62:63] op_sel:[0,0] op_sel_hi:[0,1]
	s_nop 0
	v_pk_fma_f32 v[114:115], v[114:115], v[62:63], v[116:117] op_sel:[1,1,0] op_sel_hi:[1,0,1] neg_lo:[0,1,0]
	v_pk_add_f32 v[116:117], v[120:121], v[124:125]
	v_pk_add_f32 v[120:121], v[120:121], v[124:125] neg_lo:[0,1] neg_hi:[0,1]
	s_nop 0
	v_pk_mul_f32 v[124:125], v[120:121], v[62:63] op_sel:[0,0] op_sel_hi:[0,1]
	s_nop 0
	v_pk_fma_f32 v[120:121], v[120:121], v[62:63], v[124:125] op_sel:[1,1,0] op_sel_hi:[1,0,1] neg_lo:[0,1,0]
	v_pk_add_f32 v[124:125], v[106:107], v[108:109]
	v_pk_add_f32 v[106:107], v[106:107], v[108:109] neg_lo:[0,1] neg_hi:[0,1]
	s_nop 0
	v_pk_mul_f32 v[108:109], v[106:107], v[62:63] op_sel:[0,0] op_sel_hi:[0,1]
	s_nop 0
	v_pk_fma_f32 v[106:107], v[106:107], v[62:63], v[108:109] op_sel:[1,1,0] op_sel_hi:[1,0,1] neg_lo:[0,1,0]
	v_pk_add_f32 v[108:109], v[112:113], v[104:105]
	v_pk_add_f32 v[104:105], v[112:113], v[104:105] neg_lo:[0,1] neg_hi:[0,1]
	s_nop 0
	v_pk_mul_f32 v[112:113], v[104:105], v[62:63] op_sel:[0,0] op_sel_hi:[0,1]
	s_nop 0
	v_pk_fma_f32 v[104:105], v[104:105], v[62:63], v[112:113] op_sel:[1,1,0] op_sel_hi:[1,0,1] neg_lo:[0,1,0]
	v_pk_add_f32 v[112:113], v[100:101], v[98:99]
	v_pk_add_f32 v[98:99], v[100:101], v[98:99] neg_lo:[0,1] neg_hi:[0,1]
	s_nop 0
	v_pk_mul_f32 v[100:101], v[98:99], v[62:63] op_sel:[0,0] op_sel_hi:[0,1]
	s_nop 0
	v_pk_fma_f32 v[98:99], v[98:99], v[62:63], v[100:101] op_sel:[1,1,0] op_sel_hi:[1,0,1] neg_lo:[0,1,0]
	v_pk_add_f32 v[100:101], v[102:103], v[110:111]
	v_pk_add_f32 v[102:103], v[102:103], v[110:111] neg_lo:[0,1] neg_hi:[0,1]
	s_nop 0
	v_pk_mul_f32 v[110:111], v[102:103], v[62:63] op_sel:[0,0] op_sel_hi:[0,1]
	s_nop 0
	v_pk_fma_f32 v[102:103], v[102:103], v[62:63], v[110:111] op_sel:[1,1,0] op_sel_hi:[1,0,1] neg_lo:[0,1,0]
	v_pk_add_f32 v[110:111], v[90:91], v[92:93]
	v_pk_add_f32 v[90:91], v[90:91], v[92:93] neg_lo:[0,1] neg_hi:[0,1]
	s_nop 0
	v_pk_mul_f32 v[92:93], v[90:91], v[62:63] op_sel:[0,0] op_sel_hi:[0,1]
	s_nop 0
	v_pk_fma_f32 v[90:91], v[90:91], v[62:63], v[92:93] op_sel:[1,1,0] op_sel_hi:[1,0,1] neg_lo:[0,1,0]
	v_pk_add_f32 v[92:93], v[126:127], v[88:89]
	v_pk_add_f32 v[88:89], v[126:127], v[88:89] neg_lo:[0,1] neg_hi:[0,1]
	s_nop 0
	v_pk_mul_f32 v[126:127], v[88:89], v[62:63] op_sel:[0,0] op_sel_hi:[0,1]
	s_nop 0
	v_pk_fma_f32 v[88:89], v[88:89], v[62:63], v[126:127] op_sel:[1,1,0] op_sel_hi:[1,0,1] neg_lo:[0,1,0]
	v_pk_add_f32 v[126:127], v[84:85], v[82:83]
	v_pk_add_f32 v[82:83], v[84:85], v[82:83] neg_lo:[0,1] neg_hi:[0,1]
	s_nop 0
	v_pk_mul_f32 v[84:85], v[82:83], v[62:63] op_sel:[0,0] op_sel_hi:[0,1]
	s_nop 0
	v_pk_fma_f32 v[82:83], v[82:83], v[62:63], v[84:85] op_sel:[1,1,0] op_sel_hi:[1,0,1] neg_lo:[0,1,0]
	v_pk_add_f32 v[84:85], v[86:87], v[94:95]
	v_pk_add_f32 v[86:87], v[86:87], v[94:95] neg_lo:[0,1] neg_hi:[0,1]
	s_nop 0
	v_pk_mul_f32 v[94:95], v[86:87], v[62:63] op_sel:[0,0] op_sel_hi:[0,1]
	s_nop 0
	v_pk_fma_f32 v[86:87], v[86:87], v[62:63], v[94:95] op_sel:[1,1,0] op_sel_hi:[1,0,1] neg_lo:[0,1,0]
	v_pk_add_f32 v[94:95], v[76:77], v[74:75]
	v_pk_add_f32 v[74:75], v[76:77], v[74:75] neg_lo:[0,1] neg_hi:[0,1]
	s_nop 0
	v_pk_mul_f32 v[76:77], v[74:75], v[62:63] op_sel:[0,0] op_sel_hi:[0,1]
	s_nop 0
	v_pk_fma_f32 v[74:75], v[74:75], v[62:63], v[76:77] op_sel:[1,1,0] op_sel_hi:[1,0,1] neg_lo:[0,1,0]
	v_pk_add_f32 v[76:77], v[78:79], v[70:71]
	v_pk_add_f32 v[70:71], v[78:79], v[70:71] neg_lo:[0,1] neg_hi:[0,1]
	s_nop 0
	v_pk_mul_f32 v[78:79], v[70:71], v[62:63] op_sel:[0,0] op_sel_hi:[0,1]
	s_nop 0
	v_pk_fma_f32 v[70:71], v[70:71], v[62:63], v[78:79] op_sel:[1,1,0] op_sel_hi:[1,0,1] neg_lo:[0,1,0]
	v_pk_add_f32 v[78:79], v[66:67], v[68:69]
	v_pk_add_f32 v[66:67], v[66:67], v[68:69] neg_lo:[0,1] neg_hi:[0,1]
	s_nop 0
	v_pk_mul_f32 v[68:69], v[66:67], v[62:63] op_sel:[0,0] op_sel_hi:[0,1]
	s_nop 0
	v_pk_fma_f32 v[66:67], v[66:67], v[62:63], v[68:69] op_sel:[1,1,0] op_sel_hi:[1,0,1] neg_lo:[0,1,0]
	ds_write2_b64 v132, v[72:73], v[80:81] offset1:33
	ds_write2_b64 v132, v[130:131], v[96:97] offset0:66 offset1:99
	ds_write2_b64 v132, v[122:123], v[118:119] offset0:132 offset1:165
	ds_write2_b64 v132, v[128:129], v[114:115] offset0:198 offset1:231
	ds_write2_b64 v133, v[116:117], v[120:121] offset0:8 offset1:41
	ds_write2_b64 v133, v[124:125], v[106:107] offset0:74 offset1:107
	ds_write2_b64 v133, v[108:109], v[104:105] offset0:140 offset1:173
	ds_write2_b64 v133, v[112:113], v[98:99] offset0:206 offset1:239
	ds_write2_b64 v134, v[100:101], v[102:103] offset0:16 offset1:49
	ds_write2_b64 v134, v[110:111], v[90:91] offset0:82 offset1:115
	ds_write2_b64 v134, v[92:93], v[88:89] offset0:148 offset1:181
	ds_write2_b64 v134, v[126:127], v[82:83] offset0:214 offset1:247
	ds_write2_b64 v135, v[84:85], v[86:87] offset0:24 offset1:57
	ds_write2_b64 v135, v[94:95], v[74:75] offset0:90 offset1:123
	ds_write2_b64 v135, v[76:77], v[70:71] offset0:156 offset1:189
	ds_write2_b64 v135, v[78:79], v[66:67] offset0:222 offset1:255
	s_andn2_b64 exec, exec, s[14:15]
	s_cbranch_execnz .LBB0_1022
; template <int LOGN, int R, int DLOG, bool INV, int MODE, class F>
; __device__ __forceinline__ void fft_pass(float2* X, const F& f) {
;     ...
;   __syncthreads();
; template <int LOGN>
; __device__ __forceinline__ void fft_last_to_regs(const float2* X, c32 (&kf)[32]) {
;     ...
;   const int pb = tid0 * 33;
;   c32 v[32];
; #pragma unroll
;   for (int j = 0; j < 32; ++j) v[j] = Xc[pb + j];
;   butterflies<5, false>(v, 0.f);
.LBB0_1023:
	s_or_b64 exec, exec, s[0:1]
	v_mov_b32_e32 v0, v196
	s_waitcnt lgkmcnt(0)
	s_barrier
	s_mov_b32 s7, s95
	v_mul_lo_u32 v0, v0, s61
	v_add_u32_e32 v32, 0, v0
	ds_read_b64 v[0:1], v32
	ds_read_b64 v[2:3], v32 offset:8
	ds_read_b64 v[4:5], v32 offset:16
	ds_read_b64 v[6:7], v32 offset:24
	ds_read_b64 v[8:9], v32 offset:32
	ds_read_b64 v[10:11], v32 offset:40
	ds_read_b64 v[12:13], v32 offset:48
	ds_read_b64 v[14:15], v32 offset:56
	ds_read_b64 v[16:17], v32 offset:64
	ds_read_b64 v[18:19], v32 offset:72
	ds_read_b64 v[20:21], v32 offset:80
	ds_read_b64 v[22:23], v32 offset:88
	ds_read_b64 v[24:25], v32 offset:96
	ds_read_b64 v[26:27], v32 offset:104
	ds_read_b64 v[28:29], v32 offset:112
	ds_read_b64 v[30:31], v32 offset:120
	ds_read_b64 v[34:35], v32 offset:128
	ds_read_b64 v[36:37], v32 offset:136
	ds_read_b64 v[38:39], v32 offset:144
	ds_read_b64 v[40:41], v32 offset:152
	ds_read_b64 v[42:43], v32 offset:160
	ds_read_b64 v[44:45], v32 offset:168
	ds_read_b64 v[46:47], v32 offset:176
	ds_read_b64 v[48:49], v32 offset:184
	ds_read_b64 v[50:51], v32 offset:192
	ds_read_b64 v[52:53], v32 offset:200
	ds_read_b64 v[54:55], v32 offset:208
	ds_read_b64 v[56:57], v32 offset:216
	ds_read_b64 v[58:59], v32 offset:224
	ds_read_b64 v[60:61], v32 offset:232
	ds_read_b64 v[62:63], v32 offset:240
	ds_read_b64 v[64:65], v32 offset:248
	s_waitcnt lgkmcnt(14)
	v_pk_add_f32 v[66:67], v[0:1], v[34:35]
	v_pk_add_f32 v[34:35], v[0:1], v[34:35] neg_lo:[0,1] neg_hi:[0,1]
	v_mov_b64_e32 v[0:1], s[6:7]
	v_pk_mul_f32 v[68:69], v[34:35], v[0:1] op_sel:[0,0] op_sel_hi:[0,1]
	s_mov_b32 s0, s19
	s_mov_b32 s1, s30
	v_pk_fma_f32 v[34:35], v[34:35], v[0:1], v[68:69] op_sel:[1,1,0] op_sel_hi:[1,0,1] neg_lo:[0,1,0]
	v_pk_add_f32 v[68:69], v[2:3], v[36:37]
	v_pk_add_f32 v[2:3], v[2:3], v[36:37] neg_lo:[0,1] neg_hi:[0,1]
	v_mov_b64_e32 v[36:37], s[0:1]
	v_pk_mul_f32 v[70:71], v[2:3], v[36:37] op_sel:[0,0] op_sel_hi:[0,1]
	s_mov_b32 s0, s9
	s_mov_b32 s1, s76
	v_pk_fma_f32 v[36:37], v[2:3], v[36:37], v[70:71] op_sel:[1,1,0] op_sel_hi:[1,0,1] neg_lo:[0,1,0]
	s_waitcnt lgkmcnt(12)
	v_pk_add_f32 v[70:71], v[4:5], v[38:39]
	v_pk_add_f32 v[2:3], v[4:5], v[38:39] neg_lo:[0,1] neg_hi:[0,1]
	v_mov_b64_e32 v[4:5], s[0:1]
	v_pk_mul_f32 v[38:39], v[2:3], v[4:5] op_sel:[0,0] op_sel_hi:[0,1]
	s_mov_b32 s0, s57
	s_mov_b32 s1, s68
	v_pk_fma_f32 v[38:39], v[2:3], v[4:5], v[38:39] op_sel:[1,1,0] op_sel_hi:[1,0,1] neg_lo:[0,1,0]
	v_pk_add_f32 v[72:73], v[6:7], v[40:41]
	v_pk_add_f32 v[2:3], v[6:7], v[40:41] neg_lo:[0,1] neg_hi:[0,1]
	v_mov_b64_e32 v[6:7], s[0:1]
	v_pk_mul_f32 v[40:41], v[2:3], v[6:7] op_sel:[0,0] op_sel_hi:[0,1]
	s_mov_b32 s0, s73
	s_mov_b32 s1, s72
	v_pk_fma_f32 v[6:7], v[2:3], v[6:7], v[40:41] op_sel:[1,1,0] op_sel_hi:[1,0,1] neg_lo:[0,1,0]
	s_waitcnt lgkmcnt(10)
	v_pk_add_f32 v[40:41], v[8:9], v[42:43]
	v_pk_add_f32 v[2:3], v[8:9], v[42:43] neg_lo:[0,1] neg_hi:[0,1]
	v_mov_b64_e32 v[8:9], s[0:1]
	v_pk_mul_f32 v[42:43], v[2:3], v[8:9] op_sel:[0,0] op_sel_hi:[0,1]
	s_mov_b32 s0, s56
	s_mov_b32 s1, s16
	v_pk_fma_f32 v[42:43], v[2:3], v[8:9], v[42:43] op_sel:[1,1,0] op_sel_hi:[1,0,1] neg_lo:[0,1,0]
	v_pk_add_f32 v[74:75], v[10:11], v[44:45]
	v_pk_add_f32 v[2:3], v[10:11], v[44:45] neg_lo:[0,1] neg_hi:[0,1]
	v_mov_b64_e32 v[10:11], s[0:1]
	v_pk_mul_f32 v[44:45], v[2:3], v[10:11] op_sel:[0,0] op_sel_hi:[0,1]
	s_mov_b32 s0, s8
	s_mov_b32 s1, s10
	v_pk_fma_f32 v[10:11], v[2:3], v[10:11], v[44:45] op_sel:[1,1,0] op_sel_hi:[1,0,1] neg_lo:[0,1,0]
	s_waitcnt lgkmcnt(8)
	v_pk_add_f32 v[44:45], v[12:13], v[46:47]
	v_pk_add_f32 v[2:3], v[12:13], v[46:47] neg_lo:[0,1] neg_hi:[0,1]
	v_mov_b64_e32 v[12:13], s[0:1]
	v_pk_mul_f32 v[46:47], v[2:3], v[12:13] op_sel:[0,0] op_sel_hi:[0,1]
	s_mov_b32 s0, s18
	s_mov_b32 s1, s4
	v_pk_fma_f32 v[46:47], v[2:3], v[12:13], v[46:47] op_sel:[1,1,0] op_sel_hi:[1,0,1] neg_lo:[0,1,0]
	v_pk_add_f32 v[76:77], v[14:15], v[48:49]
	v_pk_add_f32 v[2:3], v[14:15], v[48:49] neg_lo:[0,1] neg_hi:[0,1]
	v_mov_b64_e32 v[14:15], s[0:1]
	v_pk_mul_f32 v[48:49], v[2:3], v[14:15] op_sel:[0,0] op_sel_hi:[0,1]
	s_mov_b32 s88, s94
	v_pk_fma_f32 v[14:15], v[2:3], v[14:15], v[48:49] op_sel:[1,1,0] op_sel_hi:[1,0,1] neg_lo:[0,1,0]
	s_waitcnt lgkmcnt(6)
	v_pk_add_f32 v[48:49], v[16:17], v[50:51]
	v_pk_add_f32 v[16:17], v[16:17], v[50:51] neg_lo:[0,1] neg_hi:[0,1]
	v_mov_b64_e32 v[2:3], s[88:89]
	v_pk_mul_f32 v[50:51], v[16:17], v[2:3] op_sel:[0,0] op_sel_hi:[0,1]
	s_mov_b32 s31, s4
	v_pk_fma_f32 v[16:17], v[16:17], v[2:3], v[50:51] op_sel:[1,1,0] op_sel_hi:[1,0,1] neg_lo:[0,1,0]
	v_pk_add_f32 v[50:51], v[18:19], v[52:53]
	v_pk_add_f32 v[18:19], v[18:19], v[52:53] neg_lo:[0,1] neg_hi:[0,1]
	v_mov_b64_e32 v[52:53], s[30:31]
	v_pk_mul_f32 v[78:79], v[18:19], v[52:53] op_sel:[0,0] op_sel_hi:[0,1]
	s_mov_b32 s77, s10
	v_pk_fma_f32 v[18:19], v[18:19], v[52:53], v[78:79] op_sel:[1,1,0] op_sel_hi:[1,0,1] neg_lo:[0,1,0]
	s_waitcnt lgkmcnt(4)
	v_pk_add_f32 v[52:53], v[20:21], v[54:55]
	v_pk_add_f32 v[20:21], v[20:21], v[54:55] neg_lo:[0,1] neg_hi:[0,1]
	v_mov_b64_e32 v[54:55], s[76:77]
	v_pk_mul_f32 v[78:79], v[20:21], v[54:55] op_sel:[0,0] op_sel_hi:[0,1]
	s_mov_b32 s69, s16
	v_pk_fma_f32 v[20:21], v[20:21], v[54:55], v[78:79] op_sel:[1,1,0] op_sel_hi:[1,0,1] neg_lo:[0,1,0]
	v_pk_add_f32 v[78:79], v[22:23], v[56:57]
	v_pk_add_f32 v[22:23], v[22:23], v[56:57] neg_lo:[0,1] neg_hi:[0,1]
	v_mov_b64_e32 v[56:57], s[68:69]
	v_pk_mul_f32 v[80:81], v[22:23], v[56:57] op_sel:[0,0] op_sel_hi:[0,1]
	s_mov_b32 s0, s72
	s_mov_b32 s1, s72
	v_pk_fma_f32 v[22:23], v[22:23], v[56:57], v[80:81] op_sel:[1,1,0] op_sel_hi:[1,0,1] neg_lo:[0,1,0]
	s_waitcnt lgkmcnt(2)
; __device__ __forceinline__ float2 cmul(float2 a, float2 b) { return make_float2(a.x * b.x - a.y * b.y, a.x * b.y + a.y * b.x); }
; template <int R, bool INV>
; __device__ __forceinline__ void butterflies(c32 (&v)[1 << R], float turns0) {
;     ...
;   for (int kk = 0; kk < R; ++kk) {
;     const int k = INV ? (R - 1 - kk) : kk;
;     const int hd = RAD >> (k + 1);
; #pragma unroll
;     for (int j = 0; j < RAD; ++j) {
;       if ((j & hd) == 0) {
;         const int m = (j & (hd - 1)) * (16 / hd);
;         const float2 c = make_float2(TC[m], INV ? TS[m] : -TS[m]);
;         const float2 twf = cmul(tbs[k], c);
;         const c32 tw = {twf.x, twf.y};
;         const c32 a = v[j], b = v[j + hd];
;         if (!INV) { v[j] = a + b; v[j + hd] = cmul_pk(a - b, tw); }
;         else { const c32 bt = cmul_pk(b, tw); v[j] = a + bt; v[j + hd] = a - bt; }
;       }
;     }
;   }
; template <int LOGN>
; __device__ __forceinline__ void fft_last_to_regs(const float2* X, c32 (&kf)[32]) {
;     ...
;   __syncthreads();
	v_pk_add_f32 v[56:57], v[24:25], v[58:59]
	v_pk_add_f32 v[24:25], v[24:25], v[58:59] neg_lo:[0,1] neg_hi:[0,1]
	v_mov_b64_e32 v[58:59], s[0:1]
	v_pk_mul_f32 v[80:81], v[24:25], v[58:59] op_sel:[0,0] op_sel_hi:[0,1]
	s_mov_b32 s17, s68
	v_pk_fma_f32 v[24:25], v[24:25], v[58:59], v[80:81] op_sel:[1,1,0] op_sel_hi:[1,0,1] neg_lo:[0,1,0]
	v_pk_add_f32 v[80:81], v[26:27], v[60:61]
	v_pk_add_f32 v[26:27], v[26:27], v[60:61] neg_lo:[0,1] neg_hi:[0,1]
	v_mov_b64_e32 v[60:61], s[16:17]
	v_pk_mul_f32 v[82:83], v[26:27], v[60:61] op_sel:[0,0] op_sel_hi:[0,1]
	s_mov_b32 s11, s76
	v_pk_fma_f32 v[26:27], v[26:27], v[60:61], v[82:83] op_sel:[1,1,0] op_sel_hi:[1,0,1] neg_lo:[0,1,0]
	s_waitcnt lgkmcnt(0)
	v_pk_add_f32 v[60:61], v[28:29], v[62:63]
	v_pk_add_f32 v[28:29], v[28:29], v[62:63] neg_lo:[0,1] neg_hi:[0,1]
	v_mov_b64_e32 v[62:63], s[10:11]
	v_pk_mul_f32 v[82:83], v[28:29], v[62:63] op_sel:[0,0] op_sel_hi:[0,1]
	s_mov_b32 s5, s30
	v_pk_fma_f32 v[28:29], v[28:29], v[62:63], v[82:83] op_sel:[1,1,0] op_sel_hi:[1,0,1] neg_lo:[0,1,0]
	v_pk_add_f32 v[82:83], v[30:31], v[64:65]
	v_pk_add_f32 v[30:31], v[30:31], v[64:65] neg_lo:[0,1] neg_hi:[0,1]
	v_mov_b64_e32 v[64:65], s[4:5]
	v_pk_mul_f32 v[84:85], v[30:31], v[64:65] op_sel:[0,0] op_sel_hi:[0,1]
	v_mov_b32_e32 v130, v196
	v_pk_fma_f32 v[30:31], v[30:31], v[64:65], v[84:85] op_sel:[1,1,0] op_sel_hi:[1,0,1] neg_lo:[0,1,0]
	v_pk_add_f32 v[64:65], v[66:67], v[48:49]
	v_pk_add_f32 v[48:49], v[66:67], v[48:49] neg_lo:[0,1] neg_hi:[0,1]
	s_nop 0
	v_pk_mul_f32 v[66:67], v[48:49], v[0:1] op_sel:[0,0] op_sel_hi:[0,1]
	s_barrier
	v_pk_fma_f32 v[48:49], v[48:49], v[0:1], v[66:67] op_sel:[1,1,0] op_sel_hi:[1,0,1] neg_lo:[0,1,0]
	v_pk_add_f32 v[66:67], v[68:69], v[50:51]
	v_pk_add_f32 v[50:51], v[68:69], v[50:51] neg_lo:[0,1] neg_hi:[0,1]
	s_nop 0
	v_pk_mul_f32 v[68:69], v[50:51], v[4:5] op_sel:[0,0] op_sel_hi:[0,1]
	s_and_b64 vcc, exec, s[40:41]
	v_pk_fma_f32 v[50:51], v[50:51], v[4:5], v[68:69] op_sel:[1,1,0] op_sel_hi:[1,0,1] neg_lo:[0,1,0]
	v_pk_add_f32 v[68:69], v[70:71], v[52:53]
	v_pk_add_f32 v[52:53], v[70:71], v[52:53] neg_lo:[0,1] neg_hi:[0,1]
	v_lshlrev_b32_e32 v32, 3, v130
	v_pk_mul_f32 v[70:71], v[52:53], v[8:9] op_sel:[0,0] op_sel_hi:[0,1]
	s_nop 0
	v_pk_fma_f32 v[52:53], v[52:53], v[8:9], v[70:71] op_sel:[1,1,0] op_sel_hi:[1,0,1] neg_lo:[0,1,0]
	v_pk_add_f32 v[70:71], v[72:73], v[78:79]
	v_pk_add_f32 v[72:73], v[72:73], v[78:79] neg_lo:[0,1] neg_hi:[0,1]
	s_nop 0
	v_pk_mul_f32 v[78:79], v[72:73], v[12:13] op_sel:[0,0] op_sel_hi:[0,1]
	s_nop 0
	v_pk_fma_f32 v[72:73], v[72:73], v[12:13], v[78:79] op_sel:[1,1,0] op_sel_hi:[1,0,1] neg_lo:[0,1,0]
	v_pk_add_f32 v[78:79], v[40:41], v[56:57]
	v_pk_add_f32 v[40:41], v[40:41], v[56:57] neg_lo:[0,1] neg_hi:[0,1]
	s_nop 0
	v_pk_mul_f32 v[56:57], v[40:41], v[2:3] op_sel:[0,0] op_sel_hi:[0,1]
	s_nop 0
	v_pk_fma_f32 v[40:41], v[40:41], v[2:3], v[56:57] op_sel:[1,1,0] op_sel_hi:[1,0,1] neg_lo:[0,1,0]
	v_pk_add_f32 v[56:57], v[74:75], v[80:81]
	v_pk_add_f32 v[74:75], v[74:75], v[80:81] neg_lo:[0,1] neg_hi:[0,1]
	v_pk_add_f32 v[84:85], v[48:49], v[40:41]
	v_pk_mul_f32 v[80:81], v[74:75], v[54:55] op_sel:[0,0] op_sel_hi:[0,1]
	v_pk_add_f32 v[40:41], v[48:49], v[40:41] neg_lo:[0,1] neg_hi:[0,1]
	v_pk_fma_f32 v[74:75], v[74:75], v[54:55], v[80:81] op_sel:[1,1,0] op_sel_hi:[1,0,1] neg_lo:[0,1,0]
	v_pk_add_f32 v[80:81], v[44:45], v[60:61]
	v_pk_add_f32 v[44:45], v[44:45], v[60:61] neg_lo:[0,1] neg_hi:[0,1]
	v_pk_mul_f32 v[48:49], v[40:41], v[0:1] op_sel:[0,0] op_sel_hi:[0,1]
	s_nop 0
	v_pk_mul_f32 v[60:61], v[44:45], v[58:59] op_sel:[0,0] op_sel_hi:[0,1]
	v_pk_fma_f32 v[40:41], v[40:41], v[0:1], v[48:49] op_sel:[1,1,0] op_sel_hi:[1,0,1] neg_lo:[0,1,0]
	v_pk_add_f32 v[48:49], v[50:51], v[74:75]
	v_pk_fma_f32 v[44:45], v[44:45], v[58:59], v[60:61] op_sel:[1,1,0] op_sel_hi:[1,0,1] neg_lo:[0,1,0]
	v_pk_add_f32 v[60:61], v[76:77], v[82:83]
	v_pk_add_f32 v[76:77], v[76:77], v[82:83] neg_lo:[0,1] neg_hi:[0,1]
	v_pk_add_f32 v[50:51], v[50:51], v[74:75] neg_lo:[0,1] neg_hi:[0,1]
	v_pk_mul_f32 v[82:83], v[76:77], v[62:63] op_sel:[0,0] op_sel_hi:[0,1]
	v_pk_add_f32 v[86:87], v[52:53], v[44:45]
	v_pk_fma_f32 v[76:77], v[76:77], v[62:63], v[82:83] op_sel:[1,1,0] op_sel_hi:[1,0,1] neg_lo:[0,1,0]
	v_pk_add_f32 v[82:83], v[34:35], v[16:17]
	v_pk_add_f32 v[16:17], v[34:35], v[16:17] neg_lo:[0,1] neg_hi:[0,1]
	v_pk_add_f32 v[44:45], v[52:53], v[44:45] neg_lo:[0,1] neg_hi:[0,1]
	v_pk_mul_f32 v[34:35], v[16:17], v[0:1] op_sel:[0,0] op_sel_hi:[0,1]
	s_nop 0
	v_pk_fma_f32 v[16:17], v[16:17], v[0:1], v[34:35] op_sel:[1,1,0] op_sel_hi:[1,0,1] neg_lo:[0,1,0]
	v_pk_add_f32 v[34:35], v[36:37], v[18:19]
	v_pk_add_f32 v[18:19], v[36:37], v[18:19] neg_lo:[0,1] neg_hi:[0,1]
	v_pk_mul_f32 v[52:53], v[44:45], v[2:3] op_sel:[0,0] op_sel_hi:[0,1]
	s_nop 0
	v_pk_mul_f32 v[36:37], v[18:19], v[4:5] op_sel:[0,0] op_sel_hi:[0,1]
	v_pk_fma_f32 v[44:45], v[44:45], v[2:3], v[52:53] op_sel:[1,1,0] op_sel_hi:[1,0,1] neg_lo:[0,1,0]
	v_pk_add_f32 v[52:53], v[72:73], v[76:77]
	v_pk_fma_f32 v[4:5], v[18:19], v[4:5], v[36:37] op_sel:[1,1,0] op_sel_hi:[1,0,1] neg_lo:[0,1,0]
	v_pk_add_f32 v[18:19], v[38:39], v[20:21]
	v_pk_add_f32 v[20:21], v[38:39], v[20:21] neg_lo:[0,1] neg_hi:[0,1]
	v_pk_add_f32 v[88:89], v[40:41], v[44:45]
	v_pk_mul_f32 v[36:37], v[20:21], v[8:9] op_sel:[0,0] op_sel_hi:[0,1]
	s_nop 0
	v_pk_fma_f32 v[20:21], v[20:21], v[8:9], v[36:37] op_sel:[1,1,0] op_sel_hi:[1,0,1] neg_lo:[0,1,0]
	v_pk_add_f32 v[36:37], v[6:7], v[22:23]
	v_pk_add_f32 v[6:7], v[6:7], v[22:23] neg_lo:[0,1] neg_hi:[0,1]
	s_nop 0
	v_pk_mul_f32 v[22:23], v[6:7], v[12:13] op_sel:[0,0] op_sel_hi:[0,1]
	s_nop 0
; __device__ __forceinline__ float2 cmul(float2 a, float2 b) { return make_float2(a.x * b.x - a.y * b.y, a.x * b.y + a.y * b.x); }
; template <int R, bool INV>
; __device__ __forceinline__ void butterflies(c32 (&v)[1 << R], float turns0) {
;     ...
;   for (int kk = 0; kk < R; ++kk) {
;     const int k = INV ? (R - 1 - kk) : kk;
;     const int hd = RAD >> (k + 1);
; #pragma unroll
;     for (int j = 0; j < RAD; ++j) {
;       if ((j & hd) == 0) {
;         const int m = (j & (hd - 1)) * (16 / hd);
;         const float2 c = make_float2(TC[m], INV ? TS[m] : -TS[m]);
;         const float2 twf = cmul(tbs[k], c);
;         const c32 tw = {twf.x, twf.y};
;         const c32 a = v[j], b = v[j + hd];
;         if (!INV) { v[j] = a + b; v[j + hd] = cmul_pk(a - b, tw); }
;         else { const c32 bt = cmul_pk(b, tw); v[j] = a + bt; v[j + hd] = a - bt; }
;       }
;     }
;   }
	v_pk_fma_f32 v[6:7], v[6:7], v[12:13], v[22:23] op_sel:[1,1,0] op_sel_hi:[1,0,1] neg_lo:[0,1,0]
	v_pk_add_f32 v[12:13], v[42:43], v[24:25]
	v_pk_add_f32 v[22:23], v[42:43], v[24:25] neg_lo:[0,1] neg_hi:[0,1]
	v_pk_add_f32 v[42:43], v[64:65], v[78:79] neg_lo:[0,1] neg_hi:[0,1]
	v_pk_mul_f32 v[24:25], v[22:23], v[2:3] op_sel:[0,0] op_sel_hi:[0,1]
	v_pk_add_f32 v[100:101], v[82:83], v[12:13]
	v_pk_fma_f32 v[22:23], v[22:23], v[2:3], v[24:25] op_sel:[1,1,0] op_sel_hi:[1,0,1] neg_lo:[0,1,0]
	v_pk_add_f32 v[24:25], v[10:11], v[26:27]
	v_pk_add_f32 v[10:11], v[10:11], v[26:27] neg_lo:[0,1] neg_hi:[0,1]
	v_pk_add_f32 v[104:105], v[34:35], v[24:25]
	v_pk_mul_f32 v[26:27], v[10:11], v[54:55] op_sel:[0,0] op_sel_hi:[0,1]
	v_pk_add_f32 v[24:25], v[34:35], v[24:25] neg_lo:[0,1] neg_hi:[0,1]
	v_pk_fma_f32 v[10:11], v[10:11], v[54:55], v[26:27] op_sel:[1,1,0] op_sel_hi:[1,0,1] neg_lo:[0,1,0]
	v_pk_add_f32 v[26:27], v[46:47], v[28:29]
	v_pk_add_f32 v[28:29], v[46:47], v[28:29] neg_lo:[0,1] neg_hi:[0,1]
	v_pk_mul_f32 v[34:35], v[24:25], v[8:9] op_sel:[0,0] op_sel_hi:[0,1]
	v_pk_mul_f32 v[46:47], v[42:43], v[0:1] op_sel:[0,0] op_sel_hi:[0,1]
	v_pk_add_f32 v[54:55], v[66:67], v[56:57] neg_lo:[0,1] neg_hi:[0,1]
	v_pk_mul_f32 v[38:39], v[28:29], v[58:59] op_sel:[0,0] op_sel_hi:[0,1]
	v_pk_fma_f32 v[24:25], v[24:25], v[8:9], v[34:35] op_sel:[1,1,0] op_sel_hi:[1,0,1] neg_lo:[0,1,0]
	v_pk_add_f32 v[34:35], v[18:19], v[26:27]
	v_pk_fma_f32 v[28:29], v[28:29], v[58:59], v[38:39] op_sel:[1,1,0] op_sel_hi:[1,0,1] neg_lo:[0,1,0]
	v_pk_add_f32 v[38:39], v[14:15], v[30:31]
	v_pk_add_f32 v[18:19], v[18:19], v[26:27] neg_lo:[0,1] neg_hi:[0,1]
	v_pk_add_f32 v[14:15], v[14:15], v[30:31] neg_lo:[0,1] neg_hi:[0,1]
	v_pk_mul_f32 v[26:27], v[18:19], v[2:3] op_sel:[0,0] op_sel_hi:[0,1]
	v_pk_fma_f32 v[42:43], v[42:43], v[0:1], v[46:47] op_sel:[1,1,0] op_sel_hi:[1,0,1] neg_lo:[0,1,0]
	v_pk_add_f32 v[46:47], v[66:67], v[56:57]
	v_pk_mul_f32 v[30:31], v[14:15], v[62:63] op_sel:[0,0] op_sel_hi:[0,1]
	v_pk_fma_f32 v[18:19], v[18:19], v[2:3], v[26:27] op_sel:[1,1,0] op_sel_hi:[1,0,1] neg_lo:[0,1,0]
	v_pk_add_f32 v[26:27], v[36:37], v[38:39]
	v_pk_add_f32 v[36:37], v[36:37], v[38:39] neg_lo:[0,1] neg_hi:[0,1]
	v_pk_fma_f32 v[14:15], v[14:15], v[62:63], v[30:31] op_sel:[1,1,0] op_sel_hi:[1,0,1] neg_lo:[0,1,0]
	v_pk_add_f32 v[30:31], v[64:65], v[78:79]
	v_pk_mul_f32 v[38:39], v[36:37], v[58:59] op_sel:[0,0] op_sel_hi:[0,1]
	v_pk_add_f32 v[62:63], v[68:69], v[80:81] neg_lo:[0,1] neg_hi:[0,1]
	v_pk_fma_f32 v[36:37], v[36:37], v[58:59], v[38:39] op_sel:[1,1,0] op_sel_hi:[1,0,1] neg_lo:[0,1,0]
	v_pk_add_f32 v[38:39], v[16:17], v[22:23]
	v_pk_mul_f32 v[64:65], v[62:63], v[2:3] op_sel:[0,0] op_sel_hi:[0,1]
	v_pk_add_f32 v[16:17], v[16:17], v[22:23] neg_lo:[0,1] neg_hi:[0,1]
	v_pk_fma_f32 v[62:63], v[62:63], v[2:3], v[64:65] op_sel:[1,1,0] op_sel_hi:[1,0,1] neg_lo:[0,1,0]
	v_pk_add_f32 v[64:65], v[70:71], v[60:61]
	v_pk_mul_f32 v[22:23], v[16:17], v[0:1] op_sel:[0,0] op_sel_hi:[0,1]
	v_pk_add_f32 v[60:61], v[70:71], v[60:61] neg_lo:[0,1] neg_hi:[0,1]
	v_pk_fma_f32 v[16:17], v[16:17], v[0:1], v[22:23] op_sel:[1,1,0] op_sel_hi:[1,0,1] neg_lo:[0,1,0]
	v_pk_add_f32 v[22:23], v[4:5], v[10:11]
	v_pk_mul_f32 v[66:67], v[60:61], v[58:59] op_sel:[0,0] op_sel_hi:[0,1]
	v_pk_add_f32 v[4:5], v[4:5], v[10:11] neg_lo:[0,1] neg_hi:[0,1]
	v_pk_mul_f32 v[56:57], v[54:55], v[8:9] op_sel:[0,0] op_sel_hi:[0,1]
	v_pk_fma_f32 v[60:61], v[60:61], v[58:59], v[66:67] op_sel:[1,1,0] op_sel_hi:[1,0,1] neg_lo:[0,1,0]
	v_pk_mul_f32 v[66:67], v[50:51], v[8:9] op_sel:[0,0] op_sel_hi:[0,1]
	v_pk_add_f32 v[12:13], v[82:83], v[12:13] neg_lo:[0,1] neg_hi:[0,1]
	v_pk_mul_f32 v[10:11], v[4:5], v[8:9] op_sel:[0,0] op_sel_hi:[0,1]
	v_pk_fma_f32 v[54:55], v[54:55], v[8:9], v[56:57] op_sel:[1,1,0] op_sel_hi:[1,0,1] neg_lo:[0,1,0]
	v_pk_fma_f32 v[50:51], v[50:51], v[8:9], v[66:67] op_sel:[1,1,0] op_sel_hi:[1,0,1] neg_lo:[0,1,0]
	v_pk_add_f32 v[56:57], v[68:69], v[80:81]
	v_pk_fma_f32 v[4:5], v[4:5], v[8:9], v[10:11] op_sel:[1,1,0] op_sel_hi:[1,0,1] neg_lo:[0,1,0]
	v_pk_add_f32 v[8:9], v[20:21], v[28:29]
	v_pk_add_f32 v[10:11], v[20:21], v[28:29] neg_lo:[0,1] neg_hi:[0,1]
	v_pk_add_f32 v[66:67], v[72:73], v[76:77] neg_lo:[0,1] neg_hi:[0,1]
	v_pk_mul_f32 v[20:21], v[10:11], v[2:3] op_sel:[0,0] op_sel_hi:[0,1]
	v_pk_add_f32 v[80:81], v[84:85], v[86:87]
	v_pk_fma_f32 v[10:11], v[10:11], v[2:3], v[20:21] op_sel:[1,1,0] op_sel_hi:[1,0,1] neg_lo:[0,1,0]
	v_pk_add_f32 v[20:21], v[6:7], v[14:15]
	v_pk_add_f32 v[6:7], v[6:7], v[14:15] neg_lo:[0,1] neg_hi:[0,1]
	v_pk_mul_f32 v[68:69], v[66:67], v[58:59] op_sel:[0,0] op_sel_hi:[0,1]
	v_pk_add_f32 v[102:103], v[104:105], v[26:27]
	v_pk_mul_f32 v[14:15], v[6:7], v[58:59] op_sel:[0,0] op_sel_hi:[0,1]
	v_pk_fma_f32 v[96:97], v[66:67], v[58:59], v[68:69] op_sel:[1,1,0] op_sel_hi:[1,0,1] neg_lo:[0,1,0]
	v_pk_mul_f32 v[66:67], v[12:13], v[0:1] op_sel:[0,0] op_sel_hi:[0,1]
	v_pk_add_f32 v[70:71], v[46:47], v[64:65]
	v_pk_fma_f32 v[6:7], v[6:7], v[58:59], v[14:15] op_sel:[1,1,0] op_sel_hi:[1,0,1] neg_lo:[0,1,0]
	v_pk_add_f32 v[14:15], v[30:31], v[56:57] neg_lo:[0,1] neg_hi:[0,1]
	v_pk_fma_f32 v[12:13], v[12:13], v[0:1], v[66:67] op_sel:[1,1,0] op_sel_hi:[1,0,1] neg_lo:[0,1,0]
	v_pk_add_f32 v[94:95], v[50:51], v[96:97]
	v_pk_mul_f32 v[28:29], v[14:15], v[0:1] op_sel:[0,0] op_sel_hi:[0,1]
	v_pk_add_f32 v[66:67], v[30:31], v[56:57]
	v_pk_fma_f32 v[68:69], v[14:15], v[0:1], v[28:29] op_sel:[1,1,0] op_sel_hi:[1,0,1] neg_lo:[0,1,0]
	v_pk_add_f32 v[14:15], v[46:47], v[64:65] neg_lo:[0,1] neg_hi:[0,1]
	v_pk_add_f32 v[112:113], v[38:39], v[8:9]
	v_pk_mul_f32 v[28:29], v[14:15], v[2:3] op_sel:[0,0] op_sel_hi:[0,1]
; __device__ __forceinline__ float2 cmul(float2 a, float2 b) { return make_float2(a.x * b.x - a.y * b.y, a.x * b.y + a.y * b.x); }
; template <int R, bool INV>
; __device__ __forceinline__ void butterflies(c32 (&v)[1 << R], float turns0) {
;     ...
;   for (int kk = 0; kk < R; ++kk) {
;     const int k = INV ? (R - 1 - kk) : kk;
;     const int hd = RAD >> (k + 1);
; #pragma unroll
;     for (int j = 0; j < RAD; ++j) {
;       if ((j & hd) == 0) {
;         const int m = (j & (hd - 1)) * (16 / hd);
;         const float2 c = make_float2(TC[m], INV ? TS[m] : -TS[m]);
;         const float2 twf = cmul(tbs[k], c);
;         const c32 tw = {twf.x, twf.y};
;         const c32 a = v[j], b = v[j + hd];
;         if (!INV) { v[j] = a + b; v[j + hd] = cmul_pk(a - b, tw); }
;         else { const c32 bt = cmul_pk(b, tw); v[j] = a + bt; v[j + hd] = a - bt; }
;       }
;     }
;   }
	v_pk_add_f32 v[8:9], v[38:39], v[8:9] neg_lo:[0,1] neg_hi:[0,1]
	v_pk_fma_f32 v[74:75], v[14:15], v[2:3], v[28:29] op_sel:[1,1,0] op_sel_hi:[1,0,1] neg_lo:[0,1,0]
	v_pk_add_f32 v[14:15], v[42:43], v[62:63] neg_lo:[0,1] neg_hi:[0,1]
	v_pk_add_f32 v[126:127], v[4:5], v[6:7]
	v_pk_mul_f32 v[28:29], v[14:15], v[0:1] op_sel:[0,0] op_sel_hi:[0,1]
	v_pk_add_f32 v[4:5], v[4:5], v[6:7] neg_lo:[0,1] neg_hi:[0,1]
	v_pk_fma_f32 v[76:77], v[14:15], v[0:1], v[28:29] op_sel:[1,1,0] op_sel_hi:[1,0,1] neg_lo:[0,1,0]
	v_pk_add_f32 v[14:15], v[54:55], v[60:61] neg_lo:[0,1] neg_hi:[0,1]
	v_pk_mul_f32 v[6:7], v[4:5], v[2:3] op_sel:[0,0] op_sel_hi:[0,1]
	v_pk_add_f32 v[72:73], v[42:43], v[62:63]
	v_pk_mul_f32 v[28:29], v[14:15], v[2:3] op_sel:[0,0] op_sel_hi:[0,1]
	v_pk_fma_f32 v[128:129], v[4:5], v[2:3], v[6:7] op_sel:[1,1,0] op_sel_hi:[1,0,1] neg_lo:[0,1,0]
	v_pk_add_f32 v[78:79], v[54:55], v[60:61]
	v_pk_fma_f32 v[82:83], v[14:15], v[2:3], v[28:29] op_sel:[1,1,0] op_sel_hi:[1,0,1] neg_lo:[0,1,0]
	v_pk_add_f32 v[14:15], v[84:85], v[86:87] neg_lo:[0,1] neg_hi:[0,1]
	v_pk_add_f32 v[86:87], v[48:49], v[52:53]
	v_pk_mul_f32 v[28:29], v[14:15], v[0:1] op_sel:[0,0] op_sel_hi:[0,1]
	v_pk_add_f32 v[110:111], v[24:25], v[36:37]
	v_pk_fma_f32 v[84:85], v[14:15], v[0:1], v[28:29] op_sel:[1,1,0] op_sel_hi:[1,0,1] neg_lo:[0,1,0]
	v_pk_add_f32 v[14:15], v[48:49], v[52:53] neg_lo:[0,1] neg_hi:[0,1]
	v_pk_add_f32 v[118:119], v[22:23], v[20:21]
	v_pk_mul_f32 v[28:29], v[14:15], v[2:3] op_sel:[0,0] op_sel_hi:[0,1]
	v_pk_add_f32 v[120:121], v[16:17], v[10:11]
	v_pk_fma_f32 v[90:91], v[14:15], v[2:3], v[28:29] op_sel:[1,1,0] op_sel_hi:[1,0,1] neg_lo:[0,1,0]
	v_pk_add_f32 v[14:15], v[40:41], v[44:45] neg_lo:[0,1] neg_hi:[0,1]
	s_nop 0
	v_pk_mul_f32 v[28:29], v[14:15], v[0:1] op_sel:[0,0] op_sel_hi:[0,1]
	s_nop 0
	v_pk_fma_f32 v[92:93], v[14:15], v[0:1], v[28:29] op_sel:[1,1,0] op_sel_hi:[1,0,1] neg_lo:[0,1,0]
	v_pk_add_f32 v[14:15], v[50:51], v[96:97] neg_lo:[0,1] neg_hi:[0,1]
	v_pk_add_f32 v[96:97], v[100:101], v[34:35]
	v_pk_mul_f32 v[28:29], v[14:15], v[2:3] op_sel:[0,0] op_sel_hi:[0,1]
	s_nop 0
	v_pk_fma_f32 v[98:99], v[14:15], v[2:3], v[28:29] op_sel:[1,1,0] op_sel_hi:[1,0,1] neg_lo:[0,1,0]
	v_pk_add_f32 v[14:15], v[100:101], v[34:35] neg_lo:[0,1] neg_hi:[0,1]
	s_nop 0
	v_pk_mul_f32 v[28:29], v[14:15], v[0:1] op_sel:[0,0] op_sel_hi:[0,1]
	s_nop 0
	v_pk_fma_f32 v[100:101], v[14:15], v[0:1], v[28:29] op_sel:[1,1,0] op_sel_hi:[1,0,1] neg_lo:[0,1,0]
	v_pk_add_f32 v[14:15], v[104:105], v[26:27] neg_lo:[0,1] neg_hi:[0,1]
	v_pk_add_f32 v[104:105], v[12:13], v[18:19]
	v_pk_add_f32 v[12:13], v[12:13], v[18:19] neg_lo:[0,1] neg_hi:[0,1]
	v_pk_mul_f32 v[26:27], v[14:15], v[2:3] op_sel:[0,0] op_sel_hi:[0,1]
	s_nop 0
	v_pk_fma_f32 v[106:107], v[14:15], v[2:3], v[26:27] op_sel:[1,1,0] op_sel_hi:[1,0,1] neg_lo:[0,1,0]
	v_pk_mul_f32 v[14:15], v[12:13], v[0:1] op_sel:[0,0] op_sel_hi:[0,1]
	s_nop 0
	v_pk_fma_f32 v[108:109], v[12:13], v[0:1], v[14:15] op_sel:[1,1,0] op_sel_hi:[1,0,1] neg_lo:[0,1,0]
	v_pk_add_f32 v[12:13], v[24:25], v[36:37] neg_lo:[0,1] neg_hi:[0,1]
	s_nop 0
	v_pk_mul_f32 v[14:15], v[12:13], v[2:3] op_sel:[0,0] op_sel_hi:[0,1]
	s_nop 0
	v_pk_fma_f32 v[114:115], v[12:13], v[2:3], v[14:15] op_sel:[1,1,0] op_sel_hi:[1,0,1] neg_lo:[0,1,0]
	v_pk_mul_f32 v[12:13], v[8:9], v[0:1] op_sel:[0,0] op_sel_hi:[0,1]
	s_nop 0
	v_pk_fma_f32 v[116:117], v[8:9], v[0:1], v[12:13] op_sel:[1,1,0] op_sel_hi:[1,0,1] neg_lo:[0,1,0]
	v_pk_add_f32 v[8:9], v[22:23], v[20:21] neg_lo:[0,1] neg_hi:[0,1]
	s_nop 0
	v_pk_mul_f32 v[12:13], v[8:9], v[2:3] op_sel:[0,0] op_sel_hi:[0,1]
	s_nop 0
	v_pk_fma_f32 v[122:123], v[8:9], v[2:3], v[12:13] op_sel:[1,1,0] op_sel_hi:[1,0,1] neg_lo:[0,1,0]
	v_pk_add_f32 v[2:3], v[66:67], v[70:71] neg_lo:[0,1] neg_hi:[0,1]
	v_pk_add_f32 v[8:9], v[16:17], v[10:11] neg_lo:[0,1] neg_hi:[0,1]
	v_pk_mul_f32 v[4:5], v[2:3], v[0:1] op_sel:[0,0] op_sel_hi:[0,1]
	v_and_b32_e32 v16, 0x3ff, v130
	v_pk_fma_f32 v[64:65], v[2:3], v[0:1], v[4:5] op_sel:[1,1,0] op_sel_hi:[1,0,1] neg_lo:[0,1,0]
	v_pk_add_f32 v[2:3], v[68:69], v[74:75] neg_lo:[0,1] neg_hi:[0,1]
	v_pk_mul_f32 v[10:11], v[8:9], v[0:1] op_sel:[0,0] op_sel_hi:[0,1]
	s_nop 0
	v_pk_mul_f32 v[4:5], v[2:3], v[0:1] op_sel:[0,0] op_sel_hi:[0,1]
	v_pk_fma_f32 v[124:125], v[8:9], v[0:1], v[10:11] op_sel:[1,1,0] op_sel_hi:[1,0,1] neg_lo:[0,1,0]
	s_nop 0
	v_pk_fma_f32 v[62:63], v[2:3], v[0:1], v[4:5] op_sel:[1,1,0] op_sel_hi:[1,0,1] neg_lo:[0,1,0]
	v_pk_add_f32 v[2:3], v[72:73], v[78:79] neg_lo:[0,1] neg_hi:[0,1]
	s_nop 0
	v_pk_mul_f32 v[4:5], v[2:3], v[0:1] op_sel:[0,0] op_sel_hi:[0,1]
; __device__ __forceinline__ float2 cmul(float2 a, float2 b) { return make_float2(a.x * b.x - a.y * b.y, a.x * b.y + a.y * b.x); }
; template <int R, bool INV>
; __device__ __forceinline__ void butterflies(c32 (&v)[1 << R], float turns0) {
;     ...
;   for (int kk = 0; kk < R; ++kk) {
;     const int k = INV ? (R - 1 - kk) : kk;
;     const int hd = RAD >> (k + 1);
; #pragma unroll
;     for (int j = 0; j < RAD; ++j) {
;       if ((j & hd) == 0) {
;         const int m = (j & (hd - 1)) * (16 / hd);
;         const float2 c = make_float2(TC[m], INV ? TS[m] : -TS[m]);
;         const float2 twf = cmul(tbs[k], c);
;         const c32 tw = {twf.x, twf.y};
;         const c32 a = v[j], b = v[j + hd];
;         if (!INV) { v[j] = a + b; v[j + hd] = cmul_pk(a - b, tw); }
;         else { const c32 bt = cmul_pk(b, tw); v[j] = a + bt; v[j + hd] = a - bt; }
;       }
;     }
;   }
; template <int LOGN, int R, int DLOG, bool INV, int MODE, class F>
; __device__ __forceinline__ void fft_pass(float2* X, const F& f) {
;     ...
;   auto fetch = [&](int g, c32 (&dst)[RAD]) {
;     const int base = gbase(g);
; #pragma unroll
;     for (int j = 0; j < RAD; ++j) { if constexpr (MODE == 1) { const float2 sv = f(base + (j << DLOG)); dst[j] = (c32){sv.x, sv.y}; } }
;   };
;   c32 nxt[RAD];
;   if constexpr (MODE == 1) fetch(tid0, nxt);
	s_nop 0
	v_pk_fma_f32 v[60:61], v[2:3], v[0:1], v[4:5] op_sel:[1,1,0] op_sel_hi:[1,0,1] neg_lo:[0,1,0]
	v_pk_add_f32 v[2:3], v[76:77], v[82:83] neg_lo:[0,1] neg_hi:[0,1]
	s_nop 0
	v_pk_mul_f32 v[4:5], v[2:3], v[0:1] op_sel:[0,0] op_sel_hi:[0,1]
	s_nop 0
	v_pk_fma_f32 v[58:59], v[2:3], v[0:1], v[4:5] op_sel:[1,1,0] op_sel_hi:[1,0,1] neg_lo:[0,1,0]
	v_pk_add_f32 v[2:3], v[80:81], v[86:87] neg_lo:[0,1] neg_hi:[0,1]
	s_nop 0
	v_pk_mul_f32 v[4:5], v[2:3], v[0:1] op_sel:[0,0] op_sel_hi:[0,1]
	s_nop 0
	v_pk_fma_f32 v[56:57], v[2:3], v[0:1], v[4:5] op_sel:[1,1,0] op_sel_hi:[1,0,1] neg_lo:[0,1,0]
	v_pk_add_f32 v[2:3], v[84:85], v[90:91] neg_lo:[0,1] neg_hi:[0,1]
	s_nop 0
	v_pk_mul_f32 v[4:5], v[2:3], v[0:1] op_sel:[0,0] op_sel_hi:[0,1]
	s_nop 0
	v_pk_fma_f32 v[54:55], v[2:3], v[0:1], v[4:5] op_sel:[1,1,0] op_sel_hi:[1,0,1] neg_lo:[0,1,0]
	v_pk_add_f32 v[2:3], v[88:89], v[94:95] neg_lo:[0,1] neg_hi:[0,1]
	s_nop 0
	v_pk_mul_f32 v[4:5], v[2:3], v[0:1] op_sel:[0,0] op_sel_hi:[0,1]
	s_nop 0
	v_pk_fma_f32 v[52:53], v[2:3], v[0:1], v[4:5] op_sel:[1,1,0] op_sel_hi:[1,0,1] neg_lo:[0,1,0]
	v_pk_add_f32 v[2:3], v[92:93], v[98:99] neg_lo:[0,1] neg_hi:[0,1]
	s_nop 0
	v_pk_mul_f32 v[4:5], v[2:3], v[0:1] op_sel:[0,0] op_sel_hi:[0,1]
	s_nop 0
	v_pk_fma_f32 v[50:51], v[2:3], v[0:1], v[4:5] op_sel:[1,1,0] op_sel_hi:[1,0,1] neg_lo:[0,1,0]
	v_pk_add_f32 v[2:3], v[96:97], v[102:103] neg_lo:[0,1] neg_hi:[0,1]
	s_nop 0
	v_pk_mul_f32 v[4:5], v[2:3], v[0:1] op_sel:[0,0] op_sel_hi:[0,1]
	s_nop 0
	v_pk_fma_f32 v[48:49], v[2:3], v[0:1], v[4:5] op_sel:[1,1,0] op_sel_hi:[1,0,1] neg_lo:[0,1,0]
	v_pk_add_f32 v[2:3], v[100:101], v[106:107] neg_lo:[0,1] neg_hi:[0,1]
	s_nop 0
	v_pk_mul_f32 v[4:5], v[2:3], v[0:1] op_sel:[0,0] op_sel_hi:[0,1]
	s_nop 0
	v_pk_fma_f32 v[46:47], v[2:3], v[0:1], v[4:5] op_sel:[1,1,0] op_sel_hi:[1,0,1] neg_lo:[0,1,0]
	v_pk_add_f32 v[2:3], v[104:105], v[110:111] neg_lo:[0,1] neg_hi:[0,1]
	s_nop 0
	v_pk_mul_f32 v[4:5], v[2:3], v[0:1] op_sel:[0,0] op_sel_hi:[0,1]
	s_nop 0
	v_pk_fma_f32 v[44:45], v[2:3], v[0:1], v[4:5] op_sel:[1,1,0] op_sel_hi:[1,0,1] neg_lo:[0,1,0]
	v_pk_add_f32 v[2:3], v[108:109], v[114:115] neg_lo:[0,1] neg_hi:[0,1]
	s_nop 0
	v_pk_mul_f32 v[4:5], v[2:3], v[0:1] op_sel:[0,0] op_sel_hi:[0,1]
	s_nop 0
	v_pk_fma_f32 v[42:43], v[2:3], v[0:1], v[4:5] op_sel:[1,1,0] op_sel_hi:[1,0,1] neg_lo:[0,1,0]
	v_pk_add_f32 v[2:3], v[112:113], v[118:119] neg_lo:[0,1] neg_hi:[0,1]
	s_nop 0
	v_pk_mul_f32 v[4:5], v[2:3], v[0:1] op_sel:[0,0] op_sel_hi:[0,1]
	s_nop 0
	v_pk_fma_f32 v[40:41], v[2:3], v[0:1], v[4:5] op_sel:[1,1,0] op_sel_hi:[1,0,1] neg_lo:[0,1,0]
	v_pk_add_f32 v[2:3], v[116:117], v[122:123] neg_lo:[0,1] neg_hi:[0,1]
	s_nop 0
	v_pk_mul_f32 v[4:5], v[2:3], v[0:1] op_sel:[0,0] op_sel_hi:[0,1]
	s_nop 0
	v_pk_fma_f32 v[38:39], v[2:3], v[0:1], v[4:5] op_sel:[1,1,0] op_sel_hi:[1,0,1] neg_lo:[0,1,0]
	v_pk_add_f32 v[2:3], v[120:121], v[126:127] neg_lo:[0,1] neg_hi:[0,1]
	s_nop 0
	v_pk_mul_f32 v[4:5], v[2:3], v[0:1] op_sel:[0,0] op_sel_hi:[0,1]
	s_nop 0
	v_pk_fma_f32 v[36:37], v[2:3], v[0:1], v[4:5] op_sel:[1,1,0] op_sel_hi:[1,0,1] neg_lo:[0,1,0]
	v_pk_add_f32 v[2:3], v[124:125], v[128:129] neg_lo:[0,1] neg_hi:[0,1]
	s_nop 0
	v_pk_mul_f32 v[4:5], v[2:3], v[0:1] op_sel:[0,0] op_sel_hi:[0,1]
	s_nop 0
	v_pk_fma_f32 v[34:35], v[2:3], v[0:1], v[4:5] op_sel:[1,1,0] op_sel_hi:[1,0,1] neg_lo:[0,1,0]
	v_and_or_b32 v0, v32, s79, v16
	v_ashrrev_i32_e32 v1, 31, v0
	v_lshl_add_u64 v[14:15], v[0:1], 2, s[34:35]
	v_lshlrev_b32_e32 v207, 2, v0
	v_add_u32_e32 v208, 0x1000, v207
	v_add_u32_e32 v209, 0x2000, v207
	v_add_u32_e32 v210, 0x3000, v207
	v_add_u32_e32 v211, 0x4000, v207
	v_add_u32_e32 v212, 0x5000, v207
	v_add_u32_e32 v213, 0x6000, v207
	v_add_u32_e32 v214, 0x7000, v207
	global_load_dword v207, v207, s[34:35]
	global_load_dword v208, v208, s[34:35]
	global_load_dword v209, v209, s[34:35]
	global_load_dword v210, v210, s[34:35]
	global_load_dword v211, v211, s[34:35]
	global_load_dword v212, v212, s[34:35]
	global_load_dword v213, v213, s[34:35]
	global_load_dword v214, v214, s[34:35]
	s_waitcnt vmcnt(7)
	v_mov_b32_e32 v1, v207
	s_waitcnt vmcnt(0)
	v_lshlrev_b32_e32 v0, 16, v1
	v_and_b32_e32 v1, 0xffff0000, v1
	s_cbranch_vccnz .LBB0_1025
	v_cvt_f32_u32_e32 v2, v16
	v_mul_f32_e32 v3, 0x38800000, v2
	v_sin_f32_e32 v2, v3
	v_cos_f32_e32 v4, v3
	v_pk_mul_f32 v[2:3], v[2:3], v[0:1] op_sel:[0,1] op_sel_hi:[0,0]
	v_pk_fma_f32 v[6:7], v[4:5], v[0:1], v[2:3]
	v_pk_fma_f32 v[0:1], v[4:5], v[0:1], v[2:3] op_sel_hi:[0,1,1] neg_lo:[0,0,1] neg_hi:[0,0,1]
	v_mov_b32_e32 v7, v1
	v_mov_b64_e32 v[0:1], v[6:7]

; __device__ __forceinline__ float2 cmul(float2 a, float2 b) { return make_float2(a.x * b.x - a.y * b.y, a.x * b.y + a.y * b.x); }
; template <int R, bool INV>
; __device__ __forceinline__ void butterflies(c32 (&v)[1 << R], float turns0) {
;     ...
;   for (int kk = 0; kk < R; ++kk) {
;     const int k = INV ? (R - 1 - kk) : kk;
;     const int hd = RAD >> (k + 1);
; #pragma unroll
;     for (int j = 0; j < RAD; ++j) {
;       if ((j & hd) == 0) {
;         const int m = (j & (hd - 1)) * (16 / hd);
;         const float2 c = make_float2(TC[m], INV ? TS[m] : -TS[m]);
;         const float2 twf = cmul(tbs[k], c);
;         const c32 tw = {twf.x, twf.y};
;         const c32 a = v[j], b = v[j + hd];
;         if (!INV) { v[j] = a + b; v[j + hd] = cmul_pk(a - b, tw); }
;         else { const c32 bt = cmul_pk(b, tw); v[j] = a + bt; v[j + hd] = a - bt; }
;       }
;     }
;   }
; template <int LOGN, int R, int DLOG, bool INV, int MODE, class F>
; __device__ __forceinline__ void fft_pass(float2* X, const F& f) {
;     ...
;   for (int g = tid0; g < NGR; g += 512) {
;     const int lo = g & (dmin - 1), base = gbase(g), pb = phys(base);
;     c32 v[RAD];
;     if constexpr (MODE == 1) {
; #pragma unroll
;       for (int j = 0; j < RAD; ++j) v[j] = nxt[j];
;       if (g + 512 < NGR) fetch(g + 512, nxt);
;     } else {
; #pragma unroll
;       for (int j = 0; j < RAD; ++j) v[j] = Xc[(DLOG >= 5) ? pb + j * PSTEP : phys(base + (j << DLOG))];
;     }
;     butterflies<R, INV>(v, (float)lo / (float)(RAD << DLOG));
.LBB0_1063:
	v_and_b32_e32 v172, 0xfffffc00, v171
	v_ashrrev_i32_e32 v173, 2, v172
	v_add_u32_e32 v173, 0, v173
	v_lshlrev_b32_e32 v172, 3, v172
	v_lshlrev_b32_e32 v174, 3, v32
	v_add3_u32 v197, v173, v172, v174
	v_add_u32_e32 v207, 0x800, v197
	v_add_u32_e32 v248, 0x1000, v197
	ds_read_b64 v[172:173], v197
	ds_read_b64 v[174:175], v197 offset:264
	ds_read_b64 v[176:177], v197 offset:528
	ds_read_b64 v[178:179], v197 offset:792
	ds_read_b64 v[180:181], v197 offset:1056
	ds_read_b64 v[182:183], v197 offset:1320
	ds_read_b64 v[184:185], v197 offset:1584
	ds_read_b64 v[186:187], v197 offset:1848
	ds_read_b64 v[188:189], v207 offset:64
	ds_read_b64 v[190:191], v207 offset:328
	ds_read_b64 v[192:193], v207 offset:592
	ds_read_b64 v[194:195], v207 offset:856
	ds_read_b64 v[212:213], v207 offset:1120
	ds_read_b64 v[214:215], v207 offset:1384
	ds_read_b64 v[216:217], v207 offset:1648
	ds_read_b64 v[218:219], v207 offset:1912
	ds_read_b64 v[220:221], v248 offset:128
	ds_read_b64 v[222:223], v248 offset:392
	ds_read_b64 v[224:225], v248 offset:656
	ds_read_b64 v[226:227], v248 offset:920
	ds_read_b64 v[228:229], v248 offset:1184
	ds_read_b64 v[230:231], v248 offset:1448
	ds_read_b64 v[232:233], v248 offset:1712
	ds_read_b64 v[234:235], v248 offset:1976
	v_add_u32_e32 v249, 0x1800, v197
	s_waitcnt lgkmcnt(6)
	v_pk_add_f32 v[198:199], v[172:173], v[220:221]
	v_pk_add_f32 v[172:173], v[172:173], v[220:221] neg_lo:[0,1] neg_hi:[0,1]
	ds_read_b64 v[236:237], v249 offset:192
	ds_read_b64 v[238:239], v249 offset:456
	ds_read_b64 v[240:241], v249 offset:720
	ds_read_b64 v[242:243], v249 offset:984
	ds_read_b64 v[244:245], v249 offset:1248
	ds_read_b64 v[246:247], v249 offset:1512
	ds_read_b64 v[208:209], v249 offset:1776
	ds_read_b64 v[210:211], v249 offset:2040
	v_pk_mul_f32 v[220:221], v[172:173], v[0:1] op_sel:[0,0] op_sel_hi:[0,1]
	v_add_u32_e32 v170, 0x200, v170
	v_pk_fma_f32 v[172:173], v[172:173], v[0:1], v[220:221] op_sel:[1,1,0] op_sel_hi:[1,0,1] neg_lo:[0,1,0]
	v_pk_add_f32 v[220:221], v[174:175], v[222:223]
	v_pk_add_f32 v[174:175], v[174:175], v[222:223] neg_lo:[0,1] neg_hi:[0,1]
	v_cmp_lt_i32_e32 vcc, -1, v170
	v_pk_mul_f32 v[222:223], v[174:175], v[24:25] op_sel:[0,0] op_sel_hi:[0,1]
	v_add_u32_e32 v171, 0x4000, v171
	v_pk_fma_f32 v[174:175], v[174:175], v[24:25], v[222:223] op_sel:[1,1,0] op_sel_hi:[1,0,1] neg_lo:[0,1,0]
	s_waitcnt lgkmcnt(12)
	v_pk_add_f32 v[222:223], v[176:177], v[224:225]
	v_pk_add_f32 v[176:177], v[176:177], v[224:225] neg_lo:[0,1] neg_hi:[0,1]
	s_or_b64 s[14:15], vcc, s[14:15]
	v_pk_mul_f32 v[224:225], v[176:177], v[16:17] op_sel:[0,0] op_sel_hi:[0,1]
	s_nop 0
	v_pk_fma_f32 v[176:177], v[176:177], v[16:17], v[224:225] op_sel:[1,1,0] op_sel_hi:[1,0,1] neg_lo:[0,1,0]
	v_pk_add_f32 v[224:225], v[178:179], v[226:227]
	v_pk_add_f32 v[178:179], v[178:179], v[226:227] neg_lo:[0,1] neg_hi:[0,1]
	s_nop 0
	v_pk_mul_f32 v[226:227], v[178:179], v[8:9] op_sel:[0,0] op_sel_hi:[0,1]
	s_nop 0
	v_pk_fma_f32 v[178:179], v[178:179], v[8:9], v[226:227] op_sel:[1,1,0] op_sel_hi:[1,0,1] neg_lo:[0,1,0]
	s_waitcnt lgkmcnt(10)
	v_pk_add_f32 v[226:227], v[180:181], v[228:229]
	v_pk_add_f32 v[180:181], v[180:181], v[228:229] neg_lo:[0,1] neg_hi:[0,1]
	s_nop 0
	v_pk_mul_f32 v[228:229], v[180:181], v[4:5] op_sel:[0,0] op_sel_hi:[0,1]
	s_nop 0
	v_pk_fma_f32 v[180:181], v[180:181], v[4:5], v[228:229] op_sel:[1,1,0] op_sel_hi:[1,0,1] neg_lo:[0,1,0]
	v_pk_add_f32 v[228:229], v[182:183], v[230:231]
	v_pk_add_f32 v[182:183], v[182:183], v[230:231] neg_lo:[0,1] neg_hi:[0,1]
	s_nop 0
	v_pk_mul_f32 v[230:231], v[182:183], v[14:15] op_sel:[0,0] op_sel_hi:[0,1]
	s_nop 0
	v_pk_fma_f32 v[182:183], v[182:183], v[14:15], v[230:231] op_sel:[1,1,0] op_sel_hi:[1,0,1] neg_lo:[0,1,0]
	s_waitcnt lgkmcnt(8)
	v_pk_add_f32 v[230:231], v[184:185], v[232:233]
	v_pk_add_f32 v[184:185], v[184:185], v[232:233] neg_lo:[0,1] neg_hi:[0,1]
	s_nop 0
	v_pk_mul_f32 v[232:233], v[184:185], v[22:23] op_sel:[0,0] op_sel_hi:[0,1]
	s_nop 0
	v_pk_fma_f32 v[184:185], v[184:185], v[22:23], v[232:233] op_sel:[1,1,0] op_sel_hi:[1,0,1] neg_lo:[0,1,0]
	v_pk_add_f32 v[232:233], v[186:187], v[234:235]
	v_pk_add_f32 v[186:187], v[186:187], v[234:235] neg_lo:[0,1] neg_hi:[0,1]
	s_nop 0
	v_pk_mul_f32 v[234:235], v[186:187], v[30:31] op_sel:[0,0] op_sel_hi:[0,1]
	s_nop 0
	v_pk_fma_f32 v[186:187], v[186:187], v[30:31], v[234:235] op_sel:[1,1,0] op_sel_hi:[1,0,1] neg_lo:[0,1,0]
	s_waitcnt lgkmcnt(6)
	v_pk_add_f32 v[234:235], v[188:189], v[236:237]
	v_pk_add_f32 v[188:189], v[188:189], v[236:237] neg_lo:[0,1] neg_hi:[0,1]
	s_nop 0
	v_pk_mul_f32 v[236:237], v[188:189], v[2:3] op_sel:[0,0] op_sel_hi:[0,1]
	s_nop 0
	v_pk_fma_f32 v[188:189], v[188:189], v[2:3], v[236:237] op_sel:[1,1,0] op_sel_hi:[1,0,1] neg_lo:[0,1,0]
	v_pk_add_f32 v[236:237], v[190:191], v[238:239]
	v_pk_add_f32 v[190:191], v[190:191], v[238:239] neg_lo:[0,1] neg_hi:[0,1]
	s_nop 0
	v_pk_mul_f32 v[238:239], v[190:191], v[28:29] op_sel:[0,0] op_sel_hi:[0,1]
	s_nop 0
	v_pk_fma_f32 v[190:191], v[190:191], v[28:29], v[238:239] op_sel:[1,1,0] op_sel_hi:[1,0,1] neg_lo:[0,1,0]
	s_waitcnt lgkmcnt(4)
	v_pk_add_f32 v[238:239], v[192:193], v[240:241]
	v_pk_add_f32 v[192:193], v[192:193], v[240:241] neg_lo:[0,1] neg_hi:[0,1]
	s_nop 0
	v_pk_mul_f32 v[240:241], v[192:193], v[20:21] op_sel:[0,0] op_sel_hi:[0,1]
	s_nop 0
	v_pk_fma_f32 v[192:193], v[192:193], v[20:21], v[240:241] op_sel:[1,1,0] op_sel_hi:[1,0,1] neg_lo:[0,1,0]
	v_pk_add_f32 v[240:241], v[194:195], v[242:243]
	v_pk_add_f32 v[194:195], v[194:195], v[242:243] neg_lo:[0,1] neg_hi:[0,1]
	s_nop 0
	v_pk_mul_f32 v[242:243], v[194:195], v[12:13] op_sel:[0,0] op_sel_hi:[0,1]
	s_nop 0
	v_pk_fma_f32 v[194:195], v[194:195], v[12:13], v[242:243] op_sel:[1,1,0] op_sel_hi:[1,0,1] neg_lo:[0,1,0]
	s_waitcnt lgkmcnt(2)
; __device__ __forceinline__ float2 cmul(float2 a, float2 b) { return make_float2(a.x * b.x - a.y * b.y, a.x * b.y + a.y * b.x); }
; __device__ __forceinline__ c32 cmul_pk(c32 a, c32 b) {
;   c32 t, r;
;   asm("v_pk_mul_f32 %0, %1, %2 op_sel:[0,0] op_sel_hi:[0,1]" : "=v"(t) : "v"(a), "v"(b));
;   asm("v_pk_fma_f32 %0, %1, %2, %3 op_sel:[1,1,0] op_sel_hi:[1,0,1] neg_lo:[0,1,0]" : "=v"(r) : "v"(a), "v"(b), "v"(t));
;   return r;
; }
; template <int R, bool INV>
; __device__ __forceinline__ void butterflies(c32 (&v)[1 << R], float turns0) {
;     ...
;   for (int kk = 0; kk < R; ++kk) {
;     const int k = INV ? (R - 1 - kk) : kk;
;     const int hd = RAD >> (k + 1);
; #pragma unroll
;     for (int j = 0; j < RAD; ++j) {
;       if ((j & hd) == 0) {
;         const int m = (j & (hd - 1)) * (16 / hd);
;         const float2 c = make_float2(TC[m], INV ? TS[m] : -TS[m]);
;         const float2 twf = cmul(tbs[k], c);
;         const c32 tw = {twf.x, twf.y};
;         const c32 a = v[j], b = v[j + hd];
;         if (!INV) { v[j] = a + b; v[j + hd] = cmul_pk(a - b, tw); }
;         else { const c32 bt = cmul_pk(b, tw); v[j] = a + bt; v[j + hd] = a - bt; }
;       }
;     }
;   }
	v_pk_add_f32 v[242:243], v[212:213], v[244:245]
	v_pk_add_f32 v[212:213], v[212:213], v[244:245] neg_lo:[0,1] neg_hi:[0,1]
	s_nop 0
	v_pk_mul_f32 v[244:245], v[212:213], v[6:7] op_sel:[0,0] op_sel_hi:[0,1]
	s_nop 0
	v_pk_fma_f32 v[212:213], v[212:213], v[6:7], v[244:245] op_sel:[1,1,0] op_sel_hi:[1,0,1] neg_lo:[0,1,0]
	v_pk_add_f32 v[244:245], v[214:215], v[246:247]
	v_pk_add_f32 v[214:215], v[214:215], v[246:247] neg_lo:[0,1] neg_hi:[0,1]
	s_nop 0
	v_pk_mul_f32 v[246:247], v[214:215], v[10:11] op_sel:[0,0] op_sel_hi:[0,1]
	s_nop 0
	v_pk_fma_f32 v[214:215], v[214:215], v[10:11], v[246:247] op_sel:[1,1,0] op_sel_hi:[1,0,1] neg_lo:[0,1,0]
	s_waitcnt lgkmcnt(0)
	v_pk_add_f32 v[246:247], v[216:217], v[208:209]
	v_pk_add_f32 v[208:209], v[216:217], v[208:209] neg_lo:[0,1] neg_hi:[0,1]
	s_nop 0
	v_pk_mul_f32 v[216:217], v[208:209], v[18:19] op_sel:[0,0] op_sel_hi:[0,1]
	s_nop 0
	v_pk_fma_f32 v[208:209], v[208:209], v[18:19], v[216:217] op_sel:[1,1,0] op_sel_hi:[1,0,1] neg_lo:[0,1,0]
	v_pk_add_f32 v[216:217], v[218:219], v[210:211]
	v_pk_add_f32 v[210:211], v[218:219], v[210:211] neg_lo:[0,1] neg_hi:[0,1]
	s_nop 0
	v_pk_mul_f32 v[218:219], v[210:211], v[26:27] op_sel:[0,0] op_sel_hi:[0,1]
	s_nop 0
	v_pk_fma_f32 v[210:211], v[210:211], v[26:27], v[218:219] op_sel:[1,1,0] op_sel_hi:[1,0,1] neg_lo:[0,1,0]
	v_pk_add_f32 v[218:219], v[198:199], v[234:235]
	v_pk_add_f32 v[198:199], v[198:199], v[234:235] neg_lo:[0,1] neg_hi:[0,1]
	s_nop 0
	v_pk_mul_f32 v[234:235], v[198:199], v[130:131] op_sel:[0,0] op_sel_hi:[0,1]
	s_nop 0
	v_pk_fma_f32 v[198:199], v[198:199], v[130:131], v[234:235] op_sel:[1,1,0] op_sel_hi:[1,0,1] neg_lo:[0,1,0]
	v_pk_add_f32 v[234:235], v[220:221], v[236:237]
	v_pk_add_f32 v[220:221], v[220:221], v[236:237] neg_lo:[0,1] neg_hi:[0,1]
	s_nop 0
	v_pk_mul_f32 v[236:237], v[220:221], v[138:139] op_sel:[0,0] op_sel_hi:[0,1]
	s_nop 0
	v_pk_fma_f32 v[220:221], v[220:221], v[138:139], v[236:237] op_sel:[1,1,0] op_sel_hi:[1,0,1] neg_lo:[0,1,0]
	v_pk_add_f32 v[236:237], v[222:223], v[238:239]
	v_pk_add_f32 v[222:223], v[222:223], v[238:239] neg_lo:[0,1] neg_hi:[0,1]
	s_nop 0
	v_pk_mul_f32 v[238:239], v[222:223], v[134:135] op_sel:[0,0] op_sel_hi:[0,1]
	s_nop 0
	v_pk_fma_f32 v[222:223], v[222:223], v[134:135], v[238:239] op_sel:[1,1,0] op_sel_hi:[1,0,1] neg_lo:[0,1,0]
	v_pk_add_f32 v[238:239], v[224:225], v[240:241]
	v_pk_add_f32 v[224:225], v[224:225], v[240:241] neg_lo:[0,1] neg_hi:[0,1]
	s_nop 0
	v_pk_mul_f32 v[240:241], v[224:225], v[144:145] op_sel:[0,0] op_sel_hi:[0,1]
	s_nop 0
	v_pk_fma_f32 v[224:225], v[224:225], v[144:145], v[240:241] op_sel:[1,1,0] op_sel_hi:[1,0,1] neg_lo:[0,1,0]
	v_pk_add_f32 v[240:241], v[226:227], v[242:243]
	v_pk_add_f32 v[226:227], v[226:227], v[242:243] neg_lo:[0,1] neg_hi:[0,1]
	s_nop 0
	v_pk_mul_f32 v[242:243], v[226:227], v[132:133] op_sel:[0,0] op_sel_hi:[0,1]
	s_nop 0
	v_pk_fma_f32 v[226:227], v[226:227], v[132:133], v[242:243] op_sel:[1,1,0] op_sel_hi:[1,0,1] neg_lo:[0,1,0]
	v_pk_add_f32 v[242:243], v[228:229], v[244:245]
	v_pk_add_f32 v[228:229], v[228:229], v[244:245] neg_lo:[0,1] neg_hi:[0,1]
	s_nop 0
	v_pk_mul_f32 v[244:245], v[228:229], v[142:143] op_sel:[0,0] op_sel_hi:[0,1]
	s_nop 0
	v_pk_fma_f32 v[228:229], v[228:229], v[142:143], v[244:245] op_sel:[1,1,0] op_sel_hi:[1,0,1] neg_lo:[0,1,0]
	v_pk_add_f32 v[244:245], v[230:231], v[246:247]
	v_pk_add_f32 v[230:231], v[230:231], v[246:247] neg_lo:[0,1] neg_hi:[0,1]
	s_nop 0
	v_pk_mul_f32 v[246:247], v[230:231], v[136:137] op_sel:[0,0] op_sel_hi:[0,1]
	s_nop 0
	v_pk_fma_f32 v[230:231], v[230:231], v[136:137], v[246:247] op_sel:[1,1,0] op_sel_hi:[1,0,1] neg_lo:[0,1,0]
	v_pk_add_f32 v[246:247], v[232:233], v[216:217]
	v_pk_add_f32 v[216:217], v[232:233], v[216:217] neg_lo:[0,1] neg_hi:[0,1]
	s_nop 0
	v_pk_mul_f32 v[232:233], v[216:217], v[140:141] op_sel:[0,0] op_sel_hi:[0,1]
	s_nop 0
	v_pk_fma_f32 v[216:217], v[216:217], v[140:141], v[232:233] op_sel:[1,1,0] op_sel_hi:[1,0,1] neg_lo:[0,1,0]
	v_pk_add_f32 v[232:233], v[172:173], v[188:189]
	v_pk_add_f32 v[172:173], v[172:173], v[188:189] neg_lo:[0,1] neg_hi:[0,1]
	s_nop 0
	v_pk_mul_f32 v[188:189], v[172:173], v[130:131] op_sel:[0,0] op_sel_hi:[0,1]
	s_nop 0
	v_pk_fma_f32 v[172:173], v[172:173], v[130:131], v[188:189] op_sel:[1,1,0] op_sel_hi:[1,0,1] neg_lo:[0,1,0]
	v_pk_add_f32 v[188:189], v[174:175], v[190:191]
	v_pk_add_f32 v[174:175], v[174:175], v[190:191] neg_lo:[0,1] neg_hi:[0,1]
	s_nop 0
	v_pk_mul_f32 v[190:191], v[174:175], v[138:139] op_sel:[0,0] op_sel_hi:[0,1]
	s_nop 0
	v_pk_fma_f32 v[174:175], v[174:175], v[138:139], v[190:191] op_sel:[1,1,0] op_sel_hi:[1,0,1] neg_lo:[0,1,0]
	v_pk_add_f32 v[190:191], v[176:177], v[192:193]
	v_pk_add_f32 v[176:177], v[176:177], v[192:193] neg_lo:[0,1] neg_hi:[0,1]
	s_nop 0
	v_pk_mul_f32 v[192:193], v[176:177], v[134:135] op_sel:[0,0] op_sel_hi:[0,1]
	s_nop 0
	v_pk_fma_f32 v[176:177], v[176:177], v[134:135], v[192:193] op_sel:[1,1,0] op_sel_hi:[1,0,1] neg_lo:[0,1,0]
	v_pk_add_f32 v[192:193], v[178:179], v[194:195]
	v_pk_add_f32 v[178:179], v[178:179], v[194:195] neg_lo:[0,1] neg_hi:[0,1]
	s_nop 0
	v_pk_mul_f32 v[194:195], v[178:179], v[144:145] op_sel:[0,0] op_sel_hi:[0,1]
	s_nop 0
	v_pk_fma_f32 v[178:179], v[178:179], v[144:145], v[194:195] op_sel:[1,1,0] op_sel_hi:[1,0,1] neg_lo:[0,1,0]
	v_pk_add_f32 v[194:195], v[180:181], v[212:213]
	v_pk_add_f32 v[180:181], v[180:181], v[212:213] neg_lo:[0,1] neg_hi:[0,1]
	s_nop 0
	v_pk_mul_f32 v[212:213], v[180:181], v[132:133] op_sel:[0,0] op_sel_hi:[0,1]
	s_nop 0
	v_pk_fma_f32 v[180:181], v[180:181], v[132:133], v[212:213] op_sel:[1,1,0] op_sel_hi:[1,0,1] neg_lo:[0,1,0]
	v_pk_add_f32 v[212:213], v[182:183], v[214:215]
; __device__ __forceinline__ float2 cmul(float2 a, float2 b) { return make_float2(a.x * b.x - a.y * b.y, a.x * b.y + a.y * b.x); }
; __device__ __forceinline__ c32 cmul_pk(c32 a, c32 b) {
;   c32 t, r;
;   asm("v_pk_mul_f32 %0, %1, %2 op_sel:[0,0] op_sel_hi:[0,1]" : "=v"(t) : "v"(a), "v"(b));
;   asm("v_pk_fma_f32 %0, %1, %2, %3 op_sel:[1,1,0] op_sel_hi:[1,0,1] neg_lo:[0,1,0]" : "=v"(r) : "v"(a), "v"(b), "v"(t));
;   return r;
; }
; template <int R, bool INV>
; __device__ __forceinline__ void butterflies(c32 (&v)[1 << R], float turns0) {
;     ...
;   for (int kk = 0; kk < R; ++kk) {
;     const int k = INV ? (R - 1 - kk) : kk;
;     const int hd = RAD >> (k + 1);
; #pragma unroll
;     for (int j = 0; j < RAD; ++j) {
;       if ((j & hd) == 0) {
;         const int m = (j & (hd - 1)) * (16 / hd);
;         const float2 c = make_float2(TC[m], INV ? TS[m] : -TS[m]);
;         const float2 twf = cmul(tbs[k], c);
;         const c32 tw = {twf.x, twf.y};
;         const c32 a = v[j], b = v[j + hd];
;         if (!INV) { v[j] = a + b; v[j + hd] = cmul_pk(a - b, tw); }
;         else { const c32 bt = cmul_pk(b, tw); v[j] = a + bt; v[j + hd] = a - bt; }
;       }
;     }
;   }
	v_pk_add_f32 v[182:183], v[182:183], v[214:215] neg_lo:[0,1] neg_hi:[0,1]
	s_nop 0
	v_pk_mul_f32 v[214:215], v[182:183], v[142:143] op_sel:[0,0] op_sel_hi:[0,1]
	s_nop 0
	v_pk_fma_f32 v[182:183], v[182:183], v[142:143], v[214:215] op_sel:[1,1,0] op_sel_hi:[1,0,1] neg_lo:[0,1,0]
	v_pk_add_f32 v[214:215], v[184:185], v[208:209]
	v_pk_add_f32 v[184:185], v[184:185], v[208:209] neg_lo:[0,1] neg_hi:[0,1]
	s_nop 0
	v_pk_mul_f32 v[208:209], v[184:185], v[136:137] op_sel:[0,0] op_sel_hi:[0,1]
	s_nop 0
	v_pk_fma_f32 v[184:185], v[184:185], v[136:137], v[208:209] op_sel:[1,1,0] op_sel_hi:[1,0,1] neg_lo:[0,1,0]
	v_pk_add_f32 v[208:209], v[186:187], v[210:211]
	v_pk_add_f32 v[186:187], v[186:187], v[210:211] neg_lo:[0,1] neg_hi:[0,1]
	s_nop 0
	v_pk_mul_f32 v[210:211], v[186:187], v[140:141] op_sel:[0,0] op_sel_hi:[0,1]
	s_nop 0
	v_pk_fma_f32 v[186:187], v[186:187], v[140:141], v[210:211] op_sel:[1,1,0] op_sel_hi:[1,0,1] neg_lo:[0,1,0]
	v_pk_add_f32 v[210:211], v[218:219], v[240:241]
	v_pk_add_f32 v[218:219], v[218:219], v[240:241] neg_lo:[0,1] neg_hi:[0,1]
	s_nop 0
	v_pk_mul_f32 v[240:241], v[218:219], v[146:147] op_sel:[0,0] op_sel_hi:[0,1]
	s_nop 0
	v_pk_fma_f32 v[218:219], v[218:219], v[146:147], v[240:241] op_sel:[1,1,0] op_sel_hi:[1,0,1] neg_lo:[0,1,0]
	v_pk_add_f32 v[240:241], v[234:235], v[242:243]
	v_pk_add_f32 v[234:235], v[234:235], v[242:243] neg_lo:[0,1] neg_hi:[0,1]
	s_nop 0
	v_pk_mul_f32 v[242:243], v[234:235], v[150:151] op_sel:[0,0] op_sel_hi:[0,1]
	s_nop 0
	v_pk_fma_f32 v[234:235], v[234:235], v[150:151], v[242:243] op_sel:[1,1,0] op_sel_hi:[1,0,1] neg_lo:[0,1,0]
	v_pk_add_f32 v[242:243], v[236:237], v[244:245]
	v_pk_add_f32 v[236:237], v[236:237], v[244:245] neg_lo:[0,1] neg_hi:[0,1]
	s_nop 0
	v_pk_mul_f32 v[244:245], v[236:237], v[148:149] op_sel:[0,0] op_sel_hi:[0,1]
	s_nop 0
	v_pk_fma_f32 v[236:237], v[236:237], v[148:149], v[244:245] op_sel:[1,1,0] op_sel_hi:[1,0,1] neg_lo:[0,1,0]
	v_pk_add_f32 v[244:245], v[238:239], v[246:247]
	v_pk_add_f32 v[238:239], v[238:239], v[246:247] neg_lo:[0,1] neg_hi:[0,1]
	s_nop 0
	v_pk_mul_f32 v[246:247], v[238:239], v[152:153] op_sel:[0,0] op_sel_hi:[0,1]
	s_nop 0
	v_pk_fma_f32 v[238:239], v[238:239], v[152:153], v[246:247] op_sel:[1,1,0] op_sel_hi:[1,0,1] neg_lo:[0,1,0]
	v_pk_add_f32 v[246:247], v[198:199], v[226:227]
	v_pk_add_f32 v[198:199], v[198:199], v[226:227] neg_lo:[0,1] neg_hi:[0,1]
	s_nop 0
	v_pk_mul_f32 v[226:227], v[198:199], v[146:147] op_sel:[0,0] op_sel_hi:[0,1]
	s_nop 0
	v_pk_fma_f32 v[198:199], v[198:199], v[146:147], v[226:227] op_sel:[1,1,0] op_sel_hi:[1,0,1] neg_lo:[0,1,0]
	v_pk_add_f32 v[226:227], v[220:221], v[228:229]
	v_pk_add_f32 v[220:221], v[220:221], v[228:229] neg_lo:[0,1] neg_hi:[0,1]
	s_nop 0
	v_pk_mul_f32 v[228:229], v[220:221], v[150:151] op_sel:[0,0] op_sel_hi:[0,1]
	s_nop 0
	v_pk_fma_f32 v[220:221], v[220:221], v[150:151], v[228:229] op_sel:[1,1,0] op_sel_hi:[1,0,1] neg_lo:[0,1,0]
	v_pk_add_f32 v[228:229], v[222:223], v[230:231]
	v_pk_add_f32 v[222:223], v[222:223], v[230:231] neg_lo:[0,1] neg_hi:[0,1]
	s_nop 0
	v_pk_mul_f32 v[230:231], v[222:223], v[148:149] op_sel:[0,0] op_sel_hi:[0,1]
	s_nop 0
	v_pk_fma_f32 v[222:223], v[222:223], v[148:149], v[230:231] op_sel:[1,1,0] op_sel_hi:[1,0,1] neg_lo:[0,1,0]
	v_pk_add_f32 v[230:231], v[224:225], v[216:217]
	v_pk_add_f32 v[216:217], v[224:225], v[216:217] neg_lo:[0,1] neg_hi:[0,1]
	s_nop 0
	v_pk_mul_f32 v[224:225], v[216:217], v[152:153] op_sel:[0,0] op_sel_hi:[0,1]
	s_nop 0
	v_pk_fma_f32 v[216:217], v[216:217], v[152:153], v[224:225] op_sel:[1,1,0] op_sel_hi:[1,0,1] neg_lo:[0,1,0]
	v_pk_add_f32 v[224:225], v[232:233], v[194:195]
	v_pk_add_f32 v[194:195], v[232:233], v[194:195] neg_lo:[0,1] neg_hi:[0,1]
	s_nop 0
	v_pk_mul_f32 v[232:233], v[194:195], v[146:147] op_sel:[0,0] op_sel_hi:[0,1]
	s_nop 0
	v_pk_fma_f32 v[194:195], v[194:195], v[146:147], v[232:233] op_sel:[1,1,0] op_sel_hi:[1,0,1] neg_lo:[0,1,0]
	v_pk_add_f32 v[232:233], v[188:189], v[212:213]
	v_pk_add_f32 v[188:189], v[188:189], v[212:213] neg_lo:[0,1] neg_hi:[0,1]
	s_nop 0
	v_pk_mul_f32 v[212:213], v[188:189], v[150:151] op_sel:[0,0] op_sel_hi:[0,1]
	s_nop 0
	v_pk_fma_f32 v[188:189], v[188:189], v[150:151], v[212:213] op_sel:[1,1,0] op_sel_hi:[1,0,1] neg_lo:[0,1,0]
	v_pk_add_f32 v[212:213], v[190:191], v[214:215]
	v_pk_add_f32 v[190:191], v[190:191], v[214:215] neg_lo:[0,1] neg_hi:[0,1]
	s_nop 0
	v_pk_mul_f32 v[214:215], v[190:191], v[148:149] op_sel:[0,0] op_sel_hi:[0,1]
	s_nop 0
	v_pk_fma_f32 v[190:191], v[190:191], v[148:149], v[214:215] op_sel:[1,1,0] op_sel_hi:[1,0,1] neg_lo:[0,1,0]
	v_pk_add_f32 v[214:215], v[192:193], v[208:209]
	v_pk_add_f32 v[192:193], v[192:193], v[208:209] neg_lo:[0,1] neg_hi:[0,1]
	s_nop 0
	v_pk_mul_f32 v[208:209], v[192:193], v[152:153] op_sel:[0,0] op_sel_hi:[0,1]
	s_nop 0
	v_pk_fma_f32 v[192:193], v[192:193], v[152:153], v[208:209] op_sel:[1,1,0] op_sel_hi:[1,0,1] neg_lo:[0,1,0]
	v_pk_add_f32 v[208:209], v[172:173], v[180:181]
	v_pk_add_f32 v[172:173], v[172:173], v[180:181] neg_lo:[0,1] neg_hi:[0,1]
	s_nop 0
	v_pk_mul_f32 v[180:181], v[172:173], v[146:147] op_sel:[0,0] op_sel_hi:[0,1]
	s_nop 0
	v_pk_fma_f32 v[172:173], v[172:173], v[146:147], v[180:181] op_sel:[1,1,0] op_sel_hi:[1,0,1] neg_lo:[0,1,0]
	v_pk_add_f32 v[180:181], v[174:175], v[182:183]
	v_pk_add_f32 v[174:175], v[174:175], v[182:183] neg_lo:[0,1] neg_hi:[0,1]
	s_nop 0
	v_pk_mul_f32 v[182:183], v[174:175], v[150:151] op_sel:[0,0] op_sel_hi:[0,1]
	s_nop 0
	v_pk_fma_f32 v[174:175], v[174:175], v[150:151], v[182:183] op_sel:[1,1,0] op_sel_hi:[1,0,1] neg_lo:[0,1,0]
	v_pk_add_f32 v[182:183], v[176:177], v[184:185]
	v_pk_add_f32 v[176:177], v[176:177], v[184:185] neg_lo:[0,1] neg_hi:[0,1]
; __device__ __forceinline__ float2 cmul(float2 a, float2 b) { return make_float2(a.x * b.x - a.y * b.y, a.x * b.y + a.y * b.x); }
; __device__ __forceinline__ c32 cmul_pk(c32 a, c32 b) {
;   c32 t, r;
;   asm("v_pk_mul_f32 %0, %1, %2 op_sel:[0,0] op_sel_hi:[0,1]" : "=v"(t) : "v"(a), "v"(b));
;   asm("v_pk_fma_f32 %0, %1, %2, %3 op_sel:[1,1,0] op_sel_hi:[1,0,1] neg_lo:[0,1,0]" : "=v"(r) : "v"(a), "v"(b), "v"(t));
;   return r;
; }
; template <int R, bool INV>
; __device__ __forceinline__ void butterflies(c32 (&v)[1 << R], float turns0) {
;     ...
;   for (int kk = 0; kk < R; ++kk) {
;     const int k = INV ? (R - 1 - kk) : kk;
;     const int hd = RAD >> (k + 1);
; #pragma unroll
;     for (int j = 0; j < RAD; ++j) {
;       if ((j & hd) == 0) {
;         const int m = (j & (hd - 1)) * (16 / hd);
;         const float2 c = make_float2(TC[m], INV ? TS[m] : -TS[m]);
;         const float2 twf = cmul(tbs[k], c);
;         const c32 tw = {twf.x, twf.y};
;         const c32 a = v[j], b = v[j + hd];
;         if (!INV) { v[j] = a + b; v[j + hd] = cmul_pk(a - b, tw); }
;         else { const c32 bt = cmul_pk(b, tw); v[j] = a + bt; v[j + hd] = a - bt; }
;       }
;     }
;   }
	s_nop 0
	v_pk_mul_f32 v[184:185], v[176:177], v[148:149] op_sel:[0,0] op_sel_hi:[0,1]
	s_nop 0
	v_pk_fma_f32 v[176:177], v[176:177], v[148:149], v[184:185] op_sel:[1,1,0] op_sel_hi:[1,0,1] neg_lo:[0,1,0]
	v_pk_add_f32 v[184:185], v[178:179], v[186:187]
	v_pk_add_f32 v[178:179], v[178:179], v[186:187] neg_lo:[0,1] neg_hi:[0,1]
	s_nop 0
	v_pk_mul_f32 v[186:187], v[178:179], v[152:153] op_sel:[0,0] op_sel_hi:[0,1]
	s_nop 0
	v_pk_fma_f32 v[178:179], v[178:179], v[152:153], v[186:187] op_sel:[1,1,0] op_sel_hi:[1,0,1] neg_lo:[0,1,0]
	v_pk_add_f32 v[186:187], v[210:211], v[242:243]
	v_pk_add_f32 v[210:211], v[210:211], v[242:243] neg_lo:[0,1] neg_hi:[0,1]
	s_nop 0
	v_pk_mul_f32 v[242:243], v[210:211], v[154:155] op_sel:[0,0] op_sel_hi:[0,1]
	s_nop 0
	v_pk_fma_f32 v[210:211], v[210:211], v[154:155], v[242:243] op_sel:[1,1,0] op_sel_hi:[1,0,1] neg_lo:[0,1,0]
	v_pk_add_f32 v[242:243], v[240:241], v[244:245]
	v_pk_add_f32 v[240:241], v[240:241], v[244:245] neg_lo:[0,1] neg_hi:[0,1]
	s_nop 0
	v_pk_mul_f32 v[244:245], v[240:241], v[156:157] op_sel:[0,0] op_sel_hi:[0,1]
	s_nop 0
	v_pk_fma_f32 v[240:241], v[240:241], v[156:157], v[244:245] op_sel:[1,1,0] op_sel_hi:[1,0,1] neg_lo:[0,1,0]
	v_pk_add_f32 v[244:245], v[218:219], v[236:237]
	v_pk_add_f32 v[218:219], v[218:219], v[236:237] neg_lo:[0,1] neg_hi:[0,1]
	s_nop 0
	v_pk_mul_f32 v[236:237], v[218:219], v[154:155] op_sel:[0,0] op_sel_hi:[0,1]
	s_nop 0
	v_pk_fma_f32 v[218:219], v[218:219], v[154:155], v[236:237] op_sel:[1,1,0] op_sel_hi:[1,0,1] neg_lo:[0,1,0]
	v_pk_add_f32 v[236:237], v[234:235], v[238:239]
	v_pk_add_f32 v[234:235], v[234:235], v[238:239] neg_lo:[0,1] neg_hi:[0,1]
	s_nop 0
	v_pk_mul_f32 v[238:239], v[234:235], v[156:157] op_sel:[0,0] op_sel_hi:[0,1]
	s_nop 0
	v_pk_fma_f32 v[234:235], v[234:235], v[156:157], v[238:239] op_sel:[1,1,0] op_sel_hi:[1,0,1] neg_lo:[0,1,0]
	v_pk_add_f32 v[238:239], v[246:247], v[228:229]
	v_pk_add_f32 v[228:229], v[246:247], v[228:229] neg_lo:[0,1] neg_hi:[0,1]
	s_nop 0
	v_pk_mul_f32 v[246:247], v[228:229], v[154:155] op_sel:[0,0] op_sel_hi:[0,1]
	s_nop 0
	v_pk_fma_f32 v[228:229], v[228:229], v[154:155], v[246:247] op_sel:[1,1,0] op_sel_hi:[1,0,1] neg_lo:[0,1,0]
	v_pk_add_f32 v[246:247], v[226:227], v[230:231]
	v_pk_add_f32 v[226:227], v[226:227], v[230:231] neg_lo:[0,1] neg_hi:[0,1]
	s_nop 0
	v_pk_mul_f32 v[230:231], v[226:227], v[156:157] op_sel:[0,0] op_sel_hi:[0,1]
	s_nop 0
	v_pk_fma_f32 v[226:227], v[226:227], v[156:157], v[230:231] op_sel:[1,1,0] op_sel_hi:[1,0,1] neg_lo:[0,1,0]
	v_pk_add_f32 v[230:231], v[198:199], v[222:223]
	v_pk_add_f32 v[198:199], v[198:199], v[222:223] neg_lo:[0,1] neg_hi:[0,1]
	s_nop 0
	v_pk_mul_f32 v[222:223], v[198:199], v[154:155] op_sel:[0,0] op_sel_hi:[0,1]
	s_nop 0
	v_pk_fma_f32 v[198:199], v[198:199], v[154:155], v[222:223] op_sel:[1,1,0] op_sel_hi:[1,0,1] neg_lo:[0,1,0]
	v_pk_add_f32 v[222:223], v[220:221], v[216:217]
	v_pk_add_f32 v[216:217], v[220:221], v[216:217] neg_lo:[0,1] neg_hi:[0,1]
	s_nop 0
	v_pk_mul_f32 v[220:221], v[216:217], v[156:157] op_sel:[0,0] op_sel_hi:[0,1]
	s_nop 0
	v_pk_fma_f32 v[216:217], v[216:217], v[156:157], v[220:221] op_sel:[1,1,0] op_sel_hi:[1,0,1] neg_lo:[0,1,0]
	v_pk_add_f32 v[220:221], v[224:225], v[212:213]
	v_pk_add_f32 v[212:213], v[224:225], v[212:213] neg_lo:[0,1] neg_hi:[0,1]
	s_nop 0
	v_pk_mul_f32 v[224:225], v[212:213], v[154:155] op_sel:[0,0] op_sel_hi:[0,1]
	s_nop 0
	v_pk_fma_f32 v[212:213], v[212:213], v[154:155], v[224:225] op_sel:[1,1,0] op_sel_hi:[1,0,1] neg_lo:[0,1,0]
	v_pk_add_f32 v[224:225], v[232:233], v[214:215]
	v_pk_add_f32 v[214:215], v[232:233], v[214:215] neg_lo:[0,1] neg_hi:[0,1]
	s_nop 0
	v_pk_mul_f32 v[232:233], v[214:215], v[156:157] op_sel:[0,0] op_sel_hi:[0,1]
	s_nop 0
	v_pk_fma_f32 v[214:215], v[214:215], v[156:157], v[232:233] op_sel:[1,1,0] op_sel_hi:[1,0,1] neg_lo:[0,1,0]
	v_pk_add_f32 v[232:233], v[194:195], v[190:191]
	v_pk_add_f32 v[190:191], v[194:195], v[190:191] neg_lo:[0,1] neg_hi:[0,1]
	s_nop 0
	v_pk_mul_f32 v[194:195], v[190:191], v[154:155] op_sel:[0,0] op_sel_hi:[0,1]
	s_nop 0
	v_pk_fma_f32 v[190:191], v[190:191], v[154:155], v[194:195] op_sel:[1,1,0] op_sel_hi:[1,0,1] neg_lo:[0,1,0]
	v_pk_add_f32 v[194:195], v[188:189], v[192:193]
	v_pk_add_f32 v[188:189], v[188:189], v[192:193] neg_lo:[0,1] neg_hi:[0,1]
	s_nop 0
	v_pk_mul_f32 v[192:193], v[188:189], v[156:157] op_sel:[0,0] op_sel_hi:[0,1]
	s_nop 0
	v_pk_fma_f32 v[188:189], v[188:189], v[156:157], v[192:193] op_sel:[1,1,0] op_sel_hi:[1,0,1] neg_lo:[0,1,0]
	v_pk_add_f32 v[192:193], v[208:209], v[182:183]
	v_pk_add_f32 v[182:183], v[208:209], v[182:183] neg_lo:[0,1] neg_hi:[0,1]
	s_nop 0
	v_pk_mul_f32 v[208:209], v[182:183], v[154:155] op_sel:[0,0] op_sel_hi:[0,1]
	s_nop 0
	v_pk_fma_f32 v[182:183], v[182:183], v[154:155], v[208:209] op_sel:[1,1,0] op_sel_hi:[1,0,1] neg_lo:[0,1,0]
	v_pk_add_f32 v[208:209], v[180:181], v[184:185]
	v_pk_add_f32 v[180:181], v[180:181], v[184:185] neg_lo:[0,1] neg_hi:[0,1]
	s_nop 0
	v_pk_mul_f32 v[184:185], v[180:181], v[156:157] op_sel:[0,0] op_sel_hi:[0,1]
	s_nop 0
	v_pk_fma_f32 v[180:181], v[180:181], v[156:157], v[184:185] op_sel:[1,1,0] op_sel_hi:[1,0,1] neg_lo:[0,1,0]
	v_pk_add_f32 v[184:185], v[172:173], v[176:177]
	v_pk_add_f32 v[172:173], v[172:173], v[176:177] neg_lo:[0,1] neg_hi:[0,1]
	s_nop 0
	v_pk_mul_f32 v[176:177], v[172:173], v[154:155] op_sel:[0,0] op_sel_hi:[0,1]
	s_nop 0
	v_pk_fma_f32 v[172:173], v[172:173], v[154:155], v[176:177] op_sel:[1,1,0] op_sel_hi:[1,0,1] neg_lo:[0,1,0]
	v_pk_add_f32 v[176:177], v[174:175], v[178:179]
	v_pk_add_f32 v[174:175], v[174:175], v[178:179] neg_lo:[0,1] neg_hi:[0,1]
	s_nop 0
; __device__ __forceinline__ float2 cmul(float2 a, float2 b) { return make_float2(a.x * b.x - a.y * b.y, a.x * b.y + a.y * b.x); }
; template <int R, bool INV>
; __device__ __forceinline__ void butterflies(c32 (&v)[1 << R], float turns0) {
;     ...
;   for (int kk = 0; kk < R; ++kk) {
;     const int k = INV ? (R - 1 - kk) : kk;
;     const int hd = RAD >> (k + 1);
; #pragma unroll
;     for (int j = 0; j < RAD; ++j) {
;       if ((j & hd) == 0) {
;         const int m = (j & (hd - 1)) * (16 / hd);
;         const float2 c = make_float2(TC[m], INV ? TS[m] : -TS[m]);
;         const float2 twf = cmul(tbs[k], c);
;         const c32 tw = {twf.x, twf.y};
;         const c32 a = v[j], b = v[j + hd];
;         if (!INV) { v[j] = a + b; v[j + hd] = cmul_pk(a - b, tw); }
;         else { const c32 bt = cmul_pk(b, tw); v[j] = a + bt; v[j + hd] = a - bt; }
;       }
;     }
;   }
; template <int LOGN, int R, int DLOG, bool INV, int MODE, class F>
; __device__ __forceinline__ void fft_pass(float2* X, const F& f) {
;     ...
;       for (int j = 0; j < RAD; ++j) Xc[(DLOG >= 5) ? pb + j * PSTEP : phys(base + (j << DLOG))] = v[j];
	v_pk_mul_f32 v[178:179], v[174:175], v[156:157] op_sel:[0,0] op_sel_hi:[0,1]
	s_nop 0
	v_pk_fma_f32 v[174:175], v[174:175], v[156:157], v[178:179] op_sel:[1,1,0] op_sel_hi:[1,0,1] neg_lo:[0,1,0]
	v_pk_add_f32 v[178:179], v[186:187], v[242:243]
	v_pk_add_f32 v[186:187], v[186:187], v[242:243] neg_lo:[0,1] neg_hi:[0,1]
	s_nop 0
	v_pk_mul_f32 v[242:243], v[186:187], v[158:159] op_sel:[0,0] op_sel_hi:[0,1]
	s_nop 0
	v_pk_fma_f32 v[186:187], v[186:187], v[158:159], v[242:243] op_sel:[1,1,0] op_sel_hi:[1,0,1] neg_lo:[0,1,0]
	v_pk_add_f32 v[242:243], v[210:211], v[240:241]
	v_pk_add_f32 v[210:211], v[210:211], v[240:241] neg_lo:[0,1] neg_hi:[0,1]
	s_nop 0
	v_pk_mul_f32 v[240:241], v[210:211], v[158:159] op_sel:[0,0] op_sel_hi:[0,1]
	s_nop 0
	v_pk_fma_f32 v[210:211], v[210:211], v[158:159], v[240:241] op_sel:[1,1,0] op_sel_hi:[1,0,1] neg_lo:[0,1,0]
	v_pk_add_f32 v[240:241], v[244:245], v[236:237]
	v_pk_add_f32 v[236:237], v[244:245], v[236:237] neg_lo:[0,1] neg_hi:[0,1]
	s_nop 0
	v_pk_mul_f32 v[244:245], v[236:237], v[158:159] op_sel:[0,0] op_sel_hi:[0,1]
	s_nop 0
	v_pk_fma_f32 v[236:237], v[236:237], v[158:159], v[244:245] op_sel:[1,1,0] op_sel_hi:[1,0,1] neg_lo:[0,1,0]
	v_pk_add_f32 v[244:245], v[218:219], v[234:235]
	v_pk_add_f32 v[218:219], v[218:219], v[234:235] neg_lo:[0,1] neg_hi:[0,1]
	s_nop 0
	v_pk_mul_f32 v[234:235], v[218:219], v[158:159] op_sel:[0,0] op_sel_hi:[0,1]
	s_nop 0
	v_pk_fma_f32 v[218:219], v[218:219], v[158:159], v[234:235] op_sel:[1,1,0] op_sel_hi:[1,0,1] neg_lo:[0,1,0]
	v_pk_add_f32 v[234:235], v[238:239], v[246:247]
	v_pk_add_f32 v[238:239], v[238:239], v[246:247] neg_lo:[0,1] neg_hi:[0,1]
	s_nop 0
	v_pk_mul_f32 v[246:247], v[238:239], v[158:159] op_sel:[0,0] op_sel_hi:[0,1]
	s_nop 0
	v_pk_fma_f32 v[238:239], v[238:239], v[158:159], v[246:247] op_sel:[1,1,0] op_sel_hi:[1,0,1] neg_lo:[0,1,0]
	v_pk_add_f32 v[246:247], v[228:229], v[226:227]
	v_pk_add_f32 v[226:227], v[228:229], v[226:227] neg_lo:[0,1] neg_hi:[0,1]
	s_nop 0
	v_pk_mul_f32 v[228:229], v[226:227], v[158:159] op_sel:[0,0] op_sel_hi:[0,1]
	s_nop 0
	v_pk_fma_f32 v[226:227], v[226:227], v[158:159], v[228:229] op_sel:[1,1,0] op_sel_hi:[1,0,1] neg_lo:[0,1,0]
	v_pk_add_f32 v[228:229], v[230:231], v[222:223]
	v_pk_add_f32 v[222:223], v[230:231], v[222:223] neg_lo:[0,1] neg_hi:[0,1]
	s_nop 0
	v_pk_mul_f32 v[230:231], v[222:223], v[158:159] op_sel:[0,0] op_sel_hi:[0,1]
	s_nop 0
	v_pk_fma_f32 v[222:223], v[222:223], v[158:159], v[230:231] op_sel:[1,1,0] op_sel_hi:[1,0,1] neg_lo:[0,1,0]
	v_pk_add_f32 v[230:231], v[198:199], v[216:217]
	v_pk_add_f32 v[198:199], v[198:199], v[216:217] neg_lo:[0,1] neg_hi:[0,1]
	s_nop 0
	v_pk_mul_f32 v[216:217], v[198:199], v[158:159] op_sel:[0,0] op_sel_hi:[0,1]
	s_nop 0
	v_pk_fma_f32 v[198:199], v[198:199], v[158:159], v[216:217] op_sel:[1,1,0] op_sel_hi:[1,0,1] neg_lo:[0,1,0]
	v_pk_add_f32 v[216:217], v[220:221], v[224:225]
	v_pk_add_f32 v[220:221], v[220:221], v[224:225] neg_lo:[0,1] neg_hi:[0,1]
	s_nop 0
	v_pk_mul_f32 v[224:225], v[220:221], v[158:159] op_sel:[0,0] op_sel_hi:[0,1]
	s_nop 0
	v_pk_fma_f32 v[220:221], v[220:221], v[158:159], v[224:225] op_sel:[1,1,0] op_sel_hi:[1,0,1] neg_lo:[0,1,0]
	v_pk_add_f32 v[224:225], v[212:213], v[214:215]
	v_pk_add_f32 v[212:213], v[212:213], v[214:215] neg_lo:[0,1] neg_hi:[0,1]
	s_nop 0
	v_pk_mul_f32 v[214:215], v[212:213], v[158:159] op_sel:[0,0] op_sel_hi:[0,1]
	s_nop 0
	v_pk_fma_f32 v[212:213], v[212:213], v[158:159], v[214:215] op_sel:[1,1,0] op_sel_hi:[1,0,1] neg_lo:[0,1,0]
	v_pk_add_f32 v[214:215], v[232:233], v[194:195]
	v_pk_add_f32 v[194:195], v[232:233], v[194:195] neg_lo:[0,1] neg_hi:[0,1]
	s_nop 0
	v_pk_mul_f32 v[232:233], v[194:195], v[158:159] op_sel:[0,0] op_sel_hi:[0,1]
	s_nop 0
	v_pk_fma_f32 v[194:195], v[194:195], v[158:159], v[232:233] op_sel:[1,1,0] op_sel_hi:[1,0,1] neg_lo:[0,1,0]
	v_pk_add_f32 v[232:233], v[190:191], v[188:189]
	v_pk_add_f32 v[188:189], v[190:191], v[188:189] neg_lo:[0,1] neg_hi:[0,1]
	s_nop 0
	v_pk_mul_f32 v[190:191], v[188:189], v[158:159] op_sel:[0,0] op_sel_hi:[0,1]
	s_nop 0
	v_pk_fma_f32 v[188:189], v[188:189], v[158:159], v[190:191] op_sel:[1,1,0] op_sel_hi:[1,0,1] neg_lo:[0,1,0]
	v_pk_add_f32 v[190:191], v[192:193], v[208:209]
	v_pk_add_f32 v[192:193], v[192:193], v[208:209] neg_lo:[0,1] neg_hi:[0,1]
	s_nop 0
	v_pk_mul_f32 v[208:209], v[192:193], v[158:159] op_sel:[0,0] op_sel_hi:[0,1]
	s_nop 0
	v_pk_fma_f32 v[192:193], v[192:193], v[158:159], v[208:209] op_sel:[1,1,0] op_sel_hi:[1,0,1] neg_lo:[0,1,0]
	v_pk_add_f32 v[208:209], v[182:183], v[180:181]
	v_pk_add_f32 v[180:181], v[182:183], v[180:181] neg_lo:[0,1] neg_hi:[0,1]
	s_nop 0
	v_pk_mul_f32 v[182:183], v[180:181], v[158:159] op_sel:[0,0] op_sel_hi:[0,1]
	s_nop 0
	v_pk_fma_f32 v[180:181], v[180:181], v[158:159], v[182:183] op_sel:[1,1,0] op_sel_hi:[1,0,1] neg_lo:[0,1,0]
	v_pk_add_f32 v[182:183], v[184:185], v[176:177]
	v_pk_add_f32 v[176:177], v[184:185], v[176:177] neg_lo:[0,1] neg_hi:[0,1]
	s_nop 0
	v_pk_mul_f32 v[184:185], v[176:177], v[158:159] op_sel:[0,0] op_sel_hi:[0,1]
	s_nop 0
	v_pk_fma_f32 v[176:177], v[176:177], v[158:159], v[184:185] op_sel:[1,1,0] op_sel_hi:[1,0,1] neg_lo:[0,1,0]
	v_pk_add_f32 v[184:185], v[172:173], v[174:175]
	v_pk_add_f32 v[172:173], v[172:173], v[174:175] neg_lo:[0,1] neg_hi:[0,1]
	s_nop 0
	v_pk_mul_f32 v[174:175], v[172:173], v[158:159] op_sel:[0,0] op_sel_hi:[0,1]
	s_nop 0
	v_pk_fma_f32 v[172:173], v[172:173], v[158:159], v[174:175] op_sel:[1,1,0] op_sel_hi:[1,0,1] neg_lo:[0,1,0]
	ds_write2_b64 v197, v[178:179], v[186:187] offset1:33
	ds_write2_b64 v197, v[242:243], v[210:211] offset0:66 offset1:99
	ds_write2_b64 v197, v[240:241], v[236:237] offset0:132 offset1:165
	ds_write2_b64 v197, v[244:245], v[218:219] offset0:198 offset1:231
	ds_write2_b64 v207, v[234:235], v[238:239] offset0:8 offset1:41
	ds_write2_b64 v207, v[246:247], v[226:227] offset0:74 offset1:107
	ds_write2_b64 v207, v[228:229], v[222:223] offset0:140 offset1:173
	ds_write2_b64 v207, v[230:231], v[198:199] offset0:206 offset1:239
	ds_write2_b64 v248, v[216:217], v[220:221] offset0:16 offset1:49
	ds_write2_b64 v248, v[224:225], v[212:213] offset0:82 offset1:115
	ds_write2_b64 v248, v[214:215], v[194:195] offset0:148 offset1:181
	ds_write2_b64 v248, v[232:233], v[188:189] offset0:214 offset1:247
	ds_write2_b64 v249, v[190:191], v[192:193] offset0:24 offset1:57
	ds_write2_b64 v249, v[208:209], v[180:181] offset0:90 offset1:123
	ds_write2_b64 v249, v[182:183], v[176:177] offset0:156 offset1:189
	ds_write2_b64 v249, v[184:185], v[172:173] offset0:222 offset1:255
	s_andn2_b64 exec, exec, s[14:15]
	s_cbranch_execnz .LBB0_1063
; __device__ __forceinline__ float2 cmul(float2 a, float2 b) { return make_float2(a.x * b.x - a.y * b.y, a.x * b.y + a.y * b.x); }
; template <int R, bool INV>
; __device__ __forceinline__ void butterflies(c32 (&v)[1 << R], float turns0) {
;     ...
;   for (int kk = 0; kk < R; ++kk) {
;     const int k = INV ? (R - 1 - kk) : kk;
;     const int hd = RAD >> (k + 1);
; #pragma unroll
;     for (int j = 0; j < RAD; ++j) {
;       if ((j & hd) == 0) {
;         const int m = (j & (hd - 1)) * (16 / hd);
;         const float2 c = make_float2(TC[m], INV ? TS[m] : -TS[m]);
;         const float2 twf = cmul(tbs[k], c);
;         const c32 tw = {twf.x, twf.y};
;         const c32 a = v[j], b = v[j + hd];
;         if (!INV) { v[j] = a + b; v[j + hd] = cmul_pk(a - b, tw); }
;         else { const c32 bt = cmul_pk(b, tw); v[j] = a + bt; v[j + hd] = a - bt; }
;       }
;     }
;   }
; template <int LOGN>
; __device__ __forceinline__ void fft_fused_mul(float2* X, const c32 (&kf)[32]) {
;     ...
;   int tid0 = threadIdx.x; asm volatile("" : "+v"(tid0));
;   const int pb = tid0 * 33;
;   c32 v[32];
; #pragma unroll
;   for (int j = 0; j < 32; ++j) v[j] = Xc[pb + j];
;   butterflies<5, false>(v, 0.f);
.LBB0_1064:
	s_or_b64 exec, exec, s[0:1]
	v_mov_b32_e32 v32, v196
	s_waitcnt lgkmcnt(0)
	s_barrier
	v_pk_add_f32 v[30:31], v[66:67], v[70:71]
	v_mul_lo_u32 v32, v32, s61
	v_add_u32_e32 v32, 0, v32
	v_pk_add_f32 v[28:29], v[68:69], v[74:75]
	v_pk_add_f32 v[26:27], v[72:73], v[78:79]
	v_pk_add_f32 v[24:25], v[76:77], v[82:83]
	v_pk_add_f32 v[22:23], v[80:81], v[86:87]
	v_pk_add_f32 v[20:21], v[84:85], v[90:91]
	v_pk_add_f32 v[18:19], v[88:89], v[94:95]
	v_pk_add_f32 v[16:17], v[92:93], v[98:99]
	v_pk_add_f32 v[14:15], v[96:97], v[102:103]
	v_pk_add_f32 v[12:13], v[100:101], v[106:107]
	v_pk_add_f32 v[10:11], v[104:105], v[110:111]
	v_pk_add_f32 v[8:9], v[108:109], v[114:115]
	v_pk_add_f32 v[6:7], v[112:113], v[118:119]
	v_pk_add_f32 v[4:5], v[116:117], v[122:123]
	v_pk_add_f32 v[2:3], v[120:121], v[126:127]
	v_pk_add_f32 v[0:1], v[124:125], v[128:129]
	ds_read_b64 v[66:67], v32
	ds_read_b64 v[68:69], v32 offset:8
	ds_read_b64 v[70:71], v32 offset:16
	ds_read_b64 v[72:73], v32 offset:24
	ds_read_b64 v[74:75], v32 offset:32
	ds_read_b64 v[76:77], v32 offset:40
	ds_read_b64 v[78:79], v32 offset:48
	ds_read_b64 v[80:81], v32 offset:56
	ds_read_b64 v[82:83], v32 offset:64
	ds_read_b64 v[84:85], v32 offset:72
	ds_read_b64 v[86:87], v32 offset:80
	ds_read_b64 v[88:89], v32 offset:88
	ds_read_b64 v[90:91], v32 offset:96
	ds_read_b64 v[92:93], v32 offset:104
	ds_read_b64 v[94:95], v32 offset:112
	ds_read_b64 v[96:97], v32 offset:120
	ds_read_b64 v[98:99], v32 offset:128
	ds_read_b64 v[100:101], v32 offset:136
	ds_read_b64 v[102:103], v32 offset:144
	ds_read_b64 v[104:105], v32 offset:152
	ds_read_b64 v[106:107], v32 offset:160
	ds_read_b64 v[108:109], v32 offset:168
	ds_read_b64 v[110:111], v32 offset:176
	ds_read_b64 v[112:113], v32 offset:184
	ds_read_b64 v[114:115], v32 offset:192
	ds_read_b64 v[116:117], v32 offset:200
	ds_read_b64 v[118:119], v32 offset:208
	ds_read_b64 v[120:121], v32 offset:216
	ds_read_b64 v[122:123], v32 offset:224
	ds_read_b64 v[124:125], v32 offset:232
	ds_read_b64 v[126:127], v32 offset:240
	ds_read_b64 v[128:129], v32 offset:248
	s_mov_b32 s7, s95
	s_waitcnt lgkmcnt(14)
	v_pk_add_f32 v[130:131], v[66:67], v[98:99]
	v_pk_add_f32 v[98:99], v[66:67], v[98:99] neg_lo:[0,1] neg_hi:[0,1]
	v_mov_b64_e32 v[66:67], s[6:7]
	v_pk_mul_f32 v[132:133], v[98:99], v[66:67] op_sel:[0,0] op_sel_hi:[0,1]
	s_mov_b32 s0, s19
	s_mov_b32 s1, s30
	v_pk_fma_f32 v[98:99], v[98:99], v[66:67], v[132:133] op_sel:[1,1,0] op_sel_hi:[1,0,1] neg_lo:[0,1,0]
	v_pk_add_f32 v[132:133], v[68:69], v[100:101]
	v_pk_add_f32 v[68:69], v[68:69], v[100:101] neg_lo:[0,1] neg_hi:[0,1]
	v_mov_b64_e32 v[100:101], s[0:1]
	v_pk_mul_f32 v[134:135], v[68:69], v[100:101] op_sel:[0,0] op_sel_hi:[0,1]
	s_mov_b32 s0, s9
	s_mov_b32 s1, s76
	v_pk_fma_f32 v[100:101], v[68:69], v[100:101], v[134:135] op_sel:[1,1,0] op_sel_hi:[1,0,1] neg_lo:[0,1,0]
	s_waitcnt lgkmcnt(12)
	v_pk_add_f32 v[134:135], v[70:71], v[102:103]
	v_pk_add_f32 v[68:69], v[70:71], v[102:103] neg_lo:[0,1] neg_hi:[0,1]
	v_mov_b64_e32 v[70:71], s[0:1]
	v_pk_mul_f32 v[102:103], v[68:69], v[70:71] op_sel:[0,0] op_sel_hi:[0,1]
	s_mov_b32 s0, s57
	s_mov_b32 s1, s68
	v_pk_fma_f32 v[102:103], v[68:69], v[70:71], v[102:103] op_sel:[1,1,0] op_sel_hi:[1,0,1] neg_lo:[0,1,0]
	v_pk_add_f32 v[136:137], v[72:73], v[104:105]
	v_pk_add_f32 v[68:69], v[72:73], v[104:105] neg_lo:[0,1] neg_hi:[0,1]
	v_mov_b64_e32 v[72:73], s[0:1]
	v_pk_mul_f32 v[104:105], v[68:69], v[72:73] op_sel:[0,0] op_sel_hi:[0,1]
	s_mov_b32 s0, s73
	s_mov_b32 s1, s72
	v_pk_fma_f32 v[72:73], v[68:69], v[72:73], v[104:105] op_sel:[1,1,0] op_sel_hi:[1,0,1] neg_lo:[0,1,0]
	s_waitcnt lgkmcnt(10)
	v_pk_add_f32 v[104:105], v[74:75], v[106:107]
	v_pk_add_f32 v[68:69], v[74:75], v[106:107] neg_lo:[0,1] neg_hi:[0,1]
	v_mov_b64_e32 v[74:75], s[0:1]
	v_pk_mul_f32 v[106:107], v[68:69], v[74:75] op_sel:[0,0] op_sel_hi:[0,1]
	s_mov_b32 s0, s56
	s_mov_b32 s1, s16
	v_pk_fma_f32 v[106:107], v[68:69], v[74:75], v[106:107] op_sel:[1,1,0] op_sel_hi:[1,0,1] neg_lo:[0,1,0]
	v_pk_add_f32 v[138:139], v[76:77], v[108:109]
	v_pk_add_f32 v[68:69], v[76:77], v[108:109] neg_lo:[0,1] neg_hi:[0,1]
	v_mov_b64_e32 v[76:77], s[0:1]
	v_pk_mul_f32 v[108:109], v[68:69], v[76:77] op_sel:[0,0] op_sel_hi:[0,1]
	s_mov_b32 s0, s8
	s_mov_b32 s1, s10
	v_pk_fma_f32 v[76:77], v[68:69], v[76:77], v[108:109] op_sel:[1,1,0] op_sel_hi:[1,0,1] neg_lo:[0,1,0]
	s_waitcnt lgkmcnt(8)
	v_pk_add_f32 v[108:109], v[78:79], v[110:111]
	v_pk_add_f32 v[68:69], v[78:79], v[110:111] neg_lo:[0,1] neg_hi:[0,1]
	v_mov_b64_e32 v[78:79], s[0:1]
	v_pk_mul_f32 v[110:111], v[68:69], v[78:79] op_sel:[0,0] op_sel_hi:[0,1]
	s_mov_b32 s0, s18
	s_mov_b32 s1, s4
	v_pk_fma_f32 v[110:111], v[68:69], v[78:79], v[110:111] op_sel:[1,1,0] op_sel_hi:[1,0,1] neg_lo:[0,1,0]
	v_pk_add_f32 v[140:141], v[80:81], v[112:113]
	v_pk_add_f32 v[68:69], v[80:81], v[112:113] neg_lo:[0,1] neg_hi:[0,1]
	v_mov_b64_e32 v[80:81], s[0:1]
	v_pk_mul_f32 v[112:113], v[68:69], v[80:81] op_sel:[0,0] op_sel_hi:[0,1]
	s_mov_b32 s88, s94
	v_pk_fma_f32 v[80:81], v[68:69], v[80:81], v[112:113] op_sel:[1,1,0] op_sel_hi:[1,0,1] neg_lo:[0,1,0]
	s_waitcnt lgkmcnt(6)
	v_pk_add_f32 v[112:113], v[82:83], v[114:115]
	v_pk_add_f32 v[82:83], v[82:83], v[114:115] neg_lo:[0,1] neg_hi:[0,1]
	v_mov_b64_e32 v[68:69], s[88:89]
	v_pk_mul_f32 v[114:115], v[82:83], v[68:69] op_sel:[0,0] op_sel_hi:[0,1]
	s_mov_b32 s31, s4
	v_pk_fma_f32 v[82:83], v[82:83], v[68:69], v[114:115] op_sel:[1,1,0] op_sel_hi:[1,0,1] neg_lo:[0,1,0]
	v_pk_add_f32 v[114:115], v[84:85], v[116:117]
	v_pk_add_f32 v[84:85], v[84:85], v[116:117] neg_lo:[0,1] neg_hi:[0,1]
	v_mov_b64_e32 v[116:117], s[30:31]
	v_pk_mul_f32 v[142:143], v[84:85], v[116:117] op_sel:[0,0] op_sel_hi:[0,1]
	s_mov_b32 s77, s10
	v_pk_fma_f32 v[84:85], v[84:85], v[116:117], v[142:143] op_sel:[1,1,0] op_sel_hi:[1,0,1] neg_lo:[0,1,0]
	s_waitcnt lgkmcnt(4)
; __device__ __forceinline__ float2 cmul(float2 a, float2 b) { return make_float2(a.x * b.x - a.y * b.y, a.x * b.y + a.y * b.x); }
; template <int R, bool INV>
; __device__ __forceinline__ void butterflies(c32 (&v)[1 << R], float turns0) {
;     ...
;   for (int kk = 0; kk < R; ++kk) {
;     const int k = INV ? (R - 1 - kk) : kk;
;     const int hd = RAD >> (k + 1);
; #pragma unroll
;     for (int j = 0; j < RAD; ++j) {
;       if ((j & hd) == 0) {
;         const int m = (j & (hd - 1)) * (16 / hd);
;         const float2 c = make_float2(TC[m], INV ? TS[m] : -TS[m]);
;         const float2 twf = cmul(tbs[k], c);
;         const c32 tw = {twf.x, twf.y};
;         const c32 a = v[j], b = v[j + hd];
;         if (!INV) { v[j] = a + b; v[j + hd] = cmul_pk(a - b, tw); }
;         else { const c32 bt = cmul_pk(b, tw); v[j] = a + bt; v[j + hd] = a - bt; }
;       }
;     }
;   }
	v_pk_add_f32 v[116:117], v[86:87], v[118:119]
	v_pk_add_f32 v[86:87], v[86:87], v[118:119] neg_lo:[0,1] neg_hi:[0,1]
	v_mov_b64_e32 v[118:119], s[76:77]
	v_pk_mul_f32 v[142:143], v[86:87], v[118:119] op_sel:[0,0] op_sel_hi:[0,1]
	s_mov_b32 s69, s16
	v_pk_fma_f32 v[86:87], v[86:87], v[118:119], v[142:143] op_sel:[1,1,0] op_sel_hi:[1,0,1] neg_lo:[0,1,0]
	v_pk_add_f32 v[142:143], v[88:89], v[120:121]
	v_pk_add_f32 v[88:89], v[88:89], v[120:121] neg_lo:[0,1] neg_hi:[0,1]
	v_mov_b64_e32 v[120:121], s[68:69]
	v_pk_mul_f32 v[144:145], v[88:89], v[120:121] op_sel:[0,0] op_sel_hi:[0,1]
	s_mov_b32 s0, s72
	s_mov_b32 s1, s72
	v_pk_fma_f32 v[88:89], v[88:89], v[120:121], v[144:145] op_sel:[1,1,0] op_sel_hi:[1,0,1] neg_lo:[0,1,0]
	s_waitcnt lgkmcnt(2)
	v_pk_add_f32 v[120:121], v[90:91], v[122:123]
	v_pk_add_f32 v[90:91], v[90:91], v[122:123] neg_lo:[0,1] neg_hi:[0,1]
	v_mov_b64_e32 v[122:123], s[0:1]
	v_pk_mul_f32 v[144:145], v[90:91], v[122:123] op_sel:[0,0] op_sel_hi:[0,1]
	s_mov_b32 s17, s68
	v_pk_fma_f32 v[90:91], v[90:91], v[122:123], v[144:145] op_sel:[1,1,0] op_sel_hi:[1,0,1] neg_lo:[0,1,0]
	v_pk_add_f32 v[144:145], v[92:93], v[124:125]
	v_pk_add_f32 v[92:93], v[92:93], v[124:125] neg_lo:[0,1] neg_hi:[0,1]
	v_mov_b64_e32 v[124:125], s[16:17]
	v_pk_mul_f32 v[146:147], v[92:93], v[124:125] op_sel:[0,0] op_sel_hi:[0,1]
	s_mov_b32 s11, s76
	v_pk_fma_f32 v[92:93], v[92:93], v[124:125], v[146:147] op_sel:[1,1,0] op_sel_hi:[1,0,1] neg_lo:[0,1,0]
	s_waitcnt lgkmcnt(0)
	v_pk_add_f32 v[124:125], v[94:95], v[126:127]
	v_pk_add_f32 v[94:95], v[94:95], v[126:127] neg_lo:[0,1] neg_hi:[0,1]
	v_mov_b64_e32 v[126:127], s[10:11]
	v_pk_mul_f32 v[146:147], v[94:95], v[126:127] op_sel:[0,0] op_sel_hi:[0,1]
	s_mov_b32 s5, s30
	v_pk_fma_f32 v[94:95], v[94:95], v[126:127], v[146:147] op_sel:[1,1,0] op_sel_hi:[1,0,1] neg_lo:[0,1,0]
	v_pk_add_f32 v[146:147], v[96:97], v[128:129]
	v_pk_add_f32 v[96:97], v[96:97], v[128:129] neg_lo:[0,1] neg_hi:[0,1]
	v_mov_b64_e32 v[128:129], s[4:5]
	v_pk_mul_f32 v[148:149], v[96:97], v[128:129] op_sel:[0,0] op_sel_hi:[0,1]
	s_mov_b32 s7, s94
	v_pk_fma_f32 v[96:97], v[96:97], v[128:129], v[148:149] op_sel:[1,1,0] op_sel_hi:[1,0,1] neg_lo:[0,1,0]
	v_pk_add_f32 v[128:129], v[130:131], v[112:113]
	v_pk_add_f32 v[112:113], v[130:131], v[112:113] neg_lo:[0,1] neg_hi:[0,1]
	s_mov_b32 s0, s94
	v_pk_mul_f32 v[130:131], v[112:113], v[66:67] op_sel:[0,0] op_sel_hi:[0,1]
	s_mov_b32 s1, s6
	v_pk_fma_f32 v[112:113], v[112:113], v[66:67], v[130:131] op_sel:[1,1,0] op_sel_hi:[1,0,1] neg_lo:[0,1,0]
	v_pk_add_f32 v[130:131], v[132:133], v[114:115]
	v_pk_add_f32 v[114:115], v[132:133], v[114:115] neg_lo:[0,1] neg_hi:[0,1]
	s_mov_b32 s77, s9
	v_pk_mul_f32 v[132:133], v[114:115], v[70:71] op_sel:[0,0] op_sel_hi:[0,1]
	s_mov_b32 s11, s8
	v_pk_fma_f32 v[114:115], v[114:115], v[70:71], v[132:133] op_sel:[1,1,0] op_sel_hi:[1,0,1] neg_lo:[0,1,0]
	v_pk_add_f32 v[132:133], v[134:135], v[116:117]
	v_pk_add_f32 v[116:117], v[134:135], v[116:117] neg_lo:[0,1] neg_hi:[0,1]
	s_mov_b32 s31, s19
	v_pk_mul_f32 v[134:135], v[116:117], v[74:75] op_sel:[0,0] op_sel_hi:[0,1]
	s_mov_b32 s69, s57
	v_pk_fma_f32 v[116:117], v[116:117], v[74:75], v[134:135] op_sel:[1,1,0] op_sel_hi:[1,0,1] neg_lo:[0,1,0]
	v_pk_add_f32 v[134:135], v[136:137], v[142:143]
	v_pk_add_f32 v[136:137], v[136:137], v[142:143] neg_lo:[0,1] neg_hi:[0,1]
	s_mov_b32 s17, s56
	v_pk_mul_f32 v[142:143], v[136:137], v[78:79] op_sel:[0,0] op_sel_hi:[0,1]
	s_mov_b32 s5, s18
	v_pk_fma_f32 v[136:137], v[136:137], v[78:79], v[142:143] op_sel:[1,1,0] op_sel_hi:[1,0,1] neg_lo:[0,1,0]
	v_pk_add_f32 v[142:143], v[104:105], v[120:121]
	v_pk_add_f32 v[104:105], v[104:105], v[120:121] neg_lo:[0,1] neg_hi:[0,1]
	s_nop 0
	v_pk_mul_f32 v[120:121], v[104:105], v[68:69] op_sel:[0,0] op_sel_hi:[0,1]
	s_nop 0
	v_pk_fma_f32 v[104:105], v[104:105], v[68:69], v[120:121] op_sel:[1,1,0] op_sel_hi:[1,0,1] neg_lo:[0,1,0]
	v_pk_add_f32 v[120:121], v[138:139], v[144:145]
	v_pk_add_f32 v[138:139], v[138:139], v[144:145] neg_lo:[0,1] neg_hi:[0,1]
	s_nop 0
	v_pk_mul_f32 v[144:145], v[138:139], v[118:119] op_sel:[0,0] op_sel_hi:[0,1]
	s_nop 0
	v_pk_fma_f32 v[138:139], v[138:139], v[118:119], v[144:145] op_sel:[1,1,0] op_sel_hi:[1,0,1] neg_lo:[0,1,0]
	v_pk_add_f32 v[144:145], v[108:109], v[124:125]
	v_pk_add_f32 v[108:109], v[108:109], v[124:125] neg_lo:[0,1] neg_hi:[0,1]
	s_nop 0
	v_pk_mul_f32 v[124:125], v[108:109], v[122:123] op_sel:[0,0] op_sel_hi:[0,1]
	s_nop 0
	v_pk_fma_f32 v[108:109], v[108:109], v[122:123], v[124:125] op_sel:[1,1,0] op_sel_hi:[1,0,1] neg_lo:[0,1,0]
	v_pk_add_f32 v[124:125], v[140:141], v[146:147]
	v_pk_add_f32 v[140:141], v[140:141], v[146:147] neg_lo:[0,1] neg_hi:[0,1]
	s_nop 0
	v_pk_mul_f32 v[146:147], v[140:141], v[126:127] op_sel:[0,0] op_sel_hi:[0,1]
	s_nop 0
	v_pk_fma_f32 v[140:141], v[140:141], v[126:127], v[146:147] op_sel:[1,1,0] op_sel_hi:[1,0,1] neg_lo:[0,1,0]
	v_pk_add_f32 v[146:147], v[98:99], v[82:83]
	v_pk_add_f32 v[82:83], v[98:99], v[82:83] neg_lo:[0,1] neg_hi:[0,1]
	s_nop 0
	v_pk_mul_f32 v[98:99], v[82:83], v[66:67] op_sel:[0,0] op_sel_hi:[0,1]
	s_nop 0
	v_pk_fma_f32 v[82:83], v[82:83], v[66:67], v[98:99] op_sel:[1,1,0] op_sel_hi:[1,0,1] neg_lo:[0,1,0]
	v_pk_add_f32 v[98:99], v[100:101], v[84:85]
	v_pk_add_f32 v[84:85], v[100:101], v[84:85] neg_lo:[0,1] neg_hi:[0,1]
	s_nop 0
	v_pk_mul_f32 v[100:101], v[84:85], v[70:71] op_sel:[0,0] op_sel_hi:[0,1]
	s_nop 0
	v_pk_fma_f32 v[70:71], v[84:85], v[70:71], v[100:101] op_sel:[1,1,0] op_sel_hi:[1,0,1] neg_lo:[0,1,0]
	v_pk_add_f32 v[84:85], v[102:103], v[86:87]
	v_pk_add_f32 v[86:87], v[102:103], v[86:87] neg_lo:[0,1] neg_hi:[0,1]
	s_nop 0
; __device__ __forceinline__ float2 cmul(float2 a, float2 b) { return make_float2(a.x * b.x - a.y * b.y, a.x * b.y + a.y * b.x); }
; template <int R, bool INV>
; __device__ __forceinline__ void butterflies(c32 (&v)[1 << R], float turns0) {
;     ...
;   for (int kk = 0; kk < R; ++kk) {
;     const int k = INV ? (R - 1 - kk) : kk;
;     const int hd = RAD >> (k + 1);
; #pragma unroll
;     for (int j = 0; j < RAD; ++j) {
;       if ((j & hd) == 0) {
;         const int m = (j & (hd - 1)) * (16 / hd);
;         const float2 c = make_float2(TC[m], INV ? TS[m] : -TS[m]);
;         const float2 twf = cmul(tbs[k], c);
;         const c32 tw = {twf.x, twf.y};
;         const c32 a = v[j], b = v[j + hd];
;         if (!INV) { v[j] = a + b; v[j + hd] = cmul_pk(a - b, tw); }
;         else { const c32 bt = cmul_pk(b, tw); v[j] = a + bt; v[j + hd] = a - bt; }
;       }
;     }
;   }
	v_pk_mul_f32 v[100:101], v[86:87], v[74:75] op_sel:[0,0] op_sel_hi:[0,1]
	s_nop 0
	v_pk_fma_f32 v[86:87], v[86:87], v[74:75], v[100:101] op_sel:[1,1,0] op_sel_hi:[1,0,1] neg_lo:[0,1,0]
	v_pk_add_f32 v[100:101], v[72:73], v[88:89]
	v_pk_add_f32 v[72:73], v[72:73], v[88:89] neg_lo:[0,1] neg_hi:[0,1]
	s_nop 0
	v_pk_mul_f32 v[88:89], v[72:73], v[78:79] op_sel:[0,0] op_sel_hi:[0,1]
	s_nop 0
	v_pk_fma_f32 v[72:73], v[72:73], v[78:79], v[88:89] op_sel:[1,1,0] op_sel_hi:[1,0,1] neg_lo:[0,1,0]
	v_pk_add_f32 v[78:79], v[106:107], v[90:91]
	v_pk_add_f32 v[88:89], v[106:107], v[90:91] neg_lo:[0,1] neg_hi:[0,1]
	v_pk_add_f32 v[106:107], v[128:129], v[142:143] neg_lo:[0,1] neg_hi:[0,1]
	v_pk_mul_f32 v[90:91], v[88:89], v[68:69] op_sel:[0,0] op_sel_hi:[0,1]
	s_nop 0
	v_pk_fma_f32 v[88:89], v[88:89], v[68:69], v[90:91] op_sel:[1,1,0] op_sel_hi:[1,0,1] neg_lo:[0,1,0]
	v_pk_add_f32 v[90:91], v[76:77], v[92:93]
	v_pk_add_f32 v[76:77], v[76:77], v[92:93] neg_lo:[0,1] neg_hi:[0,1]
	s_nop 0
	v_pk_mul_f32 v[92:93], v[76:77], v[118:119] op_sel:[0,0] op_sel_hi:[0,1]
	s_nop 0
	v_pk_fma_f32 v[76:77], v[76:77], v[118:119], v[92:93] op_sel:[1,1,0] op_sel_hi:[1,0,1] neg_lo:[0,1,0]
	v_pk_add_f32 v[92:93], v[110:111], v[94:95]
	v_pk_add_f32 v[94:95], v[110:111], v[94:95] neg_lo:[0,1] neg_hi:[0,1]
	v_pk_mul_f32 v[110:111], v[106:107], v[66:67] op_sel:[0,0] op_sel_hi:[0,1]
	v_pk_add_f32 v[118:119], v[130:131], v[120:121] neg_lo:[0,1] neg_hi:[0,1]
	v_pk_mul_f32 v[102:103], v[94:95], v[122:123] op_sel:[0,0] op_sel_hi:[0,1]
	v_pk_fma_f32 v[106:107], v[106:107], v[66:67], v[110:111] op_sel:[1,1,0] op_sel_hi:[1,0,1] neg_lo:[0,1,0]
	v_pk_add_f32 v[110:111], v[130:131], v[120:121]
	v_pk_fma_f32 v[94:95], v[94:95], v[122:123], v[102:103] op_sel:[1,1,0] op_sel_hi:[1,0,1] neg_lo:[0,1,0]
	v_pk_add_f32 v[102:103], v[80:81], v[96:97]
	v_pk_add_f32 v[80:81], v[80:81], v[96:97] neg_lo:[0,1] neg_hi:[0,1]
	v_pk_mul_f32 v[120:121], v[118:119], v[74:75] op_sel:[0,0] op_sel_hi:[0,1]
	s_nop 0
	v_pk_mul_f32 v[96:97], v[80:81], v[126:127] op_sel:[0,0] op_sel_hi:[0,1]
	v_pk_fma_f32 v[118:119], v[118:119], v[74:75], v[120:121] op_sel:[1,1,0] op_sel_hi:[1,0,1] neg_lo:[0,1,0]
	v_pk_add_f32 v[120:121], v[132:133], v[144:145]
	v_pk_fma_f32 v[80:81], v[80:81], v[126:127], v[96:97] op_sel:[1,1,0] op_sel_hi:[1,0,1] neg_lo:[0,1,0]
	v_pk_add_f32 v[96:97], v[128:129], v[142:143]
	v_pk_add_f32 v[126:127], v[132:133], v[144:145] neg_lo:[0,1] neg_hi:[0,1]
	s_nop 0
	v_pk_mul_f32 v[128:129], v[126:127], v[68:69] op_sel:[0,0] op_sel_hi:[0,1]
	s_nop 0
	v_pk_fma_f32 v[126:127], v[126:127], v[68:69], v[128:129] op_sel:[1,1,0] op_sel_hi:[1,0,1] neg_lo:[0,1,0]
	v_pk_add_f32 v[128:129], v[134:135], v[124:125]
	v_pk_add_f32 v[124:125], v[134:135], v[124:125] neg_lo:[0,1] neg_hi:[0,1]
	v_pk_add_f32 v[134:135], v[136:137], v[140:141] neg_lo:[0,1] neg_hi:[0,1]
	v_pk_mul_f32 v[130:131], v[124:125], v[122:123] op_sel:[0,0] op_sel_hi:[0,1]
	s_nop 0
	v_pk_fma_f32 v[124:125], v[124:125], v[122:123], v[130:131] op_sel:[1,1,0] op_sel_hi:[1,0,1] neg_lo:[0,1,0]
	v_pk_add_f32 v[130:131], v[112:113], v[104:105]
	v_pk_add_f32 v[104:105], v[112:113], v[104:105] neg_lo:[0,1] neg_hi:[0,1]
	s_nop 0
	v_pk_mul_f32 v[112:113], v[104:105], v[66:67] op_sel:[0,0] op_sel_hi:[0,1]
	s_nop 0
	v_pk_fma_f32 v[104:105], v[104:105], v[66:67], v[112:113] op_sel:[1,1,0] op_sel_hi:[1,0,1] neg_lo:[0,1,0]
	v_pk_add_f32 v[112:113], v[114:115], v[138:139]
	v_pk_add_f32 v[114:115], v[114:115], v[138:139] neg_lo:[0,1] neg_hi:[0,1]
	s_nop 0
	v_pk_mul_f32 v[132:133], v[114:115], v[74:75] op_sel:[0,0] op_sel_hi:[0,1]
	s_nop 0
	v_pk_fma_f32 v[114:115], v[114:115], v[74:75], v[132:133] op_sel:[1,1,0] op_sel_hi:[1,0,1] neg_lo:[0,1,0]
	v_pk_add_f32 v[132:133], v[116:117], v[108:109]
	v_pk_add_f32 v[108:109], v[116:117], v[108:109] neg_lo:[0,1] neg_hi:[0,1]
	s_nop 0
	v_pk_mul_f32 v[116:117], v[108:109], v[68:69] op_sel:[0,0] op_sel_hi:[0,1]
	s_nop 0
	v_pk_fma_f32 v[108:109], v[108:109], v[68:69], v[116:117] op_sel:[1,1,0] op_sel_hi:[1,0,1] neg_lo:[0,1,0]
	v_pk_add_f32 v[116:117], v[136:137], v[140:141]
	v_pk_mul_f32 v[136:137], v[134:135], v[122:123] op_sel:[0,0] op_sel_hi:[0,1]
	s_nop 0
	v_pk_fma_f32 v[134:135], v[134:135], v[122:123], v[136:137] op_sel:[1,1,0] op_sel_hi:[1,0,1] neg_lo:[0,1,0]
	v_pk_add_f32 v[136:137], v[146:147], v[78:79]
	v_pk_add_f32 v[78:79], v[146:147], v[78:79] neg_lo:[0,1] neg_hi:[0,1]
	s_nop 0
	v_pk_mul_f32 v[138:139], v[78:79], v[66:67] op_sel:[0,0] op_sel_hi:[0,1]
	s_nop 0
	v_pk_fma_f32 v[78:79], v[78:79], v[66:67], v[138:139] op_sel:[1,1,0] op_sel_hi:[1,0,1] neg_lo:[0,1,0]
	v_pk_add_f32 v[138:139], v[98:99], v[90:91]
	v_pk_add_f32 v[90:91], v[98:99], v[90:91] neg_lo:[0,1] neg_hi:[0,1]
	s_nop 0
	v_pk_mul_f32 v[98:99], v[90:91], v[74:75] op_sel:[0,0] op_sel_hi:[0,1]
	s_nop 0
	v_pk_fma_f32 v[90:91], v[90:91], v[74:75], v[98:99] op_sel:[1,1,0] op_sel_hi:[1,0,1] neg_lo:[0,1,0]
	v_pk_add_f32 v[98:99], v[84:85], v[92:93]
	v_pk_add_f32 v[84:85], v[84:85], v[92:93] neg_lo:[0,1] neg_hi:[0,1]
	s_nop 0
	v_pk_mul_f32 v[92:93], v[84:85], v[68:69] op_sel:[0,0] op_sel_hi:[0,1]
	s_nop 0
	v_pk_fma_f32 v[84:85], v[84:85], v[68:69], v[92:93] op_sel:[1,1,0] op_sel_hi:[1,0,1] neg_lo:[0,1,0]
	v_pk_add_f32 v[92:93], v[100:101], v[102:103]
	v_pk_add_f32 v[100:101], v[100:101], v[102:103] neg_lo:[0,1] neg_hi:[0,1]
	s_nop 0
	v_pk_mul_f32 v[102:103], v[100:101], v[122:123] op_sel:[0,0] op_sel_hi:[0,1]
	s_nop 0
	v_pk_fma_f32 v[100:101], v[100:101], v[122:123], v[102:103] op_sel:[1,1,0] op_sel_hi:[1,0,1] neg_lo:[0,1,0]
	v_pk_add_f32 v[102:103], v[82:83], v[88:89]
	v_pk_add_f32 v[82:83], v[82:83], v[88:89] neg_lo:[0,1] neg_hi:[0,1]
	s_nop 0
; __device__ __forceinline__ float2 cmul(float2 a, float2 b) { return make_float2(a.x * b.x - a.y * b.y, a.x * b.y + a.y * b.x); }
; template <int R, bool INV>
; __device__ __forceinline__ void butterflies(c32 (&v)[1 << R], float turns0) {
;     ...
;   for (int kk = 0; kk < R; ++kk) {
;     const int k = INV ? (R - 1 - kk) : kk;
;     const int hd = RAD >> (k + 1);
; #pragma unroll
;     for (int j = 0; j < RAD; ++j) {
;       if ((j & hd) == 0) {
;         const int m = (j & (hd - 1)) * (16 / hd);
;         const float2 c = make_float2(TC[m], INV ? TS[m] : -TS[m]);
;         const float2 twf = cmul(tbs[k], c);
;         const c32 tw = {twf.x, twf.y};
;         const c32 a = v[j], b = v[j + hd];
;         if (!INV) { v[j] = a + b; v[j + hd] = cmul_pk(a - b, tw); }
;         else { const c32 bt = cmul_pk(b, tw); v[j] = a + bt; v[j + hd] = a - bt; }
;       }
;     }
;   }
	v_pk_mul_f32 v[88:89], v[82:83], v[66:67] op_sel:[0,0] op_sel_hi:[0,1]
	s_nop 0
	v_pk_fma_f32 v[82:83], v[82:83], v[66:67], v[88:89] op_sel:[1,1,0] op_sel_hi:[1,0,1] neg_lo:[0,1,0]
	v_pk_add_f32 v[88:89], v[70:71], v[76:77]
	v_pk_add_f32 v[70:71], v[70:71], v[76:77] neg_lo:[0,1] neg_hi:[0,1]
	s_nop 0
	v_pk_mul_f32 v[76:77], v[70:71], v[74:75] op_sel:[0,0] op_sel_hi:[0,1]
	s_nop 0
	v_pk_fma_f32 v[70:71], v[70:71], v[74:75], v[76:77] op_sel:[1,1,0] op_sel_hi:[1,0,1] neg_lo:[0,1,0]
	v_pk_add_f32 v[74:75], v[86:87], v[94:95]
	v_pk_add_f32 v[76:77], v[86:87], v[94:95] neg_lo:[0,1] neg_hi:[0,1]
	v_pk_add_f32 v[94:95], v[96:97], v[120:121] neg_lo:[0,1] neg_hi:[0,1]
	v_pk_mul_f32 v[86:87], v[76:77], v[68:69] op_sel:[0,0] op_sel_hi:[0,1]
	s_nop 0
	v_pk_fma_f32 v[76:77], v[76:77], v[68:69], v[86:87] op_sel:[1,1,0] op_sel_hi:[1,0,1] neg_lo:[0,1,0]
	v_pk_add_f32 v[86:87], v[72:73], v[80:81]
	v_pk_add_f32 v[72:73], v[72:73], v[80:81] neg_lo:[0,1] neg_hi:[0,1]
	s_nop 0
	v_pk_mul_f32 v[80:81], v[72:73], v[122:123] op_sel:[0,0] op_sel_hi:[0,1]
	s_nop 0
	v_pk_fma_f32 v[72:73], v[72:73], v[122:123], v[80:81] op_sel:[1,1,0] op_sel_hi:[1,0,1] neg_lo:[0,1,0]
	v_pk_add_f32 v[80:81], v[96:97], v[120:121]
	v_pk_mul_f32 v[96:97], v[94:95], v[66:67] op_sel:[0,0] op_sel_hi:[0,1]
	s_nop 0
	v_pk_fma_f32 v[94:95], v[94:95], v[66:67], v[96:97] op_sel:[1,1,0] op_sel_hi:[1,0,1] neg_lo:[0,1,0]
	v_pk_add_f32 v[96:97], v[110:111], v[128:129]
	v_pk_add_f32 v[110:111], v[110:111], v[128:129] neg_lo:[0,1] neg_hi:[0,1]
	s_nop 0
	v_pk_mul_f32 v[120:121], v[110:111], v[68:69] op_sel:[0,0] op_sel_hi:[0,1]
	s_nop 0
	v_pk_fma_f32 v[110:111], v[110:111], v[68:69], v[120:121] op_sel:[1,1,0] op_sel_hi:[1,0,1] neg_lo:[0,1,0]
	v_pk_add_f32 v[120:121], v[106:107], v[126:127]
	v_pk_add_f32 v[106:107], v[106:107], v[126:127] neg_lo:[0,1] neg_hi:[0,1]
	v_pk_add_f32 v[126:127], v[130:131], v[132:133] neg_lo:[0,1] neg_hi:[0,1]
	v_pk_mul_f32 v[122:123], v[106:107], v[66:67] op_sel:[0,0] op_sel_hi:[0,1]
	s_nop 0
	v_pk_mul_f32 v[128:129], v[126:127], v[66:67] op_sel:[0,0] op_sel_hi:[0,1]
	v_pk_fma_f32 v[106:107], v[106:107], v[66:67], v[122:123] op_sel:[1,1,0] op_sel_hi:[1,0,1] neg_lo:[0,1,0]
	v_pk_add_f32 v[122:123], v[118:119], v[124:125]
	v_pk_fma_f32 v[126:127], v[126:127], v[66:67], v[128:129] op_sel:[1,1,0] op_sel_hi:[1,0,1] neg_lo:[0,1,0]
	v_pk_add_f32 v[128:129], v[112:113], v[116:117]
	v_pk_add_f32 v[112:113], v[112:113], v[116:117] neg_lo:[0,1] neg_hi:[0,1]
	v_pk_add_f32 v[118:119], v[118:119], v[124:125] neg_lo:[0,1] neg_hi:[0,1]
	v_pk_mul_f32 v[116:117], v[112:113], v[68:69] op_sel:[0,0] op_sel_hi:[0,1]
	s_nop 0
	v_pk_mul_f32 v[124:125], v[118:119], v[68:69] op_sel:[0,0] op_sel_hi:[0,1]
	v_pk_fma_f32 v[112:113], v[112:113], v[68:69], v[116:117] op_sel:[1,1,0] op_sel_hi:[1,0,1] neg_lo:[0,1,0]
	v_pk_add_f32 v[116:117], v[104:105], v[108:109]
	v_pk_add_f32 v[104:105], v[104:105], v[108:109] neg_lo:[0,1] neg_hi:[0,1]
	v_pk_fma_f32 v[118:119], v[118:119], v[68:69], v[124:125] op_sel:[1,1,0] op_sel_hi:[1,0,1] neg_lo:[0,1,0]
	v_pk_add_f32 v[124:125], v[130:131], v[132:133]
	v_pk_mul_f32 v[108:109], v[104:105], v[66:67] op_sel:[0,0] op_sel_hi:[0,1]
	s_nop 0
	v_pk_fma_f32 v[104:105], v[104:105], v[66:67], v[108:109] op_sel:[1,1,0] op_sel_hi:[1,0,1] neg_lo:[0,1,0]
	v_pk_add_f32 v[108:109], v[114:115], v[134:135]
	v_pk_add_f32 v[114:115], v[114:115], v[134:135] neg_lo:[0,1] neg_hi:[0,1]
	s_nop 0
	v_pk_mul_f32 v[130:131], v[114:115], v[68:69] op_sel:[0,0] op_sel_hi:[0,1]
	s_nop 0
	v_pk_fma_f32 v[114:115], v[114:115], v[68:69], v[130:131] op_sel:[1,1,0] op_sel_hi:[1,0,1] neg_lo:[0,1,0]
	v_pk_add_f32 v[130:131], v[136:137], v[98:99]
	v_pk_add_f32 v[98:99], v[136:137], v[98:99] neg_lo:[0,1] neg_hi:[0,1]
	s_nop 0
	v_pk_mul_f32 v[132:133], v[98:99], v[66:67] op_sel:[0,0] op_sel_hi:[0,1]
	s_nop 0
	v_pk_fma_f32 v[98:99], v[98:99], v[66:67], v[132:133] op_sel:[1,1,0] op_sel_hi:[1,0,1] neg_lo:[0,1,0]
	v_pk_add_f32 v[132:133], v[138:139], v[92:93]
	v_pk_add_f32 v[92:93], v[138:139], v[92:93] neg_lo:[0,1] neg_hi:[0,1]
	s_nop 0
	v_pk_mul_f32 v[134:135], v[92:93], v[68:69] op_sel:[0,0] op_sel_hi:[0,1]
	s_nop 0
	v_pk_fma_f32 v[92:93], v[92:93], v[68:69], v[134:135] op_sel:[1,1,0] op_sel_hi:[1,0,1] neg_lo:[0,1,0]
	v_pk_add_f32 v[134:135], v[78:79], v[84:85]
	v_pk_add_f32 v[78:79], v[78:79], v[84:85] neg_lo:[0,1] neg_hi:[0,1]
	s_nop 0
	v_pk_mul_f32 v[84:85], v[78:79], v[66:67] op_sel:[0,0] op_sel_hi:[0,1]
	s_nop 0
	v_pk_fma_f32 v[78:79], v[78:79], v[66:67], v[84:85] op_sel:[1,1,0] op_sel_hi:[1,0,1] neg_lo:[0,1,0]
	v_pk_add_f32 v[84:85], v[90:91], v[100:101]
	v_pk_add_f32 v[90:91], v[90:91], v[100:101] neg_lo:[0,1] neg_hi:[0,1]
	s_nop 0
	v_pk_mul_f32 v[100:101], v[90:91], v[68:69] op_sel:[0,0] op_sel_hi:[0,1]
	s_nop 0
	v_pk_fma_f32 v[90:91], v[90:91], v[68:69], v[100:101] op_sel:[1,1,0] op_sel_hi:[1,0,1] neg_lo:[0,1,0]
	v_pk_add_f32 v[100:101], v[102:103], v[74:75]
	v_pk_add_f32 v[74:75], v[102:103], v[74:75] neg_lo:[0,1] neg_hi:[0,1]
	s_nop 0
	v_pk_mul_f32 v[102:103], v[74:75], v[66:67] op_sel:[0,0] op_sel_hi:[0,1]
	s_nop 0
	v_pk_fma_f32 v[74:75], v[74:75], v[66:67], v[102:103] op_sel:[1,1,0] op_sel_hi:[1,0,1] neg_lo:[0,1,0]
	v_pk_add_f32 v[102:103], v[88:89], v[86:87]
	v_pk_add_f32 v[86:87], v[88:89], v[86:87] neg_lo:[0,1] neg_hi:[0,1]
	s_nop 0
	v_pk_mul_f32 v[88:89], v[86:87], v[68:69] op_sel:[0,0] op_sel_hi:[0,1]
	s_nop 0
	v_pk_fma_f32 v[86:87], v[86:87], v[68:69], v[88:89] op_sel:[1,1,0] op_sel_hi:[1,0,1] neg_lo:[0,1,0]
	v_pk_add_f32 v[88:89], v[82:83], v[76:77]
	v_pk_add_f32 v[76:77], v[82:83], v[76:77] neg_lo:[0,1] neg_hi:[0,1]
	s_nop 0
	v_pk_mul_f32 v[82:83], v[76:77], v[66:67] op_sel:[0,0] op_sel_hi:[0,1]
; __device__ __forceinline__ float2 cmul(float2 a, float2 b) { return make_float2(a.x * b.x - a.y * b.y, a.x * b.y + a.y * b.x); }
; template <int R, bool INV>
; __device__ __forceinline__ void butterflies(c32 (&v)[1 << R], float turns0) {
;     ...
;   for (int kk = 0; kk < R; ++kk) {
;     const int k = INV ? (R - 1 - kk) : kk;
;     const int hd = RAD >> (k + 1);
; #pragma unroll
;     for (int j = 0; j < RAD; ++j) {
;       if ((j & hd) == 0) {
;         const int m = (j & (hd - 1)) * (16 / hd);
;         const float2 c = make_float2(TC[m], INV ? TS[m] : -TS[m]);
;         const float2 twf = cmul(tbs[k], c);
;         const c32 tw = {twf.x, twf.y};
;         const c32 a = v[j], b = v[j + hd];
;         if (!INV) { v[j] = a + b; v[j + hd] = cmul_pk(a - b, tw); }
;         else { const c32 bt = cmul_pk(b, tw); v[j] = a + bt; v[j + hd] = a - bt; }
;       }
;     }
;   }
; template <int LOGN>
; __device__ __forceinline__ void fft_fused_mul(float2* X, const c32 (&kf)[32]) {
;     ...
;   for (int j = 0; j < 32; ++j) v[j] = cmul_pk(v[j], kf[j]);
	s_nop 0
	v_pk_fma_f32 v[76:77], v[76:77], v[66:67], v[82:83] op_sel:[1,1,0] op_sel_hi:[1,0,1] neg_lo:[0,1,0]
	v_pk_add_f32 v[82:83], v[70:71], v[72:73]
	v_pk_add_f32 v[70:71], v[70:71], v[72:73] neg_lo:[0,1] neg_hi:[0,1]
	s_nop 0
	v_pk_mul_f32 v[72:73], v[70:71], v[68:69] op_sel:[0,0] op_sel_hi:[0,1]
	s_nop 0
	v_pk_fma_f32 v[68:69], v[70:71], v[68:69], v[72:73] op_sel:[1,1,0] op_sel_hi:[1,0,1] neg_lo:[0,1,0]
	v_pk_add_f32 v[70:71], v[80:81], v[96:97]
	v_pk_add_f32 v[72:73], v[80:81], v[96:97] neg_lo:[0,1] neg_hi:[0,1]
	s_nop 0
	v_pk_mul_f32 v[80:81], v[72:73], v[66:67] op_sel:[0,0] op_sel_hi:[0,1]
	s_nop 0
	v_pk_fma_f32 v[72:73], v[72:73], v[66:67], v[80:81] op_sel:[1,1,0] op_sel_hi:[1,0,1] neg_lo:[0,1,0]
	v_pk_add_f32 v[80:81], v[94:95], v[110:111]
	v_pk_add_f32 v[94:95], v[94:95], v[110:111] neg_lo:[0,1] neg_hi:[0,1]
	v_pk_add_f32 v[110:111], v[120:121], v[122:123] neg_lo:[0,1] neg_hi:[0,1]
	v_pk_mul_f32 v[96:97], v[94:95], v[66:67] op_sel:[0,0] op_sel_hi:[0,1]
	s_nop 0
	v_pk_fma_f32 v[94:95], v[94:95], v[66:67], v[96:97] op_sel:[1,1,0] op_sel_hi:[1,0,1] neg_lo:[0,1,0]
	v_pk_add_f32 v[96:97], v[120:121], v[122:123]
	v_pk_mul_f32 v[120:121], v[110:111], v[66:67] op_sel:[0,0] op_sel_hi:[0,1]
	v_pk_add_f32 v[122:123], v[124:125], v[128:129] neg_lo:[0,1] neg_hi:[0,1]
	v_pk_fma_f32 v[110:111], v[110:111], v[66:67], v[120:121] op_sel:[1,1,0] op_sel_hi:[1,0,1] neg_lo:[0,1,0]
	v_pk_add_f32 v[120:121], v[106:107], v[118:119]
	v_pk_add_f32 v[106:107], v[106:107], v[118:119] neg_lo:[0,1] neg_hi:[0,1]
	s_nop 0
	v_pk_mul_f32 v[118:119], v[106:107], v[66:67] op_sel:[0,0] op_sel_hi:[0,1]
	s_nop 0
	v_pk_fma_f32 v[106:107], v[106:107], v[66:67], v[118:119] op_sel:[1,1,0] op_sel_hi:[1,0,1] neg_lo:[0,1,0]
	v_pk_add_f32 v[118:119], v[124:125], v[128:129]
	v_pk_mul_f32 v[124:125], v[122:123], v[66:67] op_sel:[0,0] op_sel_hi:[0,1]
	v_pk_add_f32 v[128:129], v[130:131], v[132:133] neg_lo:[0,1] neg_hi:[0,1]
	v_pk_fma_f32 v[122:123], v[122:123], v[66:67], v[124:125] op_sel:[1,1,0] op_sel_hi:[1,0,1] neg_lo:[0,1,0]
	v_pk_add_f32 v[124:125], v[126:127], v[112:113]
	v_pk_add_f32 v[112:113], v[126:127], v[112:113] neg_lo:[0,1] neg_hi:[0,1]
	s_nop 0
	v_pk_mul_f32 v[126:127], v[112:113], v[66:67] op_sel:[0,0] op_sel_hi:[0,1]
	s_nop 0
	v_pk_fma_f32 v[112:113], v[112:113], v[66:67], v[126:127] op_sel:[1,1,0] op_sel_hi:[1,0,1] neg_lo:[0,1,0]
	v_pk_add_f32 v[126:127], v[116:117], v[108:109]
	v_pk_add_f32 v[108:109], v[116:117], v[108:109] neg_lo:[0,1] neg_hi:[0,1]
	s_nop 0
	v_pk_mul_f32 v[116:117], v[108:109], v[66:67] op_sel:[0,0] op_sel_hi:[0,1]
	s_nop 0
	v_pk_fma_f32 v[108:109], v[108:109], v[66:67], v[116:117] op_sel:[1,1,0] op_sel_hi:[1,0,1] neg_lo:[0,1,0]
	v_pk_add_f32 v[116:117], v[104:105], v[114:115]
	v_pk_add_f32 v[104:105], v[104:105], v[114:115] neg_lo:[0,1] neg_hi:[0,1]
	s_nop 0
	v_pk_mul_f32 v[114:115], v[104:105], v[66:67] op_sel:[0,0] op_sel_hi:[0,1]
	s_nop 0
	v_pk_fma_f32 v[104:105], v[104:105], v[66:67], v[114:115] op_sel:[1,1,0] op_sel_hi:[1,0,1] neg_lo:[0,1,0]
	v_pk_add_f32 v[114:115], v[130:131], v[132:133]
	v_pk_mul_f32 v[130:131], v[128:129], v[66:67] op_sel:[0,0] op_sel_hi:[0,1]
	s_nop 0
	v_pk_fma_f32 v[128:129], v[128:129], v[66:67], v[130:131] op_sel:[1,1,0] op_sel_hi:[1,0,1] neg_lo:[0,1,0]
	v_pk_add_f32 v[130:131], v[98:99], v[92:93]
	v_pk_add_f32 v[92:93], v[98:99], v[92:93] neg_lo:[0,1] neg_hi:[0,1]
	s_nop 0
	v_pk_mul_f32 v[98:99], v[92:93], v[66:67] op_sel:[0,0] op_sel_hi:[0,1]
	s_nop 0
	v_pk_fma_f32 v[92:93], v[92:93], v[66:67], v[98:99] op_sel:[1,1,0] op_sel_hi:[1,0,1] neg_lo:[0,1,0]
	v_pk_add_f32 v[98:99], v[134:135], v[84:85]
	v_pk_add_f32 v[84:85], v[134:135], v[84:85] neg_lo:[0,1] neg_hi:[0,1]
	s_nop 0
	v_pk_mul_f32 v[132:133], v[84:85], v[66:67] op_sel:[0,0] op_sel_hi:[0,1]
	s_nop 0
	v_pk_fma_f32 v[84:85], v[84:85], v[66:67], v[132:133] op_sel:[1,1,0] op_sel_hi:[1,0,1] neg_lo:[0,1,0]
	v_pk_add_f32 v[132:133], v[78:79], v[90:91]
	v_pk_add_f32 v[78:79], v[78:79], v[90:91] neg_lo:[0,1] neg_hi:[0,1]
	s_nop 0
	v_pk_mul_f32 v[90:91], v[78:79], v[66:67] op_sel:[0,0] op_sel_hi:[0,1]
	s_nop 0
	v_pk_fma_f32 v[78:79], v[78:79], v[66:67], v[90:91] op_sel:[1,1,0] op_sel_hi:[1,0,1] neg_lo:[0,1,0]
	v_pk_add_f32 v[90:91], v[100:101], v[102:103]
	v_pk_add_f32 v[100:101], v[100:101], v[102:103] neg_lo:[0,1] neg_hi:[0,1]
	s_nop 0
	v_pk_mul_f32 v[102:103], v[100:101], v[66:67] op_sel:[0,0] op_sel_hi:[0,1]
	s_nop 0
	v_pk_fma_f32 v[100:101], v[100:101], v[66:67], v[102:103] op_sel:[1,1,0] op_sel_hi:[1,0,1] neg_lo:[0,1,0]
	v_pk_add_f32 v[102:103], v[74:75], v[86:87]
	v_pk_add_f32 v[74:75], v[74:75], v[86:87] neg_lo:[0,1] neg_hi:[0,1]
	s_nop 0
	v_pk_mul_f32 v[86:87], v[74:75], v[66:67] op_sel:[0,0] op_sel_hi:[0,1]
	s_nop 0
	v_pk_fma_f32 v[74:75], v[74:75], v[66:67], v[86:87] op_sel:[1,1,0] op_sel_hi:[1,0,1] neg_lo:[0,1,0]
	v_pk_add_f32 v[86:87], v[88:89], v[82:83]
	v_pk_add_f32 v[82:83], v[88:89], v[82:83] neg_lo:[0,1] neg_hi:[0,1]
	s_nop 0
	v_pk_mul_f32 v[88:89], v[82:83], v[66:67] op_sel:[0,0] op_sel_hi:[0,1]
	s_nop 0
	v_pk_fma_f32 v[82:83], v[82:83], v[66:67], v[88:89] op_sel:[1,1,0] op_sel_hi:[1,0,1] neg_lo:[0,1,0]
	v_pk_add_f32 v[88:89], v[76:77], v[68:69]
	v_pk_add_f32 v[68:69], v[76:77], v[68:69] neg_lo:[0,1] neg_hi:[0,1]
	s_nop 0
	v_pk_mul_f32 v[76:77], v[68:69], v[66:67] op_sel:[0,0] op_sel_hi:[0,1]
	s_nop 0
	v_pk_fma_f32 v[66:67], v[68:69], v[66:67], v[76:77] op_sel:[1,1,0] op_sel_hi:[1,0,1] neg_lo:[0,1,0]
	v_pk_mul_f32 v[68:69], v[70:71], v[30:31] op_sel:[0,0] op_sel_hi:[0,1]
	s_nop 0
	v_pk_fma_f32 v[30:31], v[70:71], v[30:31], v[68:69] op_sel:[1,1,0] op_sel_hi:[1,0,1] neg_lo:[0,1,0]
	v_pk_mul_f32 v[68:69], v[72:73], v[64:65] op_sel:[0,0] op_sel_hi:[0,1]
; __device__ __forceinline__ c32 cmul_pk(c32 a, c32 b) {
;   c32 t, r;
;   asm("v_pk_mul_f32 %0, %1, %2 op_sel:[0,0] op_sel_hi:[0,1]" : "=v"(t) : "v"(a), "v"(b));
;   asm("v_pk_fma_f32 %0, %1, %2, %3 op_sel:[1,1,0] op_sel_hi:[1,0,1] neg_lo:[0,1,0]" : "=v"(r) : "v"(a), "v"(b), "v"(t));
;   return r;
; }
; template <int LOGN>
; __device__ __forceinline__ void fft_fused_mul(float2* X, const c32 (&kf)[32]) {
;     ...
;   for (int j = 0; j < 32; ++j) v[j] = cmul_pk(v[j], kf[j]);
	s_nop 0
	v_pk_fma_f32 v[64:65], v[72:73], v[64:65], v[68:69] op_sel:[1,1,0] op_sel_hi:[1,0,1] neg_lo:[0,1,0]
	v_pk_mul_f32 v[68:69], v[80:81], v[28:29] op_sel:[0,0] op_sel_hi:[0,1]
	s_nop 0
	v_pk_fma_f32 v[28:29], v[80:81], v[28:29], v[68:69] op_sel:[1,1,0] op_sel_hi:[1,0,1] neg_lo:[0,1,0]
	v_pk_mul_f32 v[68:69], v[94:95], v[62:63] op_sel:[0,0] op_sel_hi:[0,1]
	s_nop 0
	v_pk_fma_f32 v[62:63], v[94:95], v[62:63], v[68:69] op_sel:[1,1,0] op_sel_hi:[1,0,1] neg_lo:[0,1,0]
	v_pk_mul_f32 v[68:69], v[96:97], v[26:27] op_sel:[0,0] op_sel_hi:[0,1]
	s_nop 0
	v_pk_fma_f32 v[26:27], v[96:97], v[26:27], v[68:69] op_sel:[1,1,0] op_sel_hi:[1,0,1] neg_lo:[0,1,0]
	v_pk_mul_f32 v[68:69], v[110:111], v[60:61] op_sel:[0,0] op_sel_hi:[0,1]
	s_nop 0
	v_pk_fma_f32 v[60:61], v[110:111], v[60:61], v[68:69] op_sel:[1,1,0] op_sel_hi:[1,0,1] neg_lo:[0,1,0]
	v_pk_mul_f32 v[68:69], v[120:121], v[24:25] op_sel:[0,0] op_sel_hi:[0,1]
	s_nop 0
	v_pk_fma_f32 v[24:25], v[120:121], v[24:25], v[68:69] op_sel:[1,1,0] op_sel_hi:[1,0,1] neg_lo:[0,1,0]
	v_pk_mul_f32 v[68:69], v[106:107], v[58:59] op_sel:[0,0] op_sel_hi:[0,1]
	s_nop 0
	v_pk_fma_f32 v[58:59], v[106:107], v[58:59], v[68:69] op_sel:[1,1,0] op_sel_hi:[1,0,1] neg_lo:[0,1,0]
	v_pk_mul_f32 v[68:69], v[118:119], v[22:23] op_sel:[0,0] op_sel_hi:[0,1]
	s_nop 0
	v_pk_fma_f32 v[22:23], v[118:119], v[22:23], v[68:69] op_sel:[1,1,0] op_sel_hi:[1,0,1] neg_lo:[0,1,0]
	v_pk_mul_f32 v[68:69], v[122:123], v[56:57] op_sel:[0,0] op_sel_hi:[0,1]
	s_nop 0
	v_pk_fma_f32 v[56:57], v[122:123], v[56:57], v[68:69] op_sel:[1,1,0] op_sel_hi:[1,0,1] neg_lo:[0,1,0]
	v_pk_mul_f32 v[68:69], v[124:125], v[20:21] op_sel:[0,0] op_sel_hi:[0,1]
	s_nop 0
	v_pk_fma_f32 v[20:21], v[124:125], v[20:21], v[68:69] op_sel:[1,1,0] op_sel_hi:[1,0,1] neg_lo:[0,1,0]
	v_pk_mul_f32 v[68:69], v[112:113], v[54:55] op_sel:[0,0] op_sel_hi:[0,1]
	s_nop 0
	v_pk_fma_f32 v[54:55], v[112:113], v[54:55], v[68:69] op_sel:[1,1,0] op_sel_hi:[1,0,1] neg_lo:[0,1,0]
	v_pk_mul_f32 v[68:69], v[126:127], v[18:19] op_sel:[0,0] op_sel_hi:[0,1]
	s_nop 0
	v_pk_fma_f32 v[18:19], v[126:127], v[18:19], v[68:69] op_sel:[1,1,0] op_sel_hi:[1,0,1] neg_lo:[0,1,0]
	v_pk_mul_f32 v[68:69], v[108:109], v[52:53] op_sel:[0,0] op_sel_hi:[0,1]
	s_nop 0
	v_pk_fma_f32 v[52:53], v[108:109], v[52:53], v[68:69] op_sel:[1,1,0] op_sel_hi:[1,0,1] neg_lo:[0,1,0]
	v_pk_mul_f32 v[68:69], v[116:117], v[16:17] op_sel:[0,0] op_sel_hi:[0,1]
	s_nop 0
	v_pk_fma_f32 v[16:17], v[116:117], v[16:17], v[68:69] op_sel:[1,1,0] op_sel_hi:[1,0,1] neg_lo:[0,1,0]
	v_pk_mul_f32 v[68:69], v[104:105], v[50:51] op_sel:[0,0] op_sel_hi:[0,1]
	s_nop 0
	v_pk_fma_f32 v[50:51], v[104:105], v[50:51], v[68:69] op_sel:[1,1,0] op_sel_hi:[1,0,1] neg_lo:[0,1,0]
	v_pk_mul_f32 v[68:69], v[114:115], v[14:15] op_sel:[0,0] op_sel_hi:[0,1]
	s_nop 0
	v_pk_fma_f32 v[14:15], v[114:115], v[14:15], v[68:69] op_sel:[1,1,0] op_sel_hi:[1,0,1] neg_lo:[0,1,0]
	v_pk_mul_f32 v[68:69], v[128:129], v[48:49] op_sel:[0,0] op_sel_hi:[0,1]
	s_nop 0
	v_pk_fma_f32 v[48:49], v[128:129], v[48:49], v[68:69] op_sel:[1,1,0] op_sel_hi:[1,0,1] neg_lo:[0,1,0]
	v_pk_mul_f32 v[68:69], v[130:131], v[12:13] op_sel:[0,0] op_sel_hi:[0,1]
	s_nop 0
	v_pk_fma_f32 v[12:13], v[130:131], v[12:13], v[68:69] op_sel:[1,1,0] op_sel_hi:[1,0,1] neg_lo:[0,1,0]
	v_pk_mul_f32 v[68:69], v[92:93], v[46:47] op_sel:[0,0] op_sel_hi:[0,1]
	s_nop 0
	v_pk_fma_f32 v[46:47], v[92:93], v[46:47], v[68:69] op_sel:[1,1,0] op_sel_hi:[1,0,1] neg_lo:[0,1,0]
	v_pk_mul_f32 v[68:69], v[98:99], v[10:11] op_sel:[0,0] op_sel_hi:[0,1]
	s_nop 0
	v_pk_fma_f32 v[10:11], v[98:99], v[10:11], v[68:69] op_sel:[1,1,0] op_sel_hi:[1,0,1] neg_lo:[0,1,0]
	v_pk_mul_f32 v[68:69], v[84:85], v[44:45] op_sel:[0,0] op_sel_hi:[0,1]
	s_nop 0
	v_pk_fma_f32 v[44:45], v[84:85], v[44:45], v[68:69] op_sel:[1,1,0] op_sel_hi:[1,0,1] neg_lo:[0,1,0]
	v_pk_mul_f32 v[68:69], v[132:133], v[8:9] op_sel:[0,0] op_sel_hi:[0,1]
	s_nop 0
	v_pk_fma_f32 v[8:9], v[132:133], v[8:9], v[68:69] op_sel:[1,1,0] op_sel_hi:[1,0,1] neg_lo:[0,1,0]
	v_pk_mul_f32 v[68:69], v[78:79], v[42:43] op_sel:[0,0] op_sel_hi:[0,1]
	s_nop 0
	v_pk_fma_f32 v[42:43], v[78:79], v[42:43], v[68:69] op_sel:[1,1,0] op_sel_hi:[1,0,1] neg_lo:[0,1,0]
	v_pk_mul_f32 v[68:69], v[90:91], v[6:7] op_sel:[0,0] op_sel_hi:[0,1]
	s_nop 0
	v_pk_fma_f32 v[6:7], v[90:91], v[6:7], v[68:69] op_sel:[1,1,0] op_sel_hi:[1,0,1] neg_lo:[0,1,0]
	v_pk_mul_f32 v[68:69], v[100:101], v[40:41] op_sel:[0,0] op_sel_hi:[0,1]
	s_nop 0
	v_pk_fma_f32 v[40:41], v[100:101], v[40:41], v[68:69] op_sel:[1,1,0] op_sel_hi:[1,0,1] neg_lo:[0,1,0]
	v_pk_mul_f32 v[68:69], v[102:103], v[4:5] op_sel:[0,0] op_sel_hi:[0,1]
	s_nop 0
	v_pk_fma_f32 v[4:5], v[102:103], v[4:5], v[68:69] op_sel:[1,1,0] op_sel_hi:[1,0,1] neg_lo:[0,1,0]
	v_pk_mul_f32 v[68:69], v[74:75], v[38:39] op_sel:[0,0] op_sel_hi:[0,1]
	s_nop 0
	v_pk_fma_f32 v[38:39], v[74:75], v[38:39], v[68:69] op_sel:[1,1,0] op_sel_hi:[1,0,1] neg_lo:[0,1,0]
	v_pk_mul_f32 v[68:69], v[86:87], v[2:3] op_sel:[0,0] op_sel_hi:[0,1]
	s_nop 0
	v_pk_fma_f32 v[2:3], v[86:87], v[2:3], v[68:69] op_sel:[1,1,0] op_sel_hi:[1,0,1] neg_lo:[0,1,0]
	v_pk_mul_f32 v[68:69], v[82:83], v[36:37] op_sel:[0,0] op_sel_hi:[0,1]
	s_nop 0
	v_pk_fma_f32 v[36:37], v[82:83], v[36:37], v[68:69] op_sel:[1,1,0] op_sel_hi:[1,0,1] neg_lo:[0,1,0]
	v_pk_mul_f32 v[68:69], v[88:89], v[0:1] op_sel:[0,0] op_sel_hi:[0,1]
	s_nop 0
	v_pk_fma_f32 v[68:69], v[88:89], v[0:1], v[68:69] op_sel:[1,1,0] op_sel_hi:[1,0,1] neg_lo:[0,1,0]
	v_pk_mul_f32 v[0:1], v[66:67], v[34:35] op_sel:[0,0] op_sel_hi:[0,1]
	s_nop 0
	v_pk_fma_f32 v[34:35], v[66:67], v[34:35], v[0:1] op_sel:[1,1,0] op_sel_hi:[1,0,1] neg_lo:[0,1,0]
	v_mov_b64_e32 v[0:1], s[6:7]
; __device__ __forceinline__ float2 cmul(float2 a, float2 b) { return make_float2(a.x * b.x - a.y * b.y, a.x * b.y + a.y * b.x); }
; template <int R, bool INV>
; __device__ __forceinline__ void butterflies(c32 (&v)[1 << R], float turns0) {
;     ...
;   for (int kk = 0; kk < R; ++kk) {
;     const int k = INV ? (R - 1 - kk) : kk;
;     const int hd = RAD >> (k + 1);
; #pragma unroll
;     for (int j = 0; j < RAD; ++j) {
;       if ((j & hd) == 0) {
;         const int m = (j & (hd - 1)) * (16 / hd);
;         const float2 c = make_float2(TC[m], INV ? TS[m] : -TS[m]);
;         const float2 twf = cmul(tbs[k], c);
;         const c32 tw = {twf.x, twf.y};
;         const c32 a = v[j], b = v[j + hd];
;         if (!INV) { v[j] = a + b; v[j + hd] = cmul_pk(a - b, tw); }
;         else { const c32 bt = cmul_pk(b, tw); v[j] = a + bt; v[j + hd] = a - bt; }
;       }
;     }
;   }
	v_pk_mul_f32 v[66:67], v[64:65], v[0:1] op_sel:[0,0] op_sel_hi:[0,1]
	s_nop 0
	v_pk_fma_f32 v[64:65], v[64:65], v[0:1], v[66:67] op_sel:[1,1,0] op_sel_hi:[1,0,1] neg_lo:[0,1,0]
	s_nop 0
	v_pk_add_f32 v[66:67], v[30:31], v[64:65]
	v_pk_add_f32 v[30:31], v[30:31], v[64:65] neg_lo:[0,1] neg_hi:[0,1]
	v_pk_mul_f32 v[64:65], v[62:63], v[0:1] op_sel:[0,0] op_sel_hi:[0,1]
	s_nop 0
	v_pk_fma_f32 v[62:63], v[62:63], v[0:1], v[64:65] op_sel:[1,1,0] op_sel_hi:[1,0,1] neg_lo:[0,1,0]
	s_nop 0
	v_pk_add_f32 v[64:65], v[28:29], v[62:63]
	v_pk_add_f32 v[28:29], v[28:29], v[62:63] neg_lo:[0,1] neg_hi:[0,1]
	v_pk_mul_f32 v[62:63], v[60:61], v[0:1] op_sel:[0,0] op_sel_hi:[0,1]
	s_nop 0
	v_pk_fma_f32 v[60:61], v[60:61], v[0:1], v[62:63] op_sel:[1,1,0] op_sel_hi:[1,0,1] neg_lo:[0,1,0]
	s_nop 0
	v_pk_add_f32 v[62:63], v[26:27], v[60:61]
	v_pk_add_f32 v[26:27], v[26:27], v[60:61] neg_lo:[0,1] neg_hi:[0,1]
	v_pk_mul_f32 v[60:61], v[58:59], v[0:1] op_sel:[0,0] op_sel_hi:[0,1]
	s_nop 0
	v_pk_fma_f32 v[58:59], v[58:59], v[0:1], v[60:61] op_sel:[1,1,0] op_sel_hi:[1,0,1] neg_lo:[0,1,0]
	s_nop 0
	v_pk_add_f32 v[60:61], v[24:25], v[58:59]
	v_pk_add_f32 v[24:25], v[24:25], v[58:59] neg_lo:[0,1] neg_hi:[0,1]
	v_pk_mul_f32 v[58:59], v[56:57], v[0:1] op_sel:[0,0] op_sel_hi:[0,1]
	s_nop 0
	v_pk_fma_f32 v[56:57], v[56:57], v[0:1], v[58:59] op_sel:[1,1,0] op_sel_hi:[1,0,1] neg_lo:[0,1,0]
	s_nop 0
	v_pk_add_f32 v[58:59], v[22:23], v[56:57]
	v_pk_add_f32 v[22:23], v[22:23], v[56:57] neg_lo:[0,1] neg_hi:[0,1]
	v_pk_mul_f32 v[56:57], v[54:55], v[0:1] op_sel:[0,0] op_sel_hi:[0,1]
	s_nop 0
	v_pk_fma_f32 v[54:55], v[54:55], v[0:1], v[56:57] op_sel:[1,1,0] op_sel_hi:[1,0,1] neg_lo:[0,1,0]
	s_nop 0
	v_pk_add_f32 v[56:57], v[20:21], v[54:55]
	v_pk_add_f32 v[20:21], v[20:21], v[54:55] neg_lo:[0,1] neg_hi:[0,1]
	v_pk_mul_f32 v[54:55], v[52:53], v[0:1] op_sel:[0,0] op_sel_hi:[0,1]
	s_nop 0
	v_pk_fma_f32 v[52:53], v[52:53], v[0:1], v[54:55] op_sel:[1,1,0] op_sel_hi:[1,0,1] neg_lo:[0,1,0]
	s_nop 0
	v_pk_add_f32 v[54:55], v[18:19], v[52:53]
	v_pk_add_f32 v[18:19], v[18:19], v[52:53] neg_lo:[0,1] neg_hi:[0,1]
	v_pk_mul_f32 v[52:53], v[50:51], v[0:1] op_sel:[0,0] op_sel_hi:[0,1]
	s_nop 0
	v_pk_fma_f32 v[50:51], v[50:51], v[0:1], v[52:53] op_sel:[1,1,0] op_sel_hi:[1,0,1] neg_lo:[0,1,0]
	s_nop 0
	v_pk_add_f32 v[52:53], v[16:17], v[50:51]
	v_pk_add_f32 v[16:17], v[16:17], v[50:51] neg_lo:[0,1] neg_hi:[0,1]
	v_pk_mul_f32 v[50:51], v[48:49], v[0:1] op_sel:[0,0] op_sel_hi:[0,1]
	s_nop 0
	v_pk_fma_f32 v[48:49], v[48:49], v[0:1], v[50:51] op_sel:[1,1,0] op_sel_hi:[1,0,1] neg_lo:[0,1,0]
	s_nop 0
	v_pk_add_f32 v[50:51], v[14:15], v[48:49]
	v_pk_add_f32 v[14:15], v[14:15], v[48:49] neg_lo:[0,1] neg_hi:[0,1]
	v_pk_mul_f32 v[48:49], v[46:47], v[0:1] op_sel:[0,0] op_sel_hi:[0,1]
	s_nop 0
	v_pk_fma_f32 v[46:47], v[46:47], v[0:1], v[48:49] op_sel:[1,1,0] op_sel_hi:[1,0,1] neg_lo:[0,1,0]
	s_nop 0
	v_pk_add_f32 v[48:49], v[12:13], v[46:47]
	v_pk_add_f32 v[12:13], v[12:13], v[46:47] neg_lo:[0,1] neg_hi:[0,1]
	v_pk_mul_f32 v[46:47], v[44:45], v[0:1] op_sel:[0,0] op_sel_hi:[0,1]
	s_nop 0
	v_pk_fma_f32 v[44:45], v[44:45], v[0:1], v[46:47] op_sel:[1,1,0] op_sel_hi:[1,0,1] neg_lo:[0,1,0]
	s_nop 0
	v_pk_add_f32 v[46:47], v[10:11], v[44:45]
	v_pk_add_f32 v[10:11], v[10:11], v[44:45] neg_lo:[0,1] neg_hi:[0,1]
	v_pk_mul_f32 v[44:45], v[42:43], v[0:1] op_sel:[0,0] op_sel_hi:[0,1]
	s_nop 0
	v_pk_fma_f32 v[42:43], v[42:43], v[0:1], v[44:45] op_sel:[1,1,0] op_sel_hi:[1,0,1] neg_lo:[0,1,0]
	s_nop 0
	v_pk_add_f32 v[44:45], v[8:9], v[42:43]
	v_pk_add_f32 v[8:9], v[8:9], v[42:43] neg_lo:[0,1] neg_hi:[0,1]
	v_pk_mul_f32 v[42:43], v[40:41], v[0:1] op_sel:[0,0] op_sel_hi:[0,1]
	s_nop 0
	v_pk_fma_f32 v[40:41], v[40:41], v[0:1], v[42:43] op_sel:[1,1,0] op_sel_hi:[1,0,1] neg_lo:[0,1,0]
	s_nop 0
	v_pk_add_f32 v[42:43], v[6:7], v[40:41]
	v_pk_add_f32 v[6:7], v[6:7], v[40:41] neg_lo:[0,1] neg_hi:[0,1]
	v_pk_mul_f32 v[40:41], v[38:39], v[0:1] op_sel:[0,0] op_sel_hi:[0,1]
	s_nop 0
	v_pk_fma_f32 v[38:39], v[38:39], v[0:1], v[40:41] op_sel:[1,1,0] op_sel_hi:[1,0,1] neg_lo:[0,1,0]
	s_nop 0
	v_pk_add_f32 v[40:41], v[4:5], v[38:39]
	v_pk_add_f32 v[4:5], v[4:5], v[38:39] neg_lo:[0,1] neg_hi:[0,1]
	v_pk_mul_f32 v[38:39], v[36:37], v[0:1] op_sel:[0,0] op_sel_hi:[0,1]
	s_nop 0
	v_pk_fma_f32 v[36:37], v[36:37], v[0:1], v[38:39] op_sel:[1,1,0] op_sel_hi:[1,0,1] neg_lo:[0,1,0]
	s_nop 0
	v_pk_add_f32 v[38:39], v[2:3], v[36:37]
	v_pk_add_f32 v[36:37], v[2:3], v[36:37] neg_lo:[0,1] neg_hi:[0,1]
	v_pk_mul_f32 v[2:3], v[34:35], v[0:1] op_sel:[0,0] op_sel_hi:[0,1]
	s_nop 0
	v_pk_fma_f32 v[2:3], v[34:35], v[0:1], v[2:3] op_sel:[1,1,0] op_sel_hi:[1,0,1] neg_lo:[0,1,0]
	s_nop 0
	v_pk_add_f32 v[34:35], v[68:69], v[2:3]
	v_pk_add_f32 v[68:69], v[68:69], v[2:3] neg_lo:[0,1] neg_hi:[0,1]
	v_pk_mul_f32 v[2:3], v[64:65], v[0:1] op_sel:[0,0] op_sel_hi:[0,1]
	s_nop 0
	v_pk_fma_f32 v[2:3], v[64:65], v[0:1], v[2:3] op_sel:[1,1,0] op_sel_hi:[1,0,1] neg_lo:[0,1,0]
	s_nop 0
	v_pk_add_f32 v[64:65], v[66:67], v[2:3]
	v_pk_add_f32 v[66:67], v[66:67], v[2:3] neg_lo:[0,1] neg_hi:[0,1]
	v_mov_b64_e32 v[2:3], s[0:1]
	v_pk_mul_f32 v[70:71], v[28:29], v[2:3] op_sel:[0,0] op_sel_hi:[0,1]
	s_mov_b32 s0, s73
	v_pk_fma_f32 v[28:29], v[28:29], v[2:3], v[70:71] op_sel:[1,1,0] op_sel_hi:[1,0,1] neg_lo:[0,1,0]
	s_mov_b32 s1, s73
	v_pk_add_f32 v[70:71], v[30:31], v[28:29]
	v_pk_add_f32 v[28:29], v[30:31], v[28:29] neg_lo:[0,1] neg_hi:[0,1]
	v_pk_mul_f32 v[30:31], v[60:61], v[0:1] op_sel:[0,0] op_sel_hi:[0,1]
	s_nop 0
	v_pk_fma_f32 v[30:31], v[60:61], v[0:1], v[30:31] op_sel:[1,1,0] op_sel_hi:[1,0,1] neg_lo:[0,1,0]
	s_nop 0
	v_pk_add_f32 v[60:61], v[62:63], v[30:31]
; __device__ __forceinline__ float2 cmul(float2 a, float2 b) { return make_float2(a.x * b.x - a.y * b.y, a.x * b.y + a.y * b.x); }
; template <int R, bool INV>
; __device__ __forceinline__ void butterflies(c32 (&v)[1 << R], float turns0) {
;     ...
;   for (int kk = 0; kk < R; ++kk) {
;     const int k = INV ? (R - 1 - kk) : kk;
;     const int hd = RAD >> (k + 1);
; #pragma unroll
;     for (int j = 0; j < RAD; ++j) {
;       if ((j & hd) == 0) {
;         const int m = (j & (hd - 1)) * (16 / hd);
;         const float2 c = make_float2(TC[m], INV ? TS[m] : -TS[m]);
;         const float2 twf = cmul(tbs[k], c);
;         const c32 tw = {twf.x, twf.y};
;         const c32 a = v[j], b = v[j + hd];
;         if (!INV) { v[j] = a + b; v[j + hd] = cmul_pk(a - b, tw); }
;         else { const c32 bt = cmul_pk(b, tw); v[j] = a + bt; v[j + hd] = a - bt; }
;       }
;     }
;   }
	v_pk_add_f32 v[30:31], v[62:63], v[30:31] neg_lo:[0,1] neg_hi:[0,1]
	v_pk_mul_f32 v[62:63], v[24:25], v[2:3] op_sel:[0,0] op_sel_hi:[0,1]
	s_nop 0
	v_pk_fma_f32 v[24:25], v[24:25], v[2:3], v[62:63] op_sel:[1,1,0] op_sel_hi:[1,0,1] neg_lo:[0,1,0]
	s_nop 0
	v_pk_add_f32 v[62:63], v[26:27], v[24:25]
	v_pk_add_f32 v[24:25], v[26:27], v[24:25] neg_lo:[0,1] neg_hi:[0,1]
	v_pk_mul_f32 v[26:27], v[56:57], v[0:1] op_sel:[0,0] op_sel_hi:[0,1]
	s_nop 0
	v_pk_fma_f32 v[26:27], v[56:57], v[0:1], v[26:27] op_sel:[1,1,0] op_sel_hi:[1,0,1] neg_lo:[0,1,0]
	s_nop 0
	v_pk_add_f32 v[56:57], v[58:59], v[26:27]
	v_pk_add_f32 v[26:27], v[58:59], v[26:27] neg_lo:[0,1] neg_hi:[0,1]
	v_pk_mul_f32 v[58:59], v[20:21], v[2:3] op_sel:[0,0] op_sel_hi:[0,1]
	s_nop 0
	v_pk_fma_f32 v[20:21], v[20:21], v[2:3], v[58:59] op_sel:[1,1,0] op_sel_hi:[1,0,1] neg_lo:[0,1,0]
	s_nop 0
	v_pk_add_f32 v[58:59], v[22:23], v[20:21]
	v_pk_add_f32 v[20:21], v[22:23], v[20:21] neg_lo:[0,1] neg_hi:[0,1]
	v_pk_mul_f32 v[22:23], v[52:53], v[0:1] op_sel:[0,0] op_sel_hi:[0,1]
	s_nop 0
	v_pk_fma_f32 v[22:23], v[52:53], v[0:1], v[22:23] op_sel:[1,1,0] op_sel_hi:[1,0,1] neg_lo:[0,1,0]
	s_nop 0
	v_pk_add_f32 v[52:53], v[54:55], v[22:23]
	v_pk_add_f32 v[22:23], v[54:55], v[22:23] neg_lo:[0,1] neg_hi:[0,1]
	v_pk_mul_f32 v[54:55], v[16:17], v[2:3] op_sel:[0,0] op_sel_hi:[0,1]
	s_nop 0
	v_pk_fma_f32 v[16:17], v[16:17], v[2:3], v[54:55] op_sel:[1,1,0] op_sel_hi:[1,0,1] neg_lo:[0,1,0]
	s_nop 0
	v_pk_add_f32 v[54:55], v[18:19], v[16:17]
	v_pk_add_f32 v[16:17], v[18:19], v[16:17] neg_lo:[0,1] neg_hi:[0,1]
	v_pk_mul_f32 v[18:19], v[48:49], v[0:1] op_sel:[0,0] op_sel_hi:[0,1]
	s_nop 0
	v_pk_fma_f32 v[18:19], v[48:49], v[0:1], v[18:19] op_sel:[1,1,0] op_sel_hi:[1,0,1] neg_lo:[0,1,0]
	s_nop 0
	v_pk_add_f32 v[48:49], v[50:51], v[18:19]
	v_pk_add_f32 v[18:19], v[50:51], v[18:19] neg_lo:[0,1] neg_hi:[0,1]
	v_pk_mul_f32 v[50:51], v[12:13], v[2:3] op_sel:[0,0] op_sel_hi:[0,1]
	s_nop 0
	v_pk_fma_f32 v[12:13], v[12:13], v[2:3], v[50:51] op_sel:[1,1,0] op_sel_hi:[1,0,1] neg_lo:[0,1,0]
	s_nop 0
	v_pk_add_f32 v[50:51], v[14:15], v[12:13]
	v_pk_add_f32 v[12:13], v[14:15], v[12:13] neg_lo:[0,1] neg_hi:[0,1]
	v_pk_mul_f32 v[14:15], v[44:45], v[0:1] op_sel:[0,0] op_sel_hi:[0,1]
	s_nop 0
	v_pk_fma_f32 v[14:15], v[44:45], v[0:1], v[14:15] op_sel:[1,1,0] op_sel_hi:[1,0,1] neg_lo:[0,1,0]
	s_nop 0
	v_pk_add_f32 v[44:45], v[46:47], v[14:15]
	v_pk_add_f32 v[14:15], v[46:47], v[14:15] neg_lo:[0,1] neg_hi:[0,1]
	v_pk_mul_f32 v[46:47], v[8:9], v[2:3] op_sel:[0,0] op_sel_hi:[0,1]
	s_nop 0
	v_pk_fma_f32 v[8:9], v[8:9], v[2:3], v[46:47] op_sel:[1,1,0] op_sel_hi:[1,0,1] neg_lo:[0,1,0]
	s_nop 0
	v_pk_add_f32 v[46:47], v[10:11], v[8:9]
	v_pk_add_f32 v[8:9], v[10:11], v[8:9] neg_lo:[0,1] neg_hi:[0,1]
	v_pk_mul_f32 v[10:11], v[40:41], v[0:1] op_sel:[0,0] op_sel_hi:[0,1]
	s_nop 0
	v_pk_fma_f32 v[10:11], v[40:41], v[0:1], v[10:11] op_sel:[1,1,0] op_sel_hi:[1,0,1] neg_lo:[0,1,0]
	s_nop 0
	v_pk_add_f32 v[40:41], v[42:43], v[10:11]
	v_pk_add_f32 v[10:11], v[42:43], v[10:11] neg_lo:[0,1] neg_hi:[0,1]
	v_pk_mul_f32 v[42:43], v[4:5], v[2:3] op_sel:[0,0] op_sel_hi:[0,1]
	s_nop 0
	v_pk_fma_f32 v[4:5], v[4:5], v[2:3], v[42:43] op_sel:[1,1,0] op_sel_hi:[1,0,1] neg_lo:[0,1,0]
	s_nop 0
	v_pk_add_f32 v[42:43], v[6:7], v[4:5]
	v_pk_add_f32 v[4:5], v[6:7], v[4:5] neg_lo:[0,1] neg_hi:[0,1]
	v_pk_mul_f32 v[6:7], v[34:35], v[0:1] op_sel:[0,0] op_sel_hi:[0,1]
	s_nop 0
	v_pk_fma_f32 v[6:7], v[34:35], v[0:1], v[6:7] op_sel:[1,1,0] op_sel_hi:[1,0,1] neg_lo:[0,1,0]
	s_nop 0
	v_pk_add_f32 v[34:35], v[38:39], v[6:7]
	v_pk_add_f32 v[6:7], v[38:39], v[6:7] neg_lo:[0,1] neg_hi:[0,1]
	v_pk_mul_f32 v[38:39], v[68:69], v[2:3] op_sel:[0,0] op_sel_hi:[0,1]
	s_nop 0
	v_pk_fma_f32 v[38:39], v[68:69], v[2:3], v[38:39] op_sel:[1,1,0] op_sel_hi:[1,0,1] neg_lo:[0,1,0]
	s_nop 0
	v_pk_add_f32 v[68:69], v[36:37], v[38:39]
	v_pk_add_f32 v[36:37], v[36:37], v[38:39] neg_lo:[0,1] neg_hi:[0,1]
	v_pk_mul_f32 v[38:39], v[60:61], v[0:1] op_sel:[0,0] op_sel_hi:[0,1]
	s_nop 0
	v_pk_fma_f32 v[38:39], v[60:61], v[0:1], v[38:39] op_sel:[1,1,0] op_sel_hi:[1,0,1] neg_lo:[0,1,0]
	s_nop 0
	v_pk_add_f32 v[60:61], v[64:65], v[38:39]
	v_pk_add_f32 v[38:39], v[64:65], v[38:39] neg_lo:[0,1] neg_hi:[0,1]
	v_mov_b64_e32 v[64:65], s[0:1]
	v_pk_mul_f32 v[72:73], v[62:63], v[64:65] op_sel:[0,0] op_sel_hi:[0,1]
	s_mov_b32 s0, s9
	v_pk_fma_f32 v[62:63], v[62:63], v[64:65], v[72:73] op_sel:[1,1,0] op_sel_hi:[1,0,1] neg_lo:[0,1,0]
	s_mov_b32 s1, s8
	v_pk_add_f32 v[72:73], v[70:71], v[62:63]
	v_pk_add_f32 v[62:63], v[70:71], v[62:63] neg_lo:[0,1] neg_hi:[0,1]
	v_pk_mul_f32 v[70:71], v[30:31], v[2:3] op_sel:[0,0] op_sel_hi:[0,1]
	s_nop 0
	v_pk_fma_f32 v[30:31], v[30:31], v[2:3], v[70:71] op_sel:[1,1,0] op_sel_hi:[1,0,1] neg_lo:[0,1,0]
	s_nop 0
	v_pk_add_f32 v[70:71], v[66:67], v[30:31]
	v_pk_add_f32 v[30:31], v[66:67], v[30:31] neg_lo:[0,1] neg_hi:[0,1]
	v_mov_b64_e32 v[66:67], s[72:73]
	v_pk_mul_f32 v[74:75], v[24:25], v[66:67] op_sel:[0,0] op_sel_hi:[0,1]
	s_nop 0
	v_pk_fma_f32 v[24:25], v[24:25], v[66:67], v[74:75] op_sel:[1,1,0] op_sel_hi:[1,0,1] neg_lo:[0,1,0]
	s_nop 0
	v_pk_add_f32 v[74:75], v[28:29], v[24:25]
	v_pk_add_f32 v[24:25], v[28:29], v[24:25] neg_lo:[0,1] neg_hi:[0,1]
	v_pk_mul_f32 v[28:29], v[52:53], v[0:1] op_sel:[0,0] op_sel_hi:[0,1]
	s_nop 0
	v_pk_fma_f32 v[28:29], v[52:53], v[0:1], v[28:29] op_sel:[1,1,0] op_sel_hi:[1,0,1] neg_lo:[0,1,0]
	s_nop 0
	v_pk_add_f32 v[52:53], v[56:57], v[28:29]
	v_pk_add_f32 v[28:29], v[56:57], v[28:29] neg_lo:[0,1] neg_hi:[0,1]
	v_pk_mul_f32 v[56:57], v[54:55], v[64:65] op_sel:[0,0] op_sel_hi:[0,1]
	s_nop 0
	v_pk_fma_f32 v[54:55], v[54:55], v[64:65], v[56:57] op_sel:[1,1,0] op_sel_hi:[1,0,1] neg_lo:[0,1,0]
; __device__ __forceinline__ float2 cmul(float2 a, float2 b) { return make_float2(a.x * b.x - a.y * b.y, a.x * b.y + a.y * b.x); }
; template <int R, bool INV>
; __device__ __forceinline__ void butterflies(c32 (&v)[1 << R], float turns0) {
;     ...
;   for (int kk = 0; kk < R; ++kk) {
;     const int k = INV ? (R - 1 - kk) : kk;
;     const int hd = RAD >> (k + 1);
; #pragma unroll
;     for (int j = 0; j < RAD; ++j) {
;       if ((j & hd) == 0) {
;         const int m = (j & (hd - 1)) * (16 / hd);
;         const float2 c = make_float2(TC[m], INV ? TS[m] : -TS[m]);
;         const float2 twf = cmul(tbs[k], c);
;         const c32 tw = {twf.x, twf.y};
;         const c32 a = v[j], b = v[j + hd];
;         if (!INV) { v[j] = a + b; v[j + hd] = cmul_pk(a - b, tw); }
;         else { const c32 bt = cmul_pk(b, tw); v[j] = a + bt; v[j + hd] = a - bt; }
;       }
;     }
;   }
	s_nop 0
	v_pk_add_f32 v[56:57], v[58:59], v[54:55]
	v_pk_add_f32 v[54:55], v[58:59], v[54:55] neg_lo:[0,1] neg_hi:[0,1]
	v_pk_mul_f32 v[58:59], v[22:23], v[2:3] op_sel:[0,0] op_sel_hi:[0,1]
	s_nop 0
	v_pk_fma_f32 v[22:23], v[22:23], v[2:3], v[58:59] op_sel:[1,1,0] op_sel_hi:[1,0,1] neg_lo:[0,1,0]
	s_nop 0
	v_pk_add_f32 v[58:59], v[26:27], v[22:23]
	v_pk_add_f32 v[22:23], v[26:27], v[22:23] neg_lo:[0,1] neg_hi:[0,1]
	v_pk_mul_f32 v[26:27], v[16:17], v[66:67] op_sel:[0,0] op_sel_hi:[0,1]
	s_nop 0
	v_pk_fma_f32 v[16:17], v[16:17], v[66:67], v[26:27] op_sel:[1,1,0] op_sel_hi:[1,0,1] neg_lo:[0,1,0]
	s_nop 0
	v_pk_add_f32 v[26:27], v[20:21], v[16:17]
	v_pk_add_f32 v[16:17], v[20:21], v[16:17] neg_lo:[0,1] neg_hi:[0,1]
	v_pk_mul_f32 v[20:21], v[44:45], v[0:1] op_sel:[0,0] op_sel_hi:[0,1]
	s_nop 0
	v_pk_fma_f32 v[20:21], v[44:45], v[0:1], v[20:21] op_sel:[1,1,0] op_sel_hi:[1,0,1] neg_lo:[0,1,0]
	s_nop 0
	v_pk_add_f32 v[44:45], v[48:49], v[20:21]
	v_pk_add_f32 v[20:21], v[48:49], v[20:21] neg_lo:[0,1] neg_hi:[0,1]
	v_pk_mul_f32 v[48:49], v[46:47], v[64:65] op_sel:[0,0] op_sel_hi:[0,1]
	s_nop 0
	v_pk_fma_f32 v[46:47], v[46:47], v[64:65], v[48:49] op_sel:[1,1,0] op_sel_hi:[1,0,1] neg_lo:[0,1,0]
	s_nop 0
	v_pk_add_f32 v[48:49], v[50:51], v[46:47]
	v_pk_add_f32 v[46:47], v[50:51], v[46:47] neg_lo:[0,1] neg_hi:[0,1]
	v_pk_mul_f32 v[50:51], v[14:15], v[2:3] op_sel:[0,0] op_sel_hi:[0,1]
	s_nop 0
	v_pk_fma_f32 v[14:15], v[14:15], v[2:3], v[50:51] op_sel:[1,1,0] op_sel_hi:[1,0,1] neg_lo:[0,1,0]
	s_nop 0
	v_pk_add_f32 v[50:51], v[18:19], v[14:15]
	v_pk_add_f32 v[14:15], v[18:19], v[14:15] neg_lo:[0,1] neg_hi:[0,1]
	v_pk_mul_f32 v[18:19], v[8:9], v[66:67] op_sel:[0,0] op_sel_hi:[0,1]
	s_nop 0
	v_pk_fma_f32 v[8:9], v[8:9], v[66:67], v[18:19] op_sel:[1,1,0] op_sel_hi:[1,0,1] neg_lo:[0,1,0]
	s_nop 0
	v_pk_add_f32 v[18:19], v[12:13], v[8:9]
	v_pk_add_f32 v[8:9], v[12:13], v[8:9] neg_lo:[0,1] neg_hi:[0,1]
	v_pk_mul_f32 v[12:13], v[34:35], v[0:1] op_sel:[0,0] op_sel_hi:[0,1]
	s_nop 0
	v_pk_fma_f32 v[12:13], v[34:35], v[0:1], v[12:13] op_sel:[1,1,0] op_sel_hi:[1,0,1] neg_lo:[0,1,0]
	s_nop 0
	v_pk_add_f32 v[34:35], v[40:41], v[12:13]
	v_pk_add_f32 v[12:13], v[40:41], v[12:13] neg_lo:[0,1] neg_hi:[0,1]
	v_pk_mul_f32 v[40:41], v[68:69], v[64:65] op_sel:[0,0] op_sel_hi:[0,1]
	s_nop 0
	v_pk_fma_f32 v[40:41], v[68:69], v[64:65], v[40:41] op_sel:[1,1,0] op_sel_hi:[1,0,1] neg_lo:[0,1,0]
	s_nop 0
	v_pk_add_f32 v[68:69], v[42:43], v[40:41]
	v_pk_add_f32 v[40:41], v[42:43], v[40:41] neg_lo:[0,1] neg_hi:[0,1]
	v_pk_mul_f32 v[42:43], v[6:7], v[2:3] op_sel:[0,0] op_sel_hi:[0,1]
	s_nop 0
	v_pk_fma_f32 v[6:7], v[6:7], v[2:3], v[42:43] op_sel:[1,1,0] op_sel_hi:[1,0,1] neg_lo:[0,1,0]
	s_nop 0
	v_pk_add_f32 v[42:43], v[10:11], v[6:7]
	v_pk_add_f32 v[6:7], v[10:11], v[6:7] neg_lo:[0,1] neg_hi:[0,1]
	v_pk_mul_f32 v[10:11], v[36:37], v[66:67] op_sel:[0,0] op_sel_hi:[0,1]
	s_nop 0
	v_pk_fma_f32 v[10:11], v[36:37], v[66:67], v[10:11] op_sel:[1,1,0] op_sel_hi:[1,0,1] neg_lo:[0,1,0]
	s_nop 0
	v_pk_add_f32 v[36:37], v[4:5], v[10:11]
	v_pk_add_f32 v[4:5], v[4:5], v[10:11] neg_lo:[0,1] neg_hi:[0,1]
	v_pk_mul_f32 v[10:11], v[52:53], v[0:1] op_sel:[0,0] op_sel_hi:[0,1]
	s_nop 0
	v_pk_fma_f32 v[10:11], v[52:53], v[0:1], v[10:11] op_sel:[1,1,0] op_sel_hi:[1,0,1] neg_lo:[0,1,0]
	s_nop 0
	v_pk_add_f32 v[52:53], v[60:61], v[10:11]
	v_pk_add_f32 v[10:11], v[60:61], v[10:11] neg_lo:[0,1] neg_hi:[0,1]
	v_mov_b64_e32 v[60:61], s[0:1]
	v_pk_mul_f32 v[76:77], v[56:57], v[60:61] op_sel:[0,0] op_sel_hi:[0,1]
	s_mov_b32 s0, s19
	v_pk_fma_f32 v[56:57], v[56:57], v[60:61], v[76:77] op_sel:[1,1,0] op_sel_hi:[1,0,1] neg_lo:[0,1,0]
	s_mov_b32 s1, s18
	v_pk_add_f32 v[76:77], v[72:73], v[56:57]
	v_pk_add_f32 v[56:57], v[72:73], v[56:57] neg_lo:[0,1] neg_hi:[0,1]
	v_pk_mul_f32 v[72:73], v[58:59], v[64:65] op_sel:[0,0] op_sel_hi:[0,1]
	s_nop 0
	v_pk_fma_f32 v[58:59], v[58:59], v[64:65], v[72:73] op_sel:[1,1,0] op_sel_hi:[1,0,1] neg_lo:[0,1,0]
	s_nop 0
	v_pk_add_f32 v[72:73], v[70:71], v[58:59]
	v_pk_add_f32 v[58:59], v[70:71], v[58:59] neg_lo:[0,1] neg_hi:[0,1]
	v_mov_b64_e32 v[70:71], s[8:9]
	v_pk_mul_f32 v[78:79], v[26:27], v[70:71] op_sel:[0,0] op_sel_hi:[0,1]
	s_nop 0
	v_pk_fma_f32 v[26:27], v[26:27], v[70:71], v[78:79] op_sel:[1,1,0] op_sel_hi:[1,0,1] neg_lo:[0,1,0]
	s_nop 0
	v_pk_add_f32 v[78:79], v[74:75], v[26:27]
	v_pk_add_f32 v[26:27], v[74:75], v[26:27] neg_lo:[0,1] neg_hi:[0,1]
	v_pk_mul_f32 v[74:75], v[28:29], v[2:3] op_sel:[0,0] op_sel_hi:[0,1]
	s_nop 0
	v_pk_fma_f32 v[28:29], v[28:29], v[2:3], v[74:75] op_sel:[1,1,0] op_sel_hi:[1,0,1] neg_lo:[0,1,0]
	s_nop 0
	v_pk_add_f32 v[74:75], v[38:39], v[28:29]
	v_pk_add_f32 v[28:29], v[38:39], v[28:29] neg_lo:[0,1] neg_hi:[0,1]
	v_mov_b64_e32 v[38:39], s[76:77]
	v_pk_mul_f32 v[80:81], v[54:55], v[38:39] op_sel:[0,0] op_sel_hi:[0,1]
	s_nop 0
	v_pk_fma_f32 v[54:55], v[54:55], v[38:39], v[80:81] op_sel:[1,1,0] op_sel_hi:[1,0,1] neg_lo:[0,1,0]
	s_nop 0
	v_pk_add_f32 v[80:81], v[62:63], v[54:55]
	v_pk_add_f32 v[54:55], v[62:63], v[54:55] neg_lo:[0,1] neg_hi:[0,1]
	v_pk_mul_f32 v[62:63], v[22:23], v[66:67] op_sel:[0,0] op_sel_hi:[0,1]
	s_nop 0
	v_pk_fma_f32 v[22:23], v[22:23], v[66:67], v[62:63] op_sel:[1,1,0] op_sel_hi:[1,0,1] neg_lo:[0,1,0]
	s_nop 0
	v_pk_add_f32 v[62:63], v[30:31], v[22:23]
	v_pk_add_f32 v[22:23], v[30:31], v[22:23] neg_lo:[0,1] neg_hi:[0,1]
	v_mov_b64_e32 v[30:31], s[10:11]
	v_pk_mul_f32 v[82:83], v[16:17], v[30:31] op_sel:[0,0] op_sel_hi:[0,1]
	s_nop 0
	v_pk_fma_f32 v[16:17], v[16:17], v[30:31], v[82:83] op_sel:[1,1,0] op_sel_hi:[1,0,1] neg_lo:[0,1,0]
	s_nop 0
	v_pk_add_f32 v[82:83], v[24:25], v[16:17]
	v_pk_add_f32 v[16:17], v[24:25], v[16:17] neg_lo:[0,1] neg_hi:[0,1]
; __device__ __forceinline__ float2 cmul(float2 a, float2 b) { return make_float2(a.x * b.x - a.y * b.y, a.x * b.y + a.y * b.x); }
; template <int R, bool INV>
; __device__ __forceinline__ void butterflies(c32 (&v)[1 << R], float turns0) {
;     ...
;   for (int kk = 0; kk < R; ++kk) {
;     const int k = INV ? (R - 1 - kk) : kk;
;     const int hd = RAD >> (k + 1);
; #pragma unroll
;     for (int j = 0; j < RAD; ++j) {
;       if ((j & hd) == 0) {
;         const int m = (j & (hd - 1)) * (16 / hd);
;         const float2 c = make_float2(TC[m], INV ? TS[m] : -TS[m]);
;         const float2 twf = cmul(tbs[k], c);
;         const c32 tw = {twf.x, twf.y};
;         const c32 a = v[j], b = v[j + hd];
;         if (!INV) { v[j] = a + b; v[j + hd] = cmul_pk(a - b, tw); }
;         else { const c32 bt = cmul_pk(b, tw); v[j] = a + bt; v[j + hd] = a - bt; }
;       }
;     }
;   }
	v_pk_mul_f32 v[24:25], v[34:35], v[0:1] op_sel:[0,0] op_sel_hi:[0,1]
	s_nop 0
	v_pk_fma_f32 v[24:25], v[34:35], v[0:1], v[24:25] op_sel:[1,1,0] op_sel_hi:[1,0,1] neg_lo:[0,1,0]
	s_nop 0
	v_pk_add_f32 v[34:35], v[44:45], v[24:25]
	v_pk_add_f32 v[24:25], v[44:45], v[24:25] neg_lo:[0,1] neg_hi:[0,1]
	v_pk_mul_f32 v[44:45], v[68:69], v[60:61] op_sel:[0,0] op_sel_hi:[0,1]
	s_nop 0
	v_pk_fma_f32 v[44:45], v[68:69], v[60:61], v[44:45] op_sel:[1,1,0] op_sel_hi:[1,0,1] neg_lo:[0,1,0]
	s_nop 0
	v_pk_add_f32 v[68:69], v[48:49], v[44:45]
	v_pk_add_f32 v[44:45], v[48:49], v[44:45] neg_lo:[0,1] neg_hi:[0,1]
	v_pk_mul_f32 v[48:49], v[42:43], v[64:65] op_sel:[0,0] op_sel_hi:[0,1]
	s_nop 0
	v_pk_fma_f32 v[42:43], v[42:43], v[64:65], v[48:49] op_sel:[1,1,0] op_sel_hi:[1,0,1] neg_lo:[0,1,0]
	s_nop 0
	v_pk_add_f32 v[48:49], v[50:51], v[42:43]
	v_pk_add_f32 v[42:43], v[50:51], v[42:43] neg_lo:[0,1] neg_hi:[0,1]
	v_pk_mul_f32 v[50:51], v[36:37], v[70:71] op_sel:[0,0] op_sel_hi:[0,1]
	s_nop 0
	v_pk_fma_f32 v[36:37], v[36:37], v[70:71], v[50:51] op_sel:[1,1,0] op_sel_hi:[1,0,1] neg_lo:[0,1,0]
	s_nop 0
	v_pk_add_f32 v[50:51], v[18:19], v[36:37]
	v_pk_add_f32 v[18:19], v[18:19], v[36:37] neg_lo:[0,1] neg_hi:[0,1]
	v_pk_mul_f32 v[36:37], v[12:13], v[2:3] op_sel:[0,0] op_sel_hi:[0,1]
	s_nop 0
	v_pk_fma_f32 v[12:13], v[12:13], v[2:3], v[36:37] op_sel:[1,1,0] op_sel_hi:[1,0,1] neg_lo:[0,1,0]
	s_nop 0
	v_pk_add_f32 v[36:37], v[20:21], v[12:13]
	v_pk_add_f32 v[12:13], v[20:21], v[12:13] neg_lo:[0,1] neg_hi:[0,1]
	v_pk_mul_f32 v[20:21], v[40:41], v[38:39] op_sel:[0,0] op_sel_hi:[0,1]
	s_nop 0
	v_pk_fma_f32 v[20:21], v[40:41], v[38:39], v[20:21] op_sel:[1,1,0] op_sel_hi:[1,0,1] neg_lo:[0,1,0]
	s_nop 0
	v_pk_add_f32 v[40:41], v[46:47], v[20:21]
	v_pk_add_f32 v[20:21], v[46:47], v[20:21] neg_lo:[0,1] neg_hi:[0,1]
	v_pk_mul_f32 v[46:47], v[6:7], v[66:67] op_sel:[0,0] op_sel_hi:[0,1]
	s_nop 0
	v_pk_fma_f32 v[6:7], v[6:7], v[66:67], v[46:47] op_sel:[1,1,0] op_sel_hi:[1,0,1] neg_lo:[0,1,0]
	s_nop 0
	v_pk_add_f32 v[46:47], v[14:15], v[6:7]
	v_pk_add_f32 v[6:7], v[14:15], v[6:7] neg_lo:[0,1] neg_hi:[0,1]
	v_pk_mul_f32 v[14:15], v[4:5], v[30:31] op_sel:[0,0] op_sel_hi:[0,1]
	s_nop 0
	v_pk_fma_f32 v[4:5], v[4:5], v[30:31], v[14:15] op_sel:[1,1,0] op_sel_hi:[1,0,1] neg_lo:[0,1,0]
	s_nop 0
	v_pk_add_f32 v[14:15], v[8:9], v[4:5]
	v_pk_add_f32 v[4:5], v[8:9], v[4:5] neg_lo:[0,1] neg_hi:[0,1]
	v_pk_mul_f32 v[8:9], v[34:35], v[0:1] op_sel:[0,0] op_sel_hi:[0,1]
	s_nop 0
	v_pk_fma_f32 v[0:1], v[34:35], v[0:1], v[8:9] op_sel:[1,1,0] op_sel_hi:[1,0,1] neg_lo:[0,1,0]
	v_mov_b64_e32 v[34:35], s[0:1]
	v_pk_add_f32 v[8:9], v[52:53], v[0:1]
	v_pk_add_f32 v[0:1], v[52:53], v[0:1] neg_lo:[0,1] neg_hi:[0,1]
	v_pk_mul_f32 v[52:53], v[68:69], v[34:35] op_sel:[0,0] op_sel_hi:[0,1]
	s_mov_b32 s0, s57
	v_pk_fma_f32 v[34:35], v[68:69], v[34:35], v[52:53] op_sel:[1,1,0] op_sel_hi:[1,0,1] neg_lo:[0,1,0]
	v_pk_mul_f32 v[68:69], v[48:49], v[60:61] op_sel:[0,0] op_sel_hi:[0,1]
	s_mov_b32 s1, s56
	v_pk_fma_f32 v[48:49], v[48:49], v[60:61], v[68:69] op_sel:[1,1,0] op_sel_hi:[1,0,1] neg_lo:[0,1,0]
	v_mov_b64_e32 v[68:69], s[0:1]
	v_pk_add_f32 v[60:61], v[72:73], v[48:49]
	v_pk_add_f32 v[48:49], v[72:73], v[48:49] neg_lo:[0,1] neg_hi:[0,1]
	v_pk_mul_f32 v[72:73], v[50:51], v[68:69] op_sel:[0,0] op_sel_hi:[0,1]
	v_pk_add_f32 v[52:53], v[76:77], v[34:35]
	v_pk_fma_f32 v[50:51], v[50:51], v[68:69], v[72:73] op_sel:[1,1,0] op_sel_hi:[1,0,1] neg_lo:[0,1,0]
	v_pk_mul_f32 v[72:73], v[36:37], v[64:65] op_sel:[0,0] op_sel_hi:[0,1]
	v_pk_add_f32 v[34:35], v[76:77], v[34:35] neg_lo:[0,1] neg_hi:[0,1]
	v_pk_fma_f32 v[36:37], v[36:37], v[64:65], v[72:73] op_sel:[1,1,0] op_sel_hi:[1,0,1] neg_lo:[0,1,0]
	v_mov_b64_e32 v[72:73], s[56:57]
	v_pk_add_f32 v[64:65], v[74:75], v[36:37]
	v_pk_add_f32 v[36:37], v[74:75], v[36:37] neg_lo:[0,1] neg_hi:[0,1]
	v_pk_mul_f32 v[74:75], v[40:41], v[72:73] op_sel:[0,0] op_sel_hi:[0,1]
	v_pk_add_f32 v[68:69], v[78:79], v[50:51]
	v_pk_fma_f32 v[40:41], v[40:41], v[72:73], v[74:75] op_sel:[1,1,0] op_sel_hi:[1,0,1] neg_lo:[0,1,0]
	v_pk_mul_f32 v[74:75], v[46:47], v[70:71] op_sel:[0,0] op_sel_hi:[0,1]
	v_pk_add_f32 v[50:51], v[78:79], v[50:51] neg_lo:[0,1] neg_hi:[0,1]
	v_pk_fma_f32 v[46:47], v[46:47], v[70:71], v[74:75] op_sel:[1,1,0] op_sel_hi:[1,0,1] neg_lo:[0,1,0]
	v_pk_add_f32 v[72:73], v[80:81], v[40:41]
	v_pk_add_f32 v[70:71], v[62:63], v[46:47]
	v_pk_add_f32 v[46:47], v[62:63], v[46:47] neg_lo:[0,1] neg_hi:[0,1]
	v_mov_b64_e32 v[62:63], s[18:19]
	v_pk_mul_f32 v[74:75], v[14:15], v[62:63] op_sel:[0,0] op_sel_hi:[0,1]
	v_pk_add_f32 v[40:41], v[80:81], v[40:41] neg_lo:[0,1] neg_hi:[0,1]
	v_pk_fma_f32 v[14:15], v[14:15], v[62:63], v[74:75] op_sel:[1,1,0] op_sel_hi:[1,0,1] neg_lo:[0,1,0]
	v_pk_mul_f32 v[74:75], v[24:25], v[2:3] op_sel:[0,0] op_sel_hi:[0,1]
	s_nop 0
	v_pk_fma_f32 v[2:3], v[24:25], v[2:3], v[74:75] op_sel:[1,1,0] op_sel_hi:[1,0,1] neg_lo:[0,1,0]
	v_pk_add_f32 v[62:63], v[82:83], v[14:15]
	v_pk_add_f32 v[24:25], v[10:11], v[2:3]
	v_pk_add_f32 v[2:3], v[10:11], v[2:3] neg_lo:[0,1] neg_hi:[0,1]
	v_mov_b64_e32 v[10:11], s[30:31]
	v_pk_mul_f32 v[74:75], v[44:45], v[10:11] op_sel:[0,0] op_sel_hi:[0,1]
	v_pk_add_f32 v[14:15], v[82:83], v[14:15] neg_lo:[0,1] neg_hi:[0,1]
	v_pk_fma_f32 v[10:11], v[44:45], v[10:11], v[74:75] op_sel:[1,1,0] op_sel_hi:[1,0,1] neg_lo:[0,1,0]
	s_nop 0
	v_pk_add_f32 v[44:45], v[56:57], v[10:11]
	v_pk_add_f32 v[10:11], v[56:57], v[10:11] neg_lo:[0,1] neg_hi:[0,1]
	v_pk_mul_f32 v[56:57], v[42:43], v[38:39] op_sel:[0,0] op_sel_hi:[0,1]
	s_nop 0
	v_pk_fma_f32 v[38:39], v[42:43], v[38:39], v[56:57] op_sel:[1,1,0] op_sel_hi:[1,0,1] neg_lo:[0,1,0]
	v_mov_b64_e32 v[56:57], s[68:69]
; __device__ __forceinline__ float2 cmul(float2 a, float2 b) { return make_float2(a.x * b.x - a.y * b.y, a.x * b.y + a.y * b.x); }
; __device__ __forceinline__ float2 twid(float turns) { return make_float2(__builtin_amdgcn_cosf(turns), -__builtin_amdgcn_sinf(turns)); }
; template <int R, bool INV>
; __device__ __forceinline__ void butterflies(c32 (&v)[1 << R], float turns0) {
;   constexpr int RAD = 1 << R;
;   constexpr float TC[16] = {1.0f, 0.98078528040f, 0.92387953251f, 0.83146961230f, 0.70710678119f, 0.55557023302f, 0.38268343237f, 0.19509032202f,
;                             0.0f, -0.19509032202f, -0.38268343237f, -0.55557023302f, -0.70710678119f, -0.83146961230f, -0.92387953251f, -0.98078528040f};
;   constexpr float TS[16] = {0.0f, 0.19509032202f, 0.38268343237f, 0.55557023302f, 0.70710678119f, 0.83146961230f, 0.92387953251f, 0.98078528040f,
;                             1.0f, 0.98078528040f, 0.92387953251f, 0.83146961230f, 0.70710678119f, 0.55557023302f, 0.38268343237f, 0.19509032202f};
;   float2 tbs[R];
;   tbs[0] = twid(turns0);
;   if (INV) tbs[0].y = -tbs[0].y;
; #pragma unroll
;   for (int k = 1; k < R; ++k) tbs[k] = cmul(tbs[k - 1], tbs[k - 1]);
; template <int LOGN>
; __device__ __forceinline__ void fft_fused_mul(float2* X, const c32 (&kf)[32]) {
;     ...
; #pragma unroll
;   for (int j = 0; j < 32; ++j) Xc[pb + j] = v[j];
;   __syncthreads();
	v_pk_add_f32 v[42:43], v[58:59], v[38:39]
	v_pk_add_f32 v[38:39], v[58:59], v[38:39] neg_lo:[0,1] neg_hi:[0,1]
	v_pk_mul_f32 v[58:59], v[18:19], v[56:57] op_sel:[0,0] op_sel_hi:[0,1]
	s_nop 0
	v_pk_fma_f32 v[18:19], v[18:19], v[56:57], v[58:59] op_sel:[1,1,0] op_sel_hi:[1,0,1] neg_lo:[0,1,0]
	s_nop 0
	v_pk_add_f32 v[56:57], v[26:27], v[18:19]
	v_pk_add_f32 v[18:19], v[26:27], v[18:19] neg_lo:[0,1] neg_hi:[0,1]
	v_pk_mul_f32 v[26:27], v[12:13], v[66:67] op_sel:[0,0] op_sel_hi:[0,1]
	s_nop 0
	v_pk_fma_f32 v[12:13], v[12:13], v[66:67], v[26:27] op_sel:[1,1,0] op_sel_hi:[1,0,1] neg_lo:[0,1,0]
	s_nop 0
	v_pk_add_f32 v[26:27], v[28:29], v[12:13]
	v_pk_add_f32 v[12:13], v[28:29], v[12:13] neg_lo:[0,1] neg_hi:[0,1]
	v_mov_b64_e32 v[28:29], s[16:17]
	v_pk_mul_f32 v[58:59], v[20:21], v[28:29] op_sel:[0,0] op_sel_hi:[0,1]
	s_nop 0
	v_pk_fma_f32 v[20:21], v[20:21], v[28:29], v[58:59] op_sel:[1,1,0] op_sel_hi:[1,0,1] neg_lo:[0,1,0]
	s_nop 0
	v_pk_add_f32 v[28:29], v[54:55], v[20:21]
	v_pk_add_f32 v[20:21], v[54:55], v[20:21] neg_lo:[0,1] neg_hi:[0,1]
	v_pk_mul_f32 v[54:55], v[6:7], v[30:31] op_sel:[0,0] op_sel_hi:[0,1]
	s_nop 0
	v_pk_fma_f32 v[6:7], v[6:7], v[30:31], v[54:55] op_sel:[1,1,0] op_sel_hi:[1,0,1] neg_lo:[0,1,0]
	s_nop 0
	v_pk_add_f32 v[30:31], v[22:23], v[6:7]
	v_pk_add_f32 v[6:7], v[22:23], v[6:7] neg_lo:[0,1] neg_hi:[0,1]
	v_mov_b64_e32 v[22:23], s[4:5]
	v_pk_mul_f32 v[54:55], v[4:5], v[22:23] op_sel:[0,0] op_sel_hi:[0,1]
	s_nop 0
	v_pk_fma_f32 v[4:5], v[4:5], v[22:23], v[54:55] op_sel:[1,1,0] op_sel_hi:[1,0,1] neg_lo:[0,1,0]
	s_nop 0
	v_pk_add_f32 v[22:23], v[16:17], v[4:5]
	v_pk_add_f32 v[4:5], v[16:17], v[4:5] neg_lo:[0,1] neg_hi:[0,1]
	ds_write2_b64 v32, v[8:9], v[52:53] offset1:1
	ds_write2_b64 v32, v[60:61], v[68:69] offset0:2 offset1:3
	ds_write2_b64 v32, v[64:65], v[72:73] offset0:4 offset1:5
	ds_write2_b64 v32, v[70:71], v[62:63] offset0:6 offset1:7
	ds_write2_b64 v32, v[24:25], v[44:45] offset0:8 offset1:9
	ds_write2_b64 v32, v[42:43], v[56:57] offset0:10 offset1:11
	ds_write2_b64 v32, v[26:27], v[28:29] offset0:12 offset1:13
	ds_write2_b64 v32, v[30:31], v[22:23] offset0:14 offset1:15
	ds_write2_b64 v32, v[0:1], v[34:35] offset0:16 offset1:17
	ds_write2_b64 v32, v[48:49], v[50:51] offset0:18 offset1:19
	ds_write2_b64 v32, v[36:37], v[40:41] offset0:20 offset1:21
	ds_write2_b64 v32, v[46:47], v[14:15] offset0:22 offset1:23
	ds_write2_b64 v32, v[2:3], v[10:11] offset0:24 offset1:25
	ds_write2_b64 v32, v[38:39], v[18:19] offset0:26 offset1:27
	ds_write2_b64 v32, v[12:13], v[20:21] offset0:28 offset1:29
	ds_write2_b64 v32, v[6:7], v[4:5] offset0:30 offset1:31
	v_mov_b32_e32 v65, v196
	s_waitcnt lgkmcnt(0)
	s_barrier
	s_nop 0
	v_cmp_gt_i32_e32 vcc, s33, v65
	s_and_saveexec_b64 s[0:1], vcc
	s_cbranch_execz .LBB0_1067
	v_and_b32_e32 v32, 31, v65
	v_cvt_f32_ubyte0_e32 v0, v32
	v_mul_f32_e32 v0, 0x3a800000, v0
	v_cos_f32_e32 v62, v0
	v_sin_f32_e32 v63, v0
	v_add_u32_e32 v64, 0xfffffe00, v65
	v_lshlrev_b32_e32 v65, 5, v65
	v_mul_f32_e32 v37, 0x3f3504f3, v62
	v_pk_mul_f32 v[0:1], v[62:63], v[62:63] op_sel:[1,1] op_sel_hi:[0,1]
	v_pk_fma_f32 v[28:29], v[62:63], v[62:63], v[0:1] op_sel_hi:[0,1,1] neg_lo:[0,0,1] neg_hi:[0,0,1]
	v_pk_fma_f32 v[22:23], v[62:63], v[62:63], v[0:1] op_sel_hi:[0,1,1]
	v_mov_b32_e32 v18, v28
	v_mov_b32_e32 v19, v23
	v_pk_mul_f32 v[0:1], v[18:19], v[22:23] op_sel:[0,1]
	v_pk_mul_f32 v[30:31], v[22:23], s[8:9] op_sel:[1,0]
	v_pk_fma_f32 v[12:13], v[28:29], v[18:19], v[0:1] op_sel:[0,0,1] op_sel_hi:[0,1,0] neg_lo:[0,0,1] neg_hi:[0,0,1]
	v_pk_fma_f32 v[14:15], v[28:29], v[18:19], v[0:1] op_sel:[0,0,1] op_sel_hi:[0,1,0]
	v_pk_mov_b32 v[16:17], v[14:15], v[12:13] op_sel:[1,0]
	v_mov_b32_e32 v10, v12
	v_mov_b32_e32 v11, v15
	v_pk_mul_f32 v[0:1], v[16:17], v[14:15] op_sel:[0,1]
	v_pk_mul_f32 v[34:35], v[62:63], 0 op_sel_hi:[1,0]
	v_pk_fma_f32 v[2:3], v[12:13], v[10:11], v[0:1] op_sel_hi:[0,1,1] neg_lo:[0,0,1] neg_hi:[0,0,1]
	v_pk_fma_f32 v[4:5], v[12:13], v[10:11], v[0:1] op_sel_hi:[0,1,1]
	v_pk_mov_b32 v[8:9], v[4:5], v[2:3] op_sel:[1,0]
	v_mov_b32_e32 v6, v2
	v_mov_b32_e32 v7, v5
	v_pk_mul_f32 v[0:1], v[8:9], v[4:5] op_sel:[0,1]
	v_mov_b32_e32 v56, v63
	v_pk_fma_f32 v[20:21], v[2:3], v[6:7], v[0:1] op_sel_hi:[0,1,1] neg_lo:[0,0,1] neg_hi:[0,0,1]
	v_pk_fma_f32 v[24:25], v[2:3], v[6:7], v[0:1] op_sel_hi:[0,1,1]
	v_pk_mov_b32 v[26:27], v[24:25], v[20:21] op_sel:[1,0]
	v_mul_f32_e32 v36, 0x3f3504f3, v63
	v_pk_fma_f32 v[0:1], v[26:27], 0, v[20:21] op_sel_hi:[1,0,1] neg_lo:[1,0,0] neg_hi:[1,0,0]
	v_pk_fma_f32 v[20:21], v[26:27], 0, v[24:25] op_sel_hi:[1,0,1]
	v_pk_mov_b32 v[24:25], v[22:23], v[28:29] op_sel:[1,0]
	v_mov_b32_e32 v1, v21
	v_pk_mul_f32 v[20:21], v[6:7], 0 op_sel_hi:[1,0]
	v_pk_fma_f32 v[26:27], v[28:29], s[76:77], v[30:31] op_sel:[0,0,1] op_sel_hi:[0,1,0] neg_lo:[0,0,1] neg_hi:[0,0,1]
	v_pk_add_f32 v[2:3], v[2:3], v[20:21] op_sel:[0,1] op_sel_hi:[1,0] neg_lo:[0,1] neg_hi:[0,1]
	v_pk_add_f32 v[4:5], v[4:5], v[20:21] op_sel_hi:[1,0]
	v_mul_f32_e32 v20, 0x3f3504f3, v23
	v_mov_b32_e32 v3, v5
	v_pk_fma_f32 v[4:5], v[6:7], 0, v[8:9] op_sel_hi:[1,0,1] neg_lo:[0,0,1] neg_hi:[0,0,1]
	v_pk_fma_f32 v[6:7], v[6:7], 0, v[8:9] op_sel_hi:[1,0,1]
	v_pk_mul_f32 v[8:9], v[10:11], 0 op_sel_hi:[1,0]
	v_mov_b32_e32 v5, v7
	v_pk_add_f32 v[6:7], v[12:13], v[8:9] op_sel:[0,1] op_sel_hi:[1,0] neg_lo:[0,1] neg_hi:[0,1]
	v_pk_add_f32 v[8:9], v[14:15], v[8:9] op_sel_hi:[1,0]
	v_mul_f32_e32 v14, 0x3f3504f3, v15
	v_mov_b32_e32 v7, v9
	v_pk_fma_f32 v[8:9], v[10:11], 0, v[16:17] op_sel_hi:[1,0,1] neg_lo:[0,0,1] neg_hi:[0,0,1]
	v_pk_fma_f32 v[10:11], v[10:11], 0, v[16:17] op_sel_hi:[1,0,1]
	v_pk_mul_f32 v[16:17], v[18:19], 0 op_sel_hi:[1,0]
; __device__ __forceinline__ float2 cmul(float2 a, float2 b) { return make_float2(a.x * b.x - a.y * b.y, a.x * b.y + a.y * b.x); }
; __device__ __forceinline__ float2 twid(float turns) { return make_float2(__builtin_amdgcn_cosf(turns), -__builtin_amdgcn_sinf(turns)); }
; template <int R, bool INV>
; __device__ __forceinline__ void butterflies(c32 (&v)[1 << R], float turns0) {
;     ...
;   float2 tbs[R];
;   tbs[0] = twid(turns0);
;   if (INV) tbs[0].y = -tbs[0].y;
; #pragma unroll
;   for (int k = 1; k < R; ++k) tbs[k] = cmul(tbs[k - 1], tbs[k - 1]);
; #pragma unroll
;   for (int kk = 0; kk < R; ++kk) {
;     const int k = INV ? (R - 1 - kk) : kk;
;     const int hd = RAD >> (k + 1);
; #pragma unroll
;     for (int j = 0; j < RAD; ++j) {
;       if ((j & hd) == 0) {
;         const int m = (j & (hd - 1)) * (16 / hd);
;         const float2 c = make_float2(TC[m], INV ? TS[m] : -TS[m]);
; template <int LOGN, int R, int DLOG, bool INV, int MODE, class F>
; __device__ __forceinline__ void fft_pass(float2* X, const F& f) {
;     ...
;   for (int g = tid0; g < NGR; g += 512) {
;     const int lo = g & (dmin - 1), base = gbase(g), pb = phys(base);
;     c32 v[RAD];
;     if constexpr (MODE == 1) {
; #pragma unroll
;       for (int j = 0; j < RAD; ++j) v[j] = nxt[j];
;       if (g + 512 < NGR) fetch(g + 512, nxt);
;     } else {
; #pragma unroll
;       for (int j = 0; j < RAD; ++j) v[j] = Xc[(DLOG >= 5) ? pb + j * PSTEP : phys(base + (j << DLOG))];
	v_mov_b32_e32 v9, v11
	v_mul_f32_e32 v11, 0x3f3504f3, v12
	v_fmac_f32_e32 v11, 0x3f3504f3, v15
	v_pk_fma_f32 v[12:13], v[12:13], s[72:73], v[14:15] op_sel_hi:[0,1,0] neg_lo:[0,0,1] neg_hi:[0,0,1]
	v_pk_add_f32 v[14:15], v[28:29], v[16:17] op_sel:[0,1] op_sel_hi:[1,0] neg_lo:[0,1] neg_hi:[0,1]
	v_pk_add_f32 v[16:17], v[22:23], v[16:17] op_sel_hi:[1,0]
	v_pk_fma_f32 v[20:21], v[28:29], s[72:73], v[20:21] op_sel_hi:[0,1,0] neg_lo:[0,0,1] neg_hi:[0,0,1]
	v_mov_b32_e32 v15, v17
	v_pk_fma_f32 v[16:17], v[18:19], 0, v[24:25] op_sel_hi:[1,0,1] neg_lo:[0,0,1] neg_hi:[0,0,1]
	v_pk_fma_f32 v[18:19], v[18:19], 0, v[24:25] op_sel_hi:[1,0,1]
	v_pk_fma_f32 v[24:25], v[28:29], s[10:11], v[30:31] op_sel_hi:[0,1,1] neg_lo:[0,0,1] neg_hi:[0,0,1]
	v_mov_b32_e32 v17, v19
	v_mul_f32_e32 v19, 0x3f3504f3, v28
	v_fmac_f32_e32 v19, 0x3f3504f3, v23
	v_pk_fma_f32 v[22:23], v[28:29], s[10:11], v[30:31] op_sel_hi:[0,1,1]
	v_pk_fma_f32 v[28:29], v[28:29], s[76:77], v[30:31] op_sel_hi:[0,1,0]
	v_sub_f32_e32 v30, v62, v35
	v_add_f32_e32 v31, v63, v34
	v_pk_fma_f32 v[34:35], v[62:63], 0, v[62:63] op_sel:[0,0,1] op_sel_hi:[1,0,0] neg_lo:[0,0,1] neg_hi:[0,0,1]
	v_pk_fma_f32 v[38:39], v[62:63], 0, v[62:63] op_sel:[0,0,1] op_sel_hi:[1,0,0]
	v_fmac_f32_e32 v37, 0x3f3504f3, v63
	v_pk_mul_f32 v[46:47], v[56:57], s[56:57] op_sel_hi:[0,1]
	v_pk_mul_f32 v[54:55], v[56:57], s[8:9] op_sel_hi:[0,1]
	v_pk_mul_f32 v[66:67], v[56:57], s[18:19] op_sel_hi:[0,1]
	v_mov_b32_e32 v35, v39
	v_pk_fma_f32 v[38:39], v[62:63], s[72:73], v[36:37] op_sel_hi:[0,1,0] neg_lo:[0,0,1] neg_hi:[0,0,1]
	v_pk_fma_f32 v[40:41], v[62:63], s[16:17], v[46:47] op_sel_hi:[0,1,1]
	v_pk_fma_f32 v[42:43], v[62:63], s[16:17], v[46:47] op_sel_hi:[0,1,1] neg_lo:[0,0,1] neg_hi:[0,0,1]
	v_pk_fma_f32 v[44:45], v[62:63], s[68:69], v[46:47] op_sel:[0,0,1] op_sel_hi:[0,1,0] neg_lo:[0,0,1] neg_hi:[0,0,1]
	v_pk_fma_f32 v[46:47], v[62:63], s[68:69], v[46:47] op_sel_hi:[0,1,0]
	v_pk_fma_f32 v[48:49], v[62:63], s[10:11], v[54:55] op_sel_hi:[0,1,1]
	v_pk_fma_f32 v[50:51], v[62:63], s[10:11], v[54:55] op_sel_hi:[0,1,1] neg_lo:[0,0,1] neg_hi:[0,0,1]
	v_pk_fma_f32 v[52:53], v[62:63], s[76:77], v[54:55] op_sel:[0,0,1] op_sel_hi:[0,1,0] neg_lo:[0,0,1] neg_hi:[0,0,1]
	v_pk_fma_f32 v[54:55], v[62:63], s[76:77], v[54:55] op_sel_hi:[0,1,0]
	v_pk_fma_f32 v[56:57], v[62:63], s[4:5], v[66:67] op_sel_hi:[0,1,1]
	v_pk_fma_f32 v[58:59], v[62:63], s[4:5], v[66:67] op_sel_hi:[0,1,1] neg_lo:[0,0,1] neg_hi:[0,0,1]
	v_pk_fma_f32 v[60:61], v[62:63], s[30:31], v[66:67] op_sel:[0,0,1] op_sel_hi:[0,1,0] neg_lo:[0,0,1] neg_hi:[0,0,1]
	v_pk_fma_f32 v[62:63], v[62:63], s[30:31], v[66:67] op_sel_hi:[0,1,0]
	v_mov_b32_e32 v10, v13
	v_mov_b32_e32 v18, v21
	v_mov_b32_e32 v22, v27
	v_mov_b32_e32 v28, v25
	v_mov_b32_e32 v36, v39
	v_mov_b32_e32 v40, v45
	v_mov_b32_e32 v46, v43
	v_mov_b32_e32 v48, v53
	v_mov_b32_e32 v54, v51
	v_mov_b32_e32 v56, v61
	v_mov_b32_e32 v62, v59
	s_mov_b64 s[40:41], 0
.LBB0_1066:
	v_and_b32_e32 v66, 0xfffffc00, v65
	v_ashrrev_i32_e32 v67, 2, v66
	v_add_u32_e32 v67, 0, v67
	v_lshlrev_b32_e32 v66, 3, v66
	v_lshlrev_b32_e32 v68, 3, v32
	v_add3_u32 v132, v67, v66, v68
	ds_read_b64 v[66:67], v132
	ds_read_b64 v[68:69], v132 offset:264
	ds_read_b64 v[70:71], v132 offset:528
	ds_read_b64 v[72:73], v132 offset:792
	ds_read_b64 v[74:75], v132 offset:1056
	ds_read_b64 v[76:77], v132 offset:1320
	ds_read_b64 v[78:79], v132 offset:1584
	ds_read_b64 v[80:81], v132 offset:1848
	s_waitcnt lgkmcnt(6)
	v_pk_mul_f32 v[130:131], v[68:69], v[0:1] op_sel:[0,0] op_sel_hi:[0,1]
	s_nop 0
	v_pk_fma_f32 v[68:69], v[68:69], v[0:1], v[130:131] op_sel:[1,1,0] op_sel_hi:[1,0,1] neg_lo:[0,1,0]
	v_add_u32_e32 v133, 0x800, v132
	v_pk_add_f32 v[130:131], v[66:67], v[68:69]
	v_pk_add_f32 v[66:67], v[66:67], v[68:69] neg_lo:[0,1] neg_hi:[0,1]
	s_waitcnt lgkmcnt(4)
	v_pk_mul_f32 v[68:69], v[72:73], v[0:1] op_sel:[0,0] op_sel_hi:[0,1]
	ds_read_b64 v[82:83], v133 offset:64
	ds_read_b64 v[84:85], v133 offset:328
	ds_read_b64 v[86:87], v133 offset:592
	ds_read_b64 v[88:89], v133 offset:856
	ds_read_b64 v[90:91], v133 offset:1120
	ds_read_b64 v[92:93], v133 offset:1384
	ds_read_b64 v[94:95], v133 offset:1648
	ds_read_b64 v[96:97], v133 offset:1912
	v_pk_fma_f32 v[68:69], v[72:73], v[0:1], v[68:69] op_sel:[1,1,0] op_sel_hi:[1,0,1] neg_lo:[0,1,0]
	v_add_u32_e32 v134, 0x1000, v132
	v_pk_add_f32 v[72:73], v[70:71], v[68:69]
	v_pk_add_f32 v[68:69], v[70:71], v[68:69] neg_lo:[0,1] neg_hi:[0,1]
	s_waitcnt lgkmcnt(10)
	v_pk_mul_f32 v[70:71], v[76:77], v[0:1] op_sel:[0,0] op_sel_hi:[0,1]
	ds_read_b64 v[98:99], v134 offset:128
	ds_read_b64 v[100:101], v134 offset:392
	ds_read_b64 v[102:103], v134 offset:656
	ds_read_b64 v[104:105], v134 offset:920
	ds_read_b64 v[106:107], v134 offset:1184
	ds_read_b64 v[108:109], v134 offset:1448
	ds_read_b64 v[110:111], v134 offset:1712
	ds_read_b64 v[112:113], v134 offset:1976
	v_pk_fma_f32 v[70:71], v[76:77], v[0:1], v[70:71] op_sel:[1,1,0] op_sel_hi:[1,0,1] neg_lo:[0,1,0]
	v_add_u32_e32 v135, 0x1800, v132
	v_pk_add_f32 v[76:77], v[74:75], v[70:71]
	v_pk_add_f32 v[70:71], v[74:75], v[70:71] neg_lo:[0,1] neg_hi:[0,1]
	s_waitcnt lgkmcnt(15)
	v_pk_mul_f32 v[74:75], v[80:81], v[0:1] op_sel:[0,0] op_sel_hi:[0,1]
	ds_read_b64 v[114:115], v135 offset:192
	ds_read_b64 v[116:117], v135 offset:456
	ds_read_b64 v[118:119], v135 offset:720
	ds_read_b64 v[120:121], v135 offset:984
	ds_read_b64 v[122:123], v135 offset:1248
	ds_read_b64 v[124:125], v135 offset:1512
	ds_read_b64 v[126:127], v135 offset:1776
	ds_read_b64 v[128:129], v135 offset:2040
	v_pk_fma_f32 v[74:75], v[80:81], v[0:1], v[74:75] op_sel:[1,1,0] op_sel_hi:[1,0,1] neg_lo:[0,1,0]
	v_add_u32_e32 v64, 0x200, v64
	v_pk_add_f32 v[80:81], v[78:79], v[74:75]
	v_pk_add_f32 v[74:75], v[78:79], v[74:75] neg_lo:[0,1] neg_hi:[0,1]
	s_waitcnt lgkmcnt(15)
; __device__ __forceinline__ float2 cmul(float2 a, float2 b) { return make_float2(a.x * b.x - a.y * b.y, a.x * b.y + a.y * b.x); }
; template <int R, bool INV>
; __device__ __forceinline__ void butterflies(c32 (&v)[1 << R], float turns0) {
;     ...
;     for (int j = 0; j < RAD; ++j) {
;       if ((j & hd) == 0) {
;         const int m = (j & (hd - 1)) * (16 / hd);
;         const float2 c = make_float2(TC[m], INV ? TS[m] : -TS[m]);
;         const float2 twf = cmul(tbs[k], c);
;         const c32 tw = {twf.x, twf.y};
;         const c32 a = v[j], b = v[j + hd];
;         if (!INV) { v[j] = a + b; v[j + hd] = cmul_pk(a - b, tw); }
;         else { const c32 bt = cmul_pk(b, tw); v[j] = a + bt; v[j + hd] = a - bt; }
;       }
	v_pk_mul_f32 v[78:79], v[84:85], v[0:1] op_sel:[0,0] op_sel_hi:[0,1]
	v_cmp_lt_i32_e32 vcc, -1, v64
	v_pk_fma_f32 v[78:79], v[84:85], v[0:1], v[78:79] op_sel:[1,1,0] op_sel_hi:[1,0,1] neg_lo:[0,1,0]
	v_add_u32_e32 v65, 0x4000, v65
	v_pk_add_f32 v[84:85], v[82:83], v[78:79]
	v_pk_add_f32 v[78:79], v[82:83], v[78:79] neg_lo:[0,1] neg_hi:[0,1]
	s_waitcnt lgkmcnt(15)
	v_pk_mul_f32 v[82:83], v[88:89], v[0:1] op_sel:[0,0] op_sel_hi:[0,1]
	s_or_b64 s[40:41], vcc, s[40:41]
	v_pk_fma_f32 v[82:83], v[88:89], v[0:1], v[82:83] op_sel:[1,1,0] op_sel_hi:[1,0,1] neg_lo:[0,1,0]
	s_nop 0
	v_pk_add_f32 v[88:89], v[86:87], v[82:83]
	v_pk_add_f32 v[82:83], v[86:87], v[82:83] neg_lo:[0,1] neg_hi:[0,1]
	s_waitcnt lgkmcnt(15)
	v_pk_mul_f32 v[86:87], v[92:93], v[0:1] op_sel:[0,0] op_sel_hi:[0,1]
	s_nop 0
	v_pk_fma_f32 v[86:87], v[92:93], v[0:1], v[86:87] op_sel:[1,1,0] op_sel_hi:[1,0,1] neg_lo:[0,1,0]
	s_nop 0
	v_pk_add_f32 v[92:93], v[90:91], v[86:87]
	v_pk_add_f32 v[86:87], v[90:91], v[86:87] neg_lo:[0,1] neg_hi:[0,1]
	s_waitcnt lgkmcnt(15)
	v_pk_mul_f32 v[90:91], v[96:97], v[0:1] op_sel:[0,0] op_sel_hi:[0,1]
	s_nop 0
	v_pk_fma_f32 v[90:91], v[96:97], v[0:1], v[90:91] op_sel:[1,1,0] op_sel_hi:[1,0,1] neg_lo:[0,1,0]
	s_nop 0
	v_pk_add_f32 v[96:97], v[94:95], v[90:91]
	v_pk_add_f32 v[90:91], v[94:95], v[90:91] neg_lo:[0,1] neg_hi:[0,1]
	s_waitcnt lgkmcnt(14)
	v_pk_mul_f32 v[94:95], v[100:101], v[0:1] op_sel:[0,0] op_sel_hi:[0,1]
	s_nop 0
	v_pk_fma_f32 v[94:95], v[100:101], v[0:1], v[94:95] op_sel:[1,1,0] op_sel_hi:[1,0,1] neg_lo:[0,1,0]
	s_nop 0
	v_pk_add_f32 v[100:101], v[98:99], v[94:95]
	v_pk_add_f32 v[94:95], v[98:99], v[94:95] neg_lo:[0,1] neg_hi:[0,1]
	s_waitcnt lgkmcnt(12)
	v_pk_mul_f32 v[98:99], v[104:105], v[0:1] op_sel:[0,0] op_sel_hi:[0,1]
	s_nop 0
	v_pk_fma_f32 v[98:99], v[104:105], v[0:1], v[98:99] op_sel:[1,1,0] op_sel_hi:[1,0,1] neg_lo:[0,1,0]
	s_nop 0
	v_pk_add_f32 v[104:105], v[102:103], v[98:99]
	v_pk_add_f32 v[98:99], v[102:103], v[98:99] neg_lo:[0,1] neg_hi:[0,1]
	s_waitcnt lgkmcnt(10)
	v_pk_mul_f32 v[102:103], v[108:109], v[0:1] op_sel:[0,0] op_sel_hi:[0,1]
	s_nop 0
	v_pk_fma_f32 v[102:103], v[108:109], v[0:1], v[102:103] op_sel:[1,1,0] op_sel_hi:[1,0,1] neg_lo:[0,1,0]
	s_nop 0
	v_pk_add_f32 v[108:109], v[106:107], v[102:103]
	v_pk_add_f32 v[102:103], v[106:107], v[102:103] neg_lo:[0,1] neg_hi:[0,1]
	s_waitcnt lgkmcnt(8)
	v_pk_mul_f32 v[106:107], v[112:113], v[0:1] op_sel:[0,0] op_sel_hi:[0,1]
	s_nop 0
	v_pk_fma_f32 v[106:107], v[112:113], v[0:1], v[106:107] op_sel:[1,1,0] op_sel_hi:[1,0,1] neg_lo:[0,1,0]
	s_nop 0
	v_pk_add_f32 v[112:113], v[110:111], v[106:107]
	v_pk_add_f32 v[106:107], v[110:111], v[106:107] neg_lo:[0,1] neg_hi:[0,1]
	s_waitcnt lgkmcnt(6)
	v_pk_mul_f32 v[110:111], v[116:117], v[0:1] op_sel:[0,0] op_sel_hi:[0,1]
	s_nop 0
	v_pk_fma_f32 v[110:111], v[116:117], v[0:1], v[110:111] op_sel:[1,1,0] op_sel_hi:[1,0,1] neg_lo:[0,1,0]
	s_nop 0
	v_pk_add_f32 v[116:117], v[114:115], v[110:111]
	v_pk_add_f32 v[110:111], v[114:115], v[110:111] neg_lo:[0,1] neg_hi:[0,1]
	s_waitcnt lgkmcnt(4)
	v_pk_mul_f32 v[114:115], v[120:121], v[0:1] op_sel:[0,0] op_sel_hi:[0,1]
	s_nop 0
	v_pk_fma_f32 v[114:115], v[120:121], v[0:1], v[114:115] op_sel:[1,1,0] op_sel_hi:[1,0,1] neg_lo:[0,1,0]
	s_nop 0
	v_pk_add_f32 v[120:121], v[118:119], v[114:115]
	v_pk_add_f32 v[114:115], v[118:119], v[114:115] neg_lo:[0,1] neg_hi:[0,1]
	s_waitcnt lgkmcnt(2)
	v_pk_mul_f32 v[118:119], v[124:125], v[0:1] op_sel:[0,0] op_sel_hi:[0,1]
	s_nop 0
	v_pk_fma_f32 v[118:119], v[124:125], v[0:1], v[118:119] op_sel:[1,1,0] op_sel_hi:[1,0,1] neg_lo:[0,1,0]
	s_nop 0
	v_pk_add_f32 v[124:125], v[122:123], v[118:119]
	v_pk_add_f32 v[118:119], v[122:123], v[118:119] neg_lo:[0,1] neg_hi:[0,1]
	s_waitcnt lgkmcnt(0)
	v_pk_mul_f32 v[122:123], v[128:129], v[0:1] op_sel:[0,0] op_sel_hi:[0,1]
	s_nop 0
	v_pk_fma_f32 v[122:123], v[128:129], v[0:1], v[122:123] op_sel:[1,1,0] op_sel_hi:[1,0,1] neg_lo:[0,1,0]
	s_nop 0
	v_pk_add_f32 v[128:129], v[126:127], v[122:123]
	v_pk_add_f32 v[122:123], v[126:127], v[122:123] neg_lo:[0,1] neg_hi:[0,1]
	v_pk_mul_f32 v[126:127], v[72:73], v[2:3] op_sel:[0,0] op_sel_hi:[0,1]
	s_nop 0
	v_pk_fma_f32 v[72:73], v[72:73], v[2:3], v[126:127] op_sel:[1,1,0] op_sel_hi:[1,0,1] neg_lo:[0,1,0]
	s_nop 0
	v_pk_add_f32 v[126:127], v[130:131], v[72:73]
	v_pk_add_f32 v[72:73], v[130:131], v[72:73] neg_lo:[0,1] neg_hi:[0,1]
	v_pk_mul_f32 v[130:131], v[68:69], v[4:5] op_sel:[0,0] op_sel_hi:[0,1]
	s_nop 0
	v_pk_fma_f32 v[68:69], v[68:69], v[4:5], v[130:131] op_sel:[1,1,0] op_sel_hi:[1,0,1] neg_lo:[0,1,0]
	s_nop 0
	v_pk_add_f32 v[130:131], v[66:67], v[68:69]
	v_pk_add_f32 v[66:67], v[66:67], v[68:69] neg_lo:[0,1] neg_hi:[0,1]
	v_pk_mul_f32 v[68:69], v[80:81], v[2:3] op_sel:[0,0] op_sel_hi:[0,1]
	s_nop 0
	v_pk_fma_f32 v[68:69], v[80:81], v[2:3], v[68:69] op_sel:[1,1,0] op_sel_hi:[1,0,1] neg_lo:[0,1,0]
	s_nop 0
	v_pk_add_f32 v[80:81], v[76:77], v[68:69]
	v_pk_add_f32 v[68:69], v[76:77], v[68:69] neg_lo:[0,1] neg_hi:[0,1]
	v_pk_mul_f32 v[76:77], v[74:75], v[4:5] op_sel:[0,0] op_sel_hi:[0,1]
	s_nop 0
	v_pk_fma_f32 v[74:75], v[74:75], v[4:5], v[76:77] op_sel:[1,1,0] op_sel_hi:[1,0,1] neg_lo:[0,1,0]
	s_nop 0
	v_pk_add_f32 v[76:77], v[70:71], v[74:75]
	v_pk_add_f32 v[70:71], v[70:71], v[74:75] neg_lo:[0,1] neg_hi:[0,1]
	v_pk_mul_f32 v[74:75], v[88:89], v[2:3] op_sel:[0,0] op_sel_hi:[0,1]
	s_nop 0
	v_pk_fma_f32 v[74:75], v[88:89], v[2:3], v[74:75] op_sel:[1,1,0] op_sel_hi:[1,0,1] neg_lo:[0,1,0]
	s_nop 0
	v_pk_add_f32 v[88:89], v[84:85], v[74:75]
	v_pk_add_f32 v[74:75], v[84:85], v[74:75] neg_lo:[0,1] neg_hi:[0,1]
	v_pk_mul_f32 v[84:85], v[82:83], v[4:5] op_sel:[0,0] op_sel_hi:[0,1]
	s_nop 0
; __device__ __forceinline__ float2 cmul(float2 a, float2 b) { return make_float2(a.x * b.x - a.y * b.y, a.x * b.y + a.y * b.x); }
; template <int R, bool INV>
; __device__ __forceinline__ void butterflies(c32 (&v)[1 << R], float turns0) {
;     ...
;   for (int kk = 0; kk < R; ++kk) {
;     const int k = INV ? (R - 1 - kk) : kk;
;     const int hd = RAD >> (k + 1);
; #pragma unroll
;     for (int j = 0; j < RAD; ++j) {
;       if ((j & hd) == 0) {
;         const int m = (j & (hd - 1)) * (16 / hd);
;         const float2 c = make_float2(TC[m], INV ? TS[m] : -TS[m]);
;         const float2 twf = cmul(tbs[k], c);
;         const c32 tw = {twf.x, twf.y};
;         const c32 a = v[j], b = v[j + hd];
;         if (!INV) { v[j] = a + b; v[j + hd] = cmul_pk(a - b, tw); }
;         else { const c32 bt = cmul_pk(b, tw); v[j] = a + bt; v[j + hd] = a - bt; }
;       }
	v_pk_fma_f32 v[82:83], v[82:83], v[4:5], v[84:85] op_sel:[1,1,0] op_sel_hi:[1,0,1] neg_lo:[0,1,0]
	s_nop 0
	v_pk_add_f32 v[84:85], v[78:79], v[82:83]
	v_pk_add_f32 v[78:79], v[78:79], v[82:83] neg_lo:[0,1] neg_hi:[0,1]
	v_pk_mul_f32 v[82:83], v[96:97], v[2:3] op_sel:[0,0] op_sel_hi:[0,1]
	s_nop 0
	v_pk_fma_f32 v[82:83], v[96:97], v[2:3], v[82:83] op_sel:[1,1,0] op_sel_hi:[1,0,1] neg_lo:[0,1,0]
	s_nop 0
	v_pk_add_f32 v[96:97], v[92:93], v[82:83]
	v_pk_add_f32 v[82:83], v[92:93], v[82:83] neg_lo:[0,1] neg_hi:[0,1]
	v_pk_mul_f32 v[92:93], v[90:91], v[4:5] op_sel:[0,0] op_sel_hi:[0,1]
	s_nop 0
	v_pk_fma_f32 v[90:91], v[90:91], v[4:5], v[92:93] op_sel:[1,1,0] op_sel_hi:[1,0,1] neg_lo:[0,1,0]
	s_nop 0
	v_pk_add_f32 v[92:93], v[86:87], v[90:91]
	v_pk_add_f32 v[86:87], v[86:87], v[90:91] neg_lo:[0,1] neg_hi:[0,1]
	v_pk_mul_f32 v[90:91], v[104:105], v[2:3] op_sel:[0,0] op_sel_hi:[0,1]
	s_nop 0
	v_pk_fma_f32 v[90:91], v[104:105], v[2:3], v[90:91] op_sel:[1,1,0] op_sel_hi:[1,0,1] neg_lo:[0,1,0]
	s_nop 0
	v_pk_add_f32 v[104:105], v[100:101], v[90:91]
	v_pk_add_f32 v[90:91], v[100:101], v[90:91] neg_lo:[0,1] neg_hi:[0,1]
	v_pk_mul_f32 v[100:101], v[98:99], v[4:5] op_sel:[0,0] op_sel_hi:[0,1]
	s_nop 0
	v_pk_fma_f32 v[98:99], v[98:99], v[4:5], v[100:101] op_sel:[1,1,0] op_sel_hi:[1,0,1] neg_lo:[0,1,0]
	s_nop 0
	v_pk_add_f32 v[100:101], v[94:95], v[98:99]
	v_pk_add_f32 v[94:95], v[94:95], v[98:99] neg_lo:[0,1] neg_hi:[0,1]
	v_pk_mul_f32 v[98:99], v[112:113], v[2:3] op_sel:[0,0] op_sel_hi:[0,1]
	s_nop 0
	v_pk_fma_f32 v[98:99], v[112:113], v[2:3], v[98:99] op_sel:[1,1,0] op_sel_hi:[1,0,1] neg_lo:[0,1,0]
	s_nop 0
	v_pk_add_f32 v[112:113], v[108:109], v[98:99]
	v_pk_add_f32 v[98:99], v[108:109], v[98:99] neg_lo:[0,1] neg_hi:[0,1]
	v_pk_mul_f32 v[108:109], v[106:107], v[4:5] op_sel:[0,0] op_sel_hi:[0,1]
	s_nop 0
	v_pk_fma_f32 v[106:107], v[106:107], v[4:5], v[108:109] op_sel:[1,1,0] op_sel_hi:[1,0,1] neg_lo:[0,1,0]
	s_nop 0
	v_pk_add_f32 v[108:109], v[102:103], v[106:107]
	v_pk_add_f32 v[102:103], v[102:103], v[106:107] neg_lo:[0,1] neg_hi:[0,1]
	v_pk_mul_f32 v[106:107], v[120:121], v[2:3] op_sel:[0,0] op_sel_hi:[0,1]
	s_nop 0
	v_pk_fma_f32 v[106:107], v[120:121], v[2:3], v[106:107] op_sel:[1,1,0] op_sel_hi:[1,0,1] neg_lo:[0,1,0]
	s_nop 0
	v_pk_add_f32 v[120:121], v[116:117], v[106:107]
	v_pk_add_f32 v[106:107], v[116:117], v[106:107] neg_lo:[0,1] neg_hi:[0,1]
	v_pk_mul_f32 v[116:117], v[114:115], v[4:5] op_sel:[0,0] op_sel_hi:[0,1]
	s_nop 0
	v_pk_fma_f32 v[114:115], v[114:115], v[4:5], v[116:117] op_sel:[1,1,0] op_sel_hi:[1,0,1] neg_lo:[0,1,0]
	s_nop 0
	v_pk_add_f32 v[116:117], v[110:111], v[114:115]
	v_pk_add_f32 v[110:111], v[110:111], v[114:115] neg_lo:[0,1] neg_hi:[0,1]
	v_pk_mul_f32 v[114:115], v[128:129], v[2:3] op_sel:[0,0] op_sel_hi:[0,1]
	s_nop 0
	v_pk_fma_f32 v[114:115], v[128:129], v[2:3], v[114:115] op_sel:[1,1,0] op_sel_hi:[1,0,1] neg_lo:[0,1,0]
	s_nop 0
	v_pk_add_f32 v[128:129], v[124:125], v[114:115]
	v_pk_add_f32 v[114:115], v[124:125], v[114:115] neg_lo:[0,1] neg_hi:[0,1]
	v_pk_mul_f32 v[124:125], v[122:123], v[4:5] op_sel:[0,0] op_sel_hi:[0,1]
	s_nop 0
	v_pk_fma_f32 v[122:123], v[122:123], v[4:5], v[124:125] op_sel:[1,1,0] op_sel_hi:[1,0,1] neg_lo:[0,1,0]
	s_nop 0
	v_pk_add_f32 v[124:125], v[118:119], v[122:123]
	v_pk_add_f32 v[118:119], v[118:119], v[122:123] neg_lo:[0,1] neg_hi:[0,1]
	v_pk_mul_f32 v[122:123], v[80:81], v[6:7] op_sel:[0,0] op_sel_hi:[0,1]
	s_nop 0
	v_pk_fma_f32 v[80:81], v[80:81], v[6:7], v[122:123] op_sel:[1,1,0] op_sel_hi:[1,0,1] neg_lo:[0,1,0]
	s_nop 0
	v_pk_add_f32 v[122:123], v[126:127], v[80:81]
	v_pk_add_f32 v[80:81], v[126:127], v[80:81] neg_lo:[0,1] neg_hi:[0,1]
	v_pk_mul_f32 v[126:127], v[76:77], v[10:11] op_sel:[0,0] op_sel_hi:[0,1]
	s_nop 0
	v_pk_fma_f32 v[76:77], v[76:77], v[10:11], v[126:127] op_sel:[1,1,0] op_sel_hi:[1,0,1] neg_lo:[0,1,0]
	s_nop 0
	v_pk_add_f32 v[126:127], v[130:131], v[76:77]
	v_pk_add_f32 v[76:77], v[130:131], v[76:77] neg_lo:[0,1] neg_hi:[0,1]
	v_pk_mul_f32 v[130:131], v[68:69], v[8:9] op_sel:[0,0] op_sel_hi:[0,1]
	s_nop 0
	v_pk_fma_f32 v[68:69], v[68:69], v[8:9], v[130:131] op_sel:[1,1,0] op_sel_hi:[1,0,1] neg_lo:[0,1,0]
	s_nop 0
	v_pk_add_f32 v[130:131], v[72:73], v[68:69]
	v_pk_add_f32 v[68:69], v[72:73], v[68:69] neg_lo:[0,1] neg_hi:[0,1]
	v_pk_mul_f32 v[72:73], v[70:71], v[12:13] op_sel:[0,0] op_sel_hi:[0,1]
	s_nop 0
	v_pk_fma_f32 v[70:71], v[70:71], v[12:13], v[72:73] op_sel:[1,1,0] op_sel_hi:[1,0,1] neg_lo:[0,1,0]
	s_nop 0
	v_pk_add_f32 v[72:73], v[66:67], v[70:71]
	v_pk_add_f32 v[66:67], v[66:67], v[70:71] neg_lo:[0,1] neg_hi:[0,1]
	v_pk_mul_f32 v[70:71], v[96:97], v[6:7] op_sel:[0,0] op_sel_hi:[0,1]
	s_nop 0
	v_pk_fma_f32 v[70:71], v[96:97], v[6:7], v[70:71] op_sel:[1,1,0] op_sel_hi:[1,0,1] neg_lo:[0,1,0]
	s_nop 0
	v_pk_add_f32 v[96:97], v[88:89], v[70:71]
	v_pk_add_f32 v[70:71], v[88:89], v[70:71] neg_lo:[0,1] neg_hi:[0,1]
	v_pk_mul_f32 v[88:89], v[92:93], v[10:11] op_sel:[0,0] op_sel_hi:[0,1]
	s_nop 0
	v_pk_fma_f32 v[88:89], v[92:93], v[10:11], v[88:89] op_sel:[1,1,0] op_sel_hi:[1,0,1] neg_lo:[0,1,0]
	s_nop 0
	v_pk_add_f32 v[92:93], v[84:85], v[88:89]
	v_pk_add_f32 v[84:85], v[84:85], v[88:89] neg_lo:[0,1] neg_hi:[0,1]
	v_pk_mul_f32 v[88:89], v[82:83], v[8:9] op_sel:[0,0] op_sel_hi:[0,1]
	s_nop 0
	v_pk_fma_f32 v[82:83], v[82:83], v[8:9], v[88:89] op_sel:[1,1,0] op_sel_hi:[1,0,1] neg_lo:[0,1,0]
	s_nop 0
	v_pk_add_f32 v[88:89], v[74:75], v[82:83]
	v_pk_add_f32 v[74:75], v[74:75], v[82:83] neg_lo:[0,1] neg_hi:[0,1]
	v_pk_mul_f32 v[82:83], v[86:87], v[12:13] op_sel:[0,0] op_sel_hi:[0,1]
	s_nop 0
	v_pk_fma_f32 v[82:83], v[86:87], v[12:13], v[82:83] op_sel:[1,1,0] op_sel_hi:[1,0,1] neg_lo:[0,1,0]
; __device__ __forceinline__ float2 cmul(float2 a, float2 b) { return make_float2(a.x * b.x - a.y * b.y, a.x * b.y + a.y * b.x); }
; template <int R, bool INV>
; __device__ __forceinline__ void butterflies(c32 (&v)[1 << R], float turns0) {
;     ...
;   for (int kk = 0; kk < R; ++kk) {
;     const int k = INV ? (R - 1 - kk) : kk;
;     const int hd = RAD >> (k + 1);
; #pragma unroll
;     for (int j = 0; j < RAD; ++j) {
;       if ((j & hd) == 0) {
;         const int m = (j & (hd - 1)) * (16 / hd);
;         const float2 c = make_float2(TC[m], INV ? TS[m] : -TS[m]);
;         const float2 twf = cmul(tbs[k], c);
;         const c32 tw = {twf.x, twf.y};
;         const c32 a = v[j], b = v[j + hd];
;         if (!INV) { v[j] = a + b; v[j + hd] = cmul_pk(a - b, tw); }
;         else { const c32 bt = cmul_pk(b, tw); v[j] = a + bt; v[j + hd] = a - bt; }
;       }
	s_nop 0
	v_pk_add_f32 v[86:87], v[78:79], v[82:83]
	v_pk_add_f32 v[78:79], v[78:79], v[82:83] neg_lo:[0,1] neg_hi:[0,1]
	v_pk_mul_f32 v[82:83], v[112:113], v[6:7] op_sel:[0,0] op_sel_hi:[0,1]
	s_nop 0
	v_pk_fma_f32 v[82:83], v[112:113], v[6:7], v[82:83] op_sel:[1,1,0] op_sel_hi:[1,0,1] neg_lo:[0,1,0]
	s_nop 0
	v_pk_add_f32 v[112:113], v[104:105], v[82:83]
	v_pk_add_f32 v[82:83], v[104:105], v[82:83] neg_lo:[0,1] neg_hi:[0,1]
	v_pk_mul_f32 v[104:105], v[108:109], v[10:11] op_sel:[0,0] op_sel_hi:[0,1]
	s_nop 0
	v_pk_fma_f32 v[104:105], v[108:109], v[10:11], v[104:105] op_sel:[1,1,0] op_sel_hi:[1,0,1] neg_lo:[0,1,0]
	s_nop 0
	v_pk_add_f32 v[108:109], v[100:101], v[104:105]
	v_pk_add_f32 v[100:101], v[100:101], v[104:105] neg_lo:[0,1] neg_hi:[0,1]
	v_pk_mul_f32 v[104:105], v[98:99], v[8:9] op_sel:[0,0] op_sel_hi:[0,1]
	s_nop 0
	v_pk_fma_f32 v[98:99], v[98:99], v[8:9], v[104:105] op_sel:[1,1,0] op_sel_hi:[1,0,1] neg_lo:[0,1,0]
	s_nop 0
	v_pk_add_f32 v[104:105], v[90:91], v[98:99]
	v_pk_add_f32 v[90:91], v[90:91], v[98:99] neg_lo:[0,1] neg_hi:[0,1]
	v_pk_mul_f32 v[98:99], v[102:103], v[12:13] op_sel:[0,0] op_sel_hi:[0,1]
	s_nop 0
	v_pk_fma_f32 v[98:99], v[102:103], v[12:13], v[98:99] op_sel:[1,1,0] op_sel_hi:[1,0,1] neg_lo:[0,1,0]
	s_nop 0
	v_pk_add_f32 v[102:103], v[94:95], v[98:99]
	v_pk_add_f32 v[94:95], v[94:95], v[98:99] neg_lo:[0,1] neg_hi:[0,1]
	v_pk_mul_f32 v[98:99], v[128:129], v[6:7] op_sel:[0,0] op_sel_hi:[0,1]
	s_nop 0
	v_pk_fma_f32 v[98:99], v[128:129], v[6:7], v[98:99] op_sel:[1,1,0] op_sel_hi:[1,0,1] neg_lo:[0,1,0]
	s_nop 0
	v_pk_add_f32 v[128:129], v[120:121], v[98:99]
	v_pk_add_f32 v[98:99], v[120:121], v[98:99] neg_lo:[0,1] neg_hi:[0,1]
	v_pk_mul_f32 v[120:121], v[124:125], v[10:11] op_sel:[0,0] op_sel_hi:[0,1]
	s_nop 0
	v_pk_fma_f32 v[120:121], v[124:125], v[10:11], v[120:121] op_sel:[1,1,0] op_sel_hi:[1,0,1] neg_lo:[0,1,0]
	s_nop 0
	v_pk_add_f32 v[124:125], v[116:117], v[120:121]
	v_pk_add_f32 v[116:117], v[116:117], v[120:121] neg_lo:[0,1] neg_hi:[0,1]
	v_pk_mul_f32 v[120:121], v[114:115], v[8:9] op_sel:[0,0] op_sel_hi:[0,1]
	s_nop 0
	v_pk_fma_f32 v[114:115], v[114:115], v[8:9], v[120:121] op_sel:[1,1,0] op_sel_hi:[1,0,1] neg_lo:[0,1,0]
	s_nop 0
	v_pk_add_f32 v[120:121], v[106:107], v[114:115]
	v_pk_add_f32 v[106:107], v[106:107], v[114:115] neg_lo:[0,1] neg_hi:[0,1]
	v_pk_mul_f32 v[114:115], v[118:119], v[12:13] op_sel:[0,0] op_sel_hi:[0,1]
	s_nop 0
	v_pk_fma_f32 v[114:115], v[118:119], v[12:13], v[114:115] op_sel:[1,1,0] op_sel_hi:[1,0,1] neg_lo:[0,1,0]
	s_nop 0
	v_pk_add_f32 v[118:119], v[110:111], v[114:115]
	v_pk_add_f32 v[110:111], v[110:111], v[114:115] neg_lo:[0,1] neg_hi:[0,1]
	v_pk_mul_f32 v[114:115], v[96:97], v[14:15] op_sel:[0,0] op_sel_hi:[0,1]
	s_nop 0
	v_pk_fma_f32 v[96:97], v[96:97], v[14:15], v[114:115] op_sel:[1,1,0] op_sel_hi:[1,0,1] neg_lo:[0,1,0]
	s_nop 0
	v_pk_add_f32 v[114:115], v[122:123], v[96:97]
	v_pk_add_f32 v[96:97], v[122:123], v[96:97] neg_lo:[0,1] neg_hi:[0,1]
	v_pk_mul_f32 v[122:123], v[92:93], v[22:23] op_sel:[0,0] op_sel_hi:[0,1]
	s_nop 0
	v_pk_fma_f32 v[92:93], v[92:93], v[22:23], v[122:123] op_sel:[1,1,0] op_sel_hi:[1,0,1] neg_lo:[0,1,0]
	s_nop 0
	v_pk_add_f32 v[122:123], v[126:127], v[92:93]
	v_pk_add_f32 v[92:93], v[126:127], v[92:93] neg_lo:[0,1] neg_hi:[0,1]
	v_pk_mul_f32 v[126:127], v[88:89], v[18:19] op_sel:[0,0] op_sel_hi:[0,1]
	s_nop 0
	v_pk_fma_f32 v[88:89], v[88:89], v[18:19], v[126:127] op_sel:[1,1,0] op_sel_hi:[1,0,1] neg_lo:[0,1,0]
	s_nop 0
	v_pk_add_f32 v[126:127], v[130:131], v[88:89]
	v_pk_add_f32 v[88:89], v[130:131], v[88:89] neg_lo:[0,1] neg_hi:[0,1]
	v_pk_mul_f32 v[130:131], v[86:87], v[28:29] op_sel:[0,0] op_sel_hi:[0,1]
	s_nop 0
	v_pk_fma_f32 v[86:87], v[86:87], v[28:29], v[130:131] op_sel:[1,1,0] op_sel_hi:[1,0,1] neg_lo:[0,1,0]
	s_nop 0
	v_pk_add_f32 v[130:131], v[72:73], v[86:87]
	v_pk_add_f32 v[72:73], v[72:73], v[86:87] neg_lo:[0,1] neg_hi:[0,1]
	v_pk_mul_f32 v[86:87], v[70:71], v[16:17] op_sel:[0,0] op_sel_hi:[0,1]
	s_nop 0
	v_pk_fma_f32 v[70:71], v[70:71], v[16:17], v[86:87] op_sel:[1,1,0] op_sel_hi:[1,0,1] neg_lo:[0,1,0]
	s_nop 0
	v_pk_add_f32 v[86:87], v[80:81], v[70:71]
	v_pk_add_f32 v[70:71], v[80:81], v[70:71] neg_lo:[0,1] neg_hi:[0,1]
	v_pk_mul_f32 v[80:81], v[84:85], v[26:27] op_sel:[0,0] op_sel_hi:[0,1]
	s_nop 0
	v_pk_fma_f32 v[80:81], v[84:85], v[26:27], v[80:81] op_sel:[1,1,0] op_sel_hi:[1,0,1] neg_lo:[0,1,0]
	s_nop 0
	v_pk_add_f32 v[84:85], v[76:77], v[80:81]
	v_pk_add_f32 v[76:77], v[76:77], v[80:81] neg_lo:[0,1] neg_hi:[0,1]
	v_pk_mul_f32 v[80:81], v[74:75], v[20:21] op_sel:[0,0] op_sel_hi:[0,1]
	s_nop 0
	v_pk_fma_f32 v[74:75], v[74:75], v[20:21], v[80:81] op_sel:[1,1,0] op_sel_hi:[1,0,1] neg_lo:[0,1,0]
	s_nop 0
	v_pk_add_f32 v[80:81], v[68:69], v[74:75]
	v_pk_add_f32 v[68:69], v[68:69], v[74:75] neg_lo:[0,1] neg_hi:[0,1]
	v_pk_mul_f32 v[74:75], v[78:79], v[24:25] op_sel:[0,0] op_sel_hi:[0,1]
	s_nop 0
	v_pk_fma_f32 v[74:75], v[78:79], v[24:25], v[74:75] op_sel:[1,1,0] op_sel_hi:[1,0,1] neg_lo:[0,1,0]
	s_nop 0
	v_pk_add_f32 v[78:79], v[66:67], v[74:75]
	v_pk_add_f32 v[66:67], v[66:67], v[74:75] neg_lo:[0,1] neg_hi:[0,1]
	v_pk_mul_f32 v[74:75], v[128:129], v[14:15] op_sel:[0,0] op_sel_hi:[0,1]
	s_nop 0
	v_pk_fma_f32 v[74:75], v[128:129], v[14:15], v[74:75] op_sel:[1,1,0] op_sel_hi:[1,0,1] neg_lo:[0,1,0]
	s_nop 0
	v_pk_add_f32 v[128:129], v[112:113], v[74:75]
	v_pk_add_f32 v[74:75], v[112:113], v[74:75] neg_lo:[0,1] neg_hi:[0,1]
	v_pk_mul_f32 v[112:113], v[124:125], v[22:23] op_sel:[0,0] op_sel_hi:[0,1]
	s_nop 0
	v_pk_fma_f32 v[112:113], v[124:125], v[22:23], v[112:113] op_sel:[1,1,0] op_sel_hi:[1,0,1] neg_lo:[0,1,0]
	s_nop 0
; __device__ __forceinline__ float2 cmul(float2 a, float2 b) { return make_float2(a.x * b.x - a.y * b.y, a.x * b.y + a.y * b.x); }
; template <int R, bool INV>
; __device__ __forceinline__ void butterflies(c32 (&v)[1 << R], float turns0) {
;     ...
;   for (int kk = 0; kk < R; ++kk) {
;     const int k = INV ? (R - 1 - kk) : kk;
;     const int hd = RAD >> (k + 1);
; #pragma unroll
;     for (int j = 0; j < RAD; ++j) {
;       if ((j & hd) == 0) {
;         const int m = (j & (hd - 1)) * (16 / hd);
;         const float2 c = make_float2(TC[m], INV ? TS[m] : -TS[m]);
;         const float2 twf = cmul(tbs[k], c);
;         const c32 tw = {twf.x, twf.y};
;         const c32 a = v[j], b = v[j + hd];
;         if (!INV) { v[j] = a + b; v[j + hd] = cmul_pk(a - b, tw); }
;         else { const c32 bt = cmul_pk(b, tw); v[j] = a + bt; v[j + hd] = a - bt; }
;       }
	v_pk_add_f32 v[124:125], v[108:109], v[112:113]
	v_pk_add_f32 v[108:109], v[108:109], v[112:113] neg_lo:[0,1] neg_hi:[0,1]
	v_pk_mul_f32 v[112:113], v[120:121], v[18:19] op_sel:[0,0] op_sel_hi:[0,1]
	s_nop 0
	v_pk_fma_f32 v[112:113], v[120:121], v[18:19], v[112:113] op_sel:[1,1,0] op_sel_hi:[1,0,1] neg_lo:[0,1,0]
	s_nop 0
	v_pk_add_f32 v[120:121], v[104:105], v[112:113]
	v_pk_add_f32 v[104:105], v[104:105], v[112:113] neg_lo:[0,1] neg_hi:[0,1]
	v_pk_mul_f32 v[112:113], v[118:119], v[28:29] op_sel:[0,0] op_sel_hi:[0,1]
	s_nop 0
	v_pk_fma_f32 v[112:113], v[118:119], v[28:29], v[112:113] op_sel:[1,1,0] op_sel_hi:[1,0,1] neg_lo:[0,1,0]
	s_nop 0
	v_pk_add_f32 v[118:119], v[102:103], v[112:113]
	v_pk_add_f32 v[102:103], v[102:103], v[112:113] neg_lo:[0,1] neg_hi:[0,1]
	v_pk_mul_f32 v[112:113], v[98:99], v[16:17] op_sel:[0,0] op_sel_hi:[0,1]
	s_nop 0
	v_pk_fma_f32 v[98:99], v[98:99], v[16:17], v[112:113] op_sel:[1,1,0] op_sel_hi:[1,0,1] neg_lo:[0,1,0]
	s_nop 0
	v_pk_add_f32 v[112:113], v[82:83], v[98:99]
	v_pk_add_f32 v[82:83], v[82:83], v[98:99] neg_lo:[0,1] neg_hi:[0,1]
	v_pk_mul_f32 v[98:99], v[116:117], v[26:27] op_sel:[0,0] op_sel_hi:[0,1]
	s_nop 0
	v_pk_fma_f32 v[98:99], v[116:117], v[26:27], v[98:99] op_sel:[1,1,0] op_sel_hi:[1,0,1] neg_lo:[0,1,0]
	s_nop 0
	v_pk_add_f32 v[116:117], v[100:101], v[98:99]
	v_pk_add_f32 v[98:99], v[100:101], v[98:99] neg_lo:[0,1] neg_hi:[0,1]
	v_pk_mul_f32 v[100:101], v[106:107], v[20:21] op_sel:[0,0] op_sel_hi:[0,1]
	s_nop 0
	v_pk_fma_f32 v[100:101], v[106:107], v[20:21], v[100:101] op_sel:[1,1,0] op_sel_hi:[1,0,1] neg_lo:[0,1,0]
	s_nop 0
	v_pk_add_f32 v[106:107], v[90:91], v[100:101]
	v_pk_add_f32 v[90:91], v[90:91], v[100:101] neg_lo:[0,1] neg_hi:[0,1]
	v_pk_mul_f32 v[100:101], v[110:111], v[24:25] op_sel:[0,0] op_sel_hi:[0,1]
	s_nop 0
	v_pk_fma_f32 v[100:101], v[110:111], v[24:25], v[100:101] op_sel:[1,1,0] op_sel_hi:[1,0,1] neg_lo:[0,1,0]
	s_nop 0
	v_pk_add_f32 v[110:111], v[94:95], v[100:101]
	v_pk_add_f32 v[94:95], v[94:95], v[100:101] neg_lo:[0,1] neg_hi:[0,1]
	v_pk_mul_f32 v[100:101], v[128:129], v[30:31] op_sel:[0,0] op_sel_hi:[0,1]
	s_nop 0
	v_pk_fma_f32 v[100:101], v[128:129], v[30:31], v[100:101] op_sel:[1,1,0] op_sel_hi:[1,0,1] neg_lo:[0,1,0]
	s_nop 0
	v_pk_add_f32 v[128:129], v[114:115], v[100:101]
	v_pk_add_f32 v[100:101], v[114:115], v[100:101] neg_lo:[0,1] neg_hi:[0,1]
	v_pk_mul_f32 v[114:115], v[124:125], v[56:57] op_sel:[0,0] op_sel_hi:[0,1]
	s_nop 0
	v_pk_fma_f32 v[114:115], v[124:125], v[56:57], v[114:115] op_sel:[1,1,0] op_sel_hi:[1,0,1] neg_lo:[0,1,0]
	s_nop 0
	v_pk_add_f32 v[124:125], v[122:123], v[114:115]
	v_pk_add_f32 v[114:115], v[122:123], v[114:115] neg_lo:[0,1] neg_hi:[0,1]
	v_pk_mul_f32 v[122:123], v[120:121], v[48:49] op_sel:[0,0] op_sel_hi:[0,1]
	s_nop 0
	v_pk_fma_f32 v[120:121], v[120:121], v[48:49], v[122:123] op_sel:[1,1,0] op_sel_hi:[1,0,1] neg_lo:[0,1,0]
	s_nop 0
	v_pk_add_f32 v[122:123], v[126:127], v[120:121]
	v_pk_add_f32 v[120:121], v[126:127], v[120:121] neg_lo:[0,1] neg_hi:[0,1]
	v_pk_mul_f32 v[126:127], v[118:119], v[40:41] op_sel:[0,0] op_sel_hi:[0,1]
	s_nop 0
	v_pk_fma_f32 v[118:119], v[118:119], v[40:41], v[126:127] op_sel:[1,1,0] op_sel_hi:[1,0,1] neg_lo:[0,1,0]
	s_nop 0
	v_pk_add_f32 v[126:127], v[130:131], v[118:119]
	v_pk_add_f32 v[118:119], v[130:131], v[118:119] neg_lo:[0,1] neg_hi:[0,1]
	v_pk_mul_f32 v[130:131], v[112:113], v[36:37] op_sel:[0,0] op_sel_hi:[0,1]
	s_nop 0
	v_pk_fma_f32 v[112:113], v[112:113], v[36:37], v[130:131] op_sel:[1,1,0] op_sel_hi:[1,0,1] neg_lo:[0,1,0]
	s_nop 0
	v_pk_add_f32 v[130:131], v[86:87], v[112:113]
	v_pk_add_f32 v[86:87], v[86:87], v[112:113] neg_lo:[0,1] neg_hi:[0,1]
	v_pk_mul_f32 v[112:113], v[116:117], v[46:47] op_sel:[0,0] op_sel_hi:[0,1]
	s_nop 0
	v_pk_fma_f32 v[112:113], v[116:117], v[46:47], v[112:113] op_sel:[1,1,0] op_sel_hi:[1,0,1] neg_lo:[0,1,0]
	s_nop 0
	v_pk_add_f32 v[116:117], v[84:85], v[112:113]
	v_pk_add_f32 v[84:85], v[84:85], v[112:113] neg_lo:[0,1] neg_hi:[0,1]
	v_pk_mul_f32 v[112:113], v[106:107], v[54:55] op_sel:[0,0] op_sel_hi:[0,1]
	s_nop 0
; __device__ __forceinline__ float2 cmul(float2 a, float2 b) { return make_float2(a.x * b.x - a.y * b.y, a.x * b.y + a.y * b.x); }
; template <int R, bool INV>
; __device__ __forceinline__ void butterflies(c32 (&v)[1 << R], float turns0) {
;     ...
;     for (int j = 0; j < RAD; ++j) {
;       if ((j & hd) == 0) {
;         const int m = (j & (hd - 1)) * (16 / hd);
;         const float2 c = make_float2(TC[m], INV ? TS[m] : -TS[m]);
;         const float2 twf = cmul(tbs[k], c);
;         const c32 tw = {twf.x, twf.y};
;         const c32 a = v[j], b = v[j + hd];
;         if (!INV) { v[j] = a + b; v[j + hd] = cmul_pk(a - b, tw); }
;         else { const c32 bt = cmul_pk(b, tw); v[j] = a + bt; v[j + hd] = a - bt; }
;       }
; template <int LOGN, int R, int DLOG, bool INV, int MODE, class F>
; __device__ __forceinline__ void fft_pass(float2* X, const F& f) {
;     ...
;       for (int j = 0; j < RAD; ++j) Xc[(DLOG >= 5) ? pb + j * PSTEP : phys(base + (j << DLOG))] = v[j];
;     }
;   }
	v_pk_fma_f32 v[106:107], v[106:107], v[54:55], v[112:113] op_sel:[1,1,0] op_sel_hi:[1,0,1] neg_lo:[0,1,0]
	s_nop 0
	v_pk_add_f32 v[112:113], v[80:81], v[106:107]
	v_pk_add_f32 v[80:81], v[80:81], v[106:107] neg_lo:[0,1] neg_hi:[0,1]
	v_pk_mul_f32 v[106:107], v[110:111], v[62:63] op_sel:[0,0] op_sel_hi:[0,1]
	s_nop 0
	v_pk_fma_f32 v[106:107], v[110:111], v[62:63], v[106:107] op_sel:[1,1,0] op_sel_hi:[1,0,1] neg_lo:[0,1,0]
	s_nop 0
	v_pk_add_f32 v[110:111], v[78:79], v[106:107]
	v_pk_add_f32 v[78:79], v[78:79], v[106:107] neg_lo:[0,1] neg_hi:[0,1]
	v_pk_mul_f32 v[106:107], v[74:75], v[34:35] op_sel:[0,0] op_sel_hi:[0,1]
	s_nop 0
	v_pk_fma_f32 v[74:75], v[74:75], v[34:35], v[106:107] op_sel:[1,1,0] op_sel_hi:[1,0,1] neg_lo:[0,1,0]
	s_nop 0
	v_pk_add_f32 v[106:107], v[96:97], v[74:75]
	v_pk_add_f32 v[74:75], v[96:97], v[74:75] neg_lo:[0,1] neg_hi:[0,1]
	v_pk_mul_f32 v[96:97], v[108:109], v[60:61] op_sel:[0,0] op_sel_hi:[0,1]
	s_nop 0
	v_pk_fma_f32 v[96:97], v[108:109], v[60:61], v[96:97] op_sel:[1,1,0] op_sel_hi:[1,0,1] neg_lo:[0,1,0]
	s_nop 0
	v_pk_add_f32 v[108:109], v[92:93], v[96:97]
	v_pk_add_f32 v[92:93], v[92:93], v[96:97] neg_lo:[0,1] neg_hi:[0,1]
	v_pk_mul_f32 v[96:97], v[104:105], v[52:53] op_sel:[0,0] op_sel_hi:[0,1]
	s_nop 0
	v_pk_fma_f32 v[96:97], v[104:105], v[52:53], v[96:97] op_sel:[1,1,0] op_sel_hi:[1,0,1] neg_lo:[0,1,0]
	s_nop 0
	v_pk_add_f32 v[104:105], v[88:89], v[96:97]
	v_pk_add_f32 v[88:89], v[88:89], v[96:97] neg_lo:[0,1] neg_hi:[0,1]
	v_pk_mul_f32 v[96:97], v[102:103], v[44:45] op_sel:[0,0] op_sel_hi:[0,1]
	s_nop 0
	v_pk_fma_f32 v[96:97], v[102:103], v[44:45], v[96:97] op_sel:[1,1,0] op_sel_hi:[1,0,1] neg_lo:[0,1,0]
	s_nop 0
	v_pk_add_f32 v[102:103], v[72:73], v[96:97]
	v_pk_add_f32 v[72:73], v[72:73], v[96:97] neg_lo:[0,1] neg_hi:[0,1]
	v_pk_mul_f32 v[96:97], v[82:83], v[38:39] op_sel:[0,0] op_sel_hi:[0,1]
	s_nop 0
	v_pk_fma_f32 v[82:83], v[82:83], v[38:39], v[96:97] op_sel:[1,1,0] op_sel_hi:[1,0,1] neg_lo:[0,1,0]
	s_nop 0
	v_pk_add_f32 v[96:97], v[70:71], v[82:83]
	v_pk_add_f32 v[70:71], v[70:71], v[82:83] neg_lo:[0,1] neg_hi:[0,1]
	v_pk_mul_f32 v[82:83], v[98:99], v[42:43] op_sel:[0,0] op_sel_hi:[0,1]
	s_nop 0
	v_pk_fma_f32 v[82:83], v[98:99], v[42:43], v[82:83] op_sel:[1,1,0] op_sel_hi:[1,0,1] neg_lo:[0,1,0]
	s_nop 0
	v_pk_add_f32 v[98:99], v[76:77], v[82:83]
	v_pk_add_f32 v[76:77], v[76:77], v[82:83] neg_lo:[0,1] neg_hi:[0,1]
	v_pk_mul_f32 v[82:83], v[90:91], v[50:51] op_sel:[0,0] op_sel_hi:[0,1]
	s_nop 0
	v_pk_fma_f32 v[82:83], v[90:91], v[50:51], v[82:83] op_sel:[1,1,0] op_sel_hi:[1,0,1] neg_lo:[0,1,0]
	s_nop 0
	v_pk_add_f32 v[90:91], v[68:69], v[82:83]
	v_pk_add_f32 v[68:69], v[68:69], v[82:83] neg_lo:[0,1] neg_hi:[0,1]
	v_pk_mul_f32 v[82:83], v[94:95], v[58:59] op_sel:[0,0] op_sel_hi:[0,1]
	s_nop 0
	v_pk_fma_f32 v[82:83], v[94:95], v[58:59], v[82:83] op_sel:[1,1,0] op_sel_hi:[1,0,1] neg_lo:[0,1,0]
	s_nop 0
	v_pk_add_f32 v[94:95], v[66:67], v[82:83]
	v_pk_add_f32 v[66:67], v[66:67], v[82:83] neg_lo:[0,1] neg_hi:[0,1]
	ds_write2_b64 v132, v[128:129], v[124:125] offset1:33
	ds_write2_b64 v132, v[122:123], v[126:127] offset0:66 offset1:99
	ds_write2_b64 v132, v[130:131], v[116:117] offset0:132 offset1:165
	ds_write2_b64 v132, v[112:113], v[110:111] offset0:198 offset1:231
	ds_write2_b64 v133, v[106:107], v[108:109] offset0:8 offset1:41
	ds_write2_b64 v133, v[104:105], v[102:103] offset0:74 offset1:107
	ds_write2_b64 v133, v[96:97], v[98:99] offset0:140 offset1:173
	ds_write2_b64 v133, v[90:91], v[94:95] offset0:206 offset1:239
	ds_write2_b64 v134, v[100:101], v[114:115] offset0:16 offset1:49
	ds_write2_b64 v134, v[120:121], v[118:119] offset0:82 offset1:115
	ds_write2_b64 v134, v[86:87], v[84:85] offset0:148 offset1:181
	ds_write2_b64 v134, v[80:81], v[78:79] offset0:214 offset1:247
	ds_write2_b64 v135, v[74:75], v[92:93] offset0:24 offset1:57
	ds_write2_b64 v135, v[88:89], v[72:73] offset0:90 offset1:123
	ds_write2_b64 v135, v[70:71], v[76:77] offset0:156 offset1:189
	ds_write2_b64 v135, v[68:69], v[66:67] offset0:222 offset1:255
	s_andn2_b64 exec, exec, s[40:41]
	s_cbranch_execnz .LBB0_1066
